# GEMM K-loops: removed the s_setprio 0/1 pair between the two 16-MFMA groups and the redundant post-barrier lgkmcnt(0) (no issue slots between MFMAs); plus stack2
# speedup vs baseline: 1.0092x; 1.0083x over previous
; #define PG8_STAGE(bufoff, gbase, voff) do { _Pragma("unroll") for (int _i = 0; _i < 2; ++_i) \
;         __builtin_amdgcn_global_load_lds((const unsigned*)((const char*)(gbase) + (voff)[_i]), (PG8_LAS unsigned*)(lds + (bufoff) + ldsw + _i * 8192), 16, 0, 0); } while (0)
; #define PG8_LDA(dst, b, h) do { _Pragma("unroll") for (int m = 0; m < 4; ++m) _Pragma("unroll") for (int k = 0; k < 2; ++k) dst[m][k] = *(const PG8_LAS bf16x8*)(lds + PG8_SA(b, h) + aoff + m * 2048 + k * 1024); } while (0)
; #define PG8_LDB(dst, b, h) do { _Pragma("unroll") for (int n = 0; n < 2; ++n) _Pragma("unroll") for (int k = 0; k < 2; ++k) dst[n][k] = *(const PG8_LAS bf16x8*)(lds + PG8_SB(b, h) + boff + n * 2048 + k * 1024); } while (0)
; #define PG8_MMA(ai, bj, At, Bt) do { __builtin_amdgcn_s_setprio(1); _Pragma("unroll") for (int m = 0; m < 4; ++m) _Pragma("unroll") for (int n = 0; n < 2; ++n) _Pragma("unroll") for (int k = 0; k < 2; ++k) \
;         acc[ai][bj][m][n] = __builtin_amdgcn_mfma_f32_16x16x32_bf16(Bt[n][k], At[m][k], acc[ai][bj][m][n], 0, 0, 0); __builtin_amdgcn_s_setprio(0); } while (0)
; #define PG8_WAIT_V(n) asm volatile("s_waitcnt vmcnt(" #n ")" ::: "memory")
; #define PG8_WAIT_L(n) asm volatile("s_waitcnt lgkmcnt(" #n ")" ::: "memory")
; template <class Epi, class Sched, bool ALIGN_EPI = false, bool SP2 = false>
; __device__ __forceinline__ void gemm_phase(PG8_LAS unsigned char* lds, const Gemm g, const Sched& S, const Epi& E) {
;     ...
;             const bool last = (t == nt - 2);
;             const char* a1 = cA + PG8_AK(t + 1);
;             const char* a2 = last ? nA : cA + PG8_AK(t + 2); const char* b2 = last ? nB : cB + (size_t)(t + 2) * kstep;
;             const char* a3 = last ? nA + PG8_AK(1) : cA + PG8_AK(t + 3); const char* b3 = b2 + kstep;
;             if (last && has_next) S.a_ready(nxt);
;             if constexpr (SP2) {
;             PG8_LDB(B0, 0, 0); PG8_LDB(B1, 0, 1); PG8_SCHED; PG8_LDA(At, 0, 0); PG8_STAGE(PG8_SA(1, 1), a1 + hstepA, voffA);
;             PG8_WAIT_V(8); PG8_WAIT_L(0); PG8_BAR; PG8_MMA(0, 0, At, B0); PG8_MMA(0, 1, At, B1); PG8_BAR; PG8_SCHED;
;             PG8_LDA(At, 0, 1); PG8_STAGE(PG8_SB(0, 0), b2, voffB); PG8_STAGE(PG8_SB(0, 1), b2 + hstepB, voffB); PG8_STAGE(PG8_SA(0, 0), a2, voffA);
;             PG8_WAIT_V(8); PG8_WAIT_L(0); PG8_BAR; PG8_MMA(1, 0, At, B0); PG8_MMA(1, 1, At, B1); PG8_BAR; PG8_SCHED;
.LBB0_129:
	ds_read_b128 v[132:135], v172
	ds_read_b128 v[158:161], v172 offset:1024
	ds_read_b128 v[176:179], v172 offset:2048
	ds_read_b128 v[180:183], v172 offset:3072
	ds_read_b128 v[184:187], v173
	ds_read_b128 v[188:191], v173 offset:1024
	ds_read_b128 v[192:195], v173 offset:2048
	ds_read_b128 v[196:199], v173 offset:3072
	s_add_u32 s38, s28, s34
	s_addc_u32 s39, s29, s35
	s_add_u32 s42, s38, 0x100
	s_addc_u32 s43, s39, 0
	s_add_u32 s40, s62, s34
	s_addc_u32 s41, s63, s35
	s_add_u32 s38, s38, 0x180
	s_addc_u32 s39, s39, 0
	s_cmpk_eq_i32 s34, 0x700
	s_cselect_b32 s39, s37, s39
	s_cselect_b32 s38, s31, s38
	s_cselect_b32 s41, s21, s41
	s_cselect_b32 s40, s23, s40
	s_cselect_b32 s43, s3, s43
	s_cselect_b32 s42, s10, s42
	v_lshl_add_u64 v[204:205], v[130:131], 0, s[34:35]
	s_add_i32 m0, s49, 0xc000
	ds_read_b128 v[200:203], v174
	ds_read_b128 v[208:211], v174 offset:1024
	ds_read_b128 v[212:215], v174 offset:2048
	ds_read_b128 v[216:219], v174 offset:3072
	ds_read_b128 v[220:223], v174 offset:4096
	ds_read_b128 v[224:227], v174 offset:5120
	ds_read_b128 v[228:231], v174 offset:6144
	ds_read_b128 v[232:235], v174 offset:7168
	global_load_lds_dwordx4 v[204:205], off
	v_lshl_add_u64 v[204:205], v[128:129], 0, s[34:35]
	s_add_i32 m0, s49, 0xe000
	s_nop 0
	global_load_lds_dwordx4 v[204:205], off
	s_waitcnt vmcnt(8)
	s_waitcnt lgkmcnt(0)
	s_barrier
	s_setprio 1
	v_mfma_f32_16x16x32_bf16 v[124:127], v[132:135], v[200:203], v[124:127]
	v_mfma_f32_16x16x32_bf16 v[120:123], v[176:179], v[200:203], v[120:123]
	v_mfma_f32_16x16x32_bf16 v[108:111], v[132:135], v[212:215], v[108:111]
	v_mfma_f32_16x16x32_bf16 v[104:107], v[176:179], v[212:215], v[104:107]
	v_mfma_f32_16x16x32_bf16 v[92:95], v[132:135], v[220:223], v[92:95]
	v_mfma_f32_16x16x32_bf16 v[88:91], v[176:179], v[220:223], v[88:91]
	v_mfma_f32_16x16x32_bf16 v[76:79], v[132:135], v[228:231], v[76:79]
	v_mfma_f32_16x16x32_bf16 v[72:75], v[176:179], v[228:231], v[72:75]
	v_mfma_f32_16x16x32_bf16 v[124:127], v[158:161], v[208:211], v[124:127]
	v_mfma_f32_16x16x32_bf16 v[120:123], v[180:183], v[208:211], v[120:123]
	v_mfma_f32_16x16x32_bf16 v[108:111], v[158:161], v[216:219], v[108:111]
	v_mfma_f32_16x16x32_bf16 v[104:107], v[180:183], v[216:219], v[104:107]
	v_mfma_f32_16x16x32_bf16 v[92:95], v[158:161], v[224:227], v[92:95]
	v_mfma_f32_16x16x32_bf16 v[88:91], v[180:183], v[224:227], v[88:91]
	v_mfma_f32_16x16x32_bf16 v[76:79], v[158:161], v[232:235], v[76:79]
	v_mfma_f32_16x16x32_bf16 v[72:75], v[180:183], v[232:235], v[72:75]
	v_mfma_f32_16x16x32_bf16 v[116:119], v[184:187], v[200:203], v[116:119]
	v_mfma_f32_16x16x32_bf16 v[112:115], v[192:195], v[200:203], v[112:115]
	v_mfma_f32_16x16x32_bf16 v[100:103], v[184:187], v[212:215], v[100:103]
	v_mfma_f32_16x16x32_bf16 v[96:99], v[192:195], v[212:215], v[96:99]
	v_mfma_f32_16x16x32_bf16 v[84:87], v[184:187], v[220:223], v[84:87]
	v_mfma_f32_16x16x32_bf16 v[80:83], v[192:195], v[220:223], v[80:83]
	v_mfma_f32_16x16x32_bf16 v[68:71], v[184:187], v[228:231], v[68:71]
	v_mfma_f32_16x16x32_bf16 v[64:67], v[192:195], v[228:231], v[64:67]
	v_mfma_f32_16x16x32_bf16 v[116:119], v[188:191], v[208:211], v[116:119]
	v_mfma_f32_16x16x32_bf16 v[112:115], v[196:199], v[208:211], v[112:115]
	v_mfma_f32_16x16x32_bf16 v[100:103], v[188:191], v[216:219], v[100:103]
	v_mfma_f32_16x16x32_bf16 v[96:99], v[196:199], v[216:219], v[96:99]
	v_mfma_f32_16x16x32_bf16 v[84:87], v[188:191], v[224:227], v[84:87]
	v_mfma_f32_16x16x32_bf16 v[80:83], v[196:199], v[224:227], v[80:83]
	v_mfma_f32_16x16x32_bf16 v[68:71], v[188:191], v[232:235], v[68:71]
	v_mfma_f32_16x16x32_bf16 v[64:67], v[196:199], v[232:235], v[64:67]
	s_setprio 0
	s_barrier
	s_add_i32 s65, s58, s48
	v_lshl_add_u64 v[204:205], s[40:41], 0, v[138:139]
	s_mov_b32 m0, s65
	ds_read_b128 v[200:203], v174 offset:16384
	ds_read_b128 v[208:211], v174 offset:17408
	ds_read_b128 v[212:215], v174 offset:18432
	ds_read_b128 v[216:219], v174 offset:19456
	ds_read_b128 v[220:223], v174 offset:20480
	ds_read_b128 v[224:227], v174 offset:21504
	ds_read_b128 v[228:231], v174 offset:22528
	ds_read_b128 v[232:235], v174 offset:23552
	global_load_lds_dwordx4 v[204:205], off
	s_add_i32 m0, s65, 0x2000
	s_add_u32 s66, s40, 0x40000
	v_lshl_add_u64 v[206:207], s[40:41], 0, v[142:143]
	s_addc_u32 s67, s41, 0
	s_add_i32 s65, s59, s48
	global_load_lds_dwordx4 v[206:207], off
	v_lshl_add_u64 v[236:237], s[66:67], 0, v[138:139]
	s_mov_b32 m0, s65
	s_nop 0
	global_load_lds_dwordx4 v[236:237], off
	v_lshl_add_u64 v[236:237], s[66:67], 0, v[142:143]
	s_add_i32 m0, s65, 0x2000
	s_nop 0
	global_load_lds_dwordx4 v[236:237], off
	v_lshl_add_u64 v[236:237], s[42:43], 0, v[136:137]
	s_mov_b32 m0, s49
	s_nop 0
	global_load_lds_dwordx4 v[236:237], off
	v_lshl_add_u64 v[236:237], s[42:43], 0, v[140:141]
	s_mov_b32 m0, s50
	s_nop 0
	global_load_lds_dwordx4 v[236:237], off
	s_waitcnt vmcnt(8)
	s_waitcnt lgkmcnt(0)
	s_barrier
; #define PG8_STAGE(bufoff, gbase, voff) do { _Pragma("unroll") for (int _i = 0; _i < 2; ++_i) \
;         __builtin_amdgcn_global_load_lds((const unsigned*)((const char*)(gbase) + (voff)[_i]), (PG8_LAS unsigned*)(lds + (bufoff) + ldsw + _i * 8192), 16, 0, 0); } while (0)
; #define PG8_LDA(dst, b, h) do { _Pragma("unroll") for (int m = 0; m < 4; ++m) _Pragma("unroll") for (int k = 0; k < 2; ++k) dst[m][k] = *(const PG8_LAS bf16x8*)(lds + PG8_SA(b, h) + aoff + m * 2048 + k * 1024); } while (0)
; #define PG8_LDB(dst, b, h) do { _Pragma("unroll") for (int n = 0; n < 2; ++n) _Pragma("unroll") for (int k = 0; k < 2; ++k) dst[n][k] = *(const PG8_LAS bf16x8*)(lds + PG8_SB(b, h) + boff + n * 2048 + k * 1024); } while (0)
; #define PG8_MMA(ai, bj, At, Bt) do { __builtin_amdgcn_s_setprio(1); _Pragma("unroll") for (int m = 0; m < 4; ++m) _Pragma("unroll") for (int n = 0; n < 2; ++n) _Pragma("unroll") for (int k = 0; k < 2; ++k) \
;         acc[ai][bj][m][n] = __builtin_amdgcn_mfma_f32_16x16x32_bf16(Bt[n][k], At[m][k], acc[ai][bj][m][n], 0, 0, 0); __builtin_amdgcn_s_setprio(0); } while (0)
; #define PG8_WAIT_V(n) asm volatile("s_waitcnt vmcnt(" #n ")" ::: "memory")
; #define PG8_WAIT_L(n) asm volatile("s_waitcnt lgkmcnt(" #n ")" ::: "memory")
; #define PG8_BAR __builtin_amdgcn_s_barrier()
; #define PG8_SCHED __builtin_amdgcn_sched_barrier(0)
; template <class Epi, class Sched, bool ALIGN_EPI = false, bool SP2 = false>
; __device__ __forceinline__ void gemm_phase(PG8_LAS unsigned char* lds, const Gemm g, const Sched& S, const Epi& E) {
;     ...
;             PG8_WAIT_V(8); PG8_WAIT_L(0); PG8_BAR; PG8_MMA(1, 0, At, B0); PG8_MMA(1, 1, At, B1); PG8_BAR; PG8_SCHED;
;             PG8_LDB(B0, 1, 0); PG8_LDB(B1, 1, 1); PG8_SCHED; PG8_LDA(At, 1, 0); PG8_STAGE(PG8_SA(0, 1), a2 + hstepA, voffA);
;             PG8_WAIT_V(8); PG8_WAIT_L(0); PG8_BAR; PG8_MMA(0, 0, At, B0); PG8_MMA(0, 1, At, B1); PG8_BAR; PG8_SCHED;
;             PG8_LDA(At, 1, 1); PG8_STAGE(PG8_SB(1, 0), b3, voffB); PG8_STAGE(PG8_SB(1, 1), b3 + hstepB, voffB); PG8_STAGE(PG8_SA(1, 0), a3, voffA);
;             PG8_WAIT_V(8); PG8_WAIT_L(0); PG8_BAR; PG8_MMA(1, 0, At, B0); PG8_MMA(1, 1, At, B1); PG8_BAR; PG8_SCHED;
	s_setprio 1
	v_mfma_f32_16x16x32_bf16 v[60:63], v[132:135], v[200:203], v[60:63]
	v_mfma_f32_16x16x32_bf16 v[56:59], v[176:179], v[200:203], v[56:59]
	v_mfma_f32_16x16x32_bf16 v[44:47], v[132:135], v[212:215], v[44:47]
	v_mfma_f32_16x16x32_bf16 v[40:43], v[176:179], v[212:215], v[40:43]
	v_mfma_f32_16x16x32_bf16 v[28:31], v[132:135], v[220:223], v[28:31]
	v_mfma_f32_16x16x32_bf16 v[24:27], v[176:179], v[220:223], v[24:27]
	v_mfma_f32_16x16x32_bf16 v[12:15], v[132:135], v[228:231], v[12:15]
	v_mfma_f32_16x16x32_bf16 v[8:11], v[176:179], v[228:231], v[8:11]
	v_mfma_f32_16x16x32_bf16 v[60:63], v[158:161], v[208:211], v[60:63]
	v_mfma_f32_16x16x32_bf16 v[56:59], v[180:183], v[208:211], v[56:59]
	v_mfma_f32_16x16x32_bf16 v[44:47], v[158:161], v[216:219], v[44:47]
	v_mfma_f32_16x16x32_bf16 v[40:43], v[180:183], v[216:219], v[40:43]
	v_mfma_f32_16x16x32_bf16 v[28:31], v[158:161], v[224:227], v[28:31]
	v_mfma_f32_16x16x32_bf16 v[24:27], v[180:183], v[224:227], v[24:27]
	v_mfma_f32_16x16x32_bf16 v[12:15], v[158:161], v[232:235], v[12:15]
	v_mfma_f32_16x16x32_bf16 v[8:11], v[180:183], v[232:235], v[8:11]
	v_mfma_f32_16x16x32_bf16 v[52:55], v[184:187], v[200:203], v[52:55]
	v_mfma_f32_16x16x32_bf16 v[48:51], v[192:195], v[200:203], v[48:51]
	v_mfma_f32_16x16x32_bf16 v[36:39], v[184:187], v[212:215], v[36:39]
	v_mfma_f32_16x16x32_bf16 v[32:35], v[192:195], v[212:215], v[32:35]
	v_mfma_f32_16x16x32_bf16 v[20:23], v[184:187], v[220:223], v[20:23]
	v_mfma_f32_16x16x32_bf16 v[16:19], v[192:195], v[220:223], v[16:19]
	v_mfma_f32_16x16x32_bf16 v[4:7], v[184:187], v[228:231], v[4:7]
	v_mfma_f32_16x16x32_bf16 v[0:3], v[192:195], v[228:231], v[0:3]
	v_mfma_f32_16x16x32_bf16 v[52:55], v[188:191], v[208:211], v[52:55]
	v_mfma_f32_16x16x32_bf16 v[48:51], v[196:199], v[208:211], v[48:51]
	v_mfma_f32_16x16x32_bf16 v[36:39], v[188:191], v[216:219], v[36:39]
	v_mfma_f32_16x16x32_bf16 v[32:35], v[196:199], v[216:219], v[32:35]
	v_mfma_f32_16x16x32_bf16 v[20:23], v[188:191], v[224:227], v[20:23]
	v_mfma_f32_16x16x32_bf16 v[16:19], v[196:199], v[224:227], v[16:19]
	v_mfma_f32_16x16x32_bf16 v[4:7], v[188:191], v[232:235], v[4:7]
	v_mfma_f32_16x16x32_bf16 v[0:3], v[196:199], v[232:235], v[0:3]
	s_setprio 0
	s_barrier
	s_add_i32 s65, 0, 0x18000
	v_add_u32_e32 v144, s65, v163
	s_add_i32 s66, 0, 0x1c000
	ds_read_b128 v[132:135], v144
	ds_read_b128 v[158:161], v144 offset:1024
	ds_read_b128 v[176:179], v144 offset:2048
	ds_read_b128 v[180:183], v144 offset:3072
	v_add_u32_e32 v144, s66, v163
	ds_read_b128 v[184:187], v144
	ds_read_b128 v[188:191], v144 offset:1024
	ds_read_b128 v[192:195], v144 offset:2048
	ds_read_b128 v[196:199], v144 offset:3072
	s_add_u32 s42, s42, 0x40000
	s_addc_u32 s43, s43, 0
	s_mov_b32 m0, s51
	v_lshl_add_u64 v[236:237], s[42:43], 0, v[136:137]
	ds_read_b128 v[200:203], v174 offset:32768
	ds_read_b128 v[208:211], v174 offset:33792
	ds_read_b128 v[212:215], v174 offset:34816
	ds_read_b128 v[216:219], v174 offset:35840
	ds_read_b128 v[220:223], v174 offset:36864
	ds_read_b128 v[224:227], v174 offset:37888
	ds_read_b128 v[228:231], v174 offset:38912
	ds_read_b128 v[232:235], v174 offset:39936
	global_load_lds_dwordx4 v[236:237], off
	v_lshl_add_u64 v[236:237], s[42:43], 0, v[140:141]
	s_mov_b32 m0, s52
	s_nop 0
	global_load_lds_dwordx4 v[236:237], off
	s_waitcnt vmcnt(8)
	s_waitcnt lgkmcnt(0)
	s_barrier
	s_setprio 1
	v_mfma_f32_16x16x32_bf16 v[124:127], v[132:135], v[200:203], v[124:127]
	v_mfma_f32_16x16x32_bf16 v[120:123], v[176:179], v[200:203], v[120:123]
	v_mfma_f32_16x16x32_bf16 v[108:111], v[132:135], v[212:215], v[108:111]
	v_mfma_f32_16x16x32_bf16 v[104:107], v[176:179], v[212:215], v[104:107]
	v_mfma_f32_16x16x32_bf16 v[92:95], v[132:135], v[220:223], v[92:95]
	v_mfma_f32_16x16x32_bf16 v[88:91], v[176:179], v[220:223], v[88:91]
	v_mfma_f32_16x16x32_bf16 v[76:79], v[132:135], v[228:231], v[76:79]
	v_mfma_f32_16x16x32_bf16 v[72:75], v[176:179], v[228:231], v[72:75]
	v_mfma_f32_16x16x32_bf16 v[124:127], v[158:161], v[208:211], v[124:127]
	v_mfma_f32_16x16x32_bf16 v[120:123], v[180:183], v[208:211], v[120:123]
	v_mfma_f32_16x16x32_bf16 v[108:111], v[158:161], v[216:219], v[108:111]
	v_mfma_f32_16x16x32_bf16 v[104:107], v[180:183], v[216:219], v[104:107]
	v_mfma_f32_16x16x32_bf16 v[92:95], v[158:161], v[224:227], v[92:95]
	v_mfma_f32_16x16x32_bf16 v[88:91], v[180:183], v[224:227], v[88:91]
	v_mfma_f32_16x16x32_bf16 v[76:79], v[158:161], v[232:235], v[76:79]
	v_mfma_f32_16x16x32_bf16 v[72:75], v[180:183], v[232:235], v[72:75]
	v_mfma_f32_16x16x32_bf16 v[116:119], v[184:187], v[200:203], v[116:119]
	v_mfma_f32_16x16x32_bf16 v[112:115], v[192:195], v[200:203], v[112:115]
	v_mfma_f32_16x16x32_bf16 v[100:103], v[184:187], v[212:215], v[100:103]
	v_mfma_f32_16x16x32_bf16 v[96:99], v[192:195], v[212:215], v[96:99]
	v_mfma_f32_16x16x32_bf16 v[84:87], v[184:187], v[220:223], v[84:87]
	v_mfma_f32_16x16x32_bf16 v[80:83], v[192:195], v[220:223], v[80:83]
	v_mfma_f32_16x16x32_bf16 v[68:71], v[184:187], v[228:231], v[68:71]
	v_mfma_f32_16x16x32_bf16 v[64:67], v[192:195], v[228:231], v[64:67]
	v_mfma_f32_16x16x32_bf16 v[116:119], v[188:191], v[208:211], v[116:119]
	v_mfma_f32_16x16x32_bf16 v[112:115], v[196:199], v[208:211], v[112:115]
	v_mfma_f32_16x16x32_bf16 v[100:103], v[188:191], v[216:219], v[100:103]
	v_mfma_f32_16x16x32_bf16 v[96:99], v[196:199], v[216:219], v[96:99]
	v_mfma_f32_16x16x32_bf16 v[84:87], v[188:191], v[224:227], v[84:87]
	v_mfma_f32_16x16x32_bf16 v[80:83], v[196:199], v[224:227], v[80:83]
	v_mfma_f32_16x16x32_bf16 v[68:71], v[188:191], v[232:235], v[68:71]
	v_mfma_f32_16x16x32_bf16 v[64:67], v[196:199], v[232:235], v[64:67]
	s_setprio 0
	s_barrier
; #define PG8_STAGE(bufoff, gbase, voff) do { _Pragma("unroll") for (int _i = 0; _i < 2; ++_i) \
;         __builtin_amdgcn_global_load_lds((const unsigned*)((const char*)(gbase) + (voff)[_i]), (PG8_LAS unsigned*)(lds + (bufoff) + ldsw + _i * 8192), 16, 0, 0); } while (0)
; #define PG8_LDA(dst, b, h) do { _Pragma("unroll") for (int m = 0; m < 4; ++m) _Pragma("unroll") for (int k = 0; k < 2; ++k) dst[m][k] = *(const PG8_LAS bf16x8*)(lds + PG8_SA(b, h) + aoff + m * 2048 + k * 1024); } while (0)
; #define PG8_MMA(ai, bj, At, Bt) do { __builtin_amdgcn_s_setprio(1); _Pragma("unroll") for (int m = 0; m < 4; ++m) _Pragma("unroll") for (int n = 0; n < 2; ++n) _Pragma("unroll") for (int k = 0; k < 2; ++k) \
;         acc[ai][bj][m][n] = __builtin_amdgcn_mfma_f32_16x16x32_bf16(Bt[n][k], At[m][k], acc[ai][bj][m][n], 0, 0, 0); __builtin_amdgcn_s_setprio(0); } while (0)
; #define PG8_WAIT_V(n) asm volatile("s_waitcnt vmcnt(" #n ")" ::: "memory")
; #define PG8_WAIT_L(n) asm volatile("s_waitcnt lgkmcnt(" #n ")" ::: "memory")
; #define PG8_BAR __builtin_amdgcn_s_barrier()
; #define PG8_SCHED __builtin_amdgcn_sched_barrier(0)
; template <class Epi, class Sched, bool ALIGN_EPI = false, bool SP2 = false>
; __device__ __forceinline__ void gemm_phase(PG8_LAS unsigned char* lds, const Gemm g, const Sched& S, const Epi& E) {
;     ...
;             PG8_LDA(At, 1, 1); PG8_STAGE(PG8_SB(1, 0), b3, voffB); PG8_STAGE(PG8_SB(1, 1), b3 + hstepB, voffB); PG8_STAGE(PG8_SA(1, 0), a3, voffA);
;             PG8_WAIT_V(8); PG8_WAIT_L(0); PG8_BAR; PG8_MMA(1, 0, At, B0); PG8_MMA(1, 1, At, B1); PG8_BAR; PG8_SCHED;
	s_add_i32 s42, s65, s48
	v_lshl_add_u64 v[204:205], v[204:205], 0, s[14:15]
	s_mov_b32 m0, s42
	ds_read_b128 v[200:203], v174 offset:49152
	ds_read_b128 v[208:211], v174 offset:50176
	ds_read_b128 v[212:215], v174 offset:51200
	ds_read_b128 v[216:219], v174 offset:52224
	ds_read_b128 v[220:223], v174 offset:53248
	ds_read_b128 v[224:227], v174 offset:54272
	ds_read_b128 v[228:231], v174 offset:55296
	ds_read_b128 v[232:235], v174 offset:56320
	global_load_lds_dwordx4 v[204:205], off
	s_add_i32 m0, s42, 0x2000
	s_add_u32 s40, s40, 0x40080
	v_lshl_add_u64 v[204:205], v[206:207], 0, s[14:15]
	s_addc_u32 s41, s41, 0
	s_add_i32 s42, s66, s48
	global_load_lds_dwordx4 v[204:205], off
	v_lshl_add_u64 v[204:205], s[40:41], 0, v[138:139]
	s_mov_b32 m0, s42
	s_nop 0
	global_load_lds_dwordx4 v[204:205], off
	v_lshl_add_u64 v[204:205], s[40:41], 0, v[142:143]
	s_add_i32 m0, s42, 0x2000
	s_nop 0
	global_load_lds_dwordx4 v[204:205], off
	v_lshl_add_u64 v[204:205], s[38:39], 0, v[136:137]
	s_mov_b32 m0, s53
	s_nop 0
	global_load_lds_dwordx4 v[204:205], off
	v_lshl_add_u64 v[204:205], s[38:39], 0, v[140:141]
	s_mov_b32 m0, s54
	s_nop 0
	global_load_lds_dwordx4 v[204:205], off
	s_waitcnt vmcnt(8)
	s_waitcnt lgkmcnt(0)
	s_barrier
	s_setprio 1
	v_mfma_f32_16x16x32_bf16 v[60:63], v[132:135], v[200:203], v[60:63]
	v_mfma_f32_16x16x32_bf16 v[56:59], v[176:179], v[200:203], v[56:59]
	v_mfma_f32_16x16x32_bf16 v[44:47], v[132:135], v[212:215], v[44:47]
	v_mfma_f32_16x16x32_bf16 v[40:43], v[176:179], v[212:215], v[40:43]
	v_mfma_f32_16x16x32_bf16 v[28:31], v[132:135], v[220:223], v[28:31]
	v_mfma_f32_16x16x32_bf16 v[24:27], v[176:179], v[220:223], v[24:27]
	v_mfma_f32_16x16x32_bf16 v[12:15], v[132:135], v[228:231], v[12:15]
	v_mfma_f32_16x16x32_bf16 v[8:11], v[176:179], v[228:231], v[8:11]
	v_mfma_f32_16x16x32_bf16 v[60:63], v[158:161], v[208:211], v[60:63]
	v_mfma_f32_16x16x32_bf16 v[56:59], v[180:183], v[208:211], v[56:59]
	v_mfma_f32_16x16x32_bf16 v[44:47], v[158:161], v[216:219], v[44:47]
	v_mfma_f32_16x16x32_bf16 v[40:43], v[180:183], v[216:219], v[40:43]
	v_mfma_f32_16x16x32_bf16 v[28:31], v[158:161], v[224:227], v[28:31]
	v_mfma_f32_16x16x32_bf16 v[24:27], v[180:183], v[224:227], v[24:27]
	v_mfma_f32_16x16x32_bf16 v[12:15], v[158:161], v[232:235], v[12:15]
	v_mfma_f32_16x16x32_bf16 v[8:11], v[180:183], v[232:235], v[8:11]
	v_mfma_f32_16x16x32_bf16 v[52:55], v[184:187], v[200:203], v[52:55]
	v_mfma_f32_16x16x32_bf16 v[48:51], v[192:195], v[200:203], v[48:51]
	v_mfma_f32_16x16x32_bf16 v[36:39], v[184:187], v[212:215], v[36:39]
	v_mfma_f32_16x16x32_bf16 v[32:35], v[192:195], v[212:215], v[32:35]
	v_mfma_f32_16x16x32_bf16 v[20:23], v[184:187], v[220:223], v[20:23]
	v_mfma_f32_16x16x32_bf16 v[16:19], v[192:195], v[220:223], v[16:19]
	v_mfma_f32_16x16x32_bf16 v[4:7], v[184:187], v[228:231], v[4:7]
	v_mfma_f32_16x16x32_bf16 v[0:3], v[192:195], v[228:231], v[0:3]
	v_mfma_f32_16x16x32_bf16 v[52:55], v[188:191], v[208:211], v[52:55]
	v_mfma_f32_16x16x32_bf16 v[48:51], v[196:199], v[208:211], v[48:51]
	v_mfma_f32_16x16x32_bf16 v[36:39], v[188:191], v[216:219], v[36:39]
	v_mfma_f32_16x16x32_bf16 v[32:35], v[196:199], v[216:219], v[32:35]
	v_mfma_f32_16x16x32_bf16 v[20:23], v[188:191], v[224:227], v[20:23]
	v_mfma_f32_16x16x32_bf16 v[16:19], v[196:199], v[224:227], v[16:19]
	v_mfma_f32_16x16x32_bf16 v[4:7], v[188:191], v[232:235], v[4:7]
	v_mfma_f32_16x16x32_bf16 v[0:3], v[196:199], v[232:235], v[0:3]
	s_setprio 0
	s_barrier
	s_add_i32 s64, s64, 2
	s_add_u32 s34, s34, 0x100
	s_addc_u32 s35, s35, 0
	s_cmp_gt_u32 s64, 13
	s_cbranch_scc0 .LBB0_129
	s_and_b64 vcc, exec, s[16:17]
	s_cbranch_vccz .LBB0_134
	s_barrier
	s_cmp_gt_i32 s30, 3
	s_mov_b64 s[28:29], -1
	s_cbranch_scc1 .LBB0_135

; #define PG8_STAGE(bufoff, gbase, voff) do { _Pragma("unroll") for (int _i = 0; _i < 2; ++_i) \
;         __builtin_amdgcn_global_load_lds((const unsigned*)((const char*)(gbase) + (voff)[_i]), (PG8_LAS unsigned*)(lds + (bufoff) + ldsw + _i * 8192), 16, 0, 0); } while (0)
; #define PG8_LDA(dst, b, h) do { _Pragma("unroll") for (int m = 0; m < 4; ++m) _Pragma("unroll") for (int k = 0; k < 2; ++k) dst[m][k] = *(const PG8_LAS bf16x8*)(lds + PG8_SA(b, h) + aoff + m * 2048 + k * 1024); } while (0)
; #define PG8_LDB(dst, b, h) do { _Pragma("unroll") for (int n = 0; n < 2; ++n) _Pragma("unroll") for (int k = 0; k < 2; ++k) dst[n][k] = *(const PG8_LAS bf16x8*)(lds + PG8_SB(b, h) + boff + n * 2048 + k * 1024); } while (0)
; #define PG8_MMA(ai, bj, At, Bt) do { __builtin_amdgcn_s_setprio(1); _Pragma("unroll") for (int m = 0; m < 4; ++m) _Pragma("unroll") for (int n = 0; n < 2; ++n) _Pragma("unroll") for (int k = 0; k < 2; ++k) \
;         acc[ai][bj][m][n] = __builtin_amdgcn_mfma_f32_16x16x32_bf16(Bt[n][k], At[m][k], acc[ai][bj][m][n], 0, 0, 0); __builtin_amdgcn_s_setprio(0); } while (0)
; #define PG8_WAIT_V(n) asm volatile("s_waitcnt vmcnt(" #n ")" ::: "memory")
; #define PG8_WAIT_L(n) asm volatile("s_waitcnt lgkmcnt(" #n ")" ::: "memory")
; #define PG8_BAR __builtin_amdgcn_s_barrier()
; #define PG8_SCHED __builtin_amdgcn_sched_barrier(0)
; template <class Epi, class Sched, bool ALIGN_EPI = false, bool SP2 = false>
; __device__ __forceinline__ void gemm_phase(PG8_LAS unsigned char* lds, const Gemm g, const Sched& S, const Epi& E) {
;     ...
;             const bool last = (t == nt - 2);
;             const char* a1 = cA + PG8_AK(t + 1);
;             const char* a2 = last ? nA : cA + PG8_AK(t + 2); const char* b2 = last ? nB : cB + (size_t)(t + 2) * kstep;
;             const char* a3 = last ? nA + PG8_AK(1) : cA + PG8_AK(t + 3); const char* b3 = b2 + kstep;
;             if (last && has_next) S.a_ready(nxt);
;             if constexpr (SP2) {
;             PG8_LDB(B0, 0, 0); PG8_LDB(B1, 0, 1); PG8_SCHED; PG8_LDA(At, 0, 0); PG8_STAGE(PG8_SA(1, 1), a1 + hstepA, voffA);
;             PG8_WAIT_V(8); PG8_WAIT_L(0); PG8_BAR; PG8_MMA(0, 0, At, B0); PG8_MMA(0, 1, At, B1); PG8_BAR; PG8_SCHED;
;             PG8_LDA(At, 0, 1); PG8_STAGE(PG8_SB(0, 0), b2, voffB); PG8_STAGE(PG8_SB(0, 1), b2 + hstepB, voffB); PG8_STAGE(PG8_SA(0, 0), a2, voffA);
.LBB0_332:
	ds_read_b128 v[180:183], v147
	ds_read_b128 v[184:187], v147 offset:1024
	ds_read_b128 v[188:191], v147 offset:2048
	ds_read_b128 v[192:195], v147 offset:3072
	ds_read_b128 v[196:199], v149
	ds_read_b128 v[200:203], v149 offset:1024
	ds_read_b128 v[208:211], v149 offset:2048
	ds_read_b128 v[212:215], v149 offset:3072
	s_add_u32 s42, s38, s40
	s_addc_u32 s43, s39, s41
	s_add_u32 s46, s42, 0x100
	s_addc_u32 s47, s43, 0
	s_add_u32 s44, s79, s40
	s_addc_u32 s45, s80, s41
	s_add_u32 s42, s42, 0x180
	s_addc_u32 s43, s43, 0
	s_cmpk_eq_i32 s40, 0x700
	s_cselect_b32 s43, s78, s43
	s_cselect_b32 s42, s69, s42
	s_cselect_b32 s45, s27, s45
	s_cselect_b32 s44, s37, s44
	s_cselect_b32 s47, s3, s47
	s_cselect_b32 s46, s29, s46
	v_lshl_add_u64 v[204:205], v[178:179], 0, s[40:41]
	s_add_i32 m0, s54, 0xc000
	ds_read_b128 v[216:219], v143
	ds_read_b128 v[220:223], v143 offset:1024
	ds_read_b128 v[224:227], v143 offset:2048
	ds_read_b128 v[228:231], v143 offset:3072
	ds_read_b128 v[232:235], v143 offset:4096
	ds_read_b128 v[236:239], v143 offset:5120
	ds_read_b128 v[240:243], v143 offset:6144
	ds_read_b128 v[244:247], v143 offset:7168
	global_load_lds_dwordx4 v[204:205], off
	v_lshl_add_u64 v[204:205], v[176:177], 0, s[40:41]
	s_add_i32 m0, s54, 0xe000
	s_nop 0
	global_load_lds_dwordx4 v[204:205], off
	s_waitcnt vmcnt(8)
	s_waitcnt lgkmcnt(0)
	s_barrier
	s_setprio 1
	v_mfma_f32_16x16x32_bf16 v[124:127], v[180:183], v[216:219], v[124:127]
	v_mfma_f32_16x16x32_bf16 v[120:123], v[188:191], v[216:219], v[120:123]
	v_mfma_f32_16x16x32_bf16 v[116:119], v[180:183], v[224:227], v[116:119]
	v_mfma_f32_16x16x32_bf16 v[112:115], v[188:191], v[224:227], v[112:115]
	v_mfma_f32_16x16x32_bf16 v[108:111], v[180:183], v[232:235], v[108:111]
	v_mfma_f32_16x16x32_bf16 v[104:107], v[188:191], v[232:235], v[104:107]
	v_mfma_f32_16x16x32_bf16 v[100:103], v[180:183], v[240:243], v[100:103]
	v_mfma_f32_16x16x32_bf16 v[96:99], v[188:191], v[240:243], v[96:99]
	v_mfma_f32_16x16x32_bf16 v[124:127], v[184:187], v[220:223], v[124:127]
	v_mfma_f32_16x16x32_bf16 v[120:123], v[192:195], v[220:223], v[120:123]
	v_mfma_f32_16x16x32_bf16 v[116:119], v[184:187], v[228:231], v[116:119]
	v_mfma_f32_16x16x32_bf16 v[112:115], v[192:195], v[228:231], v[112:115]
	v_mfma_f32_16x16x32_bf16 v[108:111], v[184:187], v[236:239], v[108:111]
	v_mfma_f32_16x16x32_bf16 v[104:107], v[192:195], v[236:239], v[104:107]
	v_mfma_f32_16x16x32_bf16 v[100:103], v[184:187], v[244:247], v[100:103]
	v_mfma_f32_16x16x32_bf16 v[96:99], v[192:195], v[244:247], v[96:99]
	v_mfma_f32_16x16x32_bf16 v[64:67], v[196:199], v[216:219], v[64:67]
	v_mfma_f32_16x16x32_bf16 v[56:59], v[208:211], v[216:219], v[56:59]
	v_mfma_f32_16x16x32_bf16 v[52:55], v[196:199], v[224:227], v[52:55]
	v_mfma_f32_16x16x32_bf16 v[48:51], v[208:211], v[224:227], v[48:51]
	v_mfma_f32_16x16x32_bf16 v[44:47], v[196:199], v[232:235], v[44:47]
	v_mfma_f32_16x16x32_bf16 v[40:43], v[208:211], v[232:235], v[40:43]
	v_mfma_f32_16x16x32_bf16 v[36:39], v[196:199], v[240:243], v[36:39]
	v_mfma_f32_16x16x32_bf16 v[32:35], v[208:211], v[240:243], v[32:35]
	v_mfma_f32_16x16x32_bf16 v[64:67], v[200:203], v[220:223], v[64:67]
	v_mfma_f32_16x16x32_bf16 v[56:59], v[212:215], v[220:223], v[56:59]
	v_mfma_f32_16x16x32_bf16 v[52:55], v[200:203], v[228:231], v[52:55]
	v_mfma_f32_16x16x32_bf16 v[48:51], v[212:215], v[228:231], v[48:51]
	v_mfma_f32_16x16x32_bf16 v[44:47], v[200:203], v[236:239], v[44:47]
	v_mfma_f32_16x16x32_bf16 v[40:43], v[212:215], v[236:239], v[40:43]
	v_mfma_f32_16x16x32_bf16 v[36:39], v[200:203], v[244:247], v[36:39]
	v_mfma_f32_16x16x32_bf16 v[32:35], v[212:215], v[244:247], v[32:35]
	s_setprio 0
	s_barrier
	s_add_i32 s70, s66, s53
	v_lshl_add_u64 v[204:205], s[44:45], 0, v[130:131]
	s_mov_b32 m0, s70
	ds_read_b128 v[216:219], v143 offset:16384
	ds_read_b128 v[220:223], v143 offset:17408
	ds_read_b128 v[224:227], v143 offset:18432
	ds_read_b128 v[228:231], v143 offset:19456
	ds_read_b128 v[232:235], v143 offset:20480
	ds_read_b128 v[236:239], v143 offset:21504
	ds_read_b128 v[240:243], v143 offset:22528
	ds_read_b128 v[244:247], v143 offset:23552
	global_load_lds_dwordx4 v[204:205], off
	s_add_i32 m0, s70, 0x2000
	s_add_u32 s70, s44, 0x40000
	v_lshl_add_u64 v[206:207], s[44:45], 0, v[134:135]
	s_addc_u32 s71, s45, 0
	s_add_i32 s82, s67, s53
	global_load_lds_dwordx4 v[206:207], off
	v_lshl_add_u64 v[248:249], s[70:71], 0, v[130:131]
	s_mov_b32 m0, s82
	s_nop 0
	global_load_lds_dwordx4 v[248:249], off
	v_lshl_add_u64 v[248:249], s[70:71], 0, v[134:135]
	s_add_i32 m0, s82, 0x2000
	s_nop 0
	global_load_lds_dwordx4 v[248:249], off
	v_lshl_add_u64 v[248:249], s[46:47], 0, v[128:129]
	s_mov_b32 m0, s54
	s_nop 0
	global_load_lds_dwordx4 v[248:249], off
	v_lshl_add_u64 v[248:249], s[46:47], 0, v[132:133]
	s_mov_b32 m0, s55
	s_nop 0
	global_load_lds_dwordx4 v[248:249], off
	s_waitcnt vmcnt(8)
	s_waitcnt lgkmcnt(0)
	s_barrier
; #define PG8_STAGE(bufoff, gbase, voff) do { _Pragma("unroll") for (int _i = 0; _i < 2; ++_i) \
;         __builtin_amdgcn_global_load_lds((const unsigned*)((const char*)(gbase) + (voff)[_i]), (PG8_LAS unsigned*)(lds + (bufoff) + ldsw + _i * 8192), 16, 0, 0); } while (0)
; #define PG8_LDA(dst, b, h) do { _Pragma("unroll") for (int m = 0; m < 4; ++m) _Pragma("unroll") for (int k = 0; k < 2; ++k) dst[m][k] = *(const PG8_LAS bf16x8*)(lds + PG8_SA(b, h) + aoff + m * 2048 + k * 1024); } while (0)
; #define PG8_LDB(dst, b, h) do { _Pragma("unroll") for (int n = 0; n < 2; ++n) _Pragma("unroll") for (int k = 0; k < 2; ++k) dst[n][k] = *(const PG8_LAS bf16x8*)(lds + PG8_SB(b, h) + boff + n * 2048 + k * 1024); } while (0)
; #define PG8_MMA(ai, bj, At, Bt) do { __builtin_amdgcn_s_setprio(1); _Pragma("unroll") for (int m = 0; m < 4; ++m) _Pragma("unroll") for (int n = 0; n < 2; ++n) _Pragma("unroll") for (int k = 0; k < 2; ++k) \
;         acc[ai][bj][m][n] = __builtin_amdgcn_mfma_f32_16x16x32_bf16(Bt[n][k], At[m][k], acc[ai][bj][m][n], 0, 0, 0); __builtin_amdgcn_s_setprio(0); } while (0)
; #define PG8_WAIT_V(n) asm volatile("s_waitcnt vmcnt(" #n ")" ::: "memory")
; #define PG8_WAIT_L(n) asm volatile("s_waitcnt lgkmcnt(" #n ")" ::: "memory")
; #define PG8_BAR __builtin_amdgcn_s_barrier()
; #define PG8_SCHED __builtin_amdgcn_sched_barrier(0)
; template <class Epi, class Sched, bool ALIGN_EPI = false, bool SP2 = false>
; __device__ __forceinline__ void gemm_phase(PG8_LAS unsigned char* lds, const Gemm g, const Sched& S, const Epi& E) {
;     ...
;             PG8_LDA(At, 0, 1); PG8_STAGE(PG8_SB(0, 0), b2, voffB); PG8_STAGE(PG8_SB(0, 1), b2 + hstepB, voffB); PG8_STAGE(PG8_SA(0, 0), a2, voffA);
;             PG8_WAIT_V(8); PG8_WAIT_L(0); PG8_BAR; PG8_MMA(1, 0, At, B0); PG8_MMA(1, 1, At, B1); PG8_BAR; PG8_SCHED;
;             PG8_LDB(B0, 1, 0); PG8_LDB(B1, 1, 1); PG8_SCHED; PG8_LDA(At, 1, 0); PG8_STAGE(PG8_SA(0, 1), a2 + hstepA, voffA);
;             PG8_WAIT_V(8); PG8_WAIT_L(0); PG8_BAR; PG8_MMA(0, 0, At, B0); PG8_MMA(0, 1, At, B1); PG8_BAR; PG8_SCHED;
	s_setprio 1
	v_mfma_f32_16x16x32_bf16 v[92:95], v[180:183], v[216:219], v[92:95]
	v_mfma_f32_16x16x32_bf16 v[88:91], v[188:191], v[216:219], v[88:91]
	v_mfma_f32_16x16x32_bf16 v[84:87], v[180:183], v[224:227], v[84:87]
	v_mfma_f32_16x16x32_bf16 v[80:83], v[188:191], v[224:227], v[80:83]
	v_mfma_f32_16x16x32_bf16 v[76:79], v[180:183], v[232:235], v[76:79]
	v_mfma_f32_16x16x32_bf16 v[72:75], v[188:191], v[232:235], v[72:75]
	v_mfma_f32_16x16x32_bf16 v[68:71], v[180:183], v[240:243], v[68:71]
	v_mfma_f32_16x16x32_bf16 v[60:63], v[188:191], v[240:243], v[60:63]
	v_mfma_f32_16x16x32_bf16 v[92:95], v[184:187], v[220:223], v[92:95]
	v_mfma_f32_16x16x32_bf16 v[88:91], v[192:195], v[220:223], v[88:91]
	v_mfma_f32_16x16x32_bf16 v[84:87], v[184:187], v[228:231], v[84:87]
	v_mfma_f32_16x16x32_bf16 v[80:83], v[192:195], v[228:231], v[80:83]
	v_mfma_f32_16x16x32_bf16 v[76:79], v[184:187], v[236:239], v[76:79]
	v_mfma_f32_16x16x32_bf16 v[72:75], v[192:195], v[236:239], v[72:75]
	v_mfma_f32_16x16x32_bf16 v[68:71], v[184:187], v[244:247], v[68:71]
	v_mfma_f32_16x16x32_bf16 v[60:63], v[192:195], v[244:247], v[60:63]
	v_mfma_f32_16x16x32_bf16 v[28:31], v[196:199], v[216:219], v[28:31]
	v_mfma_f32_16x16x32_bf16 v[24:27], v[208:211], v[216:219], v[24:27]
	v_mfma_f32_16x16x32_bf16 v[20:23], v[196:199], v[224:227], v[20:23]
	v_mfma_f32_16x16x32_bf16 v[16:19], v[208:211], v[224:227], v[16:19]
	v_mfma_f32_16x16x32_bf16 v[12:15], v[196:199], v[232:235], v[12:15]
	v_mfma_f32_16x16x32_bf16 v[8:11], v[208:211], v[232:235], v[8:11]
	v_mfma_f32_16x16x32_bf16 v[4:7], v[196:199], v[240:243], v[4:7]
	v_mfma_f32_16x16x32_bf16 v[0:3], v[208:211], v[240:243], v[0:3]
	v_mfma_f32_16x16x32_bf16 v[28:31], v[200:203], v[220:223], v[28:31]
	v_mfma_f32_16x16x32_bf16 v[24:27], v[212:215], v[220:223], v[24:27]
	v_mfma_f32_16x16x32_bf16 v[20:23], v[200:203], v[228:231], v[20:23]
	v_mfma_f32_16x16x32_bf16 v[16:19], v[212:215], v[228:231], v[16:19]
	v_mfma_f32_16x16x32_bf16 v[12:15], v[200:203], v[236:239], v[12:15]
	v_mfma_f32_16x16x32_bf16 v[8:11], v[212:215], v[236:239], v[8:11]
	v_mfma_f32_16x16x32_bf16 v[4:7], v[200:203], v[244:247], v[4:7]
	v_mfma_f32_16x16x32_bf16 v[0:3], v[212:215], v[244:247], v[0:3]
	s_setprio 0
	s_barrier
	s_add_i32 s70, 0, 0x18000
	v_add_u32_e32 v137, s70, v141
	s_add_i32 s71, 0, 0x1c000
	ds_read_b128 v[180:183], v137
	ds_read_b128 v[184:187], v137 offset:1024
	ds_read_b128 v[188:191], v137 offset:2048
	ds_read_b128 v[192:195], v137 offset:3072
	v_add_u32_e32 v137, s71, v141
	ds_read_b128 v[196:199], v137
	ds_read_b128 v[200:203], v137 offset:1024
	ds_read_b128 v[208:211], v137 offset:2048
	ds_read_b128 v[212:215], v137 offset:3072
	s_add_u32 s46, s46, 0x40000
	s_addc_u32 s47, s47, 0
	s_mov_b32 m0, s56
	v_lshl_add_u64 v[248:249], s[46:47], 0, v[128:129]
	ds_read_b128 v[216:219], v143 offset:32768
	ds_read_b128 v[220:223], v143 offset:33792
	ds_read_b128 v[224:227], v143 offset:34816
	ds_read_b128 v[228:231], v143 offset:35840
	ds_read_b128 v[232:235], v143 offset:36864
	ds_read_b128 v[236:239], v143 offset:37888
	ds_read_b128 v[240:243], v143 offset:38912
	ds_read_b128 v[244:247], v143 offset:39936
	global_load_lds_dwordx4 v[248:249], off
	v_lshl_add_u64 v[248:249], s[46:47], 0, v[132:133]
	s_mov_b32 m0, s57
	s_nop 0
	global_load_lds_dwordx4 v[248:249], off
	s_waitcnt vmcnt(8)
	s_waitcnt lgkmcnt(0)
	s_barrier
	s_setprio 1
	v_mfma_f32_16x16x32_bf16 v[124:127], v[180:183], v[216:219], v[124:127]
	v_mfma_f32_16x16x32_bf16 v[120:123], v[188:191], v[216:219], v[120:123]
	v_mfma_f32_16x16x32_bf16 v[116:119], v[180:183], v[224:227], v[116:119]
	v_mfma_f32_16x16x32_bf16 v[112:115], v[188:191], v[224:227], v[112:115]
	v_mfma_f32_16x16x32_bf16 v[108:111], v[180:183], v[232:235], v[108:111]
	v_mfma_f32_16x16x32_bf16 v[104:107], v[188:191], v[232:235], v[104:107]
	v_mfma_f32_16x16x32_bf16 v[100:103], v[180:183], v[240:243], v[100:103]
	v_mfma_f32_16x16x32_bf16 v[96:99], v[188:191], v[240:243], v[96:99]
	v_mfma_f32_16x16x32_bf16 v[124:127], v[184:187], v[220:223], v[124:127]
	v_mfma_f32_16x16x32_bf16 v[120:123], v[192:195], v[220:223], v[120:123]
	v_mfma_f32_16x16x32_bf16 v[116:119], v[184:187], v[228:231], v[116:119]
	v_mfma_f32_16x16x32_bf16 v[112:115], v[192:195], v[228:231], v[112:115]
	v_mfma_f32_16x16x32_bf16 v[108:111], v[184:187], v[236:239], v[108:111]
	v_mfma_f32_16x16x32_bf16 v[104:107], v[192:195], v[236:239], v[104:107]
	v_mfma_f32_16x16x32_bf16 v[100:103], v[184:187], v[244:247], v[100:103]
	v_mfma_f32_16x16x32_bf16 v[96:99], v[192:195], v[244:247], v[96:99]
	v_mfma_f32_16x16x32_bf16 v[64:67], v[196:199], v[216:219], v[64:67]
	v_mfma_f32_16x16x32_bf16 v[56:59], v[208:211], v[216:219], v[56:59]
	v_mfma_f32_16x16x32_bf16 v[52:55], v[196:199], v[224:227], v[52:55]
	v_mfma_f32_16x16x32_bf16 v[48:51], v[208:211], v[224:227], v[48:51]
	v_mfma_f32_16x16x32_bf16 v[44:47], v[196:199], v[232:235], v[44:47]
	v_mfma_f32_16x16x32_bf16 v[40:43], v[208:211], v[232:235], v[40:43]
	v_mfma_f32_16x16x32_bf16 v[36:39], v[196:199], v[240:243], v[36:39]
	v_mfma_f32_16x16x32_bf16 v[32:35], v[208:211], v[240:243], v[32:35]
	v_mfma_f32_16x16x32_bf16 v[64:67], v[200:203], v[220:223], v[64:67]
	v_mfma_f32_16x16x32_bf16 v[56:59], v[212:215], v[220:223], v[56:59]
	v_mfma_f32_16x16x32_bf16 v[52:55], v[200:203], v[228:231], v[52:55]
	v_mfma_f32_16x16x32_bf16 v[48:51], v[212:215], v[228:231], v[48:51]
	v_mfma_f32_16x16x32_bf16 v[44:47], v[200:203], v[236:239], v[44:47]
	v_mfma_f32_16x16x32_bf16 v[40:43], v[212:215], v[236:239], v[40:43]
	v_mfma_f32_16x16x32_bf16 v[36:39], v[200:203], v[244:247], v[36:39]
	v_mfma_f32_16x16x32_bf16 v[32:35], v[212:215], v[244:247], v[32:35]
	s_setprio 0
	s_barrier
; #define PG8_STAGE(bufoff, gbase, voff) do { _Pragma("unroll") for (int _i = 0; _i < 2; ++_i) \
;         __builtin_amdgcn_global_load_lds((const unsigned*)((const char*)(gbase) + (voff)[_i]), (PG8_LAS unsigned*)(lds + (bufoff) + ldsw + _i * 8192), 16, 0, 0); } while (0)
; #define PG8_LDA(dst, b, h) do { _Pragma("unroll") for (int m = 0; m < 4; ++m) _Pragma("unroll") for (int k = 0; k < 2; ++k) dst[m][k] = *(const PG8_LAS bf16x8*)(lds + PG8_SA(b, h) + aoff + m * 2048 + k * 1024); } while (0)
; #define PG8_MMA(ai, bj, At, Bt) do { __builtin_amdgcn_s_setprio(1); _Pragma("unroll") for (int m = 0; m < 4; ++m) _Pragma("unroll") for (int n = 0; n < 2; ++n) _Pragma("unroll") for (int k = 0; k < 2; ++k) \
;         acc[ai][bj][m][n] = __builtin_amdgcn_mfma_f32_16x16x32_bf16(Bt[n][k], At[m][k], acc[ai][bj][m][n], 0, 0, 0); __builtin_amdgcn_s_setprio(0); } while (0)
; #define PG8_WAIT_V(n) asm volatile("s_waitcnt vmcnt(" #n ")" ::: "memory")
; #define PG8_WAIT_L(n) asm volatile("s_waitcnt lgkmcnt(" #n ")" ::: "memory")
; #define PG8_BAR __builtin_amdgcn_s_barrier()
; #define PG8_SCHED __builtin_amdgcn_sched_barrier(0)
; template <class Epi, class Sched, bool ALIGN_EPI = false, bool SP2 = false>
; __device__ __forceinline__ void gemm_phase(PG8_LAS unsigned char* lds, const Gemm g, const Sched& S, const Epi& E) {
;     ...
;             PG8_LDA(At, 1, 1); PG8_STAGE(PG8_SB(1, 0), b3, voffB); PG8_STAGE(PG8_SB(1, 1), b3 + hstepB, voffB); PG8_STAGE(PG8_SA(1, 0), a3, voffA);
;             PG8_WAIT_V(8); PG8_WAIT_L(0); PG8_BAR; PG8_MMA(1, 0, At, B0); PG8_MMA(1, 1, At, B1); PG8_BAR; PG8_SCHED;
	s_add_i32 s46, s70, s53
	v_lshl_add_u64 v[204:205], v[204:205], 0, s[20:21]
	s_mov_b32 m0, s46
	ds_read_b128 v[216:219], v143 offset:49152
	ds_read_b128 v[220:223], v143 offset:50176
	ds_read_b128 v[224:227], v143 offset:51200
	ds_read_b128 v[228:231], v143 offset:52224
	ds_read_b128 v[232:235], v143 offset:53248
	ds_read_b128 v[236:239], v143 offset:54272
	ds_read_b128 v[240:243], v143 offset:55296
	ds_read_b128 v[244:247], v143 offset:56320
	global_load_lds_dwordx4 v[204:205], off
	s_add_i32 m0, s46, 0x2000
	s_add_u32 s44, s44, 0x40080
	v_lshl_add_u64 v[204:205], v[206:207], 0, s[20:21]
	s_addc_u32 s45, s45, 0
	s_add_i32 s46, s71, s53
	global_load_lds_dwordx4 v[204:205], off
	v_lshl_add_u64 v[204:205], s[44:45], 0, v[130:131]
	s_mov_b32 m0, s46
	s_nop 0
	global_load_lds_dwordx4 v[204:205], off
	v_lshl_add_u64 v[204:205], s[44:45], 0, v[134:135]
	s_add_i32 m0, s46, 0x2000
	s_nop 0
	global_load_lds_dwordx4 v[204:205], off
	v_lshl_add_u64 v[204:205], s[42:43], 0, v[128:129]
	s_mov_b32 m0, s62
	s_nop 0
	global_load_lds_dwordx4 v[204:205], off
	v_lshl_add_u64 v[204:205], s[42:43], 0, v[132:133]
	s_mov_b32 m0, s63
	s_nop 0
	global_load_lds_dwordx4 v[204:205], off
	s_waitcnt vmcnt(8)
	s_waitcnt lgkmcnt(0)
	s_barrier
	s_setprio 1
	v_mfma_f32_16x16x32_bf16 v[92:95], v[180:183], v[216:219], v[92:95]
	v_mfma_f32_16x16x32_bf16 v[88:91], v[188:191], v[216:219], v[88:91]
	v_mfma_f32_16x16x32_bf16 v[84:87], v[180:183], v[224:227], v[84:87]
	v_mfma_f32_16x16x32_bf16 v[80:83], v[188:191], v[224:227], v[80:83]
	v_mfma_f32_16x16x32_bf16 v[76:79], v[180:183], v[232:235], v[76:79]
	v_mfma_f32_16x16x32_bf16 v[72:75], v[188:191], v[232:235], v[72:75]
	v_mfma_f32_16x16x32_bf16 v[68:71], v[180:183], v[240:243], v[68:71]
	v_mfma_f32_16x16x32_bf16 v[60:63], v[188:191], v[240:243], v[60:63]
	v_mfma_f32_16x16x32_bf16 v[92:95], v[184:187], v[220:223], v[92:95]
	v_mfma_f32_16x16x32_bf16 v[88:91], v[192:195], v[220:223], v[88:91]
	v_mfma_f32_16x16x32_bf16 v[84:87], v[184:187], v[228:231], v[84:87]
	v_mfma_f32_16x16x32_bf16 v[80:83], v[192:195], v[228:231], v[80:83]
	v_mfma_f32_16x16x32_bf16 v[76:79], v[184:187], v[236:239], v[76:79]
	v_mfma_f32_16x16x32_bf16 v[72:75], v[192:195], v[236:239], v[72:75]
	v_mfma_f32_16x16x32_bf16 v[68:71], v[184:187], v[244:247], v[68:71]
	v_mfma_f32_16x16x32_bf16 v[60:63], v[192:195], v[244:247], v[60:63]
	v_mfma_f32_16x16x32_bf16 v[28:31], v[196:199], v[216:219], v[28:31]
	v_mfma_f32_16x16x32_bf16 v[24:27], v[208:211], v[216:219], v[24:27]
	v_mfma_f32_16x16x32_bf16 v[20:23], v[196:199], v[224:227], v[20:23]
	v_mfma_f32_16x16x32_bf16 v[16:19], v[208:211], v[224:227], v[16:19]
	v_mfma_f32_16x16x32_bf16 v[12:15], v[196:199], v[232:235], v[12:15]
	v_mfma_f32_16x16x32_bf16 v[8:11], v[208:211], v[232:235], v[8:11]
	v_mfma_f32_16x16x32_bf16 v[4:7], v[196:199], v[240:243], v[4:7]
	v_mfma_f32_16x16x32_bf16 v[0:3], v[208:211], v[240:243], v[0:3]
	v_mfma_f32_16x16x32_bf16 v[28:31], v[200:203], v[220:223], v[28:31]
	v_mfma_f32_16x16x32_bf16 v[24:27], v[212:215], v[220:223], v[24:27]
	v_mfma_f32_16x16x32_bf16 v[20:23], v[200:203], v[228:231], v[20:23]
	v_mfma_f32_16x16x32_bf16 v[16:19], v[212:215], v[228:231], v[16:19]
	v_mfma_f32_16x16x32_bf16 v[12:15], v[200:203], v[236:239], v[12:15]
	v_mfma_f32_16x16x32_bf16 v[8:11], v[212:215], v[236:239], v[8:11]
	v_mfma_f32_16x16x32_bf16 v[4:7], v[200:203], v[244:247], v[4:7]
	v_mfma_f32_16x16x32_bf16 v[0:3], v[212:215], v[244:247], v[0:3]
	s_setprio 0
	s_barrier
	s_add_i32 s81, s81, 2
	s_add_u32 s40, s40, 0x100
	s_addc_u32 s41, s41, 0
	s_cmp_gt_u32 s81, 13
	s_cbranch_scc0 .LBB0_332
	s_and_b64 vcc, exec, s[22:23]
	s_cbranch_vccz .LBB0_335
	s_barrier

; #define PG8_STAGE(bufoff, gbase, voff) do { _Pragma("unroll") for (int _i = 0; _i < 2; ++_i) \
;         __builtin_amdgcn_global_load_lds((const unsigned*)((const char*)(gbase) + (voff)[_i]), (PG8_LAS unsigned*)(lds + (bufoff) + ldsw + _i * 8192), 16, 0, 0); } while (0)
; #define PG8_LDA(dst, b, h) do { _Pragma("unroll") for (int m = 0; m < 4; ++m) _Pragma("unroll") for (int k = 0; k < 2; ++k) dst[m][k] = *(const PG8_LAS bf16x8*)(lds + PG8_SA(b, h) + aoff + m * 2048 + k * 1024); } while (0)
; #define PG8_LDB(dst, b, h) do { _Pragma("unroll") for (int n = 0; n < 2; ++n) _Pragma("unroll") for (int k = 0; k < 2; ++k) dst[n][k] = *(const PG8_LAS bf16x8*)(lds + PG8_SB(b, h) + boff + n * 2048 + k * 1024); } while (0)
; #define PG8_MMA(ai, bj, At, Bt) do { __builtin_amdgcn_s_setprio(1); _Pragma("unroll") for (int m = 0; m < 4; ++m) _Pragma("unroll") for (int n = 0; n < 2; ++n) _Pragma("unroll") for (int k = 0; k < 2; ++k) \
;         acc[ai][bj][m][n] = __builtin_amdgcn_mfma_f32_16x16x32_bf16(Bt[n][k], At[m][k], acc[ai][bj][m][n], 0, 0, 0); __builtin_amdgcn_s_setprio(0); } while (0)
; #define PG8_WAIT_V(n) asm volatile("s_waitcnt vmcnt(" #n ")" ::: "memory")
; #define PG8_WAIT_L(n) asm volatile("s_waitcnt lgkmcnt(" #n ")" ::: "memory")
; #define PG8_BAR __builtin_amdgcn_s_barrier()
; #define PG8_SCHED __builtin_amdgcn_sched_barrier(0)
; template <class Epi, class Sched, bool ALIGN_EPI = false, bool SP2 = false>
; __device__ __forceinline__ void gemm_phase(PG8_LAS unsigned char* lds, const Gemm g, const Sched& S, const Epi& E) {
;     ...
;             const bool last = (t == nt - 2);
;             const char* a1 = cA + PG8_AK(t + 1);
;             const char* a2 = last ? nA : cA + PG8_AK(t + 2); const char* b2 = last ? nB : cB + (size_t)(t + 2) * kstep;
;             const char* a3 = last ? nA + PG8_AK(1) : cA + PG8_AK(t + 3); const char* b3 = b2 + kstep;
;             if (last && has_next) S.a_ready(nxt);
;             if constexpr (SP2) {
;             PG8_LDB(B0, 0, 0); PG8_LDB(B1, 0, 1); PG8_SCHED; PG8_LDA(At, 0, 0); PG8_STAGE(PG8_SA(1, 1), a1 + hstepA, voffA);
;             PG8_WAIT_V(8); PG8_WAIT_L(0); PG8_BAR; PG8_MMA(0, 0, At, B0); PG8_MMA(0, 1, At, B1); PG8_BAR; PG8_SCHED;
;             PG8_LDA(At, 0, 1); PG8_STAGE(PG8_SB(0, 0), b2, voffB); PG8_STAGE(PG8_SB(0, 1), b2 + hstepB, voffB); PG8_STAGE(PG8_SA(0, 0), a2, voffA);
.LBB0_416:
	ds_read_b128 v[132:135], v171
	ds_read_b128 v[136:139], v171 offset:1024
	ds_read_b128 v[140:143], v171 offset:2048
	ds_read_b128 v[178:181], v171 offset:3072
	ds_read_b128 v[182:185], v173
	ds_read_b128 v[186:189], v173 offset:1024
	ds_read_b128 v[190:193], v173 offset:2048
	ds_read_b128 v[194:197], v173 offset:3072
	s_add_u32 s38, s34, s36
	s_addc_u32 s39, s35, s37
	s_add_u32 s42, s38, 0x100
	s_addc_u32 s43, s39, 0
	s_add_u32 s40, s66, s36
	s_addc_u32 s41, s67, s37
	s_add_u32 s38, s38, 0x180
	s_addc_u32 s39, s39, 0
	s_cmpk_eq_i32 s36, 0x700
	s_cselect_b32 s39, s65, s39
	s_cselect_b32 s38, s64, s38
	s_cselect_b32 s41, s23, s41
	s_cselect_b32 s40, s63, s40
	s_cselect_b32 s43, s3, s43
	s_cselect_b32 s42, s25, s42
	v_lshl_add_u64 v[206:207], v[130:131], 0, s[36:37]
	s_add_i32 m0, s31, 0xc000
	ds_read_b128 v[198:201], v175
	ds_read_b128 v[202:205], v175 offset:1024
	ds_read_b128 v[208:211], v175 offset:2048
	ds_read_b128 v[212:215], v175 offset:3072
	ds_read_b128 v[216:219], v175 offset:4096
	ds_read_b128 v[220:223], v175 offset:5120
	ds_read_b128 v[224:227], v175 offset:6144
	ds_read_b128 v[228:231], v175 offset:7168
	global_load_lds_dwordx4 v[206:207], off
	v_lshl_add_u64 v[206:207], v[128:129], 0, s[36:37]
	s_add_i32 m0, s31, 0xe000
	s_nop 0
	global_load_lds_dwordx4 v[206:207], off
	s_waitcnt vmcnt(8)
	s_waitcnt lgkmcnt(0)
	s_barrier
	s_setprio 1
	v_mfma_f32_16x16x32_bf16 v[124:127], v[132:135], v[198:201], v[124:127]
	v_mfma_f32_16x16x32_bf16 v[120:123], v[140:143], v[198:201], v[120:123]
	v_mfma_f32_16x16x32_bf16 v[116:119], v[132:135], v[208:211], v[116:119]
	v_mfma_f32_16x16x32_bf16 v[112:115], v[140:143], v[208:211], v[112:115]
	v_mfma_f32_16x16x32_bf16 v[108:111], v[132:135], v[216:219], v[108:111]
	v_mfma_f32_16x16x32_bf16 v[104:107], v[140:143], v[216:219], v[104:107]
	v_mfma_f32_16x16x32_bf16 v[100:103], v[132:135], v[224:227], v[100:103]
	v_mfma_f32_16x16x32_bf16 v[96:99], v[140:143], v[224:227], v[96:99]
	v_mfma_f32_16x16x32_bf16 v[124:127], v[136:139], v[202:205], v[124:127]
	v_mfma_f32_16x16x32_bf16 v[120:123], v[178:181], v[202:205], v[120:123]
	v_mfma_f32_16x16x32_bf16 v[116:119], v[136:139], v[212:215], v[116:119]
	v_mfma_f32_16x16x32_bf16 v[112:115], v[178:181], v[212:215], v[112:115]
	v_mfma_f32_16x16x32_bf16 v[108:111], v[136:139], v[220:223], v[108:111]
	v_mfma_f32_16x16x32_bf16 v[104:107], v[178:181], v[220:223], v[104:107]
	v_mfma_f32_16x16x32_bf16 v[100:103], v[136:139], v[228:231], v[100:103]
	v_mfma_f32_16x16x32_bf16 v[96:99], v[178:181], v[228:231], v[96:99]
	v_mfma_f32_16x16x32_bf16 v[64:67], v[182:185], v[198:201], v[64:67]
	v_mfma_f32_16x16x32_bf16 v[56:59], v[190:193], v[198:201], v[56:59]
	v_mfma_f32_16x16x32_bf16 v[52:55], v[182:185], v[208:211], v[52:55]
	v_mfma_f32_16x16x32_bf16 v[48:51], v[190:193], v[208:211], v[48:51]
	v_mfma_f32_16x16x32_bf16 v[44:47], v[182:185], v[216:219], v[44:47]
	v_mfma_f32_16x16x32_bf16 v[40:43], v[190:193], v[216:219], v[40:43]
	v_mfma_f32_16x16x32_bf16 v[36:39], v[182:185], v[224:227], v[36:39]
	v_mfma_f32_16x16x32_bf16 v[32:35], v[190:193], v[224:227], v[32:35]
	v_mfma_f32_16x16x32_bf16 v[64:67], v[186:189], v[202:205], v[64:67]
	v_mfma_f32_16x16x32_bf16 v[56:59], v[194:197], v[202:205], v[56:59]
	v_mfma_f32_16x16x32_bf16 v[52:55], v[186:189], v[212:215], v[52:55]
	v_mfma_f32_16x16x32_bf16 v[48:51], v[194:197], v[212:215], v[48:51]
	v_mfma_f32_16x16x32_bf16 v[44:47], v[186:189], v[220:223], v[44:47]
	v_mfma_f32_16x16x32_bf16 v[40:43], v[194:197], v[220:223], v[40:43]
	v_mfma_f32_16x16x32_bf16 v[36:39], v[186:189], v[228:231], v[36:39]
	v_mfma_f32_16x16x32_bf16 v[32:35], v[194:197], v[228:231], v[32:35]
	s_setprio 0
	s_barrier
	s_add_i32 s69, s59, s49
	v_lshl_add_u64 v[206:207], s[40:41], 0, v[148:149]
	s_mov_b32 m0, s69
	ds_read_b128 v[198:201], v175 offset:16384
	ds_read_b128 v[202:205], v175 offset:17408
	ds_read_b128 v[208:211], v175 offset:18432
	ds_read_b128 v[212:215], v175 offset:19456
	ds_read_b128 v[216:219], v175 offset:20480
	ds_read_b128 v[220:223], v175 offset:21504
	ds_read_b128 v[224:227], v175 offset:22528
	ds_read_b128 v[228:231], v175 offset:23552
	global_load_lds_dwordx4 v[206:207], off
	s_add_i32 m0, s69, 0x2000
	s_add_u32 s70, s40, 0x40000
	v_lshl_add_u64 v[232:233], s[40:41], 0, v[144:145]
	s_addc_u32 s71, s41, 0
	s_add_i32 s69, s60, s49
	global_load_lds_dwordx4 v[232:233], off
	v_lshl_add_u64 v[234:235], s[70:71], 0, v[148:149]
	s_mov_b32 m0, s69
	s_nop 0
	global_load_lds_dwordx4 v[234:235], off
	v_lshl_add_u64 v[234:235], s[70:71], 0, v[144:145]
	s_add_i32 m0, s69, 0x2000
	s_nop 0
	global_load_lds_dwordx4 v[234:235], off
	v_lshl_add_u64 v[234:235], s[42:43], 0, v[150:151]
	s_mov_b32 m0, s31
	s_nop 0
	global_load_lds_dwordx4 v[234:235], off
	v_lshl_add_u64 v[234:235], s[42:43], 0, v[146:147]
	s_mov_b32 m0, s52
	s_nop 0
	global_load_lds_dwordx4 v[234:235], off
	s_waitcnt vmcnt(8)
	s_waitcnt lgkmcnt(0)
	s_barrier
; #define PG8_STAGE(bufoff, gbase, voff) do { _Pragma("unroll") for (int _i = 0; _i < 2; ++_i) \
;         __builtin_amdgcn_global_load_lds((const unsigned*)((const char*)(gbase) + (voff)[_i]), (PG8_LAS unsigned*)(lds + (bufoff) + ldsw + _i * 8192), 16, 0, 0); } while (0)
; #define PG8_LDA(dst, b, h) do { _Pragma("unroll") for (int m = 0; m < 4; ++m) _Pragma("unroll") for (int k = 0; k < 2; ++k) dst[m][k] = *(const PG8_LAS bf16x8*)(lds + PG8_SA(b, h) + aoff + m * 2048 + k * 1024); } while (0)
; #define PG8_LDB(dst, b, h) do { _Pragma("unroll") for (int n = 0; n < 2; ++n) _Pragma("unroll") for (int k = 0; k < 2; ++k) dst[n][k] = *(const PG8_LAS bf16x8*)(lds + PG8_SB(b, h) + boff + n * 2048 + k * 1024); } while (0)
; #define PG8_MMA(ai, bj, At, Bt) do { __builtin_amdgcn_s_setprio(1); _Pragma("unroll") for (int m = 0; m < 4; ++m) _Pragma("unroll") for (int n = 0; n < 2; ++n) _Pragma("unroll") for (int k = 0; k < 2; ++k) \
;         acc[ai][bj][m][n] = __builtin_amdgcn_mfma_f32_16x16x32_bf16(Bt[n][k], At[m][k], acc[ai][bj][m][n], 0, 0, 0); __builtin_amdgcn_s_setprio(0); } while (0)
; #define PG8_WAIT_V(n) asm volatile("s_waitcnt vmcnt(" #n ")" ::: "memory")
; #define PG8_WAIT_L(n) asm volatile("s_waitcnt lgkmcnt(" #n ")" ::: "memory")
; #define PG8_BAR __builtin_amdgcn_s_barrier()
; #define PG8_SCHED __builtin_amdgcn_sched_barrier(0)
; template <class Epi, class Sched, bool ALIGN_EPI = false, bool SP2 = false>
; __device__ __forceinline__ void gemm_phase(PG8_LAS unsigned char* lds, const Gemm g, const Sched& S, const Epi& E) {
;     ...
;             PG8_LDA(At, 0, 1); PG8_STAGE(PG8_SB(0, 0), b2, voffB); PG8_STAGE(PG8_SB(0, 1), b2 + hstepB, voffB); PG8_STAGE(PG8_SA(0, 0), a2, voffA);
;             PG8_WAIT_V(8); PG8_WAIT_L(0); PG8_BAR; PG8_MMA(1, 0, At, B0); PG8_MMA(1, 1, At, B1); PG8_BAR; PG8_SCHED;
;             PG8_LDB(B0, 1, 0); PG8_LDB(B1, 1, 1); PG8_SCHED; PG8_LDA(At, 1, 0); PG8_STAGE(PG8_SA(0, 1), a2 + hstepA, voffA);
;             PG8_WAIT_V(8); PG8_WAIT_L(0); PG8_BAR; PG8_MMA(0, 0, At, B0); PG8_MMA(0, 1, At, B1); PG8_BAR; PG8_SCHED;
	s_setprio 1
	v_mfma_f32_16x16x32_bf16 v[92:95], v[132:135], v[198:201], v[92:95]
	v_mfma_f32_16x16x32_bf16 v[88:91], v[140:143], v[198:201], v[88:91]
	v_mfma_f32_16x16x32_bf16 v[84:87], v[132:135], v[208:211], v[84:87]
	v_mfma_f32_16x16x32_bf16 v[80:83], v[140:143], v[208:211], v[80:83]
	v_mfma_f32_16x16x32_bf16 v[76:79], v[132:135], v[216:219], v[76:79]
	v_mfma_f32_16x16x32_bf16 v[72:75], v[140:143], v[216:219], v[72:75]
	v_mfma_f32_16x16x32_bf16 v[68:71], v[132:135], v[224:227], v[68:71]
	v_mfma_f32_16x16x32_bf16 v[60:63], v[140:143], v[224:227], v[60:63]
	v_mfma_f32_16x16x32_bf16 v[92:95], v[136:139], v[202:205], v[92:95]
	v_mfma_f32_16x16x32_bf16 v[88:91], v[178:181], v[202:205], v[88:91]
	v_mfma_f32_16x16x32_bf16 v[84:87], v[136:139], v[212:215], v[84:87]
	v_mfma_f32_16x16x32_bf16 v[80:83], v[178:181], v[212:215], v[80:83]
	v_mfma_f32_16x16x32_bf16 v[76:79], v[136:139], v[220:223], v[76:79]
	v_mfma_f32_16x16x32_bf16 v[72:75], v[178:181], v[220:223], v[72:75]
	v_mfma_f32_16x16x32_bf16 v[68:71], v[136:139], v[228:231], v[68:71]
	v_mfma_f32_16x16x32_bf16 v[60:63], v[178:181], v[228:231], v[60:63]
	v_mfma_f32_16x16x32_bf16 v[28:31], v[182:185], v[198:201], v[28:31]
	v_mfma_f32_16x16x32_bf16 v[24:27], v[190:193], v[198:201], v[24:27]
	v_mfma_f32_16x16x32_bf16 v[20:23], v[182:185], v[208:211], v[20:23]
	v_mfma_f32_16x16x32_bf16 v[16:19], v[190:193], v[208:211], v[16:19]
	v_mfma_f32_16x16x32_bf16 v[12:15], v[182:185], v[216:219], v[12:15]
	v_mfma_f32_16x16x32_bf16 v[8:11], v[190:193], v[216:219], v[8:11]
	v_mfma_f32_16x16x32_bf16 v[4:7], v[182:185], v[224:227], v[4:7]
	v_mfma_f32_16x16x32_bf16 v[0:3], v[190:193], v[224:227], v[0:3]
	v_mfma_f32_16x16x32_bf16 v[28:31], v[186:189], v[202:205], v[28:31]
	v_mfma_f32_16x16x32_bf16 v[24:27], v[194:197], v[202:205], v[24:27]
	v_mfma_f32_16x16x32_bf16 v[20:23], v[186:189], v[212:215], v[20:23]
	v_mfma_f32_16x16x32_bf16 v[16:19], v[194:197], v[212:215], v[16:19]
	v_mfma_f32_16x16x32_bf16 v[12:15], v[186:189], v[220:223], v[12:15]
	v_mfma_f32_16x16x32_bf16 v[8:11], v[194:197], v[220:223], v[8:11]
	v_mfma_f32_16x16x32_bf16 v[4:7], v[186:189], v[228:231], v[4:7]
	v_mfma_f32_16x16x32_bf16 v[0:3], v[194:197], v[228:231], v[0:3]
	s_setprio 0
	s_barrier
	s_add_i32 s69, 0, 0x18000
	v_add_u32_e32 v160, s69, v163
	s_add_i32 s70, 0, 0x1c000
	ds_read_b128 v[132:135], v160
	ds_read_b128 v[136:139], v160 offset:1024
	ds_read_b128 v[140:143], v160 offset:2048
	ds_read_b128 v[178:181], v160 offset:3072
	v_add_u32_e32 v160, s70, v163
	ds_read_b128 v[182:185], v160
	ds_read_b128 v[186:189], v160 offset:1024
	ds_read_b128 v[190:193], v160 offset:2048
	ds_read_b128 v[194:197], v160 offset:3072
	s_add_u32 s42, s42, 0x40000
	s_addc_u32 s43, s43, 0
	s_mov_b32 m0, s53
	v_lshl_add_u64 v[234:235], s[42:43], 0, v[150:151]
	ds_read_b128 v[198:201], v175 offset:32768
	ds_read_b128 v[202:205], v175 offset:33792
	ds_read_b128 v[208:211], v175 offset:34816
	ds_read_b128 v[212:215], v175 offset:35840
	ds_read_b128 v[216:219], v175 offset:36864
	ds_read_b128 v[220:223], v175 offset:37888
	ds_read_b128 v[224:227], v175 offset:38912
	ds_read_b128 v[228:231], v175 offset:39936
	global_load_lds_dwordx4 v[234:235], off
	v_lshl_add_u64 v[234:235], s[42:43], 0, v[146:147]
	s_mov_b32 m0, s54
	s_nop 0
	global_load_lds_dwordx4 v[234:235], off
	s_waitcnt vmcnt(8)
	s_waitcnt lgkmcnt(0)
	s_barrier
	s_setprio 1
	v_mfma_f32_16x16x32_bf16 v[124:127], v[132:135], v[198:201], v[124:127]
	v_mfma_f32_16x16x32_bf16 v[120:123], v[140:143], v[198:201], v[120:123]
	v_mfma_f32_16x16x32_bf16 v[116:119], v[132:135], v[208:211], v[116:119]
	v_mfma_f32_16x16x32_bf16 v[112:115], v[140:143], v[208:211], v[112:115]
	v_mfma_f32_16x16x32_bf16 v[108:111], v[132:135], v[216:219], v[108:111]
	v_mfma_f32_16x16x32_bf16 v[104:107], v[140:143], v[216:219], v[104:107]
	v_mfma_f32_16x16x32_bf16 v[100:103], v[132:135], v[224:227], v[100:103]
	v_mfma_f32_16x16x32_bf16 v[96:99], v[140:143], v[224:227], v[96:99]
	v_mfma_f32_16x16x32_bf16 v[124:127], v[136:139], v[202:205], v[124:127]
	v_mfma_f32_16x16x32_bf16 v[120:123], v[178:181], v[202:205], v[120:123]
	v_mfma_f32_16x16x32_bf16 v[116:119], v[136:139], v[212:215], v[116:119]
	v_mfma_f32_16x16x32_bf16 v[112:115], v[178:181], v[212:215], v[112:115]
	v_mfma_f32_16x16x32_bf16 v[108:111], v[136:139], v[220:223], v[108:111]
	v_mfma_f32_16x16x32_bf16 v[104:107], v[178:181], v[220:223], v[104:107]
	v_mfma_f32_16x16x32_bf16 v[100:103], v[136:139], v[228:231], v[100:103]
	v_mfma_f32_16x16x32_bf16 v[96:99], v[178:181], v[228:231], v[96:99]
	v_mfma_f32_16x16x32_bf16 v[64:67], v[182:185], v[198:201], v[64:67]
	v_mfma_f32_16x16x32_bf16 v[56:59], v[190:193], v[198:201], v[56:59]
	v_mfma_f32_16x16x32_bf16 v[52:55], v[182:185], v[208:211], v[52:55]
	v_mfma_f32_16x16x32_bf16 v[48:51], v[190:193], v[208:211], v[48:51]
	v_mfma_f32_16x16x32_bf16 v[44:47], v[182:185], v[216:219], v[44:47]
	v_mfma_f32_16x16x32_bf16 v[40:43], v[190:193], v[216:219], v[40:43]
	v_mfma_f32_16x16x32_bf16 v[36:39], v[182:185], v[224:227], v[36:39]
	v_mfma_f32_16x16x32_bf16 v[32:35], v[190:193], v[224:227], v[32:35]
	v_mfma_f32_16x16x32_bf16 v[64:67], v[186:189], v[202:205], v[64:67]
	v_mfma_f32_16x16x32_bf16 v[56:59], v[194:197], v[202:205], v[56:59]
	v_mfma_f32_16x16x32_bf16 v[52:55], v[186:189], v[212:215], v[52:55]
	v_mfma_f32_16x16x32_bf16 v[48:51], v[194:197], v[212:215], v[48:51]
	v_mfma_f32_16x16x32_bf16 v[44:47], v[186:189], v[220:223], v[44:47]
	v_mfma_f32_16x16x32_bf16 v[40:43], v[194:197], v[220:223], v[40:43]
	v_mfma_f32_16x16x32_bf16 v[36:39], v[186:189], v[228:231], v[36:39]
	v_mfma_f32_16x16x32_bf16 v[32:35], v[194:197], v[228:231], v[32:35]
	s_setprio 0
	s_barrier
; #define PG8_STAGE(bufoff, gbase, voff) do { _Pragma("unroll") for (int _i = 0; _i < 2; ++_i) \
;         __builtin_amdgcn_global_load_lds((const unsigned*)((const char*)(gbase) + (voff)[_i]), (PG8_LAS unsigned*)(lds + (bufoff) + ldsw + _i * 8192), 16, 0, 0); } while (0)
; #define PG8_LDA(dst, b, h) do { _Pragma("unroll") for (int m = 0; m < 4; ++m) _Pragma("unroll") for (int k = 0; k < 2; ++k) dst[m][k] = *(const PG8_LAS bf16x8*)(lds + PG8_SA(b, h) + aoff + m * 2048 + k * 1024); } while (0)
; #define PG8_MMA(ai, bj, At, Bt) do { __builtin_amdgcn_s_setprio(1); _Pragma("unroll") for (int m = 0; m < 4; ++m) _Pragma("unroll") for (int n = 0; n < 2; ++n) _Pragma("unroll") for (int k = 0; k < 2; ++k) \
;         acc[ai][bj][m][n] = __builtin_amdgcn_mfma_f32_16x16x32_bf16(Bt[n][k], At[m][k], acc[ai][bj][m][n], 0, 0, 0); __builtin_amdgcn_s_setprio(0); } while (0)
; #define PG8_WAIT_V(n) asm volatile("s_waitcnt vmcnt(" #n ")" ::: "memory")
; #define PG8_WAIT_L(n) asm volatile("s_waitcnt lgkmcnt(" #n ")" ::: "memory")
; #define PG8_BAR __builtin_amdgcn_s_barrier()
; #define PG8_SCHED __builtin_amdgcn_sched_barrier(0)
; template <class Epi, class Sched, bool ALIGN_EPI = false, bool SP2 = false>
; __device__ __forceinline__ void gemm_phase(PG8_LAS unsigned char* lds, const Gemm g, const Sched& S, const Epi& E) {
;     ...
;             PG8_LDA(At, 1, 1); PG8_STAGE(PG8_SB(1, 0), b3, voffB); PG8_STAGE(PG8_SB(1, 1), b3 + hstepB, voffB); PG8_STAGE(PG8_SA(1, 0), a3, voffA);
;             PG8_WAIT_V(8); PG8_WAIT_L(0); PG8_BAR; PG8_MMA(1, 0, At, B0); PG8_MMA(1, 1, At, B1); PG8_BAR; PG8_SCHED;
	s_add_i32 s42, s69, s49
	v_lshl_add_u64 v[206:207], v[206:207], 0, s[16:17]
	s_mov_b32 m0, s42
	ds_read_b128 v[198:201], v175 offset:49152
	ds_read_b128 v[202:205], v175 offset:50176
	ds_read_b128 v[208:211], v175 offset:51200
	ds_read_b128 v[212:215], v175 offset:52224
	ds_read_b128 v[216:219], v175 offset:53248
	ds_read_b128 v[220:223], v175 offset:54272
	ds_read_b128 v[224:227], v175 offset:55296
	ds_read_b128 v[228:231], v175 offset:56320
	global_load_lds_dwordx4 v[206:207], off
	s_add_i32 m0, s42, 0x2000
	s_add_u32 s40, s40, 0x40080
	v_lshl_add_u64 v[206:207], v[232:233], 0, s[16:17]
	s_addc_u32 s41, s41, 0
	s_add_i32 s42, s70, s49
	global_load_lds_dwordx4 v[206:207], off
	v_lshl_add_u64 v[206:207], s[40:41], 0, v[148:149]
	s_mov_b32 m0, s42
	s_nop 0
	global_load_lds_dwordx4 v[206:207], off
	v_lshl_add_u64 v[206:207], s[40:41], 0, v[144:145]
	s_add_i32 m0, s42, 0x2000
	s_nop 0
	global_load_lds_dwordx4 v[206:207], off
	v_lshl_add_u64 v[206:207], s[38:39], 0, v[150:151]
	s_mov_b32 m0, s56
	s_nop 0
	global_load_lds_dwordx4 v[206:207], off
	v_lshl_add_u64 v[206:207], s[38:39], 0, v[146:147]
	s_mov_b32 m0, s57
	s_nop 0
	global_load_lds_dwordx4 v[206:207], off
	s_waitcnt vmcnt(8)
	s_waitcnt lgkmcnt(0)
	s_barrier
	s_setprio 1
	v_mfma_f32_16x16x32_bf16 v[92:95], v[132:135], v[198:201], v[92:95]
	v_mfma_f32_16x16x32_bf16 v[88:91], v[140:143], v[198:201], v[88:91]
	v_mfma_f32_16x16x32_bf16 v[84:87], v[132:135], v[208:211], v[84:87]
	v_mfma_f32_16x16x32_bf16 v[80:83], v[140:143], v[208:211], v[80:83]
	v_mfma_f32_16x16x32_bf16 v[76:79], v[132:135], v[216:219], v[76:79]
	v_mfma_f32_16x16x32_bf16 v[72:75], v[140:143], v[216:219], v[72:75]
	v_mfma_f32_16x16x32_bf16 v[68:71], v[132:135], v[224:227], v[68:71]
	v_mfma_f32_16x16x32_bf16 v[60:63], v[140:143], v[224:227], v[60:63]
	v_mfma_f32_16x16x32_bf16 v[92:95], v[136:139], v[202:205], v[92:95]
	v_mfma_f32_16x16x32_bf16 v[88:91], v[178:181], v[202:205], v[88:91]
	v_mfma_f32_16x16x32_bf16 v[84:87], v[136:139], v[212:215], v[84:87]
	v_mfma_f32_16x16x32_bf16 v[80:83], v[178:181], v[212:215], v[80:83]
	v_mfma_f32_16x16x32_bf16 v[76:79], v[136:139], v[220:223], v[76:79]
	v_mfma_f32_16x16x32_bf16 v[72:75], v[178:181], v[220:223], v[72:75]
	v_mfma_f32_16x16x32_bf16 v[68:71], v[136:139], v[228:231], v[68:71]
	v_mfma_f32_16x16x32_bf16 v[60:63], v[178:181], v[228:231], v[60:63]
	v_mfma_f32_16x16x32_bf16 v[28:31], v[182:185], v[198:201], v[28:31]
	v_mfma_f32_16x16x32_bf16 v[24:27], v[190:193], v[198:201], v[24:27]
	v_mfma_f32_16x16x32_bf16 v[20:23], v[182:185], v[208:211], v[20:23]
	v_mfma_f32_16x16x32_bf16 v[16:19], v[190:193], v[208:211], v[16:19]
	v_mfma_f32_16x16x32_bf16 v[12:15], v[182:185], v[216:219], v[12:15]
	v_mfma_f32_16x16x32_bf16 v[8:11], v[190:193], v[216:219], v[8:11]
	v_mfma_f32_16x16x32_bf16 v[4:7], v[182:185], v[224:227], v[4:7]
	v_mfma_f32_16x16x32_bf16 v[0:3], v[190:193], v[224:227], v[0:3]
	v_mfma_f32_16x16x32_bf16 v[28:31], v[186:189], v[202:205], v[28:31]
	v_mfma_f32_16x16x32_bf16 v[24:27], v[194:197], v[202:205], v[24:27]
	v_mfma_f32_16x16x32_bf16 v[20:23], v[186:189], v[212:215], v[20:23]
	v_mfma_f32_16x16x32_bf16 v[16:19], v[194:197], v[212:215], v[16:19]
	v_mfma_f32_16x16x32_bf16 v[12:15], v[186:189], v[220:223], v[12:15]
	v_mfma_f32_16x16x32_bf16 v[8:11], v[194:197], v[220:223], v[8:11]
	v_mfma_f32_16x16x32_bf16 v[4:7], v[186:189], v[228:231], v[4:7]
	v_mfma_f32_16x16x32_bf16 v[0:3], v[194:197], v[228:231], v[0:3]
	s_setprio 0
	s_barrier
	s_add_i32 s68, s68, 2
	s_add_u32 s36, s36, 0x100
	s_addc_u32 s37, s37, 0
	s_cmp_gt_u32 s68, 13
	s_cbranch_scc0 .LBB0_416
	s_and_b64 vcc, exec, s[18:19]
	s_cbranch_vccz .LBB0_419
	s_barrier

; #define PG8_STAGE(bufoff, gbase, voff) do { _Pragma("unroll") for (int _i = 0; _i < 2; ++_i) \
;         __builtin_amdgcn_global_load_lds((const unsigned*)((const char*)(gbase) + (voff)[_i]), (PG8_LAS unsigned*)(lds + (bufoff) + ldsw + _i * 8192), 16, 0, 0); } while (0)
; #define PG8_LDA(dst, b, h) do { _Pragma("unroll") for (int m = 0; m < 4; ++m) _Pragma("unroll") for (int k = 0; k < 2; ++k) dst[m][k] = *(const PG8_LAS bf16x8*)(lds + PG8_SA(b, h) + aoff + m * 2048 + k * 1024); } while (0)
; #define PG8_LDB(dst, b, h) do { _Pragma("unroll") for (int n = 0; n < 2; ++n) _Pragma("unroll") for (int k = 0; k < 2; ++k) dst[n][k] = *(const PG8_LAS bf16x8*)(lds + PG8_SB(b, h) + boff + n * 2048 + k * 1024); } while (0)
; #define PG8_MMA(ai, bj, At, Bt) do { __builtin_amdgcn_s_setprio(1); _Pragma("unroll") for (int m = 0; m < 4; ++m) _Pragma("unroll") for (int n = 0; n < 2; ++n) _Pragma("unroll") for (int k = 0; k < 2; ++k) \
;         acc[ai][bj][m][n] = __builtin_amdgcn_mfma_f32_16x16x32_bf16(Bt[n][k], At[m][k], acc[ai][bj][m][n], 0, 0, 0); __builtin_amdgcn_s_setprio(0); } while (0)
; #define PG8_WAIT_V(n) asm volatile("s_waitcnt vmcnt(" #n ")" ::: "memory")
; #define PG8_WAIT_L(n) asm volatile("s_waitcnt lgkmcnt(" #n ")" ::: "memory")
; #define PG8_BAR __builtin_amdgcn_s_barrier()
; #define PG8_SCHED __builtin_amdgcn_sched_barrier(0)
; template <class Epi, class Sched, bool ALIGN_EPI = false, bool SP2 = false>
; __device__ __forceinline__ void gemm_phase(PG8_LAS unsigned char* lds, const Gemm g, const Sched& S, const Epi& E) {
;     ...
;             PG8_LDB(B0, 0, 0); PG8_LDB(B1, 0, 1); PG8_SCHED; PG8_LDA(At, 0, 0); PG8_STAGE(PG8_SA(1, 1), a1 + hstepA, voffA);
;             PG8_WAIT_V(8); PG8_WAIT_L(0); PG8_BAR; PG8_MMA(0, 0, At, B0); PG8_MMA(0, 1, At, B1); PG8_BAR; PG8_SCHED;
;             PG8_LDA(At, 0, 1); PG8_STAGE(PG8_SB(0, 0), b2, voffB); PG8_STAGE(PG8_SB(0, 1), b2 + hstepB, voffB); PG8_STAGE(PG8_SA(0, 0), a2, voffA);
.LBB0_439:
	ds_read_b128 v[0:3], v145
	ds_read_b128 v[4:7], v145 offset:1024
	ds_read_b128 v[8:11], v145 offset:2048
	ds_read_b128 v[12:15], v145 offset:3072
	ds_read_b128 v[16:19], v146
	ds_read_b128 v[20:23], v146 offset:1024
	ds_read_b128 v[24:27], v146 offset:2048
	ds_read_b128 v[28:31], v146 offset:3072
	s_ashr_i32 s31, s30, 31
	s_lshl_b64 s[34:35], s[30:31], 17
	s_add_u32 s34, s49, s34
	s_addc_u32 s35, s50, s35
	s_and_b64 s[36:37], s[4:5], exec
	s_cselect_b32 s47, s35, s41
	s_cselect_b32 s46, s34, s40
	s_ashr_i32 s29, s28, 31
	s_lshl_b64 s[36:37], s[28:29], 17
	s_add_u32 s36, s51, s36
	s_addc_u32 s37, s52, s37
	s_and_b64 s[44:45], s[4:5], exec
	s_cselect_b32 s45, s37, s43
	s_cselect_b32 s44, s36, s42
	s_add_u32 s66, s40, 0x10080
	s_addc_u32 s67, s41, 0
	s_add_i32 s78, s3, 0xc000
	v_lshl_add_u64 v[64:65], s[66:67], 0, v[128:129]
	s_mov_b32 m0, s78
	s_add_i32 s29, s3, 0xe000
	ds_read_b128 v[32:35], v147
	ds_read_b128 v[36:39], v147 offset:1024
	ds_read_b128 v[40:43], v147 offset:2048
	ds_read_b128 v[44:47], v147 offset:3072
	ds_read_b128 v[48:51], v147 offset:4096
	ds_read_b128 v[52:55], v147 offset:5120
	ds_read_b128 v[56:59], v147 offset:6144
	ds_read_b128 v[60:63], v147 offset:7168
	global_load_lds_dwordx4 v[64:65], off
	v_lshl_add_u64 v[64:65], s[66:67], 0, v[132:133]
	s_mov_b32 m0, s29
	s_nop 0
	global_load_lds_dwordx4 v[64:65], off
	s_waitcnt vmcnt(8)
	s_waitcnt lgkmcnt(0)
	s_barrier
	s_setprio 1
	v_mfma_f32_16x16x32_bf16 v[64:67], v[0:3], v[32:35], 0
	v_mfma_f32_16x16x32_bf16 v[68:71], v[8:11], v[32:35], 0
	v_mfma_f32_16x16x32_bf16 v[72:75], v[0:3], v[40:43], 0
	v_mfma_f32_16x16x32_bf16 v[76:79], v[8:11], v[40:43], 0
	v_mfma_f32_16x16x32_bf16 v[80:83], v[0:3], v[48:51], 0
	v_mfma_f32_16x16x32_bf16 v[84:87], v[8:11], v[48:51], 0
	v_mfma_f32_16x16x32_bf16 v[88:91], v[0:3], v[56:59], 0
	v_mfma_f32_16x16x32_bf16 v[92:95], v[8:11], v[56:59], 0
	v_mfma_f32_16x16x32_bf16 v[64:67], v[4:7], v[36:39], v[64:67]
	v_mfma_f32_16x16x32_bf16 v[68:71], v[12:15], v[36:39], v[68:71]
	v_mfma_f32_16x16x32_bf16 v[72:75], v[4:7], v[44:47], v[72:75]
	v_mfma_f32_16x16x32_bf16 v[76:79], v[12:15], v[44:47], v[76:79]
	v_mfma_f32_16x16x32_bf16 v[80:83], v[4:7], v[52:55], v[80:83]
	v_mfma_f32_16x16x32_bf16 v[84:87], v[12:15], v[52:55], v[84:87]
	v_mfma_f32_16x16x32_bf16 v[88:91], v[4:7], v[60:63], v[88:91]
	v_mfma_f32_16x16x32_bf16 v[92:95], v[12:15], v[60:63], v[92:95]
	v_mfma_f32_16x16x32_bf16 v[96:99], v[16:19], v[32:35], 0
	v_mfma_f32_16x16x32_bf16 v[32:35], v[24:27], v[32:35], 0
	v_mfma_f32_16x16x32_bf16 v[96:99], v[20:23], v[36:39], v[96:99]
	v_mfma_f32_16x16x32_bf16 v[32:35], v[28:31], v[36:39], v[32:35]
	v_mfma_f32_16x16x32_bf16 v[36:39], v[16:19], v[40:43], 0
	v_mfma_f32_16x16x32_bf16 v[40:43], v[24:27], v[40:43], 0
	v_mfma_f32_16x16x32_bf16 v[36:39], v[20:23], v[44:47], v[36:39]
	v_mfma_f32_16x16x32_bf16 v[40:43], v[28:31], v[44:47], v[40:43]
	v_mfma_f32_16x16x32_bf16 v[44:47], v[16:19], v[48:51], 0
	v_mfma_f32_16x16x32_bf16 v[48:51], v[24:27], v[48:51], 0
	v_mfma_f32_16x16x32_bf16 v[44:47], v[20:23], v[52:55], v[44:47]
	v_mfma_f32_16x16x32_bf16 v[48:51], v[28:31], v[52:55], v[48:51]
	v_mfma_f32_16x16x32_bf16 v[52:55], v[16:19], v[56:59], 0
	v_mfma_f32_16x16x32_bf16 v[56:59], v[24:27], v[56:59], 0
	v_mfma_f32_16x16x32_bf16 v[52:55], v[20:23], v[60:63], v[52:55]
	v_mfma_f32_16x16x32_bf16 v[56:59], v[28:31], v[60:63], v[56:59]
	s_setprio 0
	s_barrier
	s_add_i32 s68, s59, s53
	v_lshl_add_u64 v[140:141], s[42:43], 0, v[130:131]
	s_add_i32 s31, s68, 0x2000
	v_lshl_add_u64 v[148:149], v[140:141], 0, s[16:17]
	s_mov_b32 m0, s68
	v_lshl_add_u64 v[204:205], s[42:43], 0, v[134:135]
	s_add_u32 s70, s42, 0x10100
	ds_read_b128 v[60:63], v147 offset:16384
	ds_read_b128 v[100:103], v147 offset:17408
	ds_read_b128 v[104:107], v147 offset:18432
	ds_read_b128 v[108:111], v147 offset:19456
	ds_read_b128 v[112:115], v147 offset:20480
	ds_read_b128 v[116:119], v147 offset:21504
	ds_read_b128 v[120:123], v147 offset:22528
	ds_read_b128 v[124:127], v147 offset:23552
	global_load_lds_dwordx4 v[148:149], off
	v_lshl_add_u64 v[148:149], v[204:205], 0, s[16:17]
	s_mov_b32 m0, s31
	s_addc_u32 s71, s43, 0
	s_add_i32 s66, s60, s53
	global_load_lds_dwordx4 v[148:149], off
	v_lshl_add_u64 v[148:149], s[70:71], 0, v[130:131]
	s_mov_b32 m0, s66
	s_add_i32 s67, s66, 0x2000
	global_load_lds_dwordx4 v[148:149], off
	v_lshl_add_u64 v[148:149], s[70:71], 0, v[134:135]
	s_mov_b32 m0, s67
	v_lshl_add_u64 v[206:207], s[40:41], 0, v[128:129]
	global_load_lds_dwordx4 v[148:149], off
	v_lshl_add_u64 v[148:149], v[206:207], 0, s[16:17]
	s_mov_b32 m0, s3
	v_lshl_add_u64 v[216:217], s[40:41], 0, v[132:133]
	global_load_lds_dwordx4 v[148:149], off
	v_lshl_add_u64 v[148:149], v[216:217], 0, s[16:17]
	s_mov_b32 m0, s39
	s_nop 0
	global_load_lds_dwordx4 v[148:149], off
	s_waitcnt vmcnt(8)
	s_waitcnt lgkmcnt(0)
	s_barrier
; #define PG8_STAGE(bufoff, gbase, voff) do { _Pragma("unroll") for (int _i = 0; _i < 2; ++_i) \
;         __builtin_amdgcn_global_load_lds((const unsigned*)((const char*)(gbase) + (voff)[_i]), (PG8_LAS unsigned*)(lds + (bufoff) + ldsw + _i * 8192), 16, 0, 0); } while (0)
; #define PG8_LDA(dst, b, h) do { _Pragma("unroll") for (int m = 0; m < 4; ++m) _Pragma("unroll") for (int k = 0; k < 2; ++k) dst[m][k] = *(const PG8_LAS bf16x8*)(lds + PG8_SA(b, h) + aoff + m * 2048 + k * 1024); } while (0)
; #define PG8_LDB(dst, b, h) do { _Pragma("unroll") for (int n = 0; n < 2; ++n) _Pragma("unroll") for (int k = 0; k < 2; ++k) dst[n][k] = *(const PG8_LAS bf16x8*)(lds + PG8_SB(b, h) + boff + n * 2048 + k * 1024); } while (0)
; #define PG8_MMA(ai, bj, At, Bt) do { __builtin_amdgcn_s_setprio(1); _Pragma("unroll") for (int m = 0; m < 4; ++m) _Pragma("unroll") for (int n = 0; n < 2; ++n) _Pragma("unroll") for (int k = 0; k < 2; ++k) \
;         acc[ai][bj][m][n] = __builtin_amdgcn_mfma_f32_16x16x32_bf16(Bt[n][k], At[m][k], acc[ai][bj][m][n], 0, 0, 0); __builtin_amdgcn_s_setprio(0); } while (0)
; #define PG8_WAIT_V(n) asm volatile("s_waitcnt vmcnt(" #n ")" ::: "memory")
; #define PG8_WAIT_L(n) asm volatile("s_waitcnt lgkmcnt(" #n ")" ::: "memory")
; #define PG8_BAR __builtin_amdgcn_s_barrier()
; #define PG8_SCHED __builtin_amdgcn_sched_barrier(0)
; template <class Epi, class Sched, bool ALIGN_EPI = false, bool SP2 = false>
; __device__ __forceinline__ void gemm_phase(PG8_LAS unsigned char* lds, const Gemm g, const Sched& S, const Epi& E) {
;     ...
;             PG8_LDA(At, 0, 1); PG8_STAGE(PG8_SB(0, 0), b2, voffB); PG8_STAGE(PG8_SB(0, 1), b2 + hstepB, voffB); PG8_STAGE(PG8_SA(0, 0), a2, voffA);
;             PG8_WAIT_V(8); PG8_WAIT_L(0); PG8_BAR; PG8_MMA(1, 0, At, B0); PG8_MMA(1, 1, At, B1); PG8_BAR; PG8_SCHED;
;             PG8_LDB(B0, 1, 0); PG8_LDB(B1, 1, 1); PG8_SCHED; PG8_LDA(At, 1, 0); PG8_STAGE(PG8_SA(0, 1), a2 + hstepA, voffA);
;             PG8_WAIT_V(8); PG8_WAIT_L(0); PG8_BAR; PG8_MMA(0, 0, At, B0); PG8_MMA(0, 1, At, B1); PG8_BAR; PG8_SCHED;
	s_setprio 1
	v_mfma_f32_16x16x32_bf16 v[148:151], v[0:3], v[60:63], 0
	v_mfma_f32_16x16x32_bf16 v[156:159], v[0:3], v[104:107], 0
	v_mfma_f32_16x16x32_bf16 v[164:167], v[0:3], v[112:115], 0
	v_mfma_f32_16x16x32_bf16 v[0:3], v[0:3], v[120:123], 0
	v_mfma_f32_16x16x32_bf16 v[148:151], v[4:7], v[100:103], v[148:151]
	v_mfma_f32_16x16x32_bf16 v[156:159], v[4:7], v[108:111], v[156:159]
	v_mfma_f32_16x16x32_bf16 v[164:167], v[4:7], v[116:119], v[164:167]
	v_mfma_f32_16x16x32_bf16 v[0:3], v[4:7], v[124:127], v[0:3]
	v_mfma_f32_16x16x32_bf16 v[4:7], v[8:11], v[120:123], 0
	v_mfma_f32_16x16x32_bf16 v[152:155], v[8:11], v[60:63], 0
	v_mfma_f32_16x16x32_bf16 v[160:163], v[8:11], v[104:107], 0
	v_mfma_f32_16x16x32_bf16 v[168:171], v[8:11], v[112:115], 0
	v_mfma_f32_16x16x32_bf16 v[4:7], v[12:15], v[124:127], v[4:7]
	v_mfma_f32_16x16x32_bf16 v[152:155], v[12:15], v[100:103], v[152:155]
	v_mfma_f32_16x16x32_bf16 v[160:163], v[12:15], v[108:111], v[160:163]
	v_mfma_f32_16x16x32_bf16 v[168:171], v[12:15], v[116:119], v[168:171]
	v_mfma_f32_16x16x32_bf16 v[8:11], v[16:19], v[60:63], 0
	v_mfma_f32_16x16x32_bf16 v[12:15], v[24:27], v[60:63], 0
	v_mfma_f32_16x16x32_bf16 v[8:11], v[20:23], v[100:103], v[8:11]
	v_mfma_f32_16x16x32_bf16 v[12:15], v[28:31], v[100:103], v[12:15]
	v_mfma_f32_16x16x32_bf16 v[60:63], v[16:19], v[104:107], 0
	v_mfma_f32_16x16x32_bf16 v[100:103], v[24:27], v[104:107], 0
	v_mfma_f32_16x16x32_bf16 v[104:107], v[16:19], v[112:115], 0
	v_mfma_f32_16x16x32_bf16 v[16:19], v[16:19], v[120:123], 0
	v_mfma_f32_16x16x32_bf16 v[60:63], v[20:23], v[108:111], v[60:63]
	v_mfma_f32_16x16x32_bf16 v[100:103], v[28:31], v[108:111], v[100:103]
	v_mfma_f32_16x16x32_bf16 v[104:107], v[20:23], v[116:119], v[104:107]
	v_mfma_f32_16x16x32_bf16 v[108:111], v[24:27], v[112:115], 0
	v_mfma_f32_16x16x32_bf16 v[16:19], v[20:23], v[124:127], v[16:19]
	v_mfma_f32_16x16x32_bf16 v[20:23], v[24:27], v[120:123], 0
	v_mfma_f32_16x16x32_bf16 v[108:111], v[28:31], v[116:119], v[108:111]
	v_mfma_f32_16x16x32_bf16 v[20:23], v[28:31], v[124:127], v[20:23]
	s_setprio 0
	s_barrier
	s_add_i32 s79, 0, 0x18000
	s_add_i32 s80, 0, 0x1c000
	v_add_u32_e32 v228, s79, v143
	v_add_u32_e32 v236, s80, v143
	ds_read_b128 v[24:27], v228
	ds_read_b128 v[28:31], v228 offset:1024
	ds_read_b128 v[112:115], v228 offset:2048
	ds_read_b128 v[116:119], v228 offset:3072
	ds_read_b128 v[120:123], v236
	ds_read_b128 v[124:127], v236 offset:1024
	ds_read_b128 v[172:175], v236 offset:2048
	ds_read_b128 v[176:179], v236 offset:3072
	s_add_u32 s70, s40, 0x10100
	s_addc_u32 s71, s41, 0
	s_mov_b32 m0, s54
	v_lshl_add_u64 v[218:219], s[70:71], 0, v[128:129]
	ds_read_b128 v[180:183], v147 offset:32768
	ds_read_b128 v[184:187], v147 offset:33792
	ds_read_b128 v[188:191], v147 offset:34816
	ds_read_b128 v[192:195], v147 offset:35840
	ds_read_b128 v[196:199], v147 offset:36864
	ds_read_b128 v[200:203], v147 offset:37888
	ds_read_b128 v[208:211], v147 offset:38912
	ds_read_b128 v[212:215], v147 offset:39936
	global_load_lds_dwordx4 v[218:219], off
	v_lshl_add_u64 v[218:219], s[70:71], 0, v[132:133]
	s_mov_b32 m0, s55
	s_nop 0
	global_load_lds_dwordx4 v[218:219], off
	s_waitcnt vmcnt(8)
	s_waitcnt lgkmcnt(0)
	s_barrier
	s_setprio 1
	v_mfma_f32_16x16x32_bf16 v[64:67], v[24:27], v[180:183], v[64:67]
	v_mfma_f32_16x16x32_bf16 v[68:71], v[112:115], v[180:183], v[68:71]
	v_mfma_f32_16x16x32_bf16 v[72:75], v[24:27], v[188:191], v[72:75]
	v_mfma_f32_16x16x32_bf16 v[76:79], v[112:115], v[188:191], v[76:79]
	v_mfma_f32_16x16x32_bf16 v[80:83], v[24:27], v[196:199], v[80:83]
	v_mfma_f32_16x16x32_bf16 v[84:87], v[112:115], v[196:199], v[84:87]
	v_mfma_f32_16x16x32_bf16 v[88:91], v[24:27], v[208:211], v[88:91]
	v_mfma_f32_16x16x32_bf16 v[92:95], v[112:115], v[208:211], v[92:95]
	v_mfma_f32_16x16x32_bf16 v[64:67], v[28:31], v[184:187], v[64:67]
	v_mfma_f32_16x16x32_bf16 v[68:71], v[116:119], v[184:187], v[68:71]
	v_mfma_f32_16x16x32_bf16 v[72:75], v[28:31], v[192:195], v[72:75]
	v_mfma_f32_16x16x32_bf16 v[76:79], v[116:119], v[192:195], v[76:79]
	v_mfma_f32_16x16x32_bf16 v[80:83], v[28:31], v[200:203], v[80:83]
	v_mfma_f32_16x16x32_bf16 v[84:87], v[116:119], v[200:203], v[84:87]
	v_mfma_f32_16x16x32_bf16 v[88:91], v[28:31], v[212:215], v[88:91]
	v_mfma_f32_16x16x32_bf16 v[92:95], v[116:119], v[212:215], v[92:95]
	v_mfma_f32_16x16x32_bf16 v[96:99], v[120:123], v[180:183], v[96:99]
	v_mfma_f32_16x16x32_bf16 v[32:35], v[172:175], v[180:183], v[32:35]
	v_mfma_f32_16x16x32_bf16 v[36:39], v[120:123], v[188:191], v[36:39]
	v_mfma_f32_16x16x32_bf16 v[40:43], v[172:175], v[188:191], v[40:43]
	v_mfma_f32_16x16x32_bf16 v[44:47], v[120:123], v[196:199], v[44:47]
	v_mfma_f32_16x16x32_bf16 v[48:51], v[172:175], v[196:199], v[48:51]
	v_mfma_f32_16x16x32_bf16 v[52:55], v[120:123], v[208:211], v[52:55]
	v_mfma_f32_16x16x32_bf16 v[56:59], v[172:175], v[208:211], v[56:59]
	v_mfma_f32_16x16x32_bf16 v[96:99], v[124:127], v[184:187], v[96:99]
	v_mfma_f32_16x16x32_bf16 v[32:35], v[176:179], v[184:187], v[32:35]
	v_mfma_f32_16x16x32_bf16 v[36:39], v[124:127], v[192:195], v[36:39]
	v_mfma_f32_16x16x32_bf16 v[40:43], v[176:179], v[192:195], v[40:43]
	v_mfma_f32_16x16x32_bf16 v[44:47], v[124:127], v[200:203], v[44:47]
	v_mfma_f32_16x16x32_bf16 v[48:51], v[176:179], v[200:203], v[48:51]
	v_mfma_f32_16x16x32_bf16 v[52:55], v[124:127], v[212:215], v[52:55]
	v_mfma_f32_16x16x32_bf16 v[56:59], v[176:179], v[212:215], v[56:59]
	s_setprio 0
	s_barrier
; #define PG8_STAGE(bufoff, gbase, voff) do { _Pragma("unroll") for (int _i = 0; _i < 2; ++_i) \
;         __builtin_amdgcn_global_load_lds((const unsigned*)((const char*)(gbase) + (voff)[_i]), (PG8_LAS unsigned*)(lds + (bufoff) + ldsw + _i * 8192), 16, 0, 0); } while (0)
; #define PG8_LDA(dst, b, h) do { _Pragma("unroll") for (int m = 0; m < 4; ++m) _Pragma("unroll") for (int k = 0; k < 2; ++k) dst[m][k] = *(const PG8_LAS bf16x8*)(lds + PG8_SA(b, h) + aoff + m * 2048 + k * 1024); } while (0)
; #define PG8_LDB(dst, b, h) do { _Pragma("unroll") for (int n = 0; n < 2; ++n) _Pragma("unroll") for (int k = 0; k < 2; ++k) dst[n][k] = *(const PG8_LAS bf16x8*)(lds + PG8_SB(b, h) + boff + n * 2048 + k * 1024); } while (0)
; #define PG8_MMA(ai, bj, At, Bt) do { __builtin_amdgcn_s_setprio(1); _Pragma("unroll") for (int m = 0; m < 4; ++m) _Pragma("unroll") for (int n = 0; n < 2; ++n) _Pragma("unroll") for (int k = 0; k < 2; ++k) \
;         acc[ai][bj][m][n] = __builtin_amdgcn_mfma_f32_16x16x32_bf16(Bt[n][k], At[m][k], acc[ai][bj][m][n], 0, 0, 0); __builtin_amdgcn_s_setprio(0); } while (0)
; #define PG8_WAIT_V(n) asm volatile("s_waitcnt vmcnt(" #n ")" ::: "memory")
; template <class Epi, class Sched, bool ALIGN_EPI = false, bool SP2 = false>
; __device__ __forceinline__ void gemm_phase(PG8_LAS unsigned char* lds, const Gemm g, const Sched& S, const Epi& E) {
;     ...
;             PG8_LDB(B0, 0, 0); PG8_LDB(B1, 0, 1); PG8_SCHED; PG8_LDA(At, 0, 0); PG8_STAGE(PG8_SA(1, 1), a1 + hstepA, voffA);
;             PG8_WAIT_V(8); PG8_WAIT_L(0); PG8_BAR; PG8_MMA(0, 0, At, B0); PG8_MMA(0, 1, At, B1); PG8_BAR; PG8_SCHED;
;             PG8_LDA(At, 0, 1); PG8_STAGE(PG8_SB(0, 0), b2, voffB); PG8_STAGE(PG8_SB(0, 1), b2 + hstepB, voffB); PG8_STAGE(PG8_SA(0, 0), a2, voffA);
;             PG8_WAIT_V(8); PG8_WAIT_L(0); PG8_BAR; PG8_MMA(1, 0, At, B0); PG8_MMA(1, 1, At, B1); PG8_BAR; PG8_SCHED;
;             PG8_LDB(B0, 1, 0); PG8_LDB(B1, 1, 1); PG8_SCHED; PG8_LDA(At, 1, 0); PG8_STAGE(PG8_SA(0, 1), a2 + hstepA, voffA);
;             PG8_WAIT_V(8); PG8_WAIT_L(0); PG8_BAR; PG8_MMA(0, 0, At, B0); PG8_MMA(0, 1, At, B1); PG8_BAR; PG8_SCHED;
;             PG8_LDA(At, 1, 1); PG8_STAGE(PG8_SB(1, 0), b3, voffB); PG8_STAGE(PG8_SB(1, 1), b3 + hstepB, voffB); PG8_STAGE(PG8_SA(1, 0), a3, voffA);
;             PG8_WAIT_V(8); PG8_WAIT_L(0); PG8_BAR; PG8_MMA(1, 0, At, B0); PG8_MMA(1, 1, At, B1); PG8_BAR; PG8_SCHED;
	s_add_i32 s79, s79, s53
	s_add_i32 s69, s79, 0x2000
	v_lshl_add_u64 v[140:141], v[140:141], 0, s[18:19]
	s_mov_b32 m0, s79
	s_add_u32 s70, s42, 0x10180
	ds_read_b128 v[180:183], v147 offset:49152
	ds_read_b128 v[184:187], v147 offset:50176
	ds_read_b128 v[188:191], v147 offset:51200
	ds_read_b128 v[192:195], v147 offset:52224
	ds_read_b128 v[196:199], v147 offset:53248
	ds_read_b128 v[200:203], v147 offset:54272
	ds_read_b128 v[208:211], v147 offset:55296
	ds_read_b128 v[212:215], v147 offset:56320
	global_load_lds_dwordx4 v[140:141], off
	v_lshl_add_u64 v[140:141], v[204:205], 0, s[18:19]
	s_mov_b32 m0, s69
	s_addc_u32 s71, s43, 0
	s_add_i32 s42, s80, s53
	global_load_lds_dwordx4 v[140:141], off
	v_lshl_add_u64 v[140:141], s[70:71], 0, v[130:131]
	s_mov_b32 m0, s42
	s_add_i32 s43, s42, 0x2000
	global_load_lds_dwordx4 v[140:141], off
	v_lshl_add_u64 v[140:141], s[70:71], 0, v[134:135]
	s_mov_b32 m0, s43
	s_nop 0
	global_load_lds_dwordx4 v[140:141], off
	v_lshl_add_u64 v[140:141], v[206:207], 0, s[18:19]
	s_mov_b32 m0, s56
	s_nop 0
	global_load_lds_dwordx4 v[140:141], off
	v_lshl_add_u64 v[140:141], v[216:217], 0, s[18:19]
	s_mov_b32 m0, s57
	s_nop 0
	global_load_lds_dwordx4 v[140:141], off
	s_waitcnt vmcnt(8)
	s_waitcnt lgkmcnt(0)
	s_barrier
	s_setprio 1
	v_mfma_f32_16x16x32_bf16 v[0:3], v[24:27], v[208:211], v[0:3]
	v_mfma_f32_16x16x32_bf16 v[4:7], v[112:115], v[208:211], v[4:7]
	v_mfma_f32_16x16x32_bf16 v[148:151], v[24:27], v[180:183], v[148:151]
	v_mfma_f32_16x16x32_bf16 v[152:155], v[112:115], v[180:183], v[152:155]
	v_mfma_f32_16x16x32_bf16 v[156:159], v[24:27], v[188:191], v[156:159]
	v_mfma_f32_16x16x32_bf16 v[160:163], v[112:115], v[188:191], v[160:163]
	v_mfma_f32_16x16x32_bf16 v[164:167], v[24:27], v[196:199], v[164:167]
	v_mfma_f32_16x16x32_bf16 v[168:171], v[112:115], v[196:199], v[168:171]
	v_mfma_f32_16x16x32_bf16 v[0:3], v[28:31], v[212:215], v[0:3]
	v_mfma_f32_16x16x32_bf16 v[4:7], v[116:119], v[212:215], v[4:7]
	v_mfma_f32_16x16x32_bf16 v[148:151], v[28:31], v[184:187], v[148:151]
	v_mfma_f32_16x16x32_bf16 v[152:155], v[116:119], v[184:187], v[152:155]
	v_mfma_f32_16x16x32_bf16 v[156:159], v[28:31], v[192:195], v[156:159]
	v_mfma_f32_16x16x32_bf16 v[160:163], v[116:119], v[192:195], v[160:163]
	v_mfma_f32_16x16x32_bf16 v[164:167], v[28:31], v[200:203], v[164:167]
	v_mfma_f32_16x16x32_bf16 v[168:171], v[116:119], v[200:203], v[168:171]
	v_mfma_f32_16x16x32_bf16 v[8:11], v[120:123], v[180:183], v[8:11]
	v_mfma_f32_16x16x32_bf16 v[12:15], v[172:175], v[180:183], v[12:15]
	v_mfma_f32_16x16x32_bf16 v[24:27], v[120:123], v[188:191], v[60:63]
	v_mfma_f32_16x16x32_bf16 v[28:31], v[172:175], v[188:191], v[100:103]
	v_mfma_f32_16x16x32_bf16 v[60:63], v[120:123], v[196:199], v[104:107]
	v_mfma_f32_16x16x32_bf16 v[100:103], v[172:175], v[196:199], v[108:111]
	v_mfma_f32_16x16x32_bf16 v[16:19], v[120:123], v[208:211], v[16:19]
	v_mfma_f32_16x16x32_bf16 v[20:23], v[172:175], v[208:211], v[20:23]
	v_mfma_f32_16x16x32_bf16 v[8:11], v[124:127], v[184:187], v[8:11]
	v_mfma_f32_16x16x32_bf16 v[12:15], v[176:179], v[184:187], v[12:15]
	v_mfma_f32_16x16x32_bf16 v[24:27], v[124:127], v[192:195], v[24:27]
	v_mfma_f32_16x16x32_bf16 v[28:31], v[176:179], v[192:195], v[28:31]
	v_mfma_f32_16x16x32_bf16 v[60:63], v[124:127], v[200:203], v[60:63]
	v_mfma_f32_16x16x32_bf16 v[100:103], v[176:179], v[200:203], v[100:103]
	v_mfma_f32_16x16x32_bf16 v[16:19], v[124:127], v[212:215], v[16:19]
	v_mfma_f32_16x16x32_bf16 v[20:23], v[176:179], v[212:215], v[20:23]
	s_setprio 0
	s_barrier
	ds_read_b128 v[104:107], v145
	ds_read_b128 v[108:111], v145 offset:1024
	ds_read_b128 v[112:115], v145 offset:2048
	ds_read_b128 v[116:119], v145 offset:3072
	ds_read_b128 v[120:123], v146
	ds_read_b128 v[124:127], v146 offset:1024
	ds_read_b128 v[172:175], v146 offset:2048
	ds_read_b128 v[176:179], v146 offset:3072
	s_add_u32 s40, s40, 0x10180
	s_addc_u32 s41, s41, 0
	s_mov_b32 m0, s78
	v_lshl_add_u64 v[140:141], s[40:41], 0, v[128:129]
	ds_read_b128 v[180:183], v147
	ds_read_b128 v[184:187], v147 offset:1024
	ds_read_b128 v[188:191], v147 offset:2048
	ds_read_b128 v[192:195], v147 offset:3072
	ds_read_b128 v[196:199], v147 offset:4096
	ds_read_b128 v[200:203], v147 offset:5120
	ds_read_b128 v[208:211], v147 offset:6144
	ds_read_b128 v[212:215], v147 offset:7168
	global_load_lds_dwordx4 v[140:141], off
	v_lshl_add_u64 v[140:141], s[40:41], 0, v[132:133]
	s_mov_b32 m0, s29
	s_nop 0
	global_load_lds_dwordx4 v[140:141], off
	s_waitcnt vmcnt(8)
	s_waitcnt lgkmcnt(0)
	s_barrier
; #define PG8_STAGE(bufoff, gbase, voff) do { _Pragma("unroll") for (int _i = 0; _i < 2; ++_i) \
;         __builtin_amdgcn_global_load_lds((const unsigned*)((const char*)(gbase) + (voff)[_i]), (PG8_LAS unsigned*)(lds + (bufoff) + ldsw + _i * 8192), 16, 0, 0); } while (0)
; #define PG8_LDA(dst, b, h) do { _Pragma("unroll") for (int m = 0; m < 4; ++m) _Pragma("unroll") for (int k = 0; k < 2; ++k) dst[m][k] = *(const PG8_LAS bf16x8*)(lds + PG8_SA(b, h) + aoff + m * 2048 + k * 1024); } while (0)
; #define PG8_LDB(dst, b, h) do { _Pragma("unroll") for (int n = 0; n < 2; ++n) _Pragma("unroll") for (int k = 0; k < 2; ++k) dst[n][k] = *(const PG8_LAS bf16x8*)(lds + PG8_SB(b, h) + boff + n * 2048 + k * 1024); } while (0)
; #define PG8_MMA(ai, bj, At, Bt) do { __builtin_amdgcn_s_setprio(1); _Pragma("unroll") for (int m = 0; m < 4; ++m) _Pragma("unroll") for (int n = 0; n < 2; ++n) _Pragma("unroll") for (int k = 0; k < 2; ++k) \
;         acc[ai][bj][m][n] = __builtin_amdgcn_mfma_f32_16x16x32_bf16(Bt[n][k], At[m][k], acc[ai][bj][m][n], 0, 0, 0); __builtin_amdgcn_s_setprio(0); } while (0)
; #define PG8_WAIT_V(n) asm volatile("s_waitcnt vmcnt(" #n ")" ::: "memory")
; #define PG8_WAIT_L(n) asm volatile("s_waitcnt lgkmcnt(" #n ")" ::: "memory")
; #define PG8_BAR __builtin_amdgcn_s_barrier()
; #define PG8_SCHED __builtin_amdgcn_sched_barrier(0)
; template <class Epi, class Sched, bool ALIGN_EPI = false, bool SP2 = false>
; __device__ __forceinline__ void gemm_phase(PG8_LAS unsigned char* lds, const Gemm g, const Sched& S, const Epi& E) {
;     ...
;             PG8_LDB(B0, 0, 0); PG8_LDB(B1, 0, 1); PG8_SCHED; PG8_LDA(At, 0, 0); PG8_STAGE(PG8_SA(1, 1), a1 + hstepA, voffA);
;             PG8_WAIT_V(8); PG8_WAIT_L(0); PG8_BAR; PG8_MMA(0, 0, At, B0); PG8_MMA(0, 1, At, B1); PG8_BAR; PG8_SCHED;
;             PG8_LDA(At, 0, 1); PG8_STAGE(PG8_SB(0, 0), b2, voffB); PG8_STAGE(PG8_SB(0, 1), b2 + hstepB, voffB); PG8_STAGE(PG8_SA(0, 0), a2, voffA);
;             PG8_WAIT_V(8); PG8_WAIT_L(0); PG8_BAR; PG8_MMA(1, 0, At, B0); PG8_MMA(1, 1, At, B1); PG8_BAR; PG8_SCHED;
	s_setprio 1
	v_mfma_f32_16x16x32_bf16 v[88:91], v[104:107], v[208:211], v[88:91]
	v_mfma_f32_16x16x32_bf16 v[64:67], v[104:107], v[180:183], v[64:67]
	v_mfma_f32_16x16x32_bf16 v[68:71], v[112:115], v[180:183], v[68:71]
	v_mfma_f32_16x16x32_bf16 v[72:75], v[104:107], v[188:191], v[72:75]
	v_mfma_f32_16x16x32_bf16 v[76:79], v[112:115], v[188:191], v[76:79]
	v_mfma_f32_16x16x32_bf16 v[80:83], v[104:107], v[196:199], v[80:83]
	v_mfma_f32_16x16x32_bf16 v[84:87], v[112:115], v[196:199], v[84:87]
	v_mfma_f32_16x16x32_bf16 v[216:219], v[108:111], v[212:215], v[88:91]
	v_mfma_f32_16x16x32_bf16 v[88:91], v[112:115], v[208:211], v[92:95]
	v_mfma_f32_16x16x32_bf16 v[64:67], v[108:111], v[184:187], v[64:67]
	v_mfma_f32_16x16x32_bf16 v[68:71], v[116:119], v[184:187], v[68:71]
	v_mfma_f32_16x16x32_bf16 v[72:75], v[108:111], v[192:195], v[72:75]
	v_mfma_f32_16x16x32_bf16 v[76:79], v[116:119], v[192:195], v[76:79]
	v_mfma_f32_16x16x32_bf16 v[80:83], v[108:111], v[200:203], v[80:83]
	v_mfma_f32_16x16x32_bf16 v[84:87], v[116:119], v[200:203], v[84:87]
	v_mfma_f32_16x16x32_bf16 v[92:95], v[116:119], v[212:215], v[88:91]
	v_mfma_f32_16x16x32_bf16 v[48:51], v[172:175], v[196:199], v[48:51]
	v_mfma_f32_16x16x32_bf16 v[88:91], v[120:123], v[180:183], v[96:99]
	v_mfma_f32_16x16x32_bf16 v[32:35], v[172:175], v[180:183], v[32:35]
	v_mfma_f32_16x16x32_bf16 v[36:39], v[120:123], v[188:191], v[36:39]
	v_mfma_f32_16x16x32_bf16 v[40:43], v[172:175], v[188:191], v[40:43]
	v_mfma_f32_16x16x32_bf16 v[44:47], v[120:123], v[196:199], v[44:47]
	v_mfma_f32_16x16x32_bf16 v[180:183], v[176:179], v[200:203], v[48:51]
	v_mfma_f32_16x16x32_bf16 v[48:51], v[120:123], v[208:211], v[52:55]
	v_mfma_f32_16x16x32_bf16 v[32:35], v[176:179], v[184:187], v[32:35]
	v_mfma_f32_16x16x32_bf16 v[36:39], v[124:127], v[192:195], v[36:39]
	v_mfma_f32_16x16x32_bf16 v[40:43], v[176:179], v[192:195], v[40:43]
	v_mfma_f32_16x16x32_bf16 v[44:47], v[124:127], v[200:203], v[44:47]
	v_mfma_f32_16x16x32_bf16 v[52:55], v[124:127], v[212:215], v[48:51]
	v_mfma_f32_16x16x32_bf16 v[48:51], v[172:175], v[208:211], v[56:59]
	v_mfma_f32_16x16x32_bf16 v[220:223], v[124:127], v[184:187], v[88:91]
	v_mfma_f32_16x16x32_bf16 v[184:187], v[176:179], v[212:215], v[48:51]
	s_setprio 0
	s_barrier
	s_mov_b32 m0, s68
	v_lshl_add_u64 v[140:141], s[44:45], 0, v[130:131]
	s_add_u32 s40, s44, 0x10000
	s_nop 0
	ds_read_b128 v[48:51], v147 offset:16384
	ds_read_b128 v[56:59], v147 offset:17408
	ds_read_b128 v[88:91], v147 offset:18432
	ds_read_b128 v[96:99], v147 offset:19456
	ds_read_b128 v[188:191], v147 offset:20480
	ds_read_b128 v[192:195], v147 offset:21504
	ds_read_b128 v[196:199], v147 offset:22528
	ds_read_b128 v[200:203], v147 offset:23552
	global_load_lds_dwordx4 v[140:141], off
	v_lshl_add_u64 v[252:253], s[44:45], 0, v[134:135]
	s_mov_b32 m0, s31
	s_addc_u32 s41, s45, 0
	global_load_lds_dwordx4 v[252:253], off
	v_lshl_add_u64 v[204:205], s[40:41], 0, v[130:131]
	s_mov_b32 m0, s66
	v_lshl_add_u64 v[136:137], s[46:47], 0, v[128:129]
	global_load_lds_dwordx4 v[204:205], off
	v_lshl_add_u64 v[204:205], s[40:41], 0, v[134:135]
	s_mov_b32 m0, s67
	v_lshl_add_u64 v[138:139], s[46:47], 0, v[132:133]
	global_load_lds_dwordx4 v[204:205], off
	s_mov_b32 m0, s3
	s_nop 0
	global_load_lds_dwordx4 v[136:137], off
	s_mov_b32 m0, s39
	s_nop 0
	global_load_lds_dwordx4 v[138:139], off
	s_waitcnt vmcnt(8)
	s_waitcnt lgkmcnt(0)
	s_barrier
	s_setprio 1
	v_mfma_f32_16x16x32_bf16 v[0:3], v[104:107], v[196:199], v[0:3]
	v_mfma_f32_16x16x32_bf16 v[4:7], v[112:115], v[196:199], v[4:7]
	v_mfma_f32_16x16x32_bf16 v[148:151], v[104:107], v[48:51], v[148:151]
	v_mfma_f32_16x16x32_bf16 v[152:155], v[112:115], v[48:51], v[152:155]
	v_mfma_f32_16x16x32_bf16 v[156:159], v[104:107], v[88:91], v[156:159]
	v_mfma_f32_16x16x32_bf16 v[160:163], v[112:115], v[88:91], v[160:163]
	v_mfma_f32_16x16x32_bf16 v[164:167], v[104:107], v[188:191], v[164:167]
	v_mfma_f32_16x16x32_bf16 v[168:171], v[112:115], v[188:191], v[168:171]
	v_mfma_f32_16x16x32_bf16 v[0:3], v[108:111], v[200:203], v[0:3]
	v_mfma_f32_16x16x32_bf16 v[4:7], v[116:119], v[200:203], v[4:7]
	v_mfma_f32_16x16x32_bf16 v[148:151], v[108:111], v[56:59], v[148:151]
	v_mfma_f32_16x16x32_bf16 v[152:155], v[116:119], v[56:59], v[152:155]
	v_mfma_f32_16x16x32_bf16 v[156:159], v[108:111], v[96:99], v[156:159]
	v_mfma_f32_16x16x32_bf16 v[160:163], v[116:119], v[96:99], v[160:163]
	v_mfma_f32_16x16x32_bf16 v[164:167], v[108:111], v[192:195], v[164:167]
	v_mfma_f32_16x16x32_bf16 v[168:171], v[116:119], v[192:195], v[168:171]
	v_mfma_f32_16x16x32_bf16 v[12:15], v[172:175], v[48:51], v[12:15]
	v_mfma_f32_16x16x32_bf16 v[208:211], v[176:179], v[56:59], v[12:15]
	v_mfma_f32_16x16x32_bf16 v[12:15], v[120:123], v[88:91], v[24:27]
	v_mfma_f32_16x16x32_bf16 v[24:27], v[124:127], v[96:99], v[12:15]
	v_mfma_f32_16x16x32_bf16 v[12:15], v[172:175], v[88:91], v[28:31]
	v_mfma_f32_16x16x32_bf16 v[212:215], v[176:179], v[96:99], v[12:15]
	v_mfma_f32_16x16x32_bf16 v[12:15], v[120:123], v[188:191], v[60:63]
	v_mfma_f32_16x16x32_bf16 v[224:227], v[124:127], v[192:195], v[12:15]
	v_mfma_f32_16x16x32_bf16 v[12:15], v[172:175], v[188:191], v[100:103]
	v_mfma_f32_16x16x32_bf16 v[8:11], v[120:123], v[48:51], v[8:11]
	v_mfma_f32_16x16x32_bf16 v[188:191], v[176:179], v[192:195], v[12:15]
	v_mfma_f32_16x16x32_bf16 v[12:15], v[120:123], v[196:199], v[16:19]
	v_mfma_f32_16x16x32_bf16 v[8:11], v[124:127], v[56:59], v[8:11]
	v_mfma_f32_16x16x32_bf16 v[192:195], v[124:127], v[200:203], v[12:15]
	v_mfma_f32_16x16x32_bf16 v[12:15], v[172:175], v[196:199], v[20:23]
	v_mfma_f32_16x16x32_bf16 v[172:175], v[176:179], v[200:203], v[12:15]
	s_setprio 0
	s_barrier
; #define PG8_STAGE(bufoff, gbase, voff) do { _Pragma("unroll") for (int _i = 0; _i < 2; ++_i) \
;         __builtin_amdgcn_global_load_lds((const unsigned*)((const char*)(gbase) + (voff)[_i]), (PG8_LAS unsigned*)(lds + (bufoff) + ldsw + _i * 8192), 16, 0, 0); } while (0)
; #define PG8_LDA(dst, b, h) do { _Pragma("unroll") for (int m = 0; m < 4; ++m) _Pragma("unroll") for (int k = 0; k < 2; ++k) dst[m][k] = *(const PG8_LAS bf16x8*)(lds + PG8_SA(b, h) + aoff + m * 2048 + k * 1024); } while (0)
; #define PG8_LDB(dst, b, h) do { _Pragma("unroll") for (int n = 0; n < 2; ++n) _Pragma("unroll") for (int k = 0; k < 2; ++k) dst[n][k] = *(const PG8_LAS bf16x8*)(lds + PG8_SB(b, h) + boff + n * 2048 + k * 1024); } while (0)
; #define PG8_MMA(ai, bj, At, Bt) do { __builtin_amdgcn_s_setprio(1); _Pragma("unroll") for (int m = 0; m < 4; ++m) _Pragma("unroll") for (int n = 0; n < 2; ++n) _Pragma("unroll") for (int k = 0; k < 2; ++k) \
;         acc[ai][bj][m][n] = __builtin_amdgcn_mfma_f32_16x16x32_bf16(Bt[n][k], At[m][k], acc[ai][bj][m][n], 0, 0, 0); __builtin_amdgcn_s_setprio(0); } while (0)
; #define PG8_WAIT_V(n) asm volatile("s_waitcnt vmcnt(" #n ")" ::: "memory")
; #define PG8_WAIT_L(n) asm volatile("s_waitcnt lgkmcnt(" #n ")" ::: "memory")
; #define PG8_BAR __builtin_amdgcn_s_barrier()
; #define PG8_SCHED __builtin_amdgcn_sched_barrier(0)
; template <class Epi, class Sched, bool ALIGN_EPI = false, bool SP2 = false>
; __device__ __forceinline__ void gemm_phase(PG8_LAS unsigned char* lds, const Gemm g, const Sched& S, const Epi& E) {
;     ...
;             PG8_LDB(B0, 1, 0); PG8_LDB(B1, 1, 1); PG8_SCHED; PG8_LDA(At, 1, 0); PG8_STAGE(PG8_SA(0, 1), a2 + hstepA, voffA);
;             PG8_WAIT_V(8); PG8_WAIT_L(0); PG8_BAR; PG8_MMA(0, 0, At, B0); PG8_MMA(0, 1, At, B1); PG8_BAR; PG8_SCHED;
;             PG8_LDA(At, 1, 1); PG8_STAGE(PG8_SB(1, 0), b3, voffB); PG8_STAGE(PG8_SB(1, 1), b3 + hstepB, voffB); PG8_STAGE(PG8_SA(1, 0), a3, voffA);
;             PG8_WAIT_V(8); PG8_WAIT_L(0); PG8_BAR; PG8_MMA(1, 0, At, B0); PG8_MMA(1, 1, At, B1); PG8_BAR; PG8_SCHED;
	s_nop 4
	ds_read_b128 v[12:15], v228
	ds_read_b128 v[16:19], v228 offset:1024
	ds_read_b128 v[176:179], v228 offset:2048
	ds_read_b128 v[196:199], v228 offset:3072
	ds_read_b128 v[200:203], v236
	ds_read_b128 v[228:231], v236 offset:1024
	ds_read_b128 v[232:235], v236 offset:2048
	ds_read_b128 v[236:239], v236 offset:3072
	s_add_u32 s40, s46, 0x10000
	s_addc_u32 s41, s47, 0
	s_mov_b32 m0, s54
	v_lshl_add_u64 v[48:49], s[40:41], 0, v[128:129]
	ds_read_b128 v[20:23], v147 offset:32768
	ds_read_b128 v[28:31], v147 offset:33792
	ds_read_b128 v[60:63], v147 offset:34816
	ds_read_b128 v[100:103], v147 offset:35840
	ds_read_b128 v[240:243], v147 offset:36864
	ds_read_b128 v[244:247], v147 offset:37888
	ds_read_b128 v[248:251], v147 offset:38912
	ds_read_b128 v[204:207], v147 offset:39936
	global_load_lds_dwordx4 v[48:49], off
	v_lshl_add_u64 v[48:49], s[40:41], 0, v[132:133]
	s_mov_b32 m0, s55
	s_nop 0
	global_load_lds_dwordx4 v[48:49], off
	s_waitcnt vmcnt(8)
	s_waitcnt lgkmcnt(0)
	s_barrier
	s_setprio 1
	v_mfma_f32_16x16x32_bf16 v[48:51], v[12:15], v[20:23], v[64:67]
	v_mfma_f32_16x16x32_bf16 v[120:123], v[16:19], v[28:31], v[48:51]
	v_mfma_f32_16x16x32_bf16 v[48:51], v[176:179], v[20:23], v[68:71]
	v_mfma_f32_16x16x32_bf16 v[112:115], v[196:199], v[28:31], v[48:51]
	v_mfma_f32_16x16x32_bf16 v[48:51], v[12:15], v[60:63], v[72:75]
	v_mfma_f32_16x16x32_bf16 v[104:107], v[16:19], v[100:103], v[48:51]
	v_mfma_f32_16x16x32_bf16 v[48:51], v[176:179], v[60:63], v[76:79]
	v_mfma_f32_16x16x32_bf16 v[96:99], v[196:199], v[100:103], v[48:51]
	v_mfma_f32_16x16x32_bf16 v[48:51], v[12:15], v[240:243], v[80:83]
	v_mfma_f32_16x16x32_bf16 v[88:91], v[16:19], v[244:247], v[48:51]
	v_mfma_f32_16x16x32_bf16 v[48:51], v[176:179], v[240:243], v[84:87]
	v_mfma_f32_16x16x32_bf16 v[80:83], v[196:199], v[244:247], v[48:51]
	v_mfma_f32_16x16x32_bf16 v[48:51], v[12:15], v[248:251], v[216:219]
	v_mfma_f32_16x16x32_bf16 v[56:59], v[16:19], v[204:207], v[48:51]
	v_mfma_f32_16x16x32_bf16 v[48:51], v[176:179], v[248:251], v[92:95]
	v_mfma_f32_16x16x32_bf16 v[48:51], v[196:199], v[204:207], v[48:51]
	v_mfma_f32_16x16x32_bf16 v[64:67], v[200:203], v[20:23], v[220:223]
	v_mfma_f32_16x16x32_bf16 v[20:23], v[232:235], v[20:23], v[32:35]
	v_mfma_f32_16x16x32_bf16 v[116:119], v[236:239], v[28:31], v[20:23]
	v_mfma_f32_16x16x32_bf16 v[20:23], v[200:203], v[60:63], v[36:39]
	v_mfma_f32_16x16x32_bf16 v[108:111], v[228:231], v[100:103], v[20:23]
	v_mfma_f32_16x16x32_bf16 v[20:23], v[232:235], v[60:63], v[40:43]
	v_mfma_f32_16x16x32_bf16 v[100:103], v[236:239], v[100:103], v[20:23]
	v_mfma_f32_16x16x32_bf16 v[20:23], v[200:203], v[240:243], v[44:47]
	v_mfma_f32_16x16x32_bf16 v[92:95], v[228:231], v[244:247], v[20:23]
	v_mfma_f32_16x16x32_bf16 v[20:23], v[232:235], v[240:243], v[180:183]
	v_mfma_f32_16x16x32_bf16 v[84:87], v[236:239], v[244:247], v[20:23]
	v_mfma_f32_16x16x32_bf16 v[20:23], v[200:203], v[248:251], v[52:55]
	v_mfma_f32_16x16x32_bf16 v[60:63], v[228:231], v[204:207], v[20:23]
	v_mfma_f32_16x16x32_bf16 v[20:23], v[232:235], v[248:251], v[184:187]
	v_mfma_f32_16x16x32_bf16 v[124:127], v[228:231], v[28:31], v[64:67]
	v_mfma_f32_16x16x32_bf16 v[52:55], v[236:239], v[204:207], v[20:23]
	s_setprio 0
	s_barrier
	s_mov_b32 m0, s79
	s_nop 2
	v_lshl_add_u64 v[20:21], v[140:141], 0, s[10:11]
	s_add_u32 s40, s44, 0x10080
	ds_read_b128 v[32:35], v147 offset:49152
	ds_read_b128 v[40:43], v147 offset:50176
	ds_read_b128 v[180:183], v147 offset:51200
	ds_read_b128 v[184:187], v147 offset:52224
	ds_read_b128 v[204:207], v147 offset:53248
	ds_read_b128 v[216:219], v147 offset:54272
	ds_read_b128 v[220:223], v147 offset:55296
	ds_read_b128 v[240:243], v147 offset:56320
	global_load_lds_dwordx4 v[20:21], off
	v_lshl_add_u64 v[20:21], v[252:253], 0, s[10:11]
	s_mov_b32 m0, s69
	s_addc_u32 s41, s45, 0
	global_load_lds_dwordx4 v[20:21], off
	v_lshl_add_u64 v[20:21], s[40:41], 0, v[130:131]
	s_mov_b32 m0, s42
	s_nop 0
	global_load_lds_dwordx4 v[20:21], off
	v_lshl_add_u64 v[20:21], s[40:41], 0, v[134:135]
	s_mov_b32 m0, s43
	s_nop 0
	global_load_lds_dwordx4 v[20:21], off
	v_lshl_add_u64 v[20:21], v[136:137], 0, s[10:11]
	s_mov_b32 m0, s56
	s_nop 0
	global_load_lds_dwordx4 v[20:21], off
	v_lshl_add_u64 v[20:21], v[138:139], 0, s[10:11]
	s_mov_b32 m0, s57
	s_nop 0
	global_load_lds_dwordx4 v[20:21], off
	s_waitcnt vmcnt(8)
	s_waitcnt lgkmcnt(0)
	s_barrier
	s_setprio 1
	v_mfma_f32_16x16x32_bf16 v[20:23], v[12:15], v[32:35], v[148:151]
	v_mfma_f32_16x16x32_bf16 v[76:79], v[16:19], v[40:43], v[20:23]
	v_mfma_f32_16x16x32_bf16 v[20:23], v[176:179], v[32:35], v[152:155]
	v_mfma_f32_16x16x32_bf16 v[68:71], v[196:199], v[40:43], v[20:23]
	v_mfma_f32_16x16x32_bf16 v[20:23], v[12:15], v[180:183], v[156:159]
	v_mfma_f32_16x16x32_bf16 v[44:47], v[16:19], v[184:187], v[20:23]
	v_mfma_f32_16x16x32_bf16 v[20:23], v[176:179], v[180:183], v[160:163]
	v_mfma_f32_16x16x32_bf16 v[36:39], v[196:199], v[184:187], v[20:23]
	v_mfma_f32_16x16x32_bf16 v[20:23], v[12:15], v[204:207], v[164:167]
	v_mfma_f32_16x16x32_bf16 v[0:3], v[12:15], v[220:223], v[0:3]
	v_mfma_f32_16x16x32_bf16 v[28:31], v[16:19], v[216:219], v[20:23]
	v_mfma_f32_16x16x32_bf16 v[20:23], v[176:179], v[204:207], v[168:171]
	v_mfma_f32_16x16x32_bf16 v[12:15], v[16:19], v[240:243], v[0:3]
	v_mfma_f32_16x16x32_bf16 v[0:3], v[176:179], v[220:223], v[4:7]
	v_mfma_f32_16x16x32_bf16 v[20:23], v[196:199], v[216:219], v[20:23]
	v_mfma_f32_16x16x32_bf16 v[4:7], v[196:199], v[240:243], v[0:3]
	v_mfma_f32_16x16x32_bf16 v[0:3], v[200:203], v[32:35], v[8:11]
	v_mfma_f32_16x16x32_bf16 v[72:75], v[228:231], v[40:43], v[0:3]
	v_mfma_f32_16x16x32_bf16 v[0:3], v[232:235], v[32:35], v[208:211]
	v_mfma_f32_16x16x32_bf16 v[64:67], v[236:239], v[40:43], v[0:3]
	v_mfma_f32_16x16x32_bf16 v[0:3], v[200:203], v[180:183], v[24:27]
	v_mfma_f32_16x16x32_bf16 v[40:43], v[228:231], v[184:187], v[0:3]
	v_mfma_f32_16x16x32_bf16 v[0:3], v[232:235], v[180:183], v[212:215]
	v_mfma_f32_16x16x32_bf16 v[32:35], v[236:239], v[184:187], v[0:3]
	v_mfma_f32_16x16x32_bf16 v[0:3], v[200:203], v[204:207], v[224:227]
	v_mfma_f32_16x16x32_bf16 v[24:27], v[228:231], v[216:219], v[0:3]
	v_mfma_f32_16x16x32_bf16 v[0:3], v[232:235], v[204:207], v[188:191]
	v_mfma_f32_16x16x32_bf16 v[16:19], v[236:239], v[216:219], v[0:3]
	v_mfma_f32_16x16x32_bf16 v[0:3], v[200:203], v[220:223], v[192:195]
	v_mfma_f32_16x16x32_bf16 v[8:11], v[228:231], v[240:243], v[0:3]
	v_mfma_f32_16x16x32_bf16 v[0:3], v[232:235], v[220:223], v[172:175]
	v_mfma_f32_16x16x32_bf16 v[0:3], v[236:239], v[240:243], v[0:3]
	s_setprio 0
	s_barrier
	s_andn2_b64 vcc, exec, s[12:13]
	s_cbranch_vccnz .LBB0_441
	s_barrier

; #define PG8_STAGE(bufoff, gbase, voff) do { _Pragma("unroll") for (int _i = 0; _i < 2; ++_i) \
;         __builtin_amdgcn_global_load_lds((const unsigned*)((const char*)(gbase) + (voff)[_i]), (PG8_LAS unsigned*)(lds + (bufoff) + ldsw + _i * 8192), 16, 0, 0); } while (0)
; #define PG8_LDA(dst, b, h) do { _Pragma("unroll") for (int m = 0; m < 4; ++m) _Pragma("unroll") for (int k = 0; k < 2; ++k) dst[m][k] = *(const PG8_LAS bf16x8*)(lds + PG8_SA(b, h) + aoff + m * 2048 + k * 1024); } while (0)
; #define PG8_LDB(dst, b, h) do { _Pragma("unroll") for (int n = 0; n < 2; ++n) _Pragma("unroll") for (int k = 0; k < 2; ++k) dst[n][k] = *(const PG8_LAS bf16x8*)(lds + PG8_SB(b, h) + boff + n * 2048 + k * 1024); } while (0)
; #define PG8_MMA(ai, bj, At, Bt) do { __builtin_amdgcn_s_setprio(1); _Pragma("unroll") for (int m = 0; m < 4; ++m) _Pragma("unroll") for (int n = 0; n < 2; ++n) _Pragma("unroll") for (int k = 0; k < 2; ++k) \
;         acc[ai][bj][m][n] = __builtin_amdgcn_mfma_f32_16x16x32_bf16(Bt[n][k], At[m][k], acc[ai][bj][m][n], 0, 0, 0); __builtin_amdgcn_s_setprio(0); } while (0)
; #define PG8_WAIT_V(n) asm volatile("s_waitcnt vmcnt(" #n ")" ::: "memory")
; #define PG8_WAIT_L(n) asm volatile("s_waitcnt lgkmcnt(" #n ")" ::: "memory")
; #define PG8_BAR __builtin_amdgcn_s_barrier()
; #define PG8_SCHED __builtin_amdgcn_sched_barrier(0)
; template <class Epi, class Sched, bool ALIGN_EPI = false, bool SP2 = false>
; __device__ __forceinline__ void gemm_phase(PG8_LAS unsigned char* lds, const Gemm g, const Sched& S, const Epi& E) {
;     ...
;             const bool last = (t == nt - 2);
;             const char* a1 = cA + PG8_AK(t + 1);
;             const char* a2 = last ? nA : cA + PG8_AK(t + 2); const char* b2 = last ? nB : cB + (size_t)(t + 2) * kstep;
;             const char* a3 = last ? nA + PG8_AK(1) : cA + PG8_AK(t + 3); const char* b3 = b2 + kstep;
;             if (last && has_next) S.a_ready(nxt);
;             if constexpr (SP2) {
;             PG8_LDB(B0, 0, 0); PG8_LDB(B1, 0, 1); PG8_SCHED; PG8_LDA(At, 0, 0); PG8_STAGE(PG8_SA(1, 1), a1 + hstepA, voffA);
;             PG8_WAIT_V(8); PG8_WAIT_L(0); PG8_BAR; PG8_MMA(0, 0, At, B0); PG8_MMA(0, 1, At, B1); PG8_BAR; PG8_SCHED;
;             PG8_LDA(At, 0, 1); PG8_STAGE(PG8_SB(0, 0), b2, voffB); PG8_STAGE(PG8_SB(0, 1), b2 + hstepB, voffB); PG8_STAGE(PG8_SA(0, 0), a2, voffA);
.LBB0_520:
	ds_read_b128 v[124:127], v210
	ds_read_b128 v[128:131], v210 offset:1024
	ds_read_b128 v[132:135], v210 offset:2048
	ds_read_b128 v[144:147], v210 offset:3072
	ds_read_b128 v[148:151], v211
	ds_read_b128 v[170:173], v211 offset:1024
	ds_read_b128 v[174:177], v211 offset:2048
	ds_read_b128 v[178:181], v211 offset:3072
	s_add_u32 s42, s38, s40
	s_addc_u32 s43, s39, s41
	s_add_u32 s46, s42, 0x100
	s_addc_u32 s47, s43, 0
	s_add_u32 s44, s79, s40
	s_addc_u32 s45, s83, s41
	s_add_u32 s42, s42, 0x180
	s_addc_u32 s43, s43, 0
	s_cmpk_eq_i32 s40, 0x1500
	s_cselect_b32 s43, s78, s43
	s_cselect_b32 s42, s3, s42
	s_cselect_b32 s45, s37, s45
	s_cselect_b32 s44, s36, s44
	s_cselect_b32 s47, s9, s47
	s_cselect_b32 s46, s8, s46
	v_lshl_add_u64 v[206:207], v[122:123], 0, s[40:41]
	s_add_i32 m0, s53, 0xc000
	ds_read_b128 v[212:215], v191
	ds_read_b128 v[216:219], v191 offset:1024
	ds_read_b128 v[220:223], v191 offset:2048
	ds_read_b128 v[224:227], v191 offset:3072
	ds_read_b128 v[228:231], v191 offset:4096
	ds_read_b128 v[232:235], v191 offset:5120
	ds_read_b128 v[236:239], v191 offset:6144
	ds_read_b128 v[240:243], v191 offset:7168
	global_load_lds_dwordx4 v[206:207], off
	v_lshl_add_u64 v[206:207], v[120:121], 0, s[40:41]
	s_add_i32 m0, s53, 0xe000
	s_nop 0
	global_load_lds_dwordx4 v[206:207], off
	s_waitcnt vmcnt(8)
	s_waitcnt lgkmcnt(0)
	s_barrier
	s_setprio 1
	v_mfma_f32_16x16x32_bf16 v[140:143], v[124:127], v[212:215], v[140:143]
	v_mfma_f32_16x16x32_bf16 v[136:139], v[132:135], v[212:215], v[136:139]
	v_mfma_f32_16x16x32_bf16 v[116:119], v[124:127], v[220:223], v[116:119]
	v_mfma_f32_16x16x32_bf16 v[112:115], v[132:135], v[220:223], v[112:115]
	v_mfma_f32_16x16x32_bf16 v[108:111], v[124:127], v[228:231], v[108:111]
	v_mfma_f32_16x16x32_bf16 v[104:107], v[132:135], v[228:231], v[104:107]
	v_mfma_f32_16x16x32_bf16 v[100:103], v[124:127], v[236:239], v[100:103]
	v_mfma_f32_16x16x32_bf16 v[96:99], v[132:135], v[236:239], v[96:99]
	v_mfma_f32_16x16x32_bf16 v[140:143], v[128:131], v[216:219], v[140:143]
	v_mfma_f32_16x16x32_bf16 v[136:139], v[144:147], v[216:219], v[136:139]
	v_mfma_f32_16x16x32_bf16 v[116:119], v[128:131], v[224:227], v[116:119]
	v_mfma_f32_16x16x32_bf16 v[112:115], v[144:147], v[224:227], v[112:115]
	v_mfma_f32_16x16x32_bf16 v[108:111], v[128:131], v[232:235], v[108:111]
	v_mfma_f32_16x16x32_bf16 v[104:107], v[144:147], v[232:235], v[104:107]
	v_mfma_f32_16x16x32_bf16 v[100:103], v[128:131], v[240:243], v[100:103]
	v_mfma_f32_16x16x32_bf16 v[96:99], v[144:147], v[240:243], v[96:99]
	v_mfma_f32_16x16x32_bf16 v[60:63], v[148:151], v[212:215], v[60:63]
	v_mfma_f32_16x16x32_bf16 v[56:59], v[174:177], v[212:215], v[56:59]
	v_mfma_f32_16x16x32_bf16 v[52:55], v[148:151], v[220:223], v[52:55]
	v_mfma_f32_16x16x32_bf16 v[48:51], v[174:177], v[220:223], v[48:51]
	v_mfma_f32_16x16x32_bf16 v[44:47], v[148:151], v[228:231], v[44:47]
	v_mfma_f32_16x16x32_bf16 v[40:43], v[174:177], v[228:231], v[40:43]
	v_mfma_f32_16x16x32_bf16 v[36:39], v[148:151], v[236:239], v[36:39]
	v_mfma_f32_16x16x32_bf16 v[32:35], v[174:177], v[236:239], v[32:35]
	v_mfma_f32_16x16x32_bf16 v[60:63], v[170:173], v[216:219], v[60:63]
	v_mfma_f32_16x16x32_bf16 v[56:59], v[178:181], v[216:219], v[56:59]
	v_mfma_f32_16x16x32_bf16 v[52:55], v[170:173], v[224:227], v[52:55]
	v_mfma_f32_16x16x32_bf16 v[48:51], v[178:181], v[224:227], v[48:51]
	v_mfma_f32_16x16x32_bf16 v[44:47], v[170:173], v[232:235], v[44:47]
	v_mfma_f32_16x16x32_bf16 v[40:43], v[178:181], v[232:235], v[40:43]
	v_mfma_f32_16x16x32_bf16 v[36:39], v[170:173], v[240:243], v[36:39]
	v_mfma_f32_16x16x32_bf16 v[32:35], v[178:181], v[240:243], v[32:35]
	s_setprio 0
	s_barrier
	s_add_i32 s70, s67, s52
	v_lshl_add_u64 v[206:207], s[44:45], 0, v[154:155]
	s_mov_b32 m0, s70
	ds_read_b128 v[212:215], v191 offset:16384
	ds_read_b128 v[216:219], v191 offset:17408
	ds_read_b128 v[220:223], v191 offset:18432
	ds_read_b128 v[224:227], v191 offset:19456
	ds_read_b128 v[228:231], v191 offset:20480
	ds_read_b128 v[232:235], v191 offset:21504
	ds_read_b128 v[236:239], v191 offset:22528
	ds_read_b128 v[240:243], v191 offset:23552
	global_load_lds_dwordx4 v[206:207], off
	s_add_i32 m0, s70, 0x2000
	s_add_u32 s70, s44, 0xb0000
	v_lshl_add_u64 v[244:245], s[44:45], 0, v[158:159]
	s_addc_u32 s71, s45, 0
	s_add_i32 s85, s68, s52
	global_load_lds_dwordx4 v[244:245], off
	v_lshl_add_u64 v[246:247], s[70:71], 0, v[154:155]
	s_mov_b32 m0, s85
	s_nop 0
	global_load_lds_dwordx4 v[246:247], off
	v_lshl_add_u64 v[246:247], s[70:71], 0, v[158:159]
	s_add_i32 m0, s85, 0x2000
	s_nop 0
	global_load_lds_dwordx4 v[246:247], off
	v_lshl_add_u64 v[246:247], s[46:47], 0, v[152:153]
	s_mov_b32 m0, s53
	s_nop 0
	global_load_lds_dwordx4 v[246:247], off
	v_lshl_add_u64 v[246:247], s[46:47], 0, v[156:157]
	s_mov_b32 m0, s54
	s_nop 0
	global_load_lds_dwordx4 v[246:247], off
	s_waitcnt vmcnt(8)
	s_waitcnt lgkmcnt(0)
	s_barrier
; #define PG8_STAGE(bufoff, gbase, voff) do { _Pragma("unroll") for (int _i = 0; _i < 2; ++_i) \
;         __builtin_amdgcn_global_load_lds((const unsigned*)((const char*)(gbase) + (voff)[_i]), (PG8_LAS unsigned*)(lds + (bufoff) + ldsw + _i * 8192), 16, 0, 0); } while (0)
; #define PG8_LDA(dst, b, h) do { _Pragma("unroll") for (int m = 0; m < 4; ++m) _Pragma("unroll") for (int k = 0; k < 2; ++k) dst[m][k] = *(const PG8_LAS bf16x8*)(lds + PG8_SA(b, h) + aoff + m * 2048 + k * 1024); } while (0)
; #define PG8_LDB(dst, b, h) do { _Pragma("unroll") for (int n = 0; n < 2; ++n) _Pragma("unroll") for (int k = 0; k < 2; ++k) dst[n][k] = *(const PG8_LAS bf16x8*)(lds + PG8_SB(b, h) + boff + n * 2048 + k * 1024); } while (0)
; #define PG8_MMA(ai, bj, At, Bt) do { __builtin_amdgcn_s_setprio(1); _Pragma("unroll") for (int m = 0; m < 4; ++m) _Pragma("unroll") for (int n = 0; n < 2; ++n) _Pragma("unroll") for (int k = 0; k < 2; ++k) \
;         acc[ai][bj][m][n] = __builtin_amdgcn_mfma_f32_16x16x32_bf16(Bt[n][k], At[m][k], acc[ai][bj][m][n], 0, 0, 0); __builtin_amdgcn_s_setprio(0); } while (0)
; #define PG8_WAIT_V(n) asm volatile("s_waitcnt vmcnt(" #n ")" ::: "memory")
; #define PG8_WAIT_L(n) asm volatile("s_waitcnt lgkmcnt(" #n ")" ::: "memory")
; #define PG8_BAR __builtin_amdgcn_s_barrier()
; #define PG8_SCHED __builtin_amdgcn_sched_barrier(0)
; template <class Epi, class Sched, bool ALIGN_EPI = false, bool SP2 = false>
; __device__ __forceinline__ void gemm_phase(PG8_LAS unsigned char* lds, const Gemm g, const Sched& S, const Epi& E) {
;     ...
;             PG8_LDA(At, 0, 1); PG8_STAGE(PG8_SB(0, 0), b2, voffB); PG8_STAGE(PG8_SB(0, 1), b2 + hstepB, voffB); PG8_STAGE(PG8_SA(0, 0), a2, voffA);
;             PG8_WAIT_V(8); PG8_WAIT_L(0); PG8_BAR; PG8_MMA(1, 0, At, B0); PG8_MMA(1, 1, At, B1); PG8_BAR; PG8_SCHED;
;             PG8_LDB(B0, 1, 0); PG8_LDB(B1, 1, 1); PG8_SCHED; PG8_LDA(At, 1, 0); PG8_STAGE(PG8_SA(0, 1), a2 + hstepA, voffA);
;             PG8_WAIT_V(8); PG8_WAIT_L(0); PG8_BAR; PG8_MMA(0, 0, At, B0); PG8_MMA(0, 1, At, B1); PG8_BAR; PG8_SCHED;
	s_setprio 1
	v_mfma_f32_16x16x32_bf16 v[92:95], v[124:127], v[212:215], v[92:95]
	v_mfma_f32_16x16x32_bf16 v[88:91], v[132:135], v[212:215], v[88:91]
	v_mfma_f32_16x16x32_bf16 v[84:87], v[124:127], v[220:223], v[84:87]
	v_mfma_f32_16x16x32_bf16 v[80:83], v[132:135], v[220:223], v[80:83]
	v_mfma_f32_16x16x32_bf16 v[76:79], v[124:127], v[228:231], v[76:79]
	v_mfma_f32_16x16x32_bf16 v[72:75], v[132:135], v[228:231], v[72:75]
	v_mfma_f32_16x16x32_bf16 v[68:71], v[124:127], v[236:239], v[68:71]
	v_mfma_f32_16x16x32_bf16 v[64:67], v[132:135], v[236:239], v[64:67]
	v_mfma_f32_16x16x32_bf16 v[92:95], v[128:131], v[216:219], v[92:95]
	v_mfma_f32_16x16x32_bf16 v[88:91], v[144:147], v[216:219], v[88:91]
	v_mfma_f32_16x16x32_bf16 v[84:87], v[128:131], v[224:227], v[84:87]
	v_mfma_f32_16x16x32_bf16 v[80:83], v[144:147], v[224:227], v[80:83]
	v_mfma_f32_16x16x32_bf16 v[76:79], v[128:131], v[232:235], v[76:79]
	v_mfma_f32_16x16x32_bf16 v[72:75], v[144:147], v[232:235], v[72:75]
	v_mfma_f32_16x16x32_bf16 v[68:71], v[128:131], v[240:243], v[68:71]
	v_mfma_f32_16x16x32_bf16 v[64:67], v[144:147], v[240:243], v[64:67]
	v_mfma_f32_16x16x32_bf16 v[28:31], v[148:151], v[212:215], v[28:31]
	v_mfma_f32_16x16x32_bf16 v[24:27], v[174:177], v[212:215], v[24:27]
	v_mfma_f32_16x16x32_bf16 v[20:23], v[148:151], v[220:223], v[20:23]
	v_mfma_f32_16x16x32_bf16 v[16:19], v[174:177], v[220:223], v[16:19]
	v_mfma_f32_16x16x32_bf16 v[12:15], v[148:151], v[228:231], v[12:15]
	v_mfma_f32_16x16x32_bf16 v[8:11], v[174:177], v[228:231], v[8:11]
	v_mfma_f32_16x16x32_bf16 v[4:7], v[148:151], v[236:239], v[4:7]
	v_mfma_f32_16x16x32_bf16 v[0:3], v[174:177], v[236:239], v[0:3]
	v_mfma_f32_16x16x32_bf16 v[28:31], v[170:173], v[216:219], v[28:31]
	v_mfma_f32_16x16x32_bf16 v[24:27], v[178:181], v[216:219], v[24:27]
	v_mfma_f32_16x16x32_bf16 v[20:23], v[170:173], v[224:227], v[20:23]
	v_mfma_f32_16x16x32_bf16 v[16:19], v[178:181], v[224:227], v[16:19]
	v_mfma_f32_16x16x32_bf16 v[12:15], v[170:173], v[232:235], v[12:15]
	v_mfma_f32_16x16x32_bf16 v[8:11], v[178:181], v[232:235], v[8:11]
	v_mfma_f32_16x16x32_bf16 v[4:7], v[170:173], v[240:243], v[4:7]
	v_mfma_f32_16x16x32_bf16 v[0:3], v[178:181], v[240:243], v[0:3]
	s_setprio 0
	s_barrier
	s_add_i32 s70, 0, 0x18000
	s_add_i32 s71, 0, 0x1c000
	v_add_u32_e32 v144, s70, v185
	v_add_u32_e32 v161, s71, v185
	ds_read_b128 v[124:127], v144
	ds_read_b128 v[128:131], v144 offset:1024
	ds_read_b128 v[132:135], v144 offset:2048
	ds_read_b128 v[144:147], v144 offset:3072
	ds_read_b128 v[148:151], v161
	ds_read_b128 v[170:173], v161 offset:1024
	ds_read_b128 v[174:177], v161 offset:2048
	ds_read_b128 v[178:181], v161 offset:3072
	s_add_u32 s46, s46, 0xb0000
	s_addc_u32 s47, s47, 0
	s_mov_b32 m0, s55
	v_lshl_add_u64 v[246:247], s[46:47], 0, v[152:153]
	ds_read_b128 v[212:215], v191 offset:32768
	ds_read_b128 v[216:219], v191 offset:33792
	ds_read_b128 v[220:223], v191 offset:34816
	ds_read_b128 v[224:227], v191 offset:35840
	ds_read_b128 v[228:231], v191 offset:36864
	ds_read_b128 v[232:235], v191 offset:37888
	ds_read_b128 v[236:239], v191 offset:38912
	ds_read_b128 v[240:243], v191 offset:39936
	global_load_lds_dwordx4 v[246:247], off
	v_lshl_add_u64 v[246:247], s[46:47], 0, v[156:157]
	s_mov_b32 m0, s56
	s_nop 0
	global_load_lds_dwordx4 v[246:247], off
	s_waitcnt vmcnt(8)
	s_waitcnt lgkmcnt(0)
	s_barrier
	s_setprio 1
	v_mfma_f32_16x16x32_bf16 v[140:143], v[124:127], v[212:215], v[140:143]
	v_mfma_f32_16x16x32_bf16 v[136:139], v[132:135], v[212:215], v[136:139]
	v_mfma_f32_16x16x32_bf16 v[116:119], v[124:127], v[220:223], v[116:119]
	v_mfma_f32_16x16x32_bf16 v[112:115], v[132:135], v[220:223], v[112:115]
	v_mfma_f32_16x16x32_bf16 v[108:111], v[124:127], v[228:231], v[108:111]
	v_mfma_f32_16x16x32_bf16 v[104:107], v[132:135], v[228:231], v[104:107]
	v_mfma_f32_16x16x32_bf16 v[100:103], v[124:127], v[236:239], v[100:103]
	v_mfma_f32_16x16x32_bf16 v[96:99], v[132:135], v[236:239], v[96:99]
	v_mfma_f32_16x16x32_bf16 v[140:143], v[128:131], v[216:219], v[140:143]
	v_mfma_f32_16x16x32_bf16 v[136:139], v[144:147], v[216:219], v[136:139]
	v_mfma_f32_16x16x32_bf16 v[116:119], v[128:131], v[224:227], v[116:119]
	v_mfma_f32_16x16x32_bf16 v[112:115], v[144:147], v[224:227], v[112:115]
	v_mfma_f32_16x16x32_bf16 v[108:111], v[128:131], v[232:235], v[108:111]
	v_mfma_f32_16x16x32_bf16 v[104:107], v[144:147], v[232:235], v[104:107]
	v_mfma_f32_16x16x32_bf16 v[100:103], v[128:131], v[240:243], v[100:103]
	v_mfma_f32_16x16x32_bf16 v[96:99], v[144:147], v[240:243], v[96:99]
	v_mfma_f32_16x16x32_bf16 v[60:63], v[148:151], v[212:215], v[60:63]
	v_mfma_f32_16x16x32_bf16 v[56:59], v[174:177], v[212:215], v[56:59]
	v_mfma_f32_16x16x32_bf16 v[52:55], v[148:151], v[220:223], v[52:55]
	v_mfma_f32_16x16x32_bf16 v[48:51], v[174:177], v[220:223], v[48:51]
	v_mfma_f32_16x16x32_bf16 v[44:47], v[148:151], v[228:231], v[44:47]
	v_mfma_f32_16x16x32_bf16 v[40:43], v[174:177], v[228:231], v[40:43]
	v_mfma_f32_16x16x32_bf16 v[36:39], v[148:151], v[236:239], v[36:39]
	v_mfma_f32_16x16x32_bf16 v[32:35], v[174:177], v[236:239], v[32:35]
	v_mfma_f32_16x16x32_bf16 v[60:63], v[170:173], v[216:219], v[60:63]
	v_mfma_f32_16x16x32_bf16 v[56:59], v[178:181], v[216:219], v[56:59]
	v_mfma_f32_16x16x32_bf16 v[52:55], v[170:173], v[224:227], v[52:55]
	v_mfma_f32_16x16x32_bf16 v[48:51], v[178:181], v[224:227], v[48:51]
	v_mfma_f32_16x16x32_bf16 v[44:47], v[170:173], v[232:235], v[44:47]
	v_mfma_f32_16x16x32_bf16 v[40:43], v[178:181], v[232:235], v[40:43]
	v_mfma_f32_16x16x32_bf16 v[36:39], v[170:173], v[240:243], v[36:39]
	v_mfma_f32_16x16x32_bf16 v[32:35], v[178:181], v[240:243], v[32:35]
	s_setprio 0
	s_barrier
; #define PG8_STAGE(bufoff, gbase, voff) do { _Pragma("unroll") for (int _i = 0; _i < 2; ++_i) \
;         __builtin_amdgcn_global_load_lds((const unsigned*)((const char*)(gbase) + (voff)[_i]), (PG8_LAS unsigned*)(lds + (bufoff) + ldsw + _i * 8192), 16, 0, 0); } while (0)
; #define PG8_LDA(dst, b, h) do { _Pragma("unroll") for (int m = 0; m < 4; ++m) _Pragma("unroll") for (int k = 0; k < 2; ++k) dst[m][k] = *(const PG8_LAS bf16x8*)(lds + PG8_SA(b, h) + aoff + m * 2048 + k * 1024); } while (0)
; #define PG8_MMA(ai, bj, At, Bt) do { __builtin_amdgcn_s_setprio(1); _Pragma("unroll") for (int m = 0; m < 4; ++m) _Pragma("unroll") for (int n = 0; n < 2; ++n) _Pragma("unroll") for (int k = 0; k < 2; ++k) \
;         acc[ai][bj][m][n] = __builtin_amdgcn_mfma_f32_16x16x32_bf16(Bt[n][k], At[m][k], acc[ai][bj][m][n], 0, 0, 0); __builtin_amdgcn_s_setprio(0); } while (0)
; #define PG8_WAIT_V(n) asm volatile("s_waitcnt vmcnt(" #n ")" ::: "memory")
; #define PG8_WAIT_L(n) asm volatile("s_waitcnt lgkmcnt(" #n ")" ::: "memory")
; #define PG8_BAR __builtin_amdgcn_s_barrier()
; #define PG8_SCHED __builtin_amdgcn_sched_barrier(0)
; template <class Epi, class Sched, bool ALIGN_EPI = false, bool SP2 = false>
; __device__ __forceinline__ void gemm_phase(PG8_LAS unsigned char* lds, const Gemm g, const Sched& S, const Epi& E) {
;     ...
;             PG8_LDA(At, 1, 1); PG8_STAGE(PG8_SB(1, 0), b3, voffB); PG8_STAGE(PG8_SB(1, 1), b3 + hstepB, voffB); PG8_STAGE(PG8_SA(1, 0), a3, voffA);
;             PG8_WAIT_V(8); PG8_WAIT_L(0); PG8_BAR; PG8_MMA(1, 0, At, B0); PG8_MMA(1, 1, At, B1); PG8_BAR; PG8_SCHED;
	s_add_i32 s46, s70, s52
	v_lshl_add_u64 v[206:207], v[206:207], 0, s[26:27]
	s_mov_b32 m0, s46
	ds_read_b128 v[212:215], v191 offset:49152
	ds_read_b128 v[216:219], v191 offset:50176
	ds_read_b128 v[220:223], v191 offset:51200
	ds_read_b128 v[224:227], v191 offset:52224
	ds_read_b128 v[228:231], v191 offset:53248
	ds_read_b128 v[232:235], v191 offset:54272
	ds_read_b128 v[236:239], v191 offset:55296
	ds_read_b128 v[240:243], v191 offset:56320
	global_load_lds_dwordx4 v[206:207], off
	s_add_i32 m0, s46, 0x2000
	s_add_u32 s44, s44, 0xb0080
	v_lshl_add_u64 v[206:207], v[244:245], 0, s[26:27]
	s_addc_u32 s45, s45, 0
	s_add_i32 s46, s71, s52
	global_load_lds_dwordx4 v[206:207], off
	v_lshl_add_u64 v[206:207], s[44:45], 0, v[154:155]
	s_mov_b32 m0, s46
	s_nop 0
	global_load_lds_dwordx4 v[206:207], off
	v_lshl_add_u64 v[206:207], s[44:45], 0, v[158:159]
	s_add_i32 m0, s46, 0x2000
	s_nop 0
	global_load_lds_dwordx4 v[206:207], off
	v_lshl_add_u64 v[206:207], s[42:43], 0, v[152:153]
	s_mov_b32 m0, s63
	s_nop 0
	global_load_lds_dwordx4 v[206:207], off
	v_lshl_add_u64 v[206:207], s[42:43], 0, v[156:157]
	s_mov_b32 m0, s64
	s_nop 0
	global_load_lds_dwordx4 v[206:207], off
	s_waitcnt vmcnt(8)
	s_waitcnt lgkmcnt(0)
	s_barrier
	s_setprio 1
	v_mfma_f32_16x16x32_bf16 v[92:95], v[124:127], v[212:215], v[92:95]
	v_mfma_f32_16x16x32_bf16 v[88:91], v[132:135], v[212:215], v[88:91]
	v_mfma_f32_16x16x32_bf16 v[84:87], v[124:127], v[220:223], v[84:87]
	v_mfma_f32_16x16x32_bf16 v[80:83], v[132:135], v[220:223], v[80:83]
	v_mfma_f32_16x16x32_bf16 v[76:79], v[124:127], v[228:231], v[76:79]
	v_mfma_f32_16x16x32_bf16 v[72:75], v[132:135], v[228:231], v[72:75]
	v_mfma_f32_16x16x32_bf16 v[68:71], v[124:127], v[236:239], v[68:71]
	v_mfma_f32_16x16x32_bf16 v[64:67], v[132:135], v[236:239], v[64:67]
	v_mfma_f32_16x16x32_bf16 v[92:95], v[128:131], v[216:219], v[92:95]
	v_mfma_f32_16x16x32_bf16 v[88:91], v[144:147], v[216:219], v[88:91]
	v_mfma_f32_16x16x32_bf16 v[84:87], v[128:131], v[224:227], v[84:87]
	v_mfma_f32_16x16x32_bf16 v[80:83], v[144:147], v[224:227], v[80:83]
	v_mfma_f32_16x16x32_bf16 v[76:79], v[128:131], v[232:235], v[76:79]
	v_mfma_f32_16x16x32_bf16 v[72:75], v[144:147], v[232:235], v[72:75]
	v_mfma_f32_16x16x32_bf16 v[68:71], v[128:131], v[240:243], v[68:71]
	v_mfma_f32_16x16x32_bf16 v[64:67], v[144:147], v[240:243], v[64:67]
	v_mfma_f32_16x16x32_bf16 v[28:31], v[148:151], v[212:215], v[28:31]
	v_mfma_f32_16x16x32_bf16 v[24:27], v[174:177], v[212:215], v[24:27]
	v_mfma_f32_16x16x32_bf16 v[20:23], v[148:151], v[220:223], v[20:23]
	v_mfma_f32_16x16x32_bf16 v[16:19], v[174:177], v[220:223], v[16:19]
	v_mfma_f32_16x16x32_bf16 v[12:15], v[148:151], v[228:231], v[12:15]
	v_mfma_f32_16x16x32_bf16 v[8:11], v[174:177], v[228:231], v[8:11]
	v_mfma_f32_16x16x32_bf16 v[4:7], v[148:151], v[236:239], v[4:7]
	v_mfma_f32_16x16x32_bf16 v[0:3], v[174:177], v[236:239], v[0:3]
	v_mfma_f32_16x16x32_bf16 v[28:31], v[170:173], v[216:219], v[28:31]
	v_mfma_f32_16x16x32_bf16 v[24:27], v[178:181], v[216:219], v[24:27]
	v_mfma_f32_16x16x32_bf16 v[20:23], v[170:173], v[224:227], v[20:23]
	v_mfma_f32_16x16x32_bf16 v[16:19], v[178:181], v[224:227], v[16:19]
	v_mfma_f32_16x16x32_bf16 v[12:15], v[170:173], v[232:235], v[12:15]
	v_mfma_f32_16x16x32_bf16 v[8:11], v[178:181], v[232:235], v[8:11]
	v_mfma_f32_16x16x32_bf16 v[4:7], v[170:173], v[240:243], v[4:7]
	v_mfma_f32_16x16x32_bf16 v[0:3], v[178:181], v[240:243], v[0:3]
	s_setprio 0
	s_barrier
	s_add_i32 s84, s84, 2
	s_add_u32 s40, s40, 0x100
	s_addc_u32 s41, s41, 0
	s_cmp_gt_u32 s84, 41
	s_cbranch_scc0 .LBB0_520
	s_and_b64 vcc, exec, s[28:29]
	s_cbranch_vccz .LBB0_523
	s_barrier

; #define PG8_STAGE(bufoff, gbase, voff) do { _Pragma("unroll") for (int _i = 0; _i < 2; ++_i) \
;         __builtin_amdgcn_global_load_lds((const unsigned*)((const char*)(gbase) + (voff)[_i]), (PG8_LAS unsigned*)(lds + (bufoff) + ldsw + _i * 8192), 16, 0, 0); } while (0)
; #define PG8_LDA(dst, b, h) do { _Pragma("unroll") for (int m = 0; m < 4; ++m) _Pragma("unroll") for (int k = 0; k < 2; ++k) dst[m][k] = *(const PG8_LAS bf16x8*)(lds + PG8_SA(b, h) + aoff + m * 2048 + k * 1024); } while (0)
; #define PG8_LDB(dst, b, h) do { _Pragma("unroll") for (int n = 0; n < 2; ++n) _Pragma("unroll") for (int k = 0; k < 2; ++k) dst[n][k] = *(const PG8_LAS bf16x8*)(lds + PG8_SB(b, h) + boff + n * 2048 + k * 1024); } while (0)
; #define PG8_MMA(ai, bj, At, Bt) do { __builtin_amdgcn_s_setprio(1); _Pragma("unroll") for (int m = 0; m < 4; ++m) _Pragma("unroll") for (int n = 0; n < 2; ++n) _Pragma("unroll") for (int k = 0; k < 2; ++k) \
;         acc[ai][bj][m][n] = __builtin_amdgcn_mfma_f32_16x16x32_bf16(Bt[n][k], At[m][k], acc[ai][bj][m][n], 0, 0, 0); __builtin_amdgcn_s_setprio(0); } while (0)
; #define PG8_WAIT_V(n) asm volatile("s_waitcnt vmcnt(" #n ")" ::: "memory")
; #define PG8_WAIT_L(n) asm volatile("s_waitcnt lgkmcnt(" #n ")" ::: "memory")
; #define PG8_BAR __builtin_amdgcn_s_barrier()
; #define PG8_SCHED __builtin_amdgcn_sched_barrier(0)
; template <class Epi, class Sched, bool ALIGN_EPI = false, bool SP2 = false>
; __device__ __forceinline__ void gemm_phase(PG8_LAS unsigned char* lds, const Gemm g, const Sched& S, const Epi& E) {
;     ...
;             const bool last = (t == nt - 2);
;             const char* a1 = cA + PG8_AK(t + 1);
;             const char* a2 = last ? nA : cA + PG8_AK(t + 2); const char* b2 = last ? nB : cB + (size_t)(t + 2) * kstep;
;             const char* a3 = last ? nA + PG8_AK(1) : cA + PG8_AK(t + 3); const char* b3 = b2 + kstep;
;             if (last && has_next) S.a_ready(nxt);
;             if constexpr (SP2) {
;             PG8_LDB(B0, 0, 0); PG8_LDB(B1, 0, 1); PG8_SCHED; PG8_LDA(At, 0, 0); PG8_STAGE(PG8_SA(1, 1), a1 + hstepA, voffA);
;             PG8_WAIT_V(8); PG8_WAIT_L(0); PG8_BAR; PG8_MMA(0, 0, At, B0); PG8_MMA(0, 1, At, B1); PG8_BAR; PG8_SCHED;
;             PG8_LDA(At, 0, 1); PG8_STAGE(PG8_SB(0, 0), b2, voffB); PG8_STAGE(PG8_SB(0, 1), b2 + hstepB, voffB); PG8_STAGE(PG8_SA(0, 0), a2, voffA);
.LBB0_612:
	ds_read_b128 v[100:103], v226
	ds_read_b128 v[104:107], v226 offset:1024
	ds_read_b128 v[108:111], v226 offset:2048
	ds_read_b128 v[120:123], v226 offset:3072
	ds_read_b128 v[124:127], v227
	ds_read_b128 v[128:131], v227 offset:1024
	ds_read_b128 v[132:135], v227 offset:2048
	ds_read_b128 v[160:163], v227 offset:3072
	s_add_u32 s44, s40, s42
	s_addc_u32 s45, s41, s43
	s_add_u32 s48, s44, 0x100
	s_addc_u32 s49, s45, 0
	s_add_u32 s46, s83, s42
	s_addc_u32 s47, s84, s43
	s_add_u32 s44, s44, 0x180
	s_addc_u32 s45, s45, 0
	s_cmpk_eq_i32 s42, 0x700
	s_cselect_b32 s45, s82, s45
	s_cselect_b32 s44, s79, s44
	s_cselect_b32 s47, s29, s47
	s_cselect_b32 s46, s78, s46
	s_cselect_b32 s49, s3, s49
	s_cselect_b32 s48, s31, s48
	v_lshl_add_u64 v[236:237], v[98:99], 0, s[42:43]
	s_add_i32 m0, s57, 0xc000
	ds_read_b128 v[164:167], v209
	ds_read_b128 v[168:171], v209 offset:1024
	ds_read_b128 v[192:195], v209 offset:2048
	ds_read_b128 v[196:199], v209 offset:3072
	ds_read_b128 v[200:203], v209 offset:4096
	ds_read_b128 v[204:207], v209 offset:5120
	ds_read_b128 v[228:231], v209 offset:6144
	ds_read_b128 v[232:235], v209 offset:7168
	global_load_lds_dwordx4 v[236:237], off
	v_lshl_add_u64 v[236:237], v[96:97], 0, s[42:43]
	s_add_i32 m0, s57, 0xe000
	s_nop 0
	global_load_lds_dwordx4 v[236:237], off
	s_waitcnt vmcnt(8)
	s_waitcnt lgkmcnt(0)
	s_barrier
	s_setprio 1
	v_mfma_f32_16x16x32_bf16 v[156:159], v[100:103], v[164:167], v[156:159]
	v_mfma_f32_16x16x32_bf16 v[152:155], v[108:111], v[164:167], v[152:155]
	v_mfma_f32_16x16x32_bf16 v[148:151], v[100:103], v[192:195], v[148:151]
	v_mfma_f32_16x16x32_bf16 v[144:147], v[108:111], v[192:195], v[144:147]
	v_mfma_f32_16x16x32_bf16 v[140:143], v[100:103], v[200:203], v[140:143]
	v_mfma_f32_16x16x32_bf16 v[136:139], v[108:111], v[200:203], v[136:139]
	v_mfma_f32_16x16x32_bf16 v[116:119], v[100:103], v[228:231], v[116:119]
	v_mfma_f32_16x16x32_bf16 v[112:115], v[108:111], v[228:231], v[112:115]
	v_mfma_f32_16x16x32_bf16 v[156:159], v[104:107], v[168:171], v[156:159]
	v_mfma_f32_16x16x32_bf16 v[152:155], v[120:123], v[168:171], v[152:155]
	v_mfma_f32_16x16x32_bf16 v[148:151], v[104:107], v[196:199], v[148:151]
	v_mfma_f32_16x16x32_bf16 v[144:147], v[120:123], v[196:199], v[144:147]
	v_mfma_f32_16x16x32_bf16 v[140:143], v[104:107], v[204:207], v[140:143]
	v_mfma_f32_16x16x32_bf16 v[136:139], v[120:123], v[204:207], v[136:139]
	v_mfma_f32_16x16x32_bf16 v[116:119], v[104:107], v[232:235], v[116:119]
	v_mfma_f32_16x16x32_bf16 v[112:115], v[120:123], v[232:235], v[112:115]
	v_mfma_f32_16x16x32_bf16 v[60:63], v[124:127], v[164:167], v[60:63]
	v_mfma_f32_16x16x32_bf16 v[56:59], v[132:135], v[164:167], v[56:59]
	v_mfma_f32_16x16x32_bf16 v[52:55], v[124:127], v[192:195], v[52:55]
	v_mfma_f32_16x16x32_bf16 v[48:51], v[132:135], v[192:195], v[48:51]
	v_mfma_f32_16x16x32_bf16 v[44:47], v[124:127], v[200:203], v[44:47]
	v_mfma_f32_16x16x32_bf16 v[40:43], v[132:135], v[200:203], v[40:43]
	v_mfma_f32_16x16x32_bf16 v[36:39], v[124:127], v[228:231], v[36:39]
	v_mfma_f32_16x16x32_bf16 v[32:35], v[132:135], v[228:231], v[32:35]
	v_mfma_f32_16x16x32_bf16 v[60:63], v[128:131], v[168:171], v[60:63]
	v_mfma_f32_16x16x32_bf16 v[56:59], v[160:163], v[168:171], v[56:59]
	v_mfma_f32_16x16x32_bf16 v[52:55], v[128:131], v[196:199], v[52:55]
	v_mfma_f32_16x16x32_bf16 v[48:51], v[160:163], v[196:199], v[48:51]
	v_mfma_f32_16x16x32_bf16 v[44:47], v[128:131], v[204:207], v[44:47]
	v_mfma_f32_16x16x32_bf16 v[40:43], v[160:163], v[204:207], v[40:43]
	v_mfma_f32_16x16x32_bf16 v[36:39], v[128:131], v[232:235], v[36:39]
	v_mfma_f32_16x16x32_bf16 v[32:35], v[160:163], v[232:235], v[32:35]
	s_setprio 0
	s_barrier
	s_add_i32 s70, s69, s56
	v_lshl_add_u64 v[236:237], s[46:47], 0, v[174:175]
	s_mov_b32 m0, s70
	ds_read_b128 v[164:167], v209 offset:16384
	ds_read_b128 v[168:171], v209 offset:17408
	ds_read_b128 v[192:195], v209 offset:18432
	ds_read_b128 v[196:199], v209 offset:19456
	ds_read_b128 v[200:203], v209 offset:20480
	ds_read_b128 v[204:207], v209 offset:21504
	ds_read_b128 v[228:231], v209 offset:22528
	ds_read_b128 v[232:235], v209 offset:23552
	global_load_lds_dwordx4 v[236:237], off
	s_add_i32 m0, s70, 0x2000
	s_add_u32 s70, s46, 0x40000
	v_lshl_add_u64 v[238:239], s[46:47], 0, v[178:179]
	s_addc_u32 s71, s47, 0
	s_add_i32 s86, s80, s56
	global_load_lds_dwordx4 v[238:239], off
	v_lshl_add_u64 v[240:241], s[70:71], 0, v[174:175]
	s_mov_b32 m0, s86
	s_nop 0
	global_load_lds_dwordx4 v[240:241], off
	v_lshl_add_u64 v[240:241], s[70:71], 0, v[178:179]
	s_add_i32 m0, s86, 0x2000
	s_nop 0
	global_load_lds_dwordx4 v[240:241], off
	v_lshl_add_u64 v[240:241], s[48:49], 0, v[172:173]
	s_mov_b32 m0, s57
	s_nop 0
	global_load_lds_dwordx4 v[240:241], off
	v_lshl_add_u64 v[240:241], s[48:49], 0, v[176:177]
	s_mov_b32 m0, s58
	s_nop 0
	global_load_lds_dwordx4 v[240:241], off
	s_waitcnt vmcnt(8)
	s_waitcnt lgkmcnt(0)
	s_barrier
; #define PG8_STAGE(bufoff, gbase, voff) do { _Pragma("unroll") for (int _i = 0; _i < 2; ++_i) \
;         __builtin_amdgcn_global_load_lds((const unsigned*)((const char*)(gbase) + (voff)[_i]), (PG8_LAS unsigned*)(lds + (bufoff) + ldsw + _i * 8192), 16, 0, 0); } while (0)
; #define PG8_LDA(dst, b, h) do { _Pragma("unroll") for (int m = 0; m < 4; ++m) _Pragma("unroll") for (int k = 0; k < 2; ++k) dst[m][k] = *(const PG8_LAS bf16x8*)(lds + PG8_SA(b, h) + aoff + m * 2048 + k * 1024); } while (0)
; #define PG8_LDB(dst, b, h) do { _Pragma("unroll") for (int n = 0; n < 2; ++n) _Pragma("unroll") for (int k = 0; k < 2; ++k) dst[n][k] = *(const PG8_LAS bf16x8*)(lds + PG8_SB(b, h) + boff + n * 2048 + k * 1024); } while (0)
; #define PG8_MMA(ai, bj, At, Bt) do { __builtin_amdgcn_s_setprio(1); _Pragma("unroll") for (int m = 0; m < 4; ++m) _Pragma("unroll") for (int n = 0; n < 2; ++n) _Pragma("unroll") for (int k = 0; k < 2; ++k) \
;         acc[ai][bj][m][n] = __builtin_amdgcn_mfma_f32_16x16x32_bf16(Bt[n][k], At[m][k], acc[ai][bj][m][n], 0, 0, 0); __builtin_amdgcn_s_setprio(0); } while (0)
; #define PG8_WAIT_V(n) asm volatile("s_waitcnt vmcnt(" #n ")" ::: "memory")
; #define PG8_WAIT_L(n) asm volatile("s_waitcnt lgkmcnt(" #n ")" ::: "memory")
; #define PG8_BAR __builtin_amdgcn_s_barrier()
; #define PG8_SCHED __builtin_amdgcn_sched_barrier(0)
; template <class Epi, class Sched, bool ALIGN_EPI = false, bool SP2 = false>
; __device__ __forceinline__ void gemm_phase(PG8_LAS unsigned char* lds, const Gemm g, const Sched& S, const Epi& E) {
;     ...
;             PG8_LDA(At, 0, 1); PG8_STAGE(PG8_SB(0, 0), b2, voffB); PG8_STAGE(PG8_SB(0, 1), b2 + hstepB, voffB); PG8_STAGE(PG8_SA(0, 0), a2, voffA);
;             PG8_WAIT_V(8); PG8_WAIT_L(0); PG8_BAR; PG8_MMA(1, 0, At, B0); PG8_MMA(1, 1, At, B1); PG8_BAR; PG8_SCHED;
;             PG8_LDB(B0, 1, 0); PG8_LDB(B1, 1, 1); PG8_SCHED; PG8_LDA(At, 1, 0); PG8_STAGE(PG8_SA(0, 1), a2 + hstepA, voffA);
;             PG8_WAIT_V(8); PG8_WAIT_L(0); PG8_BAR; PG8_MMA(0, 0, At, B0); PG8_MMA(0, 1, At, B1); PG8_BAR; PG8_SCHED;
	s_setprio 1
	v_mfma_f32_16x16x32_bf16 v[92:95], v[100:103], v[164:167], v[92:95]
	v_mfma_f32_16x16x32_bf16 v[88:91], v[108:111], v[164:167], v[88:91]
	v_mfma_f32_16x16x32_bf16 v[84:87], v[100:103], v[192:195], v[84:87]
	v_mfma_f32_16x16x32_bf16 v[80:83], v[108:111], v[192:195], v[80:83]
	v_mfma_f32_16x16x32_bf16 v[76:79], v[100:103], v[200:203], v[76:79]
	v_mfma_f32_16x16x32_bf16 v[72:75], v[108:111], v[200:203], v[72:75]
	v_mfma_f32_16x16x32_bf16 v[68:71], v[100:103], v[228:231], v[68:71]
	v_mfma_f32_16x16x32_bf16 v[64:67], v[108:111], v[228:231], v[64:67]
	v_mfma_f32_16x16x32_bf16 v[92:95], v[104:107], v[168:171], v[92:95]
	v_mfma_f32_16x16x32_bf16 v[88:91], v[120:123], v[168:171], v[88:91]
	v_mfma_f32_16x16x32_bf16 v[84:87], v[104:107], v[196:199], v[84:87]
	v_mfma_f32_16x16x32_bf16 v[80:83], v[120:123], v[196:199], v[80:83]
	v_mfma_f32_16x16x32_bf16 v[76:79], v[104:107], v[204:207], v[76:79]
	v_mfma_f32_16x16x32_bf16 v[72:75], v[120:123], v[204:207], v[72:75]
	v_mfma_f32_16x16x32_bf16 v[68:71], v[104:107], v[232:235], v[68:71]
	v_mfma_f32_16x16x32_bf16 v[64:67], v[120:123], v[232:235], v[64:67]
	v_mfma_f32_16x16x32_bf16 v[28:31], v[124:127], v[164:167], v[28:31]
	v_mfma_f32_16x16x32_bf16 v[24:27], v[132:135], v[164:167], v[24:27]
	v_mfma_f32_16x16x32_bf16 v[20:23], v[124:127], v[192:195], v[20:23]
	v_mfma_f32_16x16x32_bf16 v[16:19], v[132:135], v[192:195], v[16:19]
	v_mfma_f32_16x16x32_bf16 v[12:15], v[124:127], v[200:203], v[12:15]
	v_mfma_f32_16x16x32_bf16 v[8:11], v[132:135], v[200:203], v[8:11]
	v_mfma_f32_16x16x32_bf16 v[4:7], v[124:127], v[228:231], v[4:7]
	v_mfma_f32_16x16x32_bf16 v[0:3], v[132:135], v[228:231], v[0:3]
	v_mfma_f32_16x16x32_bf16 v[28:31], v[128:131], v[168:171], v[28:31]
	v_mfma_f32_16x16x32_bf16 v[24:27], v[160:163], v[168:171], v[24:27]
	v_mfma_f32_16x16x32_bf16 v[20:23], v[128:131], v[196:199], v[20:23]
	v_mfma_f32_16x16x32_bf16 v[16:19], v[160:163], v[196:199], v[16:19]
	v_mfma_f32_16x16x32_bf16 v[12:15], v[128:131], v[204:207], v[12:15]
	v_mfma_f32_16x16x32_bf16 v[8:11], v[160:163], v[204:207], v[8:11]
	v_mfma_f32_16x16x32_bf16 v[4:7], v[128:131], v[232:235], v[4:7]
	v_mfma_f32_16x16x32_bf16 v[0:3], v[160:163], v[232:235], v[0:3]
	s_setprio 0
	s_barrier
	s_add_i32 s70, 0, 0x18000
	s_add_i32 s71, 0, 0x1c000
	v_add_u32_e32 v120, s70, v189
	v_add_u32_e32 v160, s71, v189
	ds_read_b128 v[100:103], v120
	ds_read_b128 v[104:107], v120 offset:1024
	ds_read_b128 v[108:111], v120 offset:2048
	ds_read_b128 v[120:123], v120 offset:3072
	ds_read_b128 v[124:127], v160
	ds_read_b128 v[128:131], v160 offset:1024
	ds_read_b128 v[132:135], v160 offset:2048
	ds_read_b128 v[160:163], v160 offset:3072
	s_add_u32 s48, s48, 0x40000
	s_addc_u32 s49, s49, 0
	s_mov_b32 m0, s59
	v_lshl_add_u64 v[240:241], s[48:49], 0, v[172:173]
	ds_read_b128 v[164:167], v209 offset:32768
	ds_read_b128 v[168:171], v209 offset:33792
	ds_read_b128 v[192:195], v209 offset:34816
	ds_read_b128 v[196:199], v209 offset:35840
	ds_read_b128 v[200:203], v209 offset:36864
	ds_read_b128 v[204:207], v209 offset:37888
	ds_read_b128 v[228:231], v209 offset:38912
	ds_read_b128 v[232:235], v209 offset:39936
	global_load_lds_dwordx4 v[240:241], off
	v_lshl_add_u64 v[240:241], s[48:49], 0, v[176:177]
	s_mov_b32 m0, s60
	s_nop 0
	global_load_lds_dwordx4 v[240:241], off
	s_waitcnt vmcnt(8)
	s_waitcnt lgkmcnt(0)
	s_barrier
	s_setprio 1
	v_mfma_f32_16x16x32_bf16 v[156:159], v[100:103], v[164:167], v[156:159]
	v_mfma_f32_16x16x32_bf16 v[152:155], v[108:111], v[164:167], v[152:155]
	v_mfma_f32_16x16x32_bf16 v[148:151], v[100:103], v[192:195], v[148:151]
	v_mfma_f32_16x16x32_bf16 v[144:147], v[108:111], v[192:195], v[144:147]
	v_mfma_f32_16x16x32_bf16 v[140:143], v[100:103], v[200:203], v[140:143]
	v_mfma_f32_16x16x32_bf16 v[136:139], v[108:111], v[200:203], v[136:139]
	v_mfma_f32_16x16x32_bf16 v[116:119], v[100:103], v[228:231], v[116:119]
	v_mfma_f32_16x16x32_bf16 v[112:115], v[108:111], v[228:231], v[112:115]
	v_mfma_f32_16x16x32_bf16 v[156:159], v[104:107], v[168:171], v[156:159]
	v_mfma_f32_16x16x32_bf16 v[152:155], v[120:123], v[168:171], v[152:155]
	v_mfma_f32_16x16x32_bf16 v[148:151], v[104:107], v[196:199], v[148:151]
	v_mfma_f32_16x16x32_bf16 v[144:147], v[120:123], v[196:199], v[144:147]
	v_mfma_f32_16x16x32_bf16 v[140:143], v[104:107], v[204:207], v[140:143]
	v_mfma_f32_16x16x32_bf16 v[136:139], v[120:123], v[204:207], v[136:139]
	v_mfma_f32_16x16x32_bf16 v[116:119], v[104:107], v[232:235], v[116:119]
	v_mfma_f32_16x16x32_bf16 v[112:115], v[120:123], v[232:235], v[112:115]
	v_mfma_f32_16x16x32_bf16 v[60:63], v[124:127], v[164:167], v[60:63]
	v_mfma_f32_16x16x32_bf16 v[56:59], v[132:135], v[164:167], v[56:59]
	v_mfma_f32_16x16x32_bf16 v[52:55], v[124:127], v[192:195], v[52:55]
	v_mfma_f32_16x16x32_bf16 v[48:51], v[132:135], v[192:195], v[48:51]
	v_mfma_f32_16x16x32_bf16 v[44:47], v[124:127], v[200:203], v[44:47]
	v_mfma_f32_16x16x32_bf16 v[40:43], v[132:135], v[200:203], v[40:43]
	v_mfma_f32_16x16x32_bf16 v[36:39], v[124:127], v[228:231], v[36:39]
	v_mfma_f32_16x16x32_bf16 v[32:35], v[132:135], v[228:231], v[32:35]
	v_mfma_f32_16x16x32_bf16 v[60:63], v[128:131], v[168:171], v[60:63]
	v_mfma_f32_16x16x32_bf16 v[56:59], v[160:163], v[168:171], v[56:59]
	v_mfma_f32_16x16x32_bf16 v[52:55], v[128:131], v[196:199], v[52:55]
	v_mfma_f32_16x16x32_bf16 v[48:51], v[160:163], v[196:199], v[48:51]
	v_mfma_f32_16x16x32_bf16 v[44:47], v[128:131], v[204:207], v[44:47]
	v_mfma_f32_16x16x32_bf16 v[40:43], v[160:163], v[204:207], v[40:43]
	v_mfma_f32_16x16x32_bf16 v[36:39], v[128:131], v[232:235], v[36:39]
	v_mfma_f32_16x16x32_bf16 v[32:35], v[160:163], v[232:235], v[32:35]
	s_setprio 0
	s_barrier
; #define PG8_STAGE(bufoff, gbase, voff) do { _Pragma("unroll") for (int _i = 0; _i < 2; ++_i) \
;         __builtin_amdgcn_global_load_lds((const unsigned*)((const char*)(gbase) + (voff)[_i]), (PG8_LAS unsigned*)(lds + (bufoff) + ldsw + _i * 8192), 16, 0, 0); } while (0)
; #define PG8_LDA(dst, b, h) do { _Pragma("unroll") for (int m = 0; m < 4; ++m) _Pragma("unroll") for (int k = 0; k < 2; ++k) dst[m][k] = *(const PG8_LAS bf16x8*)(lds + PG8_SA(b, h) + aoff + m * 2048 + k * 1024); } while (0)
; #define PG8_MMA(ai, bj, At, Bt) do { __builtin_amdgcn_s_setprio(1); _Pragma("unroll") for (int m = 0; m < 4; ++m) _Pragma("unroll") for (int n = 0; n < 2; ++n) _Pragma("unroll") for (int k = 0; k < 2; ++k) \
;         acc[ai][bj][m][n] = __builtin_amdgcn_mfma_f32_16x16x32_bf16(Bt[n][k], At[m][k], acc[ai][bj][m][n], 0, 0, 0); __builtin_amdgcn_s_setprio(0); } while (0)
; #define PG8_WAIT_V(n) asm volatile("s_waitcnt vmcnt(" #n ")" ::: "memory")
; #define PG8_WAIT_L(n) asm volatile("s_waitcnt lgkmcnt(" #n ")" ::: "memory")
; #define PG8_BAR __builtin_amdgcn_s_barrier()
; #define PG8_SCHED __builtin_amdgcn_sched_barrier(0)
; template <class Epi, class Sched, bool ALIGN_EPI = false, bool SP2 = false>
; __device__ __forceinline__ void gemm_phase(PG8_LAS unsigned char* lds, const Gemm g, const Sched& S, const Epi& E) {
;     ...
;             PG8_LDA(At, 1, 1); PG8_STAGE(PG8_SB(1, 0), b3, voffB); PG8_STAGE(PG8_SB(1, 1), b3 + hstepB, voffB); PG8_STAGE(PG8_SA(1, 0), a3, voffA);
;             PG8_WAIT_V(8); PG8_WAIT_L(0); PG8_BAR; PG8_MMA(1, 0, At, B0); PG8_MMA(1, 1, At, B1); PG8_BAR; PG8_SCHED;
	s_add_i32 s48, s70, s56
	v_lshl_add_u64 v[236:237], v[236:237], 0, s[10:11]
	s_mov_b32 m0, s48
	ds_read_b128 v[164:167], v209 offset:49152
	ds_read_b128 v[168:171], v209 offset:50176
	ds_read_b128 v[192:195], v209 offset:51200
	ds_read_b128 v[196:199], v209 offset:52224
	ds_read_b128 v[200:203], v209 offset:53248
	ds_read_b128 v[204:207], v209 offset:54272
	ds_read_b128 v[228:231], v209 offset:55296
	ds_read_b128 v[232:235], v209 offset:56320
	global_load_lds_dwordx4 v[236:237], off
	s_add_i32 m0, s48, 0x2000
	s_add_u32 s46, s46, 0x40080
	v_lshl_add_u64 v[236:237], v[238:239], 0, s[10:11]
	s_addc_u32 s47, s47, 0
	s_add_i32 s48, s71, s56
	global_load_lds_dwordx4 v[236:237], off
	v_lshl_add_u64 v[236:237], s[46:47], 0, v[174:175]
	s_mov_b32 m0, s48
	s_nop 0
	global_load_lds_dwordx4 v[236:237], off
	v_lshl_add_u64 v[236:237], s[46:47], 0, v[178:179]
	s_add_i32 m0, s48, 0x2000
	s_nop 0
	global_load_lds_dwordx4 v[236:237], off
	v_lshl_add_u64 v[236:237], s[44:45], 0, v[172:173]
	s_mov_b32 m0, s66
	s_nop 0
	global_load_lds_dwordx4 v[236:237], off
	v_lshl_add_u64 v[236:237], s[44:45], 0, v[176:177]
	s_mov_b32 m0, s67
	s_nop 0
	global_load_lds_dwordx4 v[236:237], off
	s_waitcnt vmcnt(8)
	s_waitcnt lgkmcnt(0)
	s_barrier
	s_setprio 1
	v_mfma_f32_16x16x32_bf16 v[92:95], v[100:103], v[164:167], v[92:95]
	v_mfma_f32_16x16x32_bf16 v[88:91], v[108:111], v[164:167], v[88:91]
	v_mfma_f32_16x16x32_bf16 v[84:87], v[100:103], v[192:195], v[84:87]
	v_mfma_f32_16x16x32_bf16 v[80:83], v[108:111], v[192:195], v[80:83]
	v_mfma_f32_16x16x32_bf16 v[76:79], v[100:103], v[200:203], v[76:79]
	v_mfma_f32_16x16x32_bf16 v[72:75], v[108:111], v[200:203], v[72:75]
	v_mfma_f32_16x16x32_bf16 v[68:71], v[100:103], v[228:231], v[68:71]
	v_mfma_f32_16x16x32_bf16 v[64:67], v[108:111], v[228:231], v[64:67]
	v_mfma_f32_16x16x32_bf16 v[92:95], v[104:107], v[168:171], v[92:95]
	v_mfma_f32_16x16x32_bf16 v[88:91], v[120:123], v[168:171], v[88:91]
	v_mfma_f32_16x16x32_bf16 v[84:87], v[104:107], v[196:199], v[84:87]
	v_mfma_f32_16x16x32_bf16 v[80:83], v[120:123], v[196:199], v[80:83]
	v_mfma_f32_16x16x32_bf16 v[76:79], v[104:107], v[204:207], v[76:79]
	v_mfma_f32_16x16x32_bf16 v[72:75], v[120:123], v[204:207], v[72:75]
	v_mfma_f32_16x16x32_bf16 v[68:71], v[104:107], v[232:235], v[68:71]
	v_mfma_f32_16x16x32_bf16 v[64:67], v[120:123], v[232:235], v[64:67]
	v_mfma_f32_16x16x32_bf16 v[28:31], v[124:127], v[164:167], v[28:31]
	v_mfma_f32_16x16x32_bf16 v[24:27], v[132:135], v[164:167], v[24:27]
	v_mfma_f32_16x16x32_bf16 v[20:23], v[124:127], v[192:195], v[20:23]
	v_mfma_f32_16x16x32_bf16 v[16:19], v[132:135], v[192:195], v[16:19]
	v_mfma_f32_16x16x32_bf16 v[12:15], v[124:127], v[200:203], v[12:15]
	v_mfma_f32_16x16x32_bf16 v[8:11], v[132:135], v[200:203], v[8:11]
	v_mfma_f32_16x16x32_bf16 v[4:7], v[124:127], v[228:231], v[4:7]
	v_mfma_f32_16x16x32_bf16 v[0:3], v[132:135], v[228:231], v[0:3]
	v_mfma_f32_16x16x32_bf16 v[28:31], v[128:131], v[168:171], v[28:31]
	v_mfma_f32_16x16x32_bf16 v[24:27], v[160:163], v[168:171], v[24:27]
	v_mfma_f32_16x16x32_bf16 v[20:23], v[128:131], v[196:199], v[20:23]
	v_mfma_f32_16x16x32_bf16 v[16:19], v[160:163], v[196:199], v[16:19]
	v_mfma_f32_16x16x32_bf16 v[12:15], v[128:131], v[204:207], v[12:15]
	v_mfma_f32_16x16x32_bf16 v[8:11], v[160:163], v[204:207], v[8:11]
	v_mfma_f32_16x16x32_bf16 v[4:7], v[128:131], v[232:235], v[4:7]
	v_mfma_f32_16x16x32_bf16 v[0:3], v[160:163], v[232:235], v[0:3]
	s_setprio 0
	s_barrier
	s_add_i32 s85, s85, 2
	s_add_u32 s42, s42, 0x100
	s_addc_u32 s43, s43, 0
	s_cmp_gt_u32 s85, 13
	s_cbranch_scc0 .LBB0_612
	s_and_b64 vcc, exec, s[24:25]
	s_cbranch_vccz .LBB0_615
	s_barrier

; #define PG8_STAGE(bufoff, gbase, voff) do { _Pragma("unroll") for (int _i = 0; _i < 2; ++_i) \
;         __builtin_amdgcn_global_load_lds((const unsigned*)((const char*)(gbase) + (voff)[_i]), (PG8_LAS unsigned*)(lds + (bufoff) + ldsw + _i * 8192), 16, 0, 0); } while (0)
; #define PG8_LDA(dst, b, h) do { _Pragma("unroll") for (int m = 0; m < 4; ++m) _Pragma("unroll") for (int k = 0; k < 2; ++k) dst[m][k] = *(const PG8_LAS bf16x8*)(lds + PG8_SA(b, h) + aoff + m * 2048 + k * 1024); } while (0)
; #define PG8_LDB(dst, b, h) do { _Pragma("unroll") for (int n = 0; n < 2; ++n) _Pragma("unroll") for (int k = 0; k < 2; ++k) dst[n][k] = *(const PG8_LAS bf16x8*)(lds + PG8_SB(b, h) + boff + n * 2048 + k * 1024); } while (0)
; #define PG8_MMA(ai, bj, At, Bt) do { __builtin_amdgcn_s_setprio(1); _Pragma("unroll") for (int m = 0; m < 4; ++m) _Pragma("unroll") for (int n = 0; n < 2; ++n) _Pragma("unroll") for (int k = 0; k < 2; ++k) \
;         acc[ai][bj][m][n] = __builtin_amdgcn_mfma_f32_16x16x32_bf16(Bt[n][k], At[m][k], acc[ai][bj][m][n], 0, 0, 0); __builtin_amdgcn_s_setprio(0); } while (0)
; #define PG8_WAIT_V(n) asm volatile("s_waitcnt vmcnt(" #n ")" ::: "memory")
; #define PG8_WAIT_L(n) asm volatile("s_waitcnt lgkmcnt(" #n ")" ::: "memory")
; #define PG8_BAR __builtin_amdgcn_s_barrier()
; #define PG8_SCHED __builtin_amdgcn_sched_barrier(0)
; template <class Epi, class Sched, bool ALIGN_EPI = false, bool SP2 = false>
; __device__ __forceinline__ void gemm_phase(PG8_LAS unsigned char* lds, const Gemm g, const Sched& S, const Epi& E) {
;     ...
;             const bool last = (t == nt - 2);
;             const char* a1 = cA + PG8_AK(t + 1);
;             const char* a2 = last ? nA : cA + PG8_AK(t + 2); const char* b2 = last ? nB : cB + (size_t)(t + 2) * kstep;
;             const char* a3 = last ? nA + PG8_AK(1) : cA + PG8_AK(t + 3); const char* b3 = b2 + kstep;
;             if (last && has_next) S.a_ready(nxt);
;             if constexpr (SP2) {
;             PG8_LDB(B0, 0, 0); PG8_LDB(B1, 0, 1); PG8_SCHED; PG8_LDA(At, 0, 0); PG8_STAGE(PG8_SA(1, 1), a1 + hstepA, voffA);
;             PG8_WAIT_V(8); PG8_WAIT_L(0); PG8_BAR; PG8_MMA(0, 0, At, B0); PG8_MMA(0, 1, At, B1); PG8_BAR; PG8_SCHED;
;             PG8_LDA(At, 0, 1); PG8_STAGE(PG8_SB(0, 0), b2, voffB); PG8_STAGE(PG8_SB(0, 1), b2 + hstepB, voffB); PG8_STAGE(PG8_SA(0, 0), a2, voffA);
.LBB0_782:
	ds_read_b128 v[100:103], v167
	ds_read_b128 v[154:157], v167 offset:1024
	ds_read_b128 v[158:161], v167 offset:2048
	ds_read_b128 v[170:173], v167 offset:3072
	ds_read_b128 v[174:177], v168
	ds_read_b128 v[178:181], v168 offset:1024
	ds_read_b128 v[182:185], v168 offset:2048
	ds_read_b128 v[186:189], v168 offset:3072
	s_add_u32 s36, s6, s34
	s_addc_u32 s37, s7, s35
	s_add_u32 s40, s36, 0x100
	s_addc_u32 s41, s37, 0
	s_add_u32 s38, s62, s34
	s_addc_u32 s39, s63, s35
	s_add_u32 s36, s36, 0x180
	s_addc_u32 s37, s37, 0
	s_cmpk_eq_i32 s34, 0x700
	s_cselect_b32 s37, s61, s37
	s_cselect_b32 s36, s31, s36
	s_cselect_b32 s39, s23, s39
	s_cselect_b32 s38, s25, s38
	s_cselect_b32 s41, s3, s41
	s_cselect_b32 s40, s9, s40
	v_lshl_add_u64 v[162:163], v[98:99], 0, s[34:35]
	s_add_i32 m0, s47, 0xc000
	ds_read_b128 v[190:193], v169
	ds_read_b128 v[194:197], v169 offset:1024
	ds_read_b128 v[198:201], v169 offset:2048
	ds_read_b128 v[202:205], v169 offset:3072
	ds_read_b128 v[206:209], v169 offset:4096
	ds_read_b128 v[210:213], v169 offset:5120
	ds_read_b128 v[214:217], v169 offset:6144
	ds_read_b128 v[218:221], v169 offset:7168
	global_load_lds_dwordx4 v[162:163], off
	v_lshl_add_u64 v[162:163], v[96:97], 0, s[34:35]
	s_add_i32 m0, s47, 0xe000
	s_nop 0
	global_load_lds_dwordx4 v[162:163], off
	s_waitcnt vmcnt(8)
	s_waitcnt lgkmcnt(0)
	s_barrier
	s_setprio 1
	v_mfma_f32_16x16x32_bf16 v[132:135], v[100:103], v[190:193], v[132:135]
	v_mfma_f32_16x16x32_bf16 v[128:131], v[158:161], v[190:193], v[128:131]
	v_mfma_f32_16x16x32_bf16 v[124:127], v[100:103], v[198:201], v[124:127]
	v_mfma_f32_16x16x32_bf16 v[120:123], v[158:161], v[198:201], v[120:123]
	v_mfma_f32_16x16x32_bf16 v[116:119], v[100:103], v[206:209], v[116:119]
	v_mfma_f32_16x16x32_bf16 v[112:115], v[158:161], v[206:209], v[112:115]
	v_mfma_f32_16x16x32_bf16 v[108:111], v[100:103], v[214:217], v[108:111]
	v_mfma_f32_16x16x32_bf16 v[104:107], v[158:161], v[214:217], v[104:107]
	v_mfma_f32_16x16x32_bf16 v[132:135], v[154:157], v[194:197], v[132:135]
	v_mfma_f32_16x16x32_bf16 v[128:131], v[170:173], v[194:197], v[128:131]
	v_mfma_f32_16x16x32_bf16 v[124:127], v[154:157], v[202:205], v[124:127]
	v_mfma_f32_16x16x32_bf16 v[120:123], v[170:173], v[202:205], v[120:123]
	v_mfma_f32_16x16x32_bf16 v[116:119], v[154:157], v[210:213], v[116:119]
	v_mfma_f32_16x16x32_bf16 v[112:115], v[170:173], v[210:213], v[112:115]
	v_mfma_f32_16x16x32_bf16 v[108:111], v[154:157], v[218:221], v[108:111]
	v_mfma_f32_16x16x32_bf16 v[104:107], v[170:173], v[218:221], v[104:107]
	v_mfma_f32_16x16x32_bf16 v[60:63], v[174:177], v[190:193], v[60:63]
	v_mfma_f32_16x16x32_bf16 v[56:59], v[182:185], v[190:193], v[56:59]
	v_mfma_f32_16x16x32_bf16 v[52:55], v[174:177], v[198:201], v[52:55]
	v_mfma_f32_16x16x32_bf16 v[48:51], v[182:185], v[198:201], v[48:51]
	v_mfma_f32_16x16x32_bf16 v[44:47], v[174:177], v[206:209], v[44:47]
	v_mfma_f32_16x16x32_bf16 v[40:43], v[182:185], v[206:209], v[40:43]
	v_mfma_f32_16x16x32_bf16 v[36:39], v[174:177], v[214:217], v[36:39]
	v_mfma_f32_16x16x32_bf16 v[32:35], v[182:185], v[214:217], v[32:35]
	v_mfma_f32_16x16x32_bf16 v[60:63], v[178:181], v[194:197], v[60:63]
	v_mfma_f32_16x16x32_bf16 v[56:59], v[186:189], v[194:197], v[56:59]
	v_mfma_f32_16x16x32_bf16 v[52:55], v[178:181], v[202:205], v[52:55]
	v_mfma_f32_16x16x32_bf16 v[48:51], v[186:189], v[202:205], v[48:51]
	v_mfma_f32_16x16x32_bf16 v[44:47], v[178:181], v[210:213], v[44:47]
	v_mfma_f32_16x16x32_bf16 v[40:43], v[186:189], v[210:213], v[40:43]
	v_mfma_f32_16x16x32_bf16 v[36:39], v[178:181], v[218:221], v[36:39]
	v_mfma_f32_16x16x32_bf16 v[32:35], v[186:189], v[218:221], v[32:35]
	s_setprio 0
	s_barrier
	s_add_i32 s65, s58, s46
	v_lshl_add_u64 v[162:163], s[38:39], 0, v[138:139]
	s_mov_b32 m0, s65
	ds_read_b128 v[190:193], v169 offset:16384
	ds_read_b128 v[194:197], v169 offset:17408
	ds_read_b128 v[198:201], v169 offset:18432
	ds_read_b128 v[202:205], v169 offset:19456
	ds_read_b128 v[206:209], v169 offset:20480
	ds_read_b128 v[210:213], v169 offset:21504
	ds_read_b128 v[214:217], v169 offset:22528
	ds_read_b128 v[218:221], v169 offset:23552
	global_load_lds_dwordx4 v[162:163], off
	s_add_i32 m0, s65, 0x2000
	s_add_u32 s66, s38, 0x40000
	v_lshl_add_u64 v[222:223], s[38:39], 0, v[142:143]
	s_addc_u32 s67, s39, 0
	s_add_i32 s65, s59, s46
	global_load_lds_dwordx4 v[222:223], off
	v_lshl_add_u64 v[224:225], s[66:67], 0, v[138:139]
	s_mov_b32 m0, s65
	s_nop 0
	global_load_lds_dwordx4 v[224:225], off
	v_lshl_add_u64 v[224:225], s[66:67], 0, v[142:143]
	s_add_i32 m0, s65, 0x2000
	s_nop 0
	global_load_lds_dwordx4 v[224:225], off
	v_lshl_add_u64 v[224:225], s[40:41], 0, v[136:137]
	s_mov_b32 m0, s47
	s_nop 0
	global_load_lds_dwordx4 v[224:225], off
	v_lshl_add_u64 v[224:225], s[40:41], 0, v[140:141]
	s_mov_b32 m0, s48
	s_nop 0
	global_load_lds_dwordx4 v[224:225], off
	s_waitcnt vmcnt(8)
	s_waitcnt lgkmcnt(0)
	s_barrier
; #define PG8_STAGE(bufoff, gbase, voff) do { _Pragma("unroll") for (int _i = 0; _i < 2; ++_i) \
;         __builtin_amdgcn_global_load_lds((const unsigned*)((const char*)(gbase) + (voff)[_i]), (PG8_LAS unsigned*)(lds + (bufoff) + ldsw + _i * 8192), 16, 0, 0); } while (0)
; #define PG8_LDA(dst, b, h) do { _Pragma("unroll") for (int m = 0; m < 4; ++m) _Pragma("unroll") for (int k = 0; k < 2; ++k) dst[m][k] = *(const PG8_LAS bf16x8*)(lds + PG8_SA(b, h) + aoff + m * 2048 + k * 1024); } while (0)
; #define PG8_LDB(dst, b, h) do { _Pragma("unroll") for (int n = 0; n < 2; ++n) _Pragma("unroll") for (int k = 0; k < 2; ++k) dst[n][k] = *(const PG8_LAS bf16x8*)(lds + PG8_SB(b, h) + boff + n * 2048 + k * 1024); } while (0)
; #define PG8_MMA(ai, bj, At, Bt) do { __builtin_amdgcn_s_setprio(1); _Pragma("unroll") for (int m = 0; m < 4; ++m) _Pragma("unroll") for (int n = 0; n < 2; ++n) _Pragma("unroll") for (int k = 0; k < 2; ++k) \
;         acc[ai][bj][m][n] = __builtin_amdgcn_mfma_f32_16x16x32_bf16(Bt[n][k], At[m][k], acc[ai][bj][m][n], 0, 0, 0); __builtin_amdgcn_s_setprio(0); } while (0)
; #define PG8_WAIT_V(n) asm volatile("s_waitcnt vmcnt(" #n ")" ::: "memory")
; #define PG8_WAIT_L(n) asm volatile("s_waitcnt lgkmcnt(" #n ")" ::: "memory")
; #define PG8_BAR __builtin_amdgcn_s_barrier()
; #define PG8_SCHED __builtin_amdgcn_sched_barrier(0)
; template <class Epi, class Sched, bool ALIGN_EPI = false, bool SP2 = false>
; __device__ __forceinline__ void gemm_phase(PG8_LAS unsigned char* lds, const Gemm g, const Sched& S, const Epi& E) {
;     ...
;             PG8_LDA(At, 0, 1); PG8_STAGE(PG8_SB(0, 0), b2, voffB); PG8_STAGE(PG8_SB(0, 1), b2 + hstepB, voffB); PG8_STAGE(PG8_SA(0, 0), a2, voffA);
;             PG8_WAIT_V(8); PG8_WAIT_L(0); PG8_BAR; PG8_MMA(1, 0, At, B0); PG8_MMA(1, 1, At, B1); PG8_BAR; PG8_SCHED;
;             PG8_LDB(B0, 1, 0); PG8_LDB(B1, 1, 1); PG8_SCHED; PG8_LDA(At, 1, 0); PG8_STAGE(PG8_SA(0, 1), a2 + hstepA, voffA);
;             PG8_WAIT_V(8); PG8_WAIT_L(0); PG8_BAR; PG8_MMA(0, 0, At, B0); PG8_MMA(0, 1, At, B1); PG8_BAR; PG8_SCHED;
	s_setprio 1
	v_mfma_f32_16x16x32_bf16 v[92:95], v[100:103], v[190:193], v[92:95]
	v_mfma_f32_16x16x32_bf16 v[88:91], v[158:161], v[190:193], v[88:91]
	v_mfma_f32_16x16x32_bf16 v[84:87], v[100:103], v[198:201], v[84:87]
	v_mfma_f32_16x16x32_bf16 v[80:83], v[158:161], v[198:201], v[80:83]
	v_mfma_f32_16x16x32_bf16 v[76:79], v[100:103], v[206:209], v[76:79]
	v_mfma_f32_16x16x32_bf16 v[72:75], v[158:161], v[206:209], v[72:75]
	v_mfma_f32_16x16x32_bf16 v[68:71], v[100:103], v[214:217], v[68:71]
	v_mfma_f32_16x16x32_bf16 v[64:67], v[158:161], v[214:217], v[64:67]
	v_mfma_f32_16x16x32_bf16 v[92:95], v[154:157], v[194:197], v[92:95]
	v_mfma_f32_16x16x32_bf16 v[88:91], v[170:173], v[194:197], v[88:91]
	v_mfma_f32_16x16x32_bf16 v[84:87], v[154:157], v[202:205], v[84:87]
	v_mfma_f32_16x16x32_bf16 v[80:83], v[170:173], v[202:205], v[80:83]
	v_mfma_f32_16x16x32_bf16 v[76:79], v[154:157], v[210:213], v[76:79]
	v_mfma_f32_16x16x32_bf16 v[72:75], v[170:173], v[210:213], v[72:75]
	v_mfma_f32_16x16x32_bf16 v[68:71], v[154:157], v[218:221], v[68:71]
	v_mfma_f32_16x16x32_bf16 v[64:67], v[170:173], v[218:221], v[64:67]
	v_mfma_f32_16x16x32_bf16 v[28:31], v[174:177], v[190:193], v[28:31]
	v_mfma_f32_16x16x32_bf16 v[24:27], v[182:185], v[190:193], v[24:27]
	v_mfma_f32_16x16x32_bf16 v[20:23], v[174:177], v[198:201], v[20:23]
	v_mfma_f32_16x16x32_bf16 v[16:19], v[182:185], v[198:201], v[16:19]
	v_mfma_f32_16x16x32_bf16 v[12:15], v[174:177], v[206:209], v[12:15]
	v_mfma_f32_16x16x32_bf16 v[8:11], v[182:185], v[206:209], v[8:11]
	v_mfma_f32_16x16x32_bf16 v[4:7], v[174:177], v[214:217], v[4:7]
	v_mfma_f32_16x16x32_bf16 v[0:3], v[182:185], v[214:217], v[0:3]
	v_mfma_f32_16x16x32_bf16 v[28:31], v[178:181], v[194:197], v[28:31]
	v_mfma_f32_16x16x32_bf16 v[24:27], v[186:189], v[194:197], v[24:27]
	v_mfma_f32_16x16x32_bf16 v[20:23], v[178:181], v[202:205], v[20:23]
	v_mfma_f32_16x16x32_bf16 v[16:19], v[186:189], v[202:205], v[16:19]
	v_mfma_f32_16x16x32_bf16 v[12:15], v[178:181], v[210:213], v[12:15]
	v_mfma_f32_16x16x32_bf16 v[8:11], v[186:189], v[210:213], v[8:11]
	v_mfma_f32_16x16x32_bf16 v[4:7], v[178:181], v[218:221], v[4:7]
	v_mfma_f32_16x16x32_bf16 v[0:3], v[186:189], v[218:221], v[0:3]
	s_setprio 0
	s_barrier
	s_add_i32 s65, 0, 0x18000
	s_add_i32 s66, 0, 0x1c000
	v_add_u32_e32 v170, s65, v165
	v_add_u32_e32 v186, s66, v165
	ds_read_b128 v[100:103], v170
	ds_read_b128 v[154:157], v170 offset:1024
	ds_read_b128 v[158:161], v170 offset:2048
	ds_read_b128 v[170:173], v170 offset:3072
	ds_read_b128 v[174:177], v186
	ds_read_b128 v[178:181], v186 offset:1024
	ds_read_b128 v[182:185], v186 offset:2048
	ds_read_b128 v[186:189], v186 offset:3072
	s_add_u32 s40, s40, 0x40000
	s_addc_u32 s41, s41, 0
	s_mov_b32 m0, s49
	v_lshl_add_u64 v[224:225], s[40:41], 0, v[136:137]
	ds_read_b128 v[190:193], v169 offset:32768
	ds_read_b128 v[194:197], v169 offset:33792
	ds_read_b128 v[198:201], v169 offset:34816
	ds_read_b128 v[202:205], v169 offset:35840
	ds_read_b128 v[206:209], v169 offset:36864
	ds_read_b128 v[210:213], v169 offset:37888
	ds_read_b128 v[214:217], v169 offset:38912
	ds_read_b128 v[218:221], v169 offset:39936
	global_load_lds_dwordx4 v[224:225], off
	v_lshl_add_u64 v[224:225], s[40:41], 0, v[140:141]
	s_mov_b32 m0, s50
	s_nop 0
	global_load_lds_dwordx4 v[224:225], off
	s_waitcnt vmcnt(8)
	s_waitcnt lgkmcnt(0)
	s_barrier
	s_setprio 1
	v_mfma_f32_16x16x32_bf16 v[132:135], v[100:103], v[190:193], v[132:135]
	v_mfma_f32_16x16x32_bf16 v[128:131], v[158:161], v[190:193], v[128:131]
	v_mfma_f32_16x16x32_bf16 v[124:127], v[100:103], v[198:201], v[124:127]
	v_mfma_f32_16x16x32_bf16 v[120:123], v[158:161], v[198:201], v[120:123]
	v_mfma_f32_16x16x32_bf16 v[116:119], v[100:103], v[206:209], v[116:119]
	v_mfma_f32_16x16x32_bf16 v[112:115], v[158:161], v[206:209], v[112:115]
	v_mfma_f32_16x16x32_bf16 v[108:111], v[100:103], v[214:217], v[108:111]
	v_mfma_f32_16x16x32_bf16 v[104:107], v[158:161], v[214:217], v[104:107]
	v_mfma_f32_16x16x32_bf16 v[132:135], v[154:157], v[194:197], v[132:135]
	v_mfma_f32_16x16x32_bf16 v[128:131], v[170:173], v[194:197], v[128:131]
	v_mfma_f32_16x16x32_bf16 v[124:127], v[154:157], v[202:205], v[124:127]
	v_mfma_f32_16x16x32_bf16 v[120:123], v[170:173], v[202:205], v[120:123]
	v_mfma_f32_16x16x32_bf16 v[116:119], v[154:157], v[210:213], v[116:119]
	v_mfma_f32_16x16x32_bf16 v[112:115], v[170:173], v[210:213], v[112:115]
	v_mfma_f32_16x16x32_bf16 v[108:111], v[154:157], v[218:221], v[108:111]
	v_mfma_f32_16x16x32_bf16 v[104:107], v[170:173], v[218:221], v[104:107]
	v_mfma_f32_16x16x32_bf16 v[60:63], v[174:177], v[190:193], v[60:63]
	v_mfma_f32_16x16x32_bf16 v[56:59], v[182:185], v[190:193], v[56:59]
	v_mfma_f32_16x16x32_bf16 v[52:55], v[174:177], v[198:201], v[52:55]
	v_mfma_f32_16x16x32_bf16 v[48:51], v[182:185], v[198:201], v[48:51]
	v_mfma_f32_16x16x32_bf16 v[44:47], v[174:177], v[206:209], v[44:47]
	v_mfma_f32_16x16x32_bf16 v[40:43], v[182:185], v[206:209], v[40:43]
	v_mfma_f32_16x16x32_bf16 v[36:39], v[174:177], v[214:217], v[36:39]
	v_mfma_f32_16x16x32_bf16 v[32:35], v[182:185], v[214:217], v[32:35]
	v_mfma_f32_16x16x32_bf16 v[60:63], v[178:181], v[194:197], v[60:63]
	v_mfma_f32_16x16x32_bf16 v[56:59], v[186:189], v[194:197], v[56:59]
	v_mfma_f32_16x16x32_bf16 v[52:55], v[178:181], v[202:205], v[52:55]
	v_mfma_f32_16x16x32_bf16 v[48:51], v[186:189], v[202:205], v[48:51]
	v_mfma_f32_16x16x32_bf16 v[44:47], v[178:181], v[210:213], v[44:47]
	v_mfma_f32_16x16x32_bf16 v[40:43], v[186:189], v[210:213], v[40:43]
	v_mfma_f32_16x16x32_bf16 v[36:39], v[178:181], v[218:221], v[36:39]
	v_mfma_f32_16x16x32_bf16 v[32:35], v[186:189], v[218:221], v[32:35]
	s_setprio 0
	s_barrier
; #define PG8_STAGE(bufoff, gbase, voff) do { _Pragma("unroll") for (int _i = 0; _i < 2; ++_i) \
;         __builtin_amdgcn_global_load_lds((const unsigned*)((const char*)(gbase) + (voff)[_i]), (PG8_LAS unsigned*)(lds + (bufoff) + ldsw + _i * 8192), 16, 0, 0); } while (0)
; #define PG8_LDA(dst, b, h) do { _Pragma("unroll") for (int m = 0; m < 4; ++m) _Pragma("unroll") for (int k = 0; k < 2; ++k) dst[m][k] = *(const PG8_LAS bf16x8*)(lds + PG8_SA(b, h) + aoff + m * 2048 + k * 1024); } while (0)
; #define PG8_MMA(ai, bj, At, Bt) do { __builtin_amdgcn_s_setprio(1); _Pragma("unroll") for (int m = 0; m < 4; ++m) _Pragma("unroll") for (int n = 0; n < 2; ++n) _Pragma("unroll") for (int k = 0; k < 2; ++k) \
;         acc[ai][bj][m][n] = __builtin_amdgcn_mfma_f32_16x16x32_bf16(Bt[n][k], At[m][k], acc[ai][bj][m][n], 0, 0, 0); __builtin_amdgcn_s_setprio(0); } while (0)
; #define PG8_WAIT_V(n) asm volatile("s_waitcnt vmcnt(" #n ")" ::: "memory")
; #define PG8_WAIT_L(n) asm volatile("s_waitcnt lgkmcnt(" #n ")" ::: "memory")
; #define PG8_BAR __builtin_amdgcn_s_barrier()
; #define PG8_SCHED __builtin_amdgcn_sched_barrier(0)
; template <class Epi, class Sched, bool ALIGN_EPI = false, bool SP2 = false>
; __device__ __forceinline__ void gemm_phase(PG8_LAS unsigned char* lds, const Gemm g, const Sched& S, const Epi& E) {
;     ...
;             PG8_LDA(At, 1, 1); PG8_STAGE(PG8_SB(1, 0), b3, voffB); PG8_STAGE(PG8_SB(1, 1), b3 + hstepB, voffB); PG8_STAGE(PG8_SA(1, 0), a3, voffA);
;             PG8_WAIT_V(8); PG8_WAIT_L(0); PG8_BAR; PG8_MMA(1, 0, At, B0); PG8_MMA(1, 1, At, B1); PG8_BAR; PG8_SCHED;
	s_add_i32 s40, s65, s46
	v_lshl_add_u64 v[162:163], v[162:163], 0, s[18:19]
	s_mov_b32 m0, s40
	ds_read_b128 v[190:193], v169 offset:49152
	ds_read_b128 v[194:197], v169 offset:50176
	ds_read_b128 v[198:201], v169 offset:51200
	ds_read_b128 v[202:205], v169 offset:52224
	ds_read_b128 v[206:209], v169 offset:53248
	ds_read_b128 v[210:213], v169 offset:54272
	ds_read_b128 v[214:217], v169 offset:55296
	ds_read_b128 v[218:221], v169 offset:56320
	global_load_lds_dwordx4 v[162:163], off
	s_add_i32 m0, s40, 0x2000
	s_add_u32 s38, s38, 0x40080
	v_lshl_add_u64 v[162:163], v[222:223], 0, s[18:19]
	s_addc_u32 s39, s39, 0
	s_add_i32 s40, s66, s46
	global_load_lds_dwordx4 v[162:163], off
	v_lshl_add_u64 v[162:163], s[38:39], 0, v[138:139]
	s_mov_b32 m0, s40
	s_nop 0
	global_load_lds_dwordx4 v[162:163], off
	v_lshl_add_u64 v[162:163], s[38:39], 0, v[142:143]
	s_add_i32 m0, s40, 0x2000
	s_nop 0
	global_load_lds_dwordx4 v[162:163], off
	v_lshl_add_u64 v[162:163], s[36:37], 0, v[136:137]
	s_mov_b32 m0, s53
	s_nop 0
	global_load_lds_dwordx4 v[162:163], off
	v_lshl_add_u64 v[162:163], s[36:37], 0, v[140:141]
	s_mov_b32 m0, s54
	s_nop 0
	global_load_lds_dwordx4 v[162:163], off
	s_waitcnt vmcnt(8)
	s_waitcnt lgkmcnt(0)
	s_barrier
	s_setprio 1
	v_mfma_f32_16x16x32_bf16 v[92:95], v[100:103], v[190:193], v[92:95]
	v_mfma_f32_16x16x32_bf16 v[88:91], v[158:161], v[190:193], v[88:91]
	v_mfma_f32_16x16x32_bf16 v[84:87], v[100:103], v[198:201], v[84:87]
	v_mfma_f32_16x16x32_bf16 v[80:83], v[158:161], v[198:201], v[80:83]
	v_mfma_f32_16x16x32_bf16 v[76:79], v[100:103], v[206:209], v[76:79]
	v_mfma_f32_16x16x32_bf16 v[72:75], v[158:161], v[206:209], v[72:75]
	v_mfma_f32_16x16x32_bf16 v[68:71], v[100:103], v[214:217], v[68:71]
	v_mfma_f32_16x16x32_bf16 v[64:67], v[158:161], v[214:217], v[64:67]
	v_mfma_f32_16x16x32_bf16 v[92:95], v[154:157], v[194:197], v[92:95]
	v_mfma_f32_16x16x32_bf16 v[88:91], v[170:173], v[194:197], v[88:91]
	v_mfma_f32_16x16x32_bf16 v[84:87], v[154:157], v[202:205], v[84:87]
	v_mfma_f32_16x16x32_bf16 v[80:83], v[170:173], v[202:205], v[80:83]
	v_mfma_f32_16x16x32_bf16 v[76:79], v[154:157], v[210:213], v[76:79]
	v_mfma_f32_16x16x32_bf16 v[72:75], v[170:173], v[210:213], v[72:75]
	v_mfma_f32_16x16x32_bf16 v[68:71], v[154:157], v[218:221], v[68:71]
	v_mfma_f32_16x16x32_bf16 v[64:67], v[170:173], v[218:221], v[64:67]
	v_mfma_f32_16x16x32_bf16 v[28:31], v[174:177], v[190:193], v[28:31]
	v_mfma_f32_16x16x32_bf16 v[24:27], v[182:185], v[190:193], v[24:27]
	v_mfma_f32_16x16x32_bf16 v[20:23], v[174:177], v[198:201], v[20:23]
	v_mfma_f32_16x16x32_bf16 v[16:19], v[182:185], v[198:201], v[16:19]
	v_mfma_f32_16x16x32_bf16 v[12:15], v[174:177], v[206:209], v[12:15]
	v_mfma_f32_16x16x32_bf16 v[8:11], v[182:185], v[206:209], v[8:11]
	v_mfma_f32_16x16x32_bf16 v[4:7], v[174:177], v[214:217], v[4:7]
	v_mfma_f32_16x16x32_bf16 v[0:3], v[182:185], v[214:217], v[0:3]
	v_mfma_f32_16x16x32_bf16 v[28:31], v[178:181], v[194:197], v[28:31]
	v_mfma_f32_16x16x32_bf16 v[24:27], v[186:189], v[194:197], v[24:27]
	v_mfma_f32_16x16x32_bf16 v[20:23], v[178:181], v[202:205], v[20:23]
	v_mfma_f32_16x16x32_bf16 v[16:19], v[186:189], v[202:205], v[16:19]
	v_mfma_f32_16x16x32_bf16 v[12:15], v[178:181], v[210:213], v[12:15]
	v_mfma_f32_16x16x32_bf16 v[8:11], v[186:189], v[210:213], v[8:11]
	v_mfma_f32_16x16x32_bf16 v[4:7], v[178:181], v[218:221], v[4:7]
	v_mfma_f32_16x16x32_bf16 v[0:3], v[186:189], v[218:221], v[0:3]
	s_setprio 0
	s_barrier
	s_add_i32 s64, s64, 2
	s_add_u32 s34, s34, 0x100
	s_addc_u32 s35, s35, 0
	s_cmp_gt_u32 s64, 13
	s_cbranch_scc0 .LBB0_782
	s_and_b64 vcc, exec, s[20:21]
	s_cbranch_vccz .LBB0_785
	s_barrier

; #define PG8_STAGE(bufoff, gbase, voff) do { _Pragma("unroll") for (int _i = 0; _i < 2; ++_i) \
;         __builtin_amdgcn_global_load_lds((const unsigned*)((const char*)(gbase) + (voff)[_i]), (PG8_LAS unsigned*)(lds + (bufoff) + ldsw + _i * 8192), 16, 0, 0); } while (0)
; #define PG8_LDA(dst, b, h) do { _Pragma("unroll") for (int m = 0; m < 4; ++m) _Pragma("unroll") for (int k = 0; k < 2; ++k) dst[m][k] = *(const PG8_LAS bf16x8*)(lds + PG8_SA(b, h) + aoff + m * 2048 + k * 1024); } while (0)
; #define PG8_LDB(dst, b, h) do { _Pragma("unroll") for (int n = 0; n < 2; ++n) _Pragma("unroll") for (int k = 0; k < 2; ++k) dst[n][k] = *(const PG8_LAS bf16x8*)(lds + PG8_SB(b, h) + boff + n * 2048 + k * 1024); } while (0)
; #define PG8_MMA(ai, bj, At, Bt) do { __builtin_amdgcn_s_setprio(1); _Pragma("unroll") for (int m = 0; m < 4; ++m) _Pragma("unroll") for (int n = 0; n < 2; ++n) _Pragma("unroll") for (int k = 0; k < 2; ++k) \
;         acc[ai][bj][m][n] = __builtin_amdgcn_mfma_f32_16x16x32_bf16(Bt[n][k], At[m][k], acc[ai][bj][m][n], 0, 0, 0); __builtin_amdgcn_s_setprio(0); } while (0)
; #define PG8_WAIT_V(n) asm volatile("s_waitcnt vmcnt(" #n ")" ::: "memory")
; #define PG8_WAIT_L(n) asm volatile("s_waitcnt lgkmcnt(" #n ")" ::: "memory")
; #define PG8_BAR __builtin_amdgcn_s_barrier()
; #define PG8_SCHED __builtin_amdgcn_sched_barrier(0)
; template <class Epi, class Sched, bool ALIGN_EPI = false, bool SP2 = false>
; __device__ __forceinline__ void gemm_phase(PG8_LAS unsigned char* lds, const Gemm g, const Sched& S, const Epi& E) {
;     ...
;             const bool last = (t == nt - 2);
;             const char* a1 = cA + PG8_AK(t + 1);
;             const char* a2 = last ? nA : cA + PG8_AK(t + 2); const char* b2 = last ? nB : cB + (size_t)(t + 2) * kstep;
;             const char* a3 = last ? nA + PG8_AK(1) : cA + PG8_AK(t + 3); const char* b3 = b2 + kstep;
;             if (last && has_next) S.a_ready(nxt);
;             if constexpr (SP2) {
;             PG8_LDB(B0, 0, 0); PG8_LDB(B1, 0, 1); PG8_SCHED; PG8_LDA(At, 0, 0); PG8_STAGE(PG8_SA(1, 1), a1 + hstepA, voffA);
;             PG8_WAIT_V(8); PG8_WAIT_L(0); PG8_BAR; PG8_MMA(0, 0, At, B0); PG8_MMA(0, 1, At, B1); PG8_BAR; PG8_SCHED;
;             PG8_LDA(At, 0, 1); PG8_STAGE(PG8_SB(0, 0), b2, voffB); PG8_STAGE(PG8_SB(0, 1), b2 + hstepB, voffB); PG8_STAGE(PG8_SA(0, 0), a2, voffA);
.LBB0_1191:
	ds_read_b128 v[128:131], v191
	ds_read_b128 v[132:135], v191 offset:1024
	ds_read_b128 v[136:139], v191 offset:2048
	ds_read_b128 v[140:143], v191 offset:3072
	ds_read_b128 v[162:165], v192
	ds_read_b128 v[166:169], v192 offset:1024
	ds_read_b128 v[194:197], v192 offset:2048
	ds_read_b128 v[198:201], v192 offset:3072
	s_add_u32 s38, s36, 0x800000
	s_addc_u32 s39, s37, 0
	s_cmp_eq_u32 s67, 12
	s_cselect_b32 s43, s3, s39
	s_cselect_b32 s42, s27, s38
	s_cselect_b32 s41, s25, s66
	s_cselect_b32 s40, s35, s65
	v_lshl_add_u64 v[170:171], s[36:37], 0, v[156:157]
	s_add_i32 m0, s50, 0xc000
	ds_read_b128 v[202:205], v174
	ds_read_b128 v[206:209], v174 offset:1024
	ds_read_b128 v[210:213], v174 offset:2048
	ds_read_b128 v[214:217], v174 offset:3072
	ds_read_b128 v[218:221], v174 offset:4096
	ds_read_b128 v[222:225], v174 offset:5120
	ds_read_b128 v[226:229], v174 offset:6144
	ds_read_b128 v[230:233], v174 offset:7168
	global_load_lds_dwordx4 v[170:171], off
	v_lshl_add_u64 v[170:171], s[36:37], 0, v[154:155]
	s_add_i32 m0, s50, 0xe000
	s_nop 0
	global_load_lds_dwordx4 v[170:171], off
	s_waitcnt vmcnt(8)
	s_waitcnt lgkmcnt(0)
	s_barrier
	s_setprio 1
	v_mfma_f32_16x16x32_bf16 v[124:127], v[128:131], v[202:205], v[124:127]
	v_mfma_f32_16x16x32_bf16 v[120:123], v[136:139], v[202:205], v[120:123]
	v_mfma_f32_16x16x32_bf16 v[116:119], v[128:131], v[210:213], v[116:119]
	v_mfma_f32_16x16x32_bf16 v[112:115], v[136:139], v[210:213], v[112:115]
	v_mfma_f32_16x16x32_bf16 v[108:111], v[128:131], v[218:221], v[108:111]
	v_mfma_f32_16x16x32_bf16 v[104:107], v[136:139], v[218:221], v[104:107]
	v_mfma_f32_16x16x32_bf16 v[100:103], v[128:131], v[226:229], v[100:103]
	v_mfma_f32_16x16x32_bf16 v[96:99], v[136:139], v[226:229], v[96:99]
	v_mfma_f32_16x16x32_bf16 v[124:127], v[132:135], v[206:209], v[124:127]
	v_mfma_f32_16x16x32_bf16 v[120:123], v[140:143], v[206:209], v[120:123]
	v_mfma_f32_16x16x32_bf16 v[116:119], v[132:135], v[214:217], v[116:119]
	v_mfma_f32_16x16x32_bf16 v[112:115], v[140:143], v[214:217], v[112:115]
	v_mfma_f32_16x16x32_bf16 v[108:111], v[132:135], v[222:225], v[108:111]
	v_mfma_f32_16x16x32_bf16 v[104:107], v[140:143], v[222:225], v[104:107]
	v_mfma_f32_16x16x32_bf16 v[100:103], v[132:135], v[230:233], v[100:103]
	v_mfma_f32_16x16x32_bf16 v[96:99], v[140:143], v[230:233], v[96:99]
	v_mfma_f32_16x16x32_bf16 v[60:63], v[162:165], v[202:205], v[60:63]
	v_mfma_f32_16x16x32_bf16 v[56:59], v[194:197], v[202:205], v[56:59]
	v_mfma_f32_16x16x32_bf16 v[52:55], v[162:165], v[210:213], v[52:55]
	v_mfma_f32_16x16x32_bf16 v[48:51], v[194:197], v[210:213], v[48:51]
	v_mfma_f32_16x16x32_bf16 v[44:47], v[162:165], v[218:221], v[44:47]
	v_mfma_f32_16x16x32_bf16 v[40:43], v[194:197], v[218:221], v[40:43]
	v_mfma_f32_16x16x32_bf16 v[36:39], v[162:165], v[226:229], v[36:39]
	v_mfma_f32_16x16x32_bf16 v[32:35], v[194:197], v[226:229], v[32:35]
	v_mfma_f32_16x16x32_bf16 v[60:63], v[166:169], v[206:209], v[60:63]
	v_mfma_f32_16x16x32_bf16 v[56:59], v[198:201], v[206:209], v[56:59]
	v_mfma_f32_16x16x32_bf16 v[52:55], v[166:169], v[214:217], v[52:55]
	v_mfma_f32_16x16x32_bf16 v[48:51], v[198:201], v[214:217], v[48:51]
	v_mfma_f32_16x16x32_bf16 v[44:47], v[166:169], v[222:225], v[44:47]
	v_mfma_f32_16x16x32_bf16 v[40:43], v[198:201], v[222:225], v[40:43]
	v_mfma_f32_16x16x32_bf16 v[36:39], v[166:169], v[230:233], v[36:39]
	v_mfma_f32_16x16x32_bf16 v[32:35], v[198:201], v[230:233], v[32:35]
	s_setprio 0
	s_barrier
	s_add_i32 s36, s62, s49
	v_lshl_add_u64 v[170:171], s[40:41], 0, v[146:147]
	s_mov_b32 m0, s36
	ds_read_b128 v[202:205], v174 offset:16384
	ds_read_b128 v[206:209], v174 offset:17408
	ds_read_b128 v[210:213], v174 offset:18432
	ds_read_b128 v[214:217], v174 offset:19456
	ds_read_b128 v[218:221], v174 offset:20480
	ds_read_b128 v[222:225], v174 offset:21504
	ds_read_b128 v[226:229], v174 offset:22528
	ds_read_b128 v[230:233], v174 offset:23552
	global_load_lds_dwordx4 v[170:171], off
	s_add_i32 m0, s36, 0x2000
	s_add_u32 s36, s40, 0x40000
	v_lshl_add_u64 v[234:235], s[40:41], 0, v[150:151]
	s_addc_u32 s37, s41, 0
	s_add_i32 s68, s63, s49
	global_load_lds_dwordx4 v[234:235], off
	v_lshl_add_u64 v[236:237], s[36:37], 0, v[146:147]
	s_mov_b32 m0, s68
	v_lshl_add_u64 v[238:239], s[42:43], 0, v[148:149]
	global_load_lds_dwordx4 v[236:237], off
	v_lshl_add_u64 v[236:237], s[36:37], 0, v[150:151]
	s_add_i32 m0, s68, 0x2000
	s_nop 0
	global_load_lds_dwordx4 v[236:237], off
	v_lshl_add_u64 v[236:237], s[42:43], 0, v[144:145]
	s_mov_b32 m0, s50
	s_nop 0
	global_load_lds_dwordx4 v[236:237], off
	s_mov_b32 m0, s51
	s_nop 0
	global_load_lds_dwordx4 v[238:239], off
	s_waitcnt vmcnt(8)
	s_waitcnt lgkmcnt(0)
	s_barrier
; #define PG8_STAGE(bufoff, gbase, voff) do { _Pragma("unroll") for (int _i = 0; _i < 2; ++_i) \
;         __builtin_amdgcn_global_load_lds((const unsigned*)((const char*)(gbase) + (voff)[_i]), (PG8_LAS unsigned*)(lds + (bufoff) + ldsw + _i * 8192), 16, 0, 0); } while (0)
; #define PG8_LDA(dst, b, h) do { _Pragma("unroll") for (int m = 0; m < 4; ++m) _Pragma("unroll") for (int k = 0; k < 2; ++k) dst[m][k] = *(const PG8_LAS bf16x8*)(lds + PG8_SA(b, h) + aoff + m * 2048 + k * 1024); } while (0)
; #define PG8_LDB(dst, b, h) do { _Pragma("unroll") for (int n = 0; n < 2; ++n) _Pragma("unroll") for (int k = 0; k < 2; ++k) dst[n][k] = *(const PG8_LAS bf16x8*)(lds + PG8_SB(b, h) + boff + n * 2048 + k * 1024); } while (0)
; #define PG8_MMA(ai, bj, At, Bt) do { __builtin_amdgcn_s_setprio(1); _Pragma("unroll") for (int m = 0; m < 4; ++m) _Pragma("unroll") for (int n = 0; n < 2; ++n) _Pragma("unroll") for (int k = 0; k < 2; ++k) \
;         acc[ai][bj][m][n] = __builtin_amdgcn_mfma_f32_16x16x32_bf16(Bt[n][k], At[m][k], acc[ai][bj][m][n], 0, 0, 0); __builtin_amdgcn_s_setprio(0); } while (0)
; #define PG8_WAIT_V(n) asm volatile("s_waitcnt vmcnt(" #n ")" ::: "memory")
; #define PG8_WAIT_L(n) asm volatile("s_waitcnt lgkmcnt(" #n ")" ::: "memory")
; #define PG8_BAR __builtin_amdgcn_s_barrier()
; #define PG8_SCHED __builtin_amdgcn_sched_barrier(0)
; template <class Epi, class Sched, bool ALIGN_EPI = false, bool SP2 = false>
; __device__ __forceinline__ void gemm_phase(PG8_LAS unsigned char* lds, const Gemm g, const Sched& S, const Epi& E) {
;     ...
;             PG8_LDA(At, 0, 1); PG8_STAGE(PG8_SB(0, 0), b2, voffB); PG8_STAGE(PG8_SB(0, 1), b2 + hstepB, voffB); PG8_STAGE(PG8_SA(0, 0), a2, voffA);
;             PG8_WAIT_V(8); PG8_WAIT_L(0); PG8_BAR; PG8_MMA(1, 0, At, B0); PG8_MMA(1, 1, At, B1); PG8_BAR; PG8_SCHED;
;             PG8_LDB(B0, 1, 0); PG8_LDB(B1, 1, 1); PG8_SCHED; PG8_LDA(At, 1, 0); PG8_STAGE(PG8_SA(0, 1), a2 + hstepA, voffA);
;             PG8_WAIT_V(8); PG8_WAIT_L(0); PG8_BAR; PG8_MMA(0, 0, At, B0); PG8_MMA(0, 1, At, B1); PG8_BAR; PG8_SCHED;
	s_setprio 1
	v_mfma_f32_16x16x32_bf16 v[92:95], v[128:131], v[202:205], v[92:95]
	v_mfma_f32_16x16x32_bf16 v[88:91], v[136:139], v[202:205], v[88:91]
	v_mfma_f32_16x16x32_bf16 v[84:87], v[128:131], v[210:213], v[84:87]
	v_mfma_f32_16x16x32_bf16 v[80:83], v[136:139], v[210:213], v[80:83]
	v_mfma_f32_16x16x32_bf16 v[76:79], v[128:131], v[218:221], v[76:79]
	v_mfma_f32_16x16x32_bf16 v[72:75], v[136:139], v[218:221], v[72:75]
	v_mfma_f32_16x16x32_bf16 v[68:71], v[128:131], v[226:229], v[68:71]
	v_mfma_f32_16x16x32_bf16 v[64:67], v[136:139], v[226:229], v[64:67]
	v_mfma_f32_16x16x32_bf16 v[92:95], v[132:135], v[206:209], v[92:95]
	v_mfma_f32_16x16x32_bf16 v[88:91], v[140:143], v[206:209], v[88:91]
	v_mfma_f32_16x16x32_bf16 v[84:87], v[132:135], v[214:217], v[84:87]
	v_mfma_f32_16x16x32_bf16 v[80:83], v[140:143], v[214:217], v[80:83]
	v_mfma_f32_16x16x32_bf16 v[76:79], v[132:135], v[222:225], v[76:79]
	v_mfma_f32_16x16x32_bf16 v[72:75], v[140:143], v[222:225], v[72:75]
	v_mfma_f32_16x16x32_bf16 v[68:71], v[132:135], v[230:233], v[68:71]
	v_mfma_f32_16x16x32_bf16 v[64:67], v[140:143], v[230:233], v[64:67]
	v_mfma_f32_16x16x32_bf16 v[28:31], v[162:165], v[202:205], v[28:31]
	v_mfma_f32_16x16x32_bf16 v[24:27], v[194:197], v[202:205], v[24:27]
	v_mfma_f32_16x16x32_bf16 v[20:23], v[162:165], v[210:213], v[20:23]
	v_mfma_f32_16x16x32_bf16 v[16:19], v[194:197], v[210:213], v[16:19]
	v_mfma_f32_16x16x32_bf16 v[12:15], v[162:165], v[218:221], v[12:15]
	v_mfma_f32_16x16x32_bf16 v[8:11], v[194:197], v[218:221], v[8:11]
	v_mfma_f32_16x16x32_bf16 v[4:7], v[162:165], v[226:229], v[4:7]
	v_mfma_f32_16x16x32_bf16 v[0:3], v[194:197], v[226:229], v[0:3]
	v_mfma_f32_16x16x32_bf16 v[28:31], v[166:169], v[206:209], v[28:31]
	v_mfma_f32_16x16x32_bf16 v[24:27], v[198:201], v[206:209], v[24:27]
	v_mfma_f32_16x16x32_bf16 v[20:23], v[166:169], v[214:217], v[20:23]
	v_mfma_f32_16x16x32_bf16 v[16:19], v[198:201], v[214:217], v[16:19]
	v_mfma_f32_16x16x32_bf16 v[12:15], v[166:169], v[222:225], v[12:15]
	v_mfma_f32_16x16x32_bf16 v[8:11], v[198:201], v[222:225], v[8:11]
	v_mfma_f32_16x16x32_bf16 v[4:7], v[166:169], v[230:233], v[4:7]
	v_mfma_f32_16x16x32_bf16 v[0:3], v[198:201], v[230:233], v[0:3]
	s_setprio 0
	s_barrier
	s_add_i32 s68, 0, 0x18000
	s_add_i32 s69, 0, 0x1c000
	v_add_u32_e32 v140, s68, v173
	v_add_u32_e32 v153, s69, v173
	ds_read_b128 v[128:131], v140
	ds_read_b128 v[132:135], v140 offset:1024
	ds_read_b128 v[136:139], v140 offset:2048
	ds_read_b128 v[140:143], v140 offset:3072
	ds_read_b128 v[162:165], v153
	ds_read_b128 v[166:169], v153 offset:1024
	ds_read_b128 v[194:197], v153 offset:2048
	ds_read_b128 v[198:201], v153 offset:3072
	s_add_u32 s36, s42, 0x8000
	s_addc_u32 s37, s43, 0
	s_mov_b32 m0, s52
	v_lshl_add_u64 v[240:241], s[36:37], 0, v[144:145]
	ds_read_b128 v[202:205], v174 offset:32768
	ds_read_b128 v[206:209], v174 offset:33792
	ds_read_b128 v[210:213], v174 offset:34816
	ds_read_b128 v[214:217], v174 offset:35840
	ds_read_b128 v[218:221], v174 offset:36864
	ds_read_b128 v[222:225], v174 offset:37888
	ds_read_b128 v[226:229], v174 offset:38912
	ds_read_b128 v[230:233], v174 offset:39936
	global_load_lds_dwordx4 v[240:241], off
	v_lshl_add_u64 v[240:241], s[36:37], 0, v[148:149]
	s_mov_b32 m0, s53
	s_nop 0
	global_load_lds_dwordx4 v[240:241], off
	s_waitcnt vmcnt(8)
	s_waitcnt lgkmcnt(0)
	s_barrier
	s_setprio 1
	v_mfma_f32_16x16x32_bf16 v[124:127], v[128:131], v[202:205], v[124:127]
	v_mfma_f32_16x16x32_bf16 v[120:123], v[136:139], v[202:205], v[120:123]
	v_mfma_f32_16x16x32_bf16 v[116:119], v[128:131], v[210:213], v[116:119]
	v_mfma_f32_16x16x32_bf16 v[112:115], v[136:139], v[210:213], v[112:115]
	v_mfma_f32_16x16x32_bf16 v[108:111], v[128:131], v[218:221], v[108:111]
	v_mfma_f32_16x16x32_bf16 v[104:107], v[136:139], v[218:221], v[104:107]
	v_mfma_f32_16x16x32_bf16 v[100:103], v[128:131], v[226:229], v[100:103]
	v_mfma_f32_16x16x32_bf16 v[96:99], v[136:139], v[226:229], v[96:99]
	v_mfma_f32_16x16x32_bf16 v[124:127], v[132:135], v[206:209], v[124:127]
	v_mfma_f32_16x16x32_bf16 v[120:123], v[140:143], v[206:209], v[120:123]
	v_mfma_f32_16x16x32_bf16 v[116:119], v[132:135], v[214:217], v[116:119]
	v_mfma_f32_16x16x32_bf16 v[112:115], v[140:143], v[214:217], v[112:115]
	v_mfma_f32_16x16x32_bf16 v[108:111], v[132:135], v[222:225], v[108:111]
	v_mfma_f32_16x16x32_bf16 v[104:107], v[140:143], v[222:225], v[104:107]
	v_mfma_f32_16x16x32_bf16 v[100:103], v[132:135], v[230:233], v[100:103]
	v_mfma_f32_16x16x32_bf16 v[96:99], v[140:143], v[230:233], v[96:99]
	v_mfma_f32_16x16x32_bf16 v[60:63], v[162:165], v[202:205], v[60:63]
	v_mfma_f32_16x16x32_bf16 v[56:59], v[194:197], v[202:205], v[56:59]
	v_mfma_f32_16x16x32_bf16 v[52:55], v[162:165], v[210:213], v[52:55]
	v_mfma_f32_16x16x32_bf16 v[48:51], v[194:197], v[210:213], v[48:51]
	v_mfma_f32_16x16x32_bf16 v[44:47], v[162:165], v[218:221], v[44:47]
	v_mfma_f32_16x16x32_bf16 v[40:43], v[194:197], v[218:221], v[40:43]
	v_mfma_f32_16x16x32_bf16 v[36:39], v[162:165], v[226:229], v[36:39]
	v_mfma_f32_16x16x32_bf16 v[32:35], v[194:197], v[226:229], v[32:35]
	v_mfma_f32_16x16x32_bf16 v[60:63], v[166:169], v[206:209], v[60:63]
	v_mfma_f32_16x16x32_bf16 v[56:59], v[198:201], v[206:209], v[56:59]
	v_mfma_f32_16x16x32_bf16 v[52:55], v[166:169], v[214:217], v[52:55]
	v_mfma_f32_16x16x32_bf16 v[48:51], v[198:201], v[214:217], v[48:51]
	v_mfma_f32_16x16x32_bf16 v[44:47], v[166:169], v[222:225], v[44:47]
	v_mfma_f32_16x16x32_bf16 v[40:43], v[198:201], v[222:225], v[40:43]
	v_mfma_f32_16x16x32_bf16 v[36:39], v[166:169], v[230:233], v[36:39]
	v_mfma_f32_16x16x32_bf16 v[32:35], v[198:201], v[230:233], v[32:35]
	s_setprio 0
	s_barrier
; #define PG8_STAGE(bufoff, gbase, voff) do { _Pragma("unroll") for (int _i = 0; _i < 2; ++_i) \
;         __builtin_amdgcn_global_load_lds((const unsigned*)((const char*)(gbase) + (voff)[_i]), (PG8_LAS unsigned*)(lds + (bufoff) + ldsw + _i * 8192), 16, 0, 0); } while (0)
; #define PG8_LDA(dst, b, h) do { _Pragma("unroll") for (int m = 0; m < 4; ++m) _Pragma("unroll") for (int k = 0; k < 2; ++k) dst[m][k] = *(const PG8_LAS bf16x8*)(lds + PG8_SA(b, h) + aoff + m * 2048 + k * 1024); } while (0)
; #define PG8_MMA(ai, bj, At, Bt) do { __builtin_amdgcn_s_setprio(1); _Pragma("unroll") for (int m = 0; m < 4; ++m) _Pragma("unroll") for (int n = 0; n < 2; ++n) _Pragma("unroll") for (int k = 0; k < 2; ++k) \
;         acc[ai][bj][m][n] = __builtin_amdgcn_mfma_f32_16x16x32_bf16(Bt[n][k], At[m][k], acc[ai][bj][m][n], 0, 0, 0); __builtin_amdgcn_s_setprio(0); } while (0)
; #define PG8_WAIT_V(n) asm volatile("s_waitcnt vmcnt(" #n ")" ::: "memory")
; #define PG8_WAIT_L(n) asm volatile("s_waitcnt lgkmcnt(" #n ")" ::: "memory")
; #define PG8_BAR __builtin_amdgcn_s_barrier()
; #define PG8_SCHED __builtin_amdgcn_sched_barrier(0)
; template <class Epi, class Sched, bool ALIGN_EPI = false, bool SP2 = false>
; __device__ __forceinline__ void gemm_phase(PG8_LAS unsigned char* lds, const Gemm g, const Sched& S, const Epi& E) {
;     ...
;             PG8_LDA(At, 1, 1); PG8_STAGE(PG8_SB(1, 0), b3, voffB); PG8_STAGE(PG8_SB(1, 1), b3 + hstepB, voffB); PG8_STAGE(PG8_SA(1, 0), a3, voffA);
;             PG8_WAIT_V(8); PG8_WAIT_L(0); PG8_BAR; PG8_MMA(1, 0, At, B0); PG8_MMA(1, 1, At, B1); PG8_BAR; PG8_SCHED;
	s_add_i32 s36, s68, s49
	v_lshl_add_u64 v[170:171], v[170:171], 0, s[18:19]
	s_mov_b32 m0, s36
	ds_read_b128 v[202:205], v174 offset:49152
	ds_read_b128 v[206:209], v174 offset:50176
	ds_read_b128 v[210:213], v174 offset:51200
	ds_read_b128 v[214:217], v174 offset:52224
	ds_read_b128 v[218:221], v174 offset:53248
	ds_read_b128 v[222:225], v174 offset:54272
	ds_read_b128 v[226:229], v174 offset:55296
	ds_read_b128 v[230:233], v174 offset:56320
	global_load_lds_dwordx4 v[170:171], off
	s_add_i32 m0, s36, 0x2000
	s_add_u32 s36, s40, 0x40080
	v_lshl_add_u64 v[170:171], v[234:235], 0, s[18:19]
	s_addc_u32 s37, s41, 0
	s_add_i32 s40, s69, s49
	global_load_lds_dwordx4 v[170:171], off
	v_lshl_add_u64 v[170:171], s[36:37], 0, v[146:147]
	s_mov_b32 m0, s40
	s_nop 0
	global_load_lds_dwordx4 v[170:171], off
	v_lshl_add_u64 v[170:171], s[36:37], 0, v[150:151]
	s_add_i32 m0, s40, 0x2000
	s_nop 0
	global_load_lds_dwordx4 v[170:171], off
	v_lshl_add_u64 v[170:171], v[236:237], 0, s[18:19]
	s_mov_b32 m0, s58
	s_nop 0
	global_load_lds_dwordx4 v[170:171], off
	v_lshl_add_u64 v[170:171], v[238:239], 0, s[18:19]
	s_mov_b32 m0, s59
	s_nop 0
	global_load_lds_dwordx4 v[170:171], off
	s_waitcnt vmcnt(8)
	s_waitcnt lgkmcnt(0)
	s_barrier
	s_setprio 1
	v_mfma_f32_16x16x32_bf16 v[92:95], v[128:131], v[202:205], v[92:95]
	v_mfma_f32_16x16x32_bf16 v[88:91], v[136:139], v[202:205], v[88:91]
	v_mfma_f32_16x16x32_bf16 v[84:87], v[128:131], v[210:213], v[84:87]
	v_mfma_f32_16x16x32_bf16 v[80:83], v[136:139], v[210:213], v[80:83]
	v_mfma_f32_16x16x32_bf16 v[76:79], v[128:131], v[218:221], v[76:79]
	v_mfma_f32_16x16x32_bf16 v[72:75], v[136:139], v[218:221], v[72:75]
	v_mfma_f32_16x16x32_bf16 v[68:71], v[128:131], v[226:229], v[68:71]
	v_mfma_f32_16x16x32_bf16 v[64:67], v[136:139], v[226:229], v[64:67]
	v_mfma_f32_16x16x32_bf16 v[92:95], v[132:135], v[206:209], v[92:95]
	v_mfma_f32_16x16x32_bf16 v[88:91], v[140:143], v[206:209], v[88:91]
	v_mfma_f32_16x16x32_bf16 v[84:87], v[132:135], v[214:217], v[84:87]
	v_mfma_f32_16x16x32_bf16 v[80:83], v[140:143], v[214:217], v[80:83]
	v_mfma_f32_16x16x32_bf16 v[76:79], v[132:135], v[222:225], v[76:79]
	v_mfma_f32_16x16x32_bf16 v[72:75], v[140:143], v[222:225], v[72:75]
	v_mfma_f32_16x16x32_bf16 v[68:71], v[132:135], v[230:233], v[68:71]
	v_mfma_f32_16x16x32_bf16 v[64:67], v[140:143], v[230:233], v[64:67]
	v_mfma_f32_16x16x32_bf16 v[28:31], v[162:165], v[202:205], v[28:31]
	v_mfma_f32_16x16x32_bf16 v[24:27], v[194:197], v[202:205], v[24:27]
	v_mfma_f32_16x16x32_bf16 v[20:23], v[162:165], v[210:213], v[20:23]
	v_mfma_f32_16x16x32_bf16 v[16:19], v[194:197], v[210:213], v[16:19]
	v_mfma_f32_16x16x32_bf16 v[12:15], v[162:165], v[218:221], v[12:15]
	v_mfma_f32_16x16x32_bf16 v[8:11], v[194:197], v[218:221], v[8:11]
	v_mfma_f32_16x16x32_bf16 v[4:7], v[162:165], v[226:229], v[4:7]
	v_mfma_f32_16x16x32_bf16 v[0:3], v[194:197], v[226:229], v[0:3]
	v_mfma_f32_16x16x32_bf16 v[28:31], v[166:169], v[206:209], v[28:31]
	v_mfma_f32_16x16x32_bf16 v[24:27], v[198:201], v[206:209], v[24:27]
	v_mfma_f32_16x16x32_bf16 v[20:23], v[166:169], v[214:217], v[20:23]
	v_mfma_f32_16x16x32_bf16 v[16:19], v[198:201], v[214:217], v[16:19]
	v_mfma_f32_16x16x32_bf16 v[12:15], v[166:169], v[222:225], v[12:15]
	v_mfma_f32_16x16x32_bf16 v[8:11], v[198:201], v[222:225], v[8:11]
	v_mfma_f32_16x16x32_bf16 v[4:7], v[166:169], v[230:233], v[4:7]
	v_mfma_f32_16x16x32_bf16 v[0:3], v[198:201], v[230:233], v[0:3]
	s_setprio 0
	s_barrier
	s_add_i32 s67, s67, 2
	s_add_u32 s65, s65, 0x100
	s_addc_u32 s66, s66, 0
	s_cmp_gt_u32 s67, 13
	s_mov_b64 s[36:37], s[38:39]
	s_cbranch_scc0 .LBB0_1191
	s_and_b64 vcc, exec, s[20:21]
	s_cbranch_vccz .LBB0_1194
	s_barrier

; #define PG8_STAGE(bufoff, gbase, voff) do { _Pragma("unroll") for (int _i = 0; _i < 2; ++_i) \
;         __builtin_amdgcn_global_load_lds((const unsigned*)((const char*)(gbase) + (voff)[_i]), (PG8_LAS unsigned*)(lds + (bufoff) + ldsw + _i * 8192), 16, 0, 0); } while (0)
; #define PG8_LDA(dst, b, h) do { _Pragma("unroll") for (int m = 0; m < 4; ++m) _Pragma("unroll") for (int k = 0; k < 2; ++k) dst[m][k] = *(const PG8_LAS bf16x8*)(lds + PG8_SA(b, h) + aoff + m * 2048 + k * 1024); } while (0)
; #define PG8_LDB(dst, b, h) do { _Pragma("unroll") for (int n = 0; n < 2; ++n) _Pragma("unroll") for (int k = 0; k < 2; ++k) dst[n][k] = *(const PG8_LAS bf16x8*)(lds + PG8_SB(b, h) + boff + n * 2048 + k * 1024); } while (0)
; #define PG8_MMA(ai, bj, At, Bt) do { __builtin_amdgcn_s_setprio(1); _Pragma("unroll") for (int m = 0; m < 4; ++m) _Pragma("unroll") for (int n = 0; n < 2; ++n) _Pragma("unroll") for (int k = 0; k < 2; ++k) \
;         acc[ai][bj][m][n] = __builtin_amdgcn_mfma_f32_16x16x32_bf16(Bt[n][k], At[m][k], acc[ai][bj][m][n], 0, 0, 0); __builtin_amdgcn_s_setprio(0); } while (0)
; #define PG8_WAIT_V(n) asm volatile("s_waitcnt vmcnt(" #n ")" ::: "memory")
; #define PG8_WAIT_L(n) asm volatile("s_waitcnt lgkmcnt(" #n ")" ::: "memory")
; #define PG8_BAR __builtin_amdgcn_s_barrier()
; #define PG8_SCHED __builtin_amdgcn_sched_barrier(0)
; template <class Epi, class Sched, bool ALIGN_EPI = false, bool SP2 = false>
; __device__ __forceinline__ void gemm_phase(PG8_LAS unsigned char* lds, const Gemm g, const Sched& S, const Epi& E) {
;     ...
;             const bool last = (t == nt - 2);
;             const char* a1 = cA + PG8_AK(t + 1);
;             const char* a2 = last ? nA : cA + PG8_AK(t + 2); const char* b2 = last ? nB : cB + (size_t)(t + 2) * kstep;
;             const char* a3 = last ? nA + PG8_AK(1) : cA + PG8_AK(t + 3); const char* b3 = b2 + kstep;
;             if (last && has_next) S.a_ready(nxt);
;             if constexpr (SP2) {
;             PG8_LDB(B0, 0, 0); PG8_LDB(B1, 0, 1); PG8_SCHED; PG8_LDA(At, 0, 0); PG8_STAGE(PG8_SA(1, 1), a1 + hstepA, voffA);
;             PG8_WAIT_V(8); PG8_WAIT_L(0); PG8_BAR; PG8_MMA(0, 0, At, B0); PG8_MMA(0, 1, At, B1); PG8_BAR; PG8_SCHED;
;             PG8_LDA(At, 0, 1); PG8_STAGE(PG8_SB(0, 0), b2, voffB); PG8_STAGE(PG8_SB(0, 1), b2 + hstepB, voffB); PG8_STAGE(PG8_SA(0, 0), a2, voffA);
.LBB0_1275:
	ds_read_b128 v[132:135], v171
	ds_read_b128 v[136:139], v171 offset:1024
	ds_read_b128 v[140:143], v171 offset:2048
	ds_read_b128 v[178:181], v171 offset:3072
	ds_read_b128 v[182:185], v173
	ds_read_b128 v[186:189], v173 offset:1024
	ds_read_b128 v[190:193], v173 offset:2048
	ds_read_b128 v[194:197], v173 offset:3072
	s_add_u32 s38, s34, s36
	s_addc_u32 s39, s35, s37
	s_add_u32 s42, s38, 0x100
	s_addc_u32 s43, s39, 0
	s_add_u32 s40, s66, s36
	s_addc_u32 s41, s67, s37
	s_add_u32 s38, s38, 0x180
	s_addc_u32 s39, s39, 0
	s_cmpk_eq_i32 s36, 0x700
	s_cselect_b32 s39, s65, s39
	s_cselect_b32 s38, s64, s38
	s_cselect_b32 s41, s23, s41
	s_cselect_b32 s40, s63, s40
	s_cselect_b32 s43, s3, s43
	s_cselect_b32 s42, s25, s42
	v_lshl_add_u64 v[230:231], v[130:131], 0, s[36:37]
	s_add_i32 m0, s31, 0xc000
	ds_read_b128 v[198:201], v175
	ds_read_b128 v[202:205], v175 offset:1024
	ds_read_b128 v[206:209], v175 offset:2048
	ds_read_b128 v[210:213], v175 offset:3072
	ds_read_b128 v[214:217], v175 offset:4096
	ds_read_b128 v[218:221], v175 offset:5120
	ds_read_b128 v[222:225], v175 offset:6144
	ds_read_b128 v[226:229], v175 offset:7168
	global_load_lds_dwordx4 v[230:231], off
	v_lshl_add_u64 v[230:231], v[128:129], 0, s[36:37]
	s_add_i32 m0, s31, 0xe000
	s_nop 0
	global_load_lds_dwordx4 v[230:231], off
	s_waitcnt vmcnt(8)
	s_waitcnt lgkmcnt(0)
	s_barrier
	s_setprio 1
	v_mfma_f32_16x16x32_bf16 v[124:127], v[132:135], v[198:201], v[124:127]
	v_mfma_f32_16x16x32_bf16 v[120:123], v[140:143], v[198:201], v[120:123]
	v_mfma_f32_16x16x32_bf16 v[116:119], v[132:135], v[206:209], v[116:119]
	v_mfma_f32_16x16x32_bf16 v[112:115], v[140:143], v[206:209], v[112:115]
	v_mfma_f32_16x16x32_bf16 v[108:111], v[132:135], v[214:217], v[108:111]
	v_mfma_f32_16x16x32_bf16 v[104:107], v[140:143], v[214:217], v[104:107]
	v_mfma_f32_16x16x32_bf16 v[100:103], v[132:135], v[222:225], v[100:103]
	v_mfma_f32_16x16x32_bf16 v[96:99], v[140:143], v[222:225], v[96:99]
	v_mfma_f32_16x16x32_bf16 v[124:127], v[136:139], v[202:205], v[124:127]
	v_mfma_f32_16x16x32_bf16 v[120:123], v[178:181], v[202:205], v[120:123]
	v_mfma_f32_16x16x32_bf16 v[116:119], v[136:139], v[210:213], v[116:119]
	v_mfma_f32_16x16x32_bf16 v[112:115], v[178:181], v[210:213], v[112:115]
	v_mfma_f32_16x16x32_bf16 v[108:111], v[136:139], v[218:221], v[108:111]
	v_mfma_f32_16x16x32_bf16 v[104:107], v[178:181], v[218:221], v[104:107]
	v_mfma_f32_16x16x32_bf16 v[100:103], v[136:139], v[226:229], v[100:103]
	v_mfma_f32_16x16x32_bf16 v[96:99], v[178:181], v[226:229], v[96:99]
	v_mfma_f32_16x16x32_bf16 v[64:67], v[182:185], v[198:201], v[64:67]
	v_mfma_f32_16x16x32_bf16 v[56:59], v[190:193], v[198:201], v[56:59]
	v_mfma_f32_16x16x32_bf16 v[52:55], v[182:185], v[206:209], v[52:55]
	v_mfma_f32_16x16x32_bf16 v[48:51], v[190:193], v[206:209], v[48:51]
	v_mfma_f32_16x16x32_bf16 v[44:47], v[182:185], v[214:217], v[44:47]
	v_mfma_f32_16x16x32_bf16 v[40:43], v[190:193], v[214:217], v[40:43]
	v_mfma_f32_16x16x32_bf16 v[36:39], v[182:185], v[222:225], v[36:39]
	v_mfma_f32_16x16x32_bf16 v[32:35], v[190:193], v[222:225], v[32:35]
	v_mfma_f32_16x16x32_bf16 v[64:67], v[186:189], v[202:205], v[64:67]
	v_mfma_f32_16x16x32_bf16 v[56:59], v[194:197], v[202:205], v[56:59]
	v_mfma_f32_16x16x32_bf16 v[52:55], v[186:189], v[210:213], v[52:55]
	v_mfma_f32_16x16x32_bf16 v[48:51], v[194:197], v[210:213], v[48:51]
	v_mfma_f32_16x16x32_bf16 v[44:47], v[186:189], v[218:221], v[44:47]
	v_mfma_f32_16x16x32_bf16 v[40:43], v[194:197], v[218:221], v[40:43]
	v_mfma_f32_16x16x32_bf16 v[36:39], v[186:189], v[226:229], v[36:39]
	v_mfma_f32_16x16x32_bf16 v[32:35], v[194:197], v[226:229], v[32:35]
	s_setprio 0
	s_barrier
	s_add_i32 s69, s59, s49
	v_lshl_add_u64 v[230:231], s[40:41], 0, v[148:149]
	s_mov_b32 m0, s69
	ds_read_b128 v[198:201], v175 offset:16384
	ds_read_b128 v[202:205], v175 offset:17408
	ds_read_b128 v[206:209], v175 offset:18432
	ds_read_b128 v[210:213], v175 offset:19456
	ds_read_b128 v[214:217], v175 offset:20480
	ds_read_b128 v[218:221], v175 offset:21504
	ds_read_b128 v[222:225], v175 offset:22528
	ds_read_b128 v[226:229], v175 offset:23552
	global_load_lds_dwordx4 v[230:231], off
	s_add_i32 m0, s69, 0x2000
	s_add_u32 s70, s40, 0x40000
	v_lshl_add_u64 v[232:233], s[40:41], 0, v[144:145]
	s_addc_u32 s71, s41, 0
	s_add_i32 s69, s60, s49
	global_load_lds_dwordx4 v[232:233], off
	v_lshl_add_u64 v[234:235], s[70:71], 0, v[148:149]
	s_mov_b32 m0, s69
	s_nop 0
	global_load_lds_dwordx4 v[234:235], off
	v_lshl_add_u64 v[234:235], s[70:71], 0, v[144:145]
	s_add_i32 m0, s69, 0x2000
	s_nop 0
	global_load_lds_dwordx4 v[234:235], off
	v_lshl_add_u64 v[234:235], s[42:43], 0, v[150:151]
	s_mov_b32 m0, s31
	s_nop 0
	global_load_lds_dwordx4 v[234:235], off
	v_lshl_add_u64 v[234:235], s[42:43], 0, v[146:147]
	s_mov_b32 m0, s52
	s_nop 0
	global_load_lds_dwordx4 v[234:235], off
	s_waitcnt vmcnt(8)
	s_waitcnt lgkmcnt(0)
	s_barrier
; #define PG8_STAGE(bufoff, gbase, voff) do { _Pragma("unroll") for (int _i = 0; _i < 2; ++_i) \
;         __builtin_amdgcn_global_load_lds((const unsigned*)((const char*)(gbase) + (voff)[_i]), (PG8_LAS unsigned*)(lds + (bufoff) + ldsw + _i * 8192), 16, 0, 0); } while (0)
; #define PG8_LDA(dst, b, h) do { _Pragma("unroll") for (int m = 0; m < 4; ++m) _Pragma("unroll") for (int k = 0; k < 2; ++k) dst[m][k] = *(const PG8_LAS bf16x8*)(lds + PG8_SA(b, h) + aoff + m * 2048 + k * 1024); } while (0)
; #define PG8_LDB(dst, b, h) do { _Pragma("unroll") for (int n = 0; n < 2; ++n) _Pragma("unroll") for (int k = 0; k < 2; ++k) dst[n][k] = *(const PG8_LAS bf16x8*)(lds + PG8_SB(b, h) + boff + n * 2048 + k * 1024); } while (0)
; #define PG8_MMA(ai, bj, At, Bt) do { __builtin_amdgcn_s_setprio(1); _Pragma("unroll") for (int m = 0; m < 4; ++m) _Pragma("unroll") for (int n = 0; n < 2; ++n) _Pragma("unroll") for (int k = 0; k < 2; ++k) \
;         acc[ai][bj][m][n] = __builtin_amdgcn_mfma_f32_16x16x32_bf16(Bt[n][k], At[m][k], acc[ai][bj][m][n], 0, 0, 0); __builtin_amdgcn_s_setprio(0); } while (0)
; #define PG8_WAIT_V(n) asm volatile("s_waitcnt vmcnt(" #n ")" ::: "memory")
; #define PG8_WAIT_L(n) asm volatile("s_waitcnt lgkmcnt(" #n ")" ::: "memory")
; #define PG8_BAR __builtin_amdgcn_s_barrier()
; #define PG8_SCHED __builtin_amdgcn_sched_barrier(0)
; template <class Epi, class Sched, bool ALIGN_EPI = false, bool SP2 = false>
; __device__ __forceinline__ void gemm_phase(PG8_LAS unsigned char* lds, const Gemm g, const Sched& S, const Epi& E) {
;     ...
;             PG8_WAIT_V(8); PG8_WAIT_L(0); PG8_BAR; PG8_MMA(1, 0, At, B0); PG8_MMA(1, 1, At, B1); PG8_BAR; PG8_SCHED;
;             PG8_LDB(B0, 1, 0); PG8_LDB(B1, 1, 1); PG8_SCHED; PG8_LDA(At, 1, 0); PG8_STAGE(PG8_SA(0, 1), a2 + hstepA, voffA);
;             PG8_WAIT_V(8); PG8_WAIT_L(0); PG8_BAR; PG8_MMA(0, 0, At, B0); PG8_MMA(0, 1, At, B1); PG8_BAR; PG8_SCHED;
	s_setprio 1
	v_mfma_f32_16x16x32_bf16 v[92:95], v[132:135], v[198:201], v[92:95]
	v_mfma_f32_16x16x32_bf16 v[88:91], v[140:143], v[198:201], v[88:91]
	v_mfma_f32_16x16x32_bf16 v[84:87], v[132:135], v[206:209], v[84:87]
	v_mfma_f32_16x16x32_bf16 v[80:83], v[140:143], v[206:209], v[80:83]
	v_mfma_f32_16x16x32_bf16 v[76:79], v[132:135], v[214:217], v[76:79]
	v_mfma_f32_16x16x32_bf16 v[72:75], v[140:143], v[214:217], v[72:75]
	v_mfma_f32_16x16x32_bf16 v[68:71], v[132:135], v[222:225], v[68:71]
	v_mfma_f32_16x16x32_bf16 v[60:63], v[140:143], v[222:225], v[60:63]
	v_mfma_f32_16x16x32_bf16 v[92:95], v[136:139], v[202:205], v[92:95]
	v_mfma_f32_16x16x32_bf16 v[88:91], v[178:181], v[202:205], v[88:91]
	v_mfma_f32_16x16x32_bf16 v[84:87], v[136:139], v[210:213], v[84:87]
	v_mfma_f32_16x16x32_bf16 v[80:83], v[178:181], v[210:213], v[80:83]
	v_mfma_f32_16x16x32_bf16 v[76:79], v[136:139], v[218:221], v[76:79]
	v_mfma_f32_16x16x32_bf16 v[72:75], v[178:181], v[218:221], v[72:75]
	v_mfma_f32_16x16x32_bf16 v[68:71], v[136:139], v[226:229], v[68:71]
	v_mfma_f32_16x16x32_bf16 v[60:63], v[178:181], v[226:229], v[60:63]
	v_mfma_f32_16x16x32_bf16 v[28:31], v[182:185], v[198:201], v[28:31]
	v_mfma_f32_16x16x32_bf16 v[24:27], v[190:193], v[198:201], v[24:27]
	v_mfma_f32_16x16x32_bf16 v[20:23], v[182:185], v[206:209], v[20:23]
	v_mfma_f32_16x16x32_bf16 v[16:19], v[190:193], v[206:209], v[16:19]
	v_mfma_f32_16x16x32_bf16 v[12:15], v[182:185], v[214:217], v[12:15]
	v_mfma_f32_16x16x32_bf16 v[8:11], v[190:193], v[214:217], v[8:11]
	v_mfma_f32_16x16x32_bf16 v[4:7], v[182:185], v[222:225], v[4:7]
	v_mfma_f32_16x16x32_bf16 v[0:3], v[190:193], v[222:225], v[0:3]
	v_mfma_f32_16x16x32_bf16 v[28:31], v[186:189], v[202:205], v[28:31]
	v_mfma_f32_16x16x32_bf16 v[24:27], v[194:197], v[202:205], v[24:27]
	v_mfma_f32_16x16x32_bf16 v[20:23], v[186:189], v[210:213], v[20:23]
	v_mfma_f32_16x16x32_bf16 v[16:19], v[194:197], v[210:213], v[16:19]
	v_mfma_f32_16x16x32_bf16 v[12:15], v[186:189], v[218:221], v[12:15]
	v_mfma_f32_16x16x32_bf16 v[8:11], v[194:197], v[218:221], v[8:11]
	v_mfma_f32_16x16x32_bf16 v[4:7], v[186:189], v[226:229], v[4:7]
	v_mfma_f32_16x16x32_bf16 v[0:3], v[194:197], v[226:229], v[0:3]
	s_setprio 0
	s_barrier
	s_add_i32 s69, 0, 0x18000
	v_add_u32_e32 v160, s69, v163
	s_add_i32 s70, 0, 0x1c000
	ds_read_b128 v[132:135], v160
	ds_read_b128 v[136:139], v160 offset:1024
	ds_read_b128 v[140:143], v160 offset:2048
	ds_read_b128 v[178:181], v160 offset:3072
	v_add_u32_e32 v160, s70, v163
	ds_read_b128 v[182:185], v160
	ds_read_b128 v[186:189], v160 offset:1024
	ds_read_b128 v[190:193], v160 offset:2048
	ds_read_b128 v[194:197], v160 offset:3072
	s_add_u32 s42, s42, 0x40000
	s_addc_u32 s43, s43, 0
	s_mov_b32 m0, s53
	v_lshl_add_u64 v[234:235], s[42:43], 0, v[150:151]
	ds_read_b128 v[198:201], v175 offset:32768
	ds_read_b128 v[202:205], v175 offset:33792
	ds_read_b128 v[206:209], v175 offset:34816
	ds_read_b128 v[210:213], v175 offset:35840
	ds_read_b128 v[214:217], v175 offset:36864
	ds_read_b128 v[218:221], v175 offset:37888
	ds_read_b128 v[222:225], v175 offset:38912
	ds_read_b128 v[226:229], v175 offset:39936
	global_load_lds_dwordx4 v[234:235], off
	v_lshl_add_u64 v[234:235], s[42:43], 0, v[146:147]
	s_mov_b32 m0, s54
	s_nop 0
	global_load_lds_dwordx4 v[234:235], off
	s_waitcnt vmcnt(8)
	s_waitcnt lgkmcnt(0)
	s_barrier
	s_setprio 1
	v_mfma_f32_16x16x32_bf16 v[124:127], v[132:135], v[198:201], v[124:127]
	v_mfma_f32_16x16x32_bf16 v[120:123], v[140:143], v[198:201], v[120:123]
	v_mfma_f32_16x16x32_bf16 v[116:119], v[132:135], v[206:209], v[116:119]
	v_mfma_f32_16x16x32_bf16 v[112:115], v[140:143], v[206:209], v[112:115]
	v_mfma_f32_16x16x32_bf16 v[108:111], v[132:135], v[214:217], v[108:111]
	v_mfma_f32_16x16x32_bf16 v[104:107], v[140:143], v[214:217], v[104:107]
	v_mfma_f32_16x16x32_bf16 v[100:103], v[132:135], v[222:225], v[100:103]
	v_mfma_f32_16x16x32_bf16 v[96:99], v[140:143], v[222:225], v[96:99]
	v_mfma_f32_16x16x32_bf16 v[124:127], v[136:139], v[202:205], v[124:127]
	v_mfma_f32_16x16x32_bf16 v[120:123], v[178:181], v[202:205], v[120:123]
	v_mfma_f32_16x16x32_bf16 v[116:119], v[136:139], v[210:213], v[116:119]
	v_mfma_f32_16x16x32_bf16 v[112:115], v[178:181], v[210:213], v[112:115]
	v_mfma_f32_16x16x32_bf16 v[108:111], v[136:139], v[218:221], v[108:111]
	v_mfma_f32_16x16x32_bf16 v[104:107], v[178:181], v[218:221], v[104:107]
	v_mfma_f32_16x16x32_bf16 v[100:103], v[136:139], v[226:229], v[100:103]
	v_mfma_f32_16x16x32_bf16 v[96:99], v[178:181], v[226:229], v[96:99]
	v_mfma_f32_16x16x32_bf16 v[64:67], v[182:185], v[198:201], v[64:67]
	v_mfma_f32_16x16x32_bf16 v[56:59], v[190:193], v[198:201], v[56:59]
	v_mfma_f32_16x16x32_bf16 v[52:55], v[182:185], v[206:209], v[52:55]
	v_mfma_f32_16x16x32_bf16 v[48:51], v[190:193], v[206:209], v[48:51]
	v_mfma_f32_16x16x32_bf16 v[44:47], v[182:185], v[214:217], v[44:47]
	v_mfma_f32_16x16x32_bf16 v[40:43], v[190:193], v[214:217], v[40:43]
	v_mfma_f32_16x16x32_bf16 v[36:39], v[182:185], v[222:225], v[36:39]
	v_mfma_f32_16x16x32_bf16 v[32:35], v[190:193], v[222:225], v[32:35]
	v_mfma_f32_16x16x32_bf16 v[64:67], v[186:189], v[202:205], v[64:67]
	v_mfma_f32_16x16x32_bf16 v[56:59], v[194:197], v[202:205], v[56:59]
	v_mfma_f32_16x16x32_bf16 v[52:55], v[186:189], v[210:213], v[52:55]
	v_mfma_f32_16x16x32_bf16 v[48:51], v[194:197], v[210:213], v[48:51]
	v_mfma_f32_16x16x32_bf16 v[44:47], v[186:189], v[218:221], v[44:47]
	v_mfma_f32_16x16x32_bf16 v[40:43], v[194:197], v[218:221], v[40:43]
	v_mfma_f32_16x16x32_bf16 v[36:39], v[186:189], v[226:229], v[36:39]
	v_mfma_f32_16x16x32_bf16 v[32:35], v[194:197], v[226:229], v[32:35]
	s_setprio 0
	s_barrier
; #define PG8_STAGE(bufoff, gbase, voff) do { _Pragma("unroll") for (int _i = 0; _i < 2; ++_i) \
;         __builtin_amdgcn_global_load_lds((const unsigned*)((const char*)(gbase) + (voff)[_i]), (PG8_LAS unsigned*)(lds + (bufoff) + ldsw + _i * 8192), 16, 0, 0); } while (0)
; #define PG8_LDA(dst, b, h) do { _Pragma("unroll") for (int m = 0; m < 4; ++m) _Pragma("unroll") for (int k = 0; k < 2; ++k) dst[m][k] = *(const PG8_LAS bf16x8*)(lds + PG8_SA(b, h) + aoff + m * 2048 + k * 1024); } while (0)
; #define PG8_MMA(ai, bj, At, Bt) do { __builtin_amdgcn_s_setprio(1); _Pragma("unroll") for (int m = 0; m < 4; ++m) _Pragma("unroll") for (int n = 0; n < 2; ++n) _Pragma("unroll") for (int k = 0; k < 2; ++k) \
;         acc[ai][bj][m][n] = __builtin_amdgcn_mfma_f32_16x16x32_bf16(Bt[n][k], At[m][k], acc[ai][bj][m][n], 0, 0, 0); __builtin_amdgcn_s_setprio(0); } while (0)
; #define PG8_WAIT_V(n) asm volatile("s_waitcnt vmcnt(" #n ")" ::: "memory")
; #define PG8_WAIT_L(n) asm volatile("s_waitcnt lgkmcnt(" #n ")" ::: "memory")
; #define PG8_BAR __builtin_amdgcn_s_barrier()
; #define PG8_SCHED __builtin_amdgcn_sched_barrier(0)
; template <class Epi, class Sched, bool ALIGN_EPI = false, bool SP2 = false>
; __device__ __forceinline__ void gemm_phase(PG8_LAS unsigned char* lds, const Gemm g, const Sched& S, const Epi& E) {
;     ...
;         for (int t = 0; t < nt; t += 2) {
;             const bool last = (t == nt - 2);
;     ...
;             PG8_LDA(At, 1, 1); PG8_STAGE(PG8_SB(1, 0), b3, voffB); PG8_STAGE(PG8_SB(1, 1), b3 + hstepB, voffB); PG8_STAGE(PG8_SA(1, 0), a3, voffA);
;             PG8_WAIT_V(8); PG8_WAIT_L(0); PG8_BAR; PG8_MMA(1, 0, At, B0); PG8_MMA(1, 1, At, B1); PG8_BAR; PG8_SCHED;
	s_add_i32 s42, s69, s49
	v_lshl_add_u64 v[230:231], v[230:231], 0, s[16:17]
	s_mov_b32 m0, s42
	ds_read_b128 v[198:201], v175 offset:49152
	ds_read_b128 v[202:205], v175 offset:50176
	ds_read_b128 v[206:209], v175 offset:51200
	ds_read_b128 v[210:213], v175 offset:52224
	ds_read_b128 v[214:217], v175 offset:53248
	ds_read_b128 v[218:221], v175 offset:54272
	ds_read_b128 v[222:225], v175 offset:55296
	ds_read_b128 v[226:229], v175 offset:56320
	global_load_lds_dwordx4 v[230:231], off
	s_add_i32 m0, s42, 0x2000
	s_add_u32 s40, s40, 0x40080
	v_lshl_add_u64 v[230:231], v[232:233], 0, s[16:17]
	s_addc_u32 s41, s41, 0
	s_add_i32 s42, s70, s49
	global_load_lds_dwordx4 v[230:231], off
	v_lshl_add_u64 v[230:231], s[40:41], 0, v[148:149]
	s_mov_b32 m0, s42
	s_nop 0
	global_load_lds_dwordx4 v[230:231], off
	v_lshl_add_u64 v[230:231], s[40:41], 0, v[144:145]
	s_add_i32 m0, s42, 0x2000
	s_nop 0
	global_load_lds_dwordx4 v[230:231], off
	v_lshl_add_u64 v[230:231], s[38:39], 0, v[150:151]
	s_mov_b32 m0, s56
	s_nop 0
	global_load_lds_dwordx4 v[230:231], off
	v_lshl_add_u64 v[230:231], s[38:39], 0, v[146:147]
	s_mov_b32 m0, s57
	s_nop 0
	global_load_lds_dwordx4 v[230:231], off
	s_waitcnt vmcnt(8)
	s_waitcnt lgkmcnt(0)
	s_barrier
	s_setprio 1
	v_mfma_f32_16x16x32_bf16 v[92:95], v[132:135], v[198:201], v[92:95]
	v_mfma_f32_16x16x32_bf16 v[88:91], v[140:143], v[198:201], v[88:91]
	v_mfma_f32_16x16x32_bf16 v[84:87], v[132:135], v[206:209], v[84:87]
	v_mfma_f32_16x16x32_bf16 v[80:83], v[140:143], v[206:209], v[80:83]
	v_mfma_f32_16x16x32_bf16 v[76:79], v[132:135], v[214:217], v[76:79]
	v_mfma_f32_16x16x32_bf16 v[72:75], v[140:143], v[214:217], v[72:75]
	v_mfma_f32_16x16x32_bf16 v[68:71], v[132:135], v[222:225], v[68:71]
	v_mfma_f32_16x16x32_bf16 v[60:63], v[140:143], v[222:225], v[60:63]
	v_mfma_f32_16x16x32_bf16 v[92:95], v[136:139], v[202:205], v[92:95]
	v_mfma_f32_16x16x32_bf16 v[88:91], v[178:181], v[202:205], v[88:91]
	v_mfma_f32_16x16x32_bf16 v[84:87], v[136:139], v[210:213], v[84:87]
	v_mfma_f32_16x16x32_bf16 v[80:83], v[178:181], v[210:213], v[80:83]
	v_mfma_f32_16x16x32_bf16 v[76:79], v[136:139], v[218:221], v[76:79]
	v_mfma_f32_16x16x32_bf16 v[72:75], v[178:181], v[218:221], v[72:75]
	v_mfma_f32_16x16x32_bf16 v[68:71], v[136:139], v[226:229], v[68:71]
	v_mfma_f32_16x16x32_bf16 v[60:63], v[178:181], v[226:229], v[60:63]
	v_mfma_f32_16x16x32_bf16 v[28:31], v[182:185], v[198:201], v[28:31]
	v_mfma_f32_16x16x32_bf16 v[24:27], v[190:193], v[198:201], v[24:27]
	v_mfma_f32_16x16x32_bf16 v[20:23], v[182:185], v[206:209], v[20:23]
	v_mfma_f32_16x16x32_bf16 v[16:19], v[190:193], v[206:209], v[16:19]
	v_mfma_f32_16x16x32_bf16 v[12:15], v[182:185], v[214:217], v[12:15]
	v_mfma_f32_16x16x32_bf16 v[8:11], v[190:193], v[214:217], v[8:11]
	v_mfma_f32_16x16x32_bf16 v[4:7], v[182:185], v[222:225], v[4:7]
	v_mfma_f32_16x16x32_bf16 v[0:3], v[190:193], v[222:225], v[0:3]
	v_mfma_f32_16x16x32_bf16 v[28:31], v[186:189], v[202:205], v[28:31]
	v_mfma_f32_16x16x32_bf16 v[24:27], v[194:197], v[202:205], v[24:27]
	v_mfma_f32_16x16x32_bf16 v[20:23], v[186:189], v[210:213], v[20:23]
	v_mfma_f32_16x16x32_bf16 v[16:19], v[194:197], v[210:213], v[16:19]
	v_mfma_f32_16x16x32_bf16 v[12:15], v[186:189], v[218:221], v[12:15]
	v_mfma_f32_16x16x32_bf16 v[8:11], v[194:197], v[218:221], v[8:11]
	v_mfma_f32_16x16x32_bf16 v[4:7], v[186:189], v[226:229], v[4:7]
	v_mfma_f32_16x16x32_bf16 v[0:3], v[194:197], v[226:229], v[0:3]
	s_setprio 0
	s_barrier
	s_add_i32 s68, s68, 2
	s_add_u32 s36, s36, 0x100
	s_addc_u32 s37, s37, 0
	s_cmp_gt_u32 s68, 13
	s_cbranch_scc0 .LBB0_1275
	s_and_b64 vcc, exec, s[18:19]
	s_cbranch_vccz .LBB0_1278
	s_barrier

; #define PG8_STAGE(bufoff, gbase, voff) do { _Pragma("unroll") for (int _i = 0; _i < 2; ++_i) \
;         __builtin_amdgcn_global_load_lds((const unsigned*)((const char*)(gbase) + (voff)[_i]), (PG8_LAS unsigned*)(lds + (bufoff) + ldsw + _i * 8192), 16, 0, 0); } while (0)
; #define PG8_LDA(dst, b, h) do { _Pragma("unroll") for (int m = 0; m < 4; ++m) _Pragma("unroll") for (int k = 0; k < 2; ++k) dst[m][k] = *(const PG8_LAS bf16x8*)(lds + PG8_SA(b, h) + aoff + m * 2048 + k * 1024); } while (0)
; #define PG8_LDB(dst, b, h) do { _Pragma("unroll") for (int n = 0; n < 2; ++n) _Pragma("unroll") for (int k = 0; k < 2; ++k) dst[n][k] = *(const PG8_LAS bf16x8*)(lds + PG8_SB(b, h) + boff + n * 2048 + k * 1024); } while (0)
; #define PG8_WAIT_V(n) asm volatile("s_waitcnt vmcnt(" #n ")" ::: "memory")
; #define PG8_WAIT_L(n) asm volatile("s_waitcnt lgkmcnt(" #n ")" ::: "memory")
; #define PG8_BAR __builtin_amdgcn_s_barrier()
; #define PG8_SCHED __builtin_amdgcn_sched_barrier(0)
; template <class Epi, class Sched, bool ALIGN_EPI = false, bool SP2 = false>
; __device__ __forceinline__ void gemm_phase(PG8_LAS unsigned char* lds, const Gemm g, const Sched& S, const Epi& E) {
;     ...
;         const bool has_next = S.next(ui + 1, nxt);
;         const char* nA = has_next ? (const char*)g.A + (size_t)nxt.pm * tstepA : cA; const char* nB = has_next ? (const char*)g.Bt + (size_t)nxt.pn * tstepB : cB;
;         for (int t = 0; t < nt; t += 2) {
;             const bool last = (t == nt - 2);
;             const char* a1 = cA + PG8_AK(t + 1);
;             const char* a2 = last ? nA : cA + PG8_AK(t + 2); const char* b2 = last ? nB : cB + (size_t)(t + 2) * kstep;
;             const char* a3 = last ? nA + PG8_AK(1) : cA + PG8_AK(t + 3); const char* b3 = b2 + kstep;
;             if (last && has_next) S.a_ready(nxt);
;             if constexpr (SP2) {
;             PG8_LDB(B0, 0, 0); PG8_LDB(B1, 0, 1); PG8_SCHED; PG8_LDA(At, 0, 0); PG8_STAGE(PG8_SA(1, 1), a1 + hstepA, voffA);
;             PG8_WAIT_V(8); PG8_WAIT_L(0); PG8_BAR; PG8_MMA(0, 0, At, B0); PG8_MMA(0, 1, At, B1); PG8_BAR; PG8_SCHED;
;             PG8_LDA(At, 0, 1); PG8_STAGE(PG8_SB(0, 0), b2, voffB); PG8_STAGE(PG8_SB(0, 1), b2 + hstepB, voffB); PG8_STAGE(PG8_SA(0, 0), a2, voffA);
;             PG8_WAIT_V(8); PG8_WAIT_L(0); PG8_BAR; PG8_MMA(1, 0, At, B0); PG8_MMA(1, 1, At, B1); PG8_BAR; PG8_SCHED;
.LBB0_1298:
	ds_read_b128 v[0:3], v145
	ds_read_b128 v[4:7], v145 offset:1024
	ds_read_b128 v[8:11], v145 offset:2048
	ds_read_b128 v[12:15], v145 offset:3072
	ds_read_b128 v[16:19], v146
	ds_read_b128 v[20:23], v146 offset:1024
	ds_read_b128 v[24:27], v146 offset:2048
	ds_read_b128 v[28:31], v146 offset:3072
	s_ashr_i32 s31, s30, 31
	s_lshl_b64 s[34:35], s[30:31], 17
	s_add_u32 s34, s49, s34
	s_addc_u32 s35, s50, s35
	s_and_b64 s[36:37], s[4:5], exec
	s_cselect_b32 s47, s35, s41
	s_cselect_b32 s46, s34, s40
	s_ashr_i32 s29, s28, 31
	s_lshl_b64 s[36:37], s[28:29], 17
	s_add_u32 s36, s51, s36
	s_addc_u32 s37, s52, s37
	s_and_b64 s[44:45], s[4:5], exec
	s_cselect_b32 s45, s37, s43
	s_cselect_b32 s44, s36, s42
	s_add_u32 s66, s40, 0x10080
	s_addc_u32 s67, s41, 0
	s_add_i32 s78, s3, 0xc000
	v_lshl_add_u64 v[64:65], s[66:67], 0, v[128:129]
	s_mov_b32 m0, s78
	s_add_i32 s29, s3, 0xe000
	ds_read_b128 v[32:35], v147
	ds_read_b128 v[36:39], v147 offset:1024
	ds_read_b128 v[40:43], v147 offset:2048
	ds_read_b128 v[44:47], v147 offset:3072
	ds_read_b128 v[48:51], v147 offset:4096
	ds_read_b128 v[52:55], v147 offset:5120
	ds_read_b128 v[56:59], v147 offset:6144
	ds_read_b128 v[60:63], v147 offset:7168
	global_load_lds_dwordx4 v[64:65], off
	v_lshl_add_u64 v[64:65], s[66:67], 0, v[132:133]
	s_mov_b32 m0, s29
	s_nop 0
	global_load_lds_dwordx4 v[64:65], off
	s_waitcnt vmcnt(8)
	s_waitcnt lgkmcnt(0)
	s_barrier
	s_setprio 1
	v_mfma_f32_16x16x32_bf16 v[64:67], v[0:3], v[32:35], 0
	v_mfma_f32_16x16x32_bf16 v[68:71], v[8:11], v[32:35], 0
	v_mfma_f32_16x16x32_bf16 v[72:75], v[0:3], v[40:43], 0
	v_mfma_f32_16x16x32_bf16 v[76:79], v[8:11], v[40:43], 0
	v_mfma_f32_16x16x32_bf16 v[80:83], v[0:3], v[48:51], 0
	v_mfma_f32_16x16x32_bf16 v[84:87], v[8:11], v[48:51], 0
	v_mfma_f32_16x16x32_bf16 v[88:91], v[0:3], v[56:59], 0
	v_mfma_f32_16x16x32_bf16 v[92:95], v[8:11], v[56:59], 0
	v_mfma_f32_16x16x32_bf16 v[64:67], v[4:7], v[36:39], v[64:67]
	v_mfma_f32_16x16x32_bf16 v[68:71], v[12:15], v[36:39], v[68:71]
	v_mfma_f32_16x16x32_bf16 v[72:75], v[4:7], v[44:47], v[72:75]
	v_mfma_f32_16x16x32_bf16 v[76:79], v[12:15], v[44:47], v[76:79]
	v_mfma_f32_16x16x32_bf16 v[80:83], v[4:7], v[52:55], v[80:83]
	v_mfma_f32_16x16x32_bf16 v[84:87], v[12:15], v[52:55], v[84:87]
	v_mfma_f32_16x16x32_bf16 v[88:91], v[4:7], v[60:63], v[88:91]
	v_mfma_f32_16x16x32_bf16 v[92:95], v[12:15], v[60:63], v[92:95]
	v_mfma_f32_16x16x32_bf16 v[96:99], v[16:19], v[32:35], 0
	v_mfma_f32_16x16x32_bf16 v[32:35], v[24:27], v[32:35], 0
	v_mfma_f32_16x16x32_bf16 v[96:99], v[20:23], v[36:39], v[96:99]
	v_mfma_f32_16x16x32_bf16 v[32:35], v[28:31], v[36:39], v[32:35]
	v_mfma_f32_16x16x32_bf16 v[36:39], v[16:19], v[40:43], 0
	v_mfma_f32_16x16x32_bf16 v[40:43], v[24:27], v[40:43], 0
	v_mfma_f32_16x16x32_bf16 v[36:39], v[20:23], v[44:47], v[36:39]
	v_mfma_f32_16x16x32_bf16 v[40:43], v[28:31], v[44:47], v[40:43]
	v_mfma_f32_16x16x32_bf16 v[44:47], v[16:19], v[48:51], 0
	v_mfma_f32_16x16x32_bf16 v[48:51], v[24:27], v[48:51], 0
	v_mfma_f32_16x16x32_bf16 v[44:47], v[20:23], v[52:55], v[44:47]
	v_mfma_f32_16x16x32_bf16 v[48:51], v[28:31], v[52:55], v[48:51]
	v_mfma_f32_16x16x32_bf16 v[52:55], v[16:19], v[56:59], 0
	v_mfma_f32_16x16x32_bf16 v[56:59], v[24:27], v[56:59], 0
	v_mfma_f32_16x16x32_bf16 v[52:55], v[20:23], v[60:63], v[52:55]
	v_mfma_f32_16x16x32_bf16 v[56:59], v[28:31], v[60:63], v[56:59]
	s_setprio 0
	s_barrier
	s_add_i32 s68, s59, s53
	v_lshl_add_u64 v[140:141], s[42:43], 0, v[130:131]
	s_add_i32 s31, s68, 0x2000
	v_lshl_add_u64 v[148:149], v[140:141], 0, s[16:17]
	s_mov_b32 m0, s68
	v_lshl_add_u64 v[212:213], s[42:43], 0, v[134:135]
	s_add_u32 s70, s42, 0x10100
	ds_read_b128 v[60:63], v147 offset:16384
	ds_read_b128 v[100:103], v147 offset:17408
	ds_read_b128 v[104:107], v147 offset:18432
	ds_read_b128 v[108:111], v147 offset:19456
	ds_read_b128 v[112:115], v147 offset:20480
	ds_read_b128 v[116:119], v147 offset:21504
	ds_read_b128 v[120:123], v147 offset:22528
	ds_read_b128 v[124:127], v147 offset:23552
	global_load_lds_dwordx4 v[148:149], off
	v_lshl_add_u64 v[148:149], v[212:213], 0, s[16:17]
	s_mov_b32 m0, s31
	s_addc_u32 s71, s43, 0
	s_add_i32 s66, s60, s53
	global_load_lds_dwordx4 v[148:149], off
	v_lshl_add_u64 v[148:149], s[70:71], 0, v[130:131]
	s_mov_b32 m0, s66
	s_add_i32 s67, s66, 0x2000
	global_load_lds_dwordx4 v[148:149], off
	v_lshl_add_u64 v[148:149], s[70:71], 0, v[134:135]
	s_mov_b32 m0, s67
	v_lshl_add_u64 v[214:215], s[40:41], 0, v[128:129]
	global_load_lds_dwordx4 v[148:149], off
	v_lshl_add_u64 v[148:149], v[214:215], 0, s[16:17]
	s_mov_b32 m0, s3
	v_lshl_add_u64 v[216:217], s[40:41], 0, v[132:133]
	global_load_lds_dwordx4 v[148:149], off
	v_lshl_add_u64 v[148:149], v[216:217], 0, s[16:17]
	s_mov_b32 m0, s39
	s_nop 0
	global_load_lds_dwordx4 v[148:149], off
	s_waitcnt vmcnt(8)
	s_waitcnt lgkmcnt(0)
	s_barrier
; #define PG8_STAGE(bufoff, gbase, voff) do { _Pragma("unroll") for (int _i = 0; _i < 2; ++_i) \
;         __builtin_amdgcn_global_load_lds((const unsigned*)((const char*)(gbase) + (voff)[_i]), (PG8_LAS unsigned*)(lds + (bufoff) + ldsw + _i * 8192), 16, 0, 0); } while (0)
; #define PG8_LDA(dst, b, h) do { _Pragma("unroll") for (int m = 0; m < 4; ++m) _Pragma("unroll") for (int k = 0; k < 2; ++k) dst[m][k] = *(const PG8_LAS bf16x8*)(lds + PG8_SA(b, h) + aoff + m * 2048 + k * 1024); } while (0)
; #define PG8_LDB(dst, b, h) do { _Pragma("unroll") for (int n = 0; n < 2; ++n) _Pragma("unroll") for (int k = 0; k < 2; ++k) dst[n][k] = *(const PG8_LAS bf16x8*)(lds + PG8_SB(b, h) + boff + n * 2048 + k * 1024); } while (0)
; #define PG8_MMA(ai, bj, At, Bt) do { __builtin_amdgcn_s_setprio(1); _Pragma("unroll") for (int m = 0; m < 4; ++m) _Pragma("unroll") for (int n = 0; n < 2; ++n) _Pragma("unroll") for (int k = 0; k < 2; ++k) \
;         acc[ai][bj][m][n] = __builtin_amdgcn_mfma_f32_16x16x32_bf16(Bt[n][k], At[m][k], acc[ai][bj][m][n], 0, 0, 0); __builtin_amdgcn_s_setprio(0); } while (0)
; #define PG8_WAIT_V(n) asm volatile("s_waitcnt vmcnt(" #n ")" ::: "memory")
; #define PG8_WAIT_L(n) asm volatile("s_waitcnt lgkmcnt(" #n ")" ::: "memory")
; #define PG8_BAR __builtin_amdgcn_s_barrier()
; #define PG8_SCHED __builtin_amdgcn_sched_barrier(0)
; template <class Epi, class Sched, bool ALIGN_EPI = false, bool SP2 = false>
; __device__ __forceinline__ void gemm_phase(PG8_LAS unsigned char* lds, const Gemm g, const Sched& S, const Epi& E) {
;     ...
;             PG8_WAIT_V(8); PG8_WAIT_L(0); PG8_BAR; PG8_MMA(1, 0, At, B0); PG8_MMA(1, 1, At, B1); PG8_BAR; PG8_SCHED;
;             PG8_LDB(B0, 1, 0); PG8_LDB(B1, 1, 1); PG8_SCHED; PG8_LDA(At, 1, 0); PG8_STAGE(PG8_SA(0, 1), a2 + hstepA, voffA);
;             PG8_WAIT_V(8); PG8_WAIT_L(0); PG8_BAR; PG8_MMA(0, 0, At, B0); PG8_MMA(0, 1, At, B1); PG8_BAR; PG8_SCHED;
	s_setprio 1
	v_mfma_f32_16x16x32_bf16 v[148:151], v[0:3], v[60:63], 0
	v_mfma_f32_16x16x32_bf16 v[156:159], v[0:3], v[104:107], 0
	v_mfma_f32_16x16x32_bf16 v[164:167], v[0:3], v[112:115], 0
	v_mfma_f32_16x16x32_bf16 v[0:3], v[0:3], v[120:123], 0
	v_mfma_f32_16x16x32_bf16 v[148:151], v[4:7], v[100:103], v[148:151]
	v_mfma_f32_16x16x32_bf16 v[156:159], v[4:7], v[108:111], v[156:159]
	v_mfma_f32_16x16x32_bf16 v[164:167], v[4:7], v[116:119], v[164:167]
	v_mfma_f32_16x16x32_bf16 v[0:3], v[4:7], v[124:127], v[0:3]
	v_mfma_f32_16x16x32_bf16 v[4:7], v[8:11], v[120:123], 0
	v_mfma_f32_16x16x32_bf16 v[152:155], v[8:11], v[60:63], 0
	v_mfma_f32_16x16x32_bf16 v[160:163], v[8:11], v[104:107], 0
	v_mfma_f32_16x16x32_bf16 v[168:171], v[8:11], v[112:115], 0
	v_mfma_f32_16x16x32_bf16 v[4:7], v[12:15], v[124:127], v[4:7]
	v_mfma_f32_16x16x32_bf16 v[152:155], v[12:15], v[100:103], v[152:155]
	v_mfma_f32_16x16x32_bf16 v[160:163], v[12:15], v[108:111], v[160:163]
	v_mfma_f32_16x16x32_bf16 v[168:171], v[12:15], v[116:119], v[168:171]
	v_mfma_f32_16x16x32_bf16 v[8:11], v[16:19], v[60:63], 0
	v_mfma_f32_16x16x32_bf16 v[12:15], v[24:27], v[60:63], 0
	v_mfma_f32_16x16x32_bf16 v[8:11], v[20:23], v[100:103], v[8:11]
	v_mfma_f32_16x16x32_bf16 v[12:15], v[28:31], v[100:103], v[12:15]
	v_mfma_f32_16x16x32_bf16 v[60:63], v[16:19], v[104:107], 0
	v_mfma_f32_16x16x32_bf16 v[100:103], v[24:27], v[104:107], 0
	v_mfma_f32_16x16x32_bf16 v[104:107], v[16:19], v[112:115], 0
	v_mfma_f32_16x16x32_bf16 v[16:19], v[16:19], v[120:123], 0
	v_mfma_f32_16x16x32_bf16 v[60:63], v[20:23], v[108:111], v[60:63]
	v_mfma_f32_16x16x32_bf16 v[100:103], v[28:31], v[108:111], v[100:103]
	v_mfma_f32_16x16x32_bf16 v[104:107], v[20:23], v[116:119], v[104:107]
	v_mfma_f32_16x16x32_bf16 v[108:111], v[24:27], v[112:115], 0
	v_mfma_f32_16x16x32_bf16 v[16:19], v[20:23], v[124:127], v[16:19]
	v_mfma_f32_16x16x32_bf16 v[20:23], v[24:27], v[120:123], 0
	v_mfma_f32_16x16x32_bf16 v[108:111], v[28:31], v[116:119], v[108:111]
	v_mfma_f32_16x16x32_bf16 v[20:23], v[28:31], v[124:127], v[20:23]
	s_setprio 0
	s_barrier
	s_add_i32 s79, 0, 0x18000
	s_add_i32 s80, 0, 0x1c000
	v_add_u32_e32 v224, s79, v143
	v_add_u32_e32 v232, s80, v143
	ds_read_b128 v[24:27], v224
	ds_read_b128 v[28:31], v224 offset:1024
	ds_read_b128 v[112:115], v224 offset:2048
	ds_read_b128 v[116:119], v224 offset:3072
	ds_read_b128 v[120:123], v232
	ds_read_b128 v[124:127], v232 offset:1024
	ds_read_b128 v[172:175], v232 offset:2048
	ds_read_b128 v[176:179], v232 offset:3072
	s_add_u32 s70, s40, 0x10100
	s_addc_u32 s71, s41, 0
	s_mov_b32 m0, s54
	v_lshl_add_u64 v[218:219], s[70:71], 0, v[128:129]
	ds_read_b128 v[180:183], v147 offset:32768
	ds_read_b128 v[184:187], v147 offset:33792
	ds_read_b128 v[188:191], v147 offset:34816
	ds_read_b128 v[192:195], v147 offset:35840
	ds_read_b128 v[196:199], v147 offset:36864
	ds_read_b128 v[200:203], v147 offset:37888
	ds_read_b128 v[204:207], v147 offset:38912
	ds_read_b128 v[208:211], v147 offset:39936
	global_load_lds_dwordx4 v[218:219], off
	v_lshl_add_u64 v[218:219], s[70:71], 0, v[132:133]
	s_mov_b32 m0, s55
	s_nop 0
	global_load_lds_dwordx4 v[218:219], off
	s_waitcnt vmcnt(8)
	s_waitcnt lgkmcnt(0)
	s_barrier
	s_setprio 1
	v_mfma_f32_16x16x32_bf16 v[64:67], v[24:27], v[180:183], v[64:67]
	v_mfma_f32_16x16x32_bf16 v[68:71], v[112:115], v[180:183], v[68:71]
	v_mfma_f32_16x16x32_bf16 v[72:75], v[24:27], v[188:191], v[72:75]
	v_mfma_f32_16x16x32_bf16 v[76:79], v[112:115], v[188:191], v[76:79]
	v_mfma_f32_16x16x32_bf16 v[80:83], v[24:27], v[196:199], v[80:83]
	v_mfma_f32_16x16x32_bf16 v[84:87], v[112:115], v[196:199], v[84:87]
	v_mfma_f32_16x16x32_bf16 v[88:91], v[24:27], v[204:207], v[88:91]
	v_mfma_f32_16x16x32_bf16 v[92:95], v[112:115], v[204:207], v[92:95]
	v_mfma_f32_16x16x32_bf16 v[64:67], v[28:31], v[184:187], v[64:67]
	v_mfma_f32_16x16x32_bf16 v[68:71], v[116:119], v[184:187], v[68:71]
	v_mfma_f32_16x16x32_bf16 v[72:75], v[28:31], v[192:195], v[72:75]
	v_mfma_f32_16x16x32_bf16 v[76:79], v[116:119], v[192:195], v[76:79]
	v_mfma_f32_16x16x32_bf16 v[80:83], v[28:31], v[200:203], v[80:83]
	v_mfma_f32_16x16x32_bf16 v[84:87], v[116:119], v[200:203], v[84:87]
	v_mfma_f32_16x16x32_bf16 v[88:91], v[28:31], v[208:211], v[88:91]
	v_mfma_f32_16x16x32_bf16 v[92:95], v[116:119], v[208:211], v[92:95]
	v_mfma_f32_16x16x32_bf16 v[96:99], v[120:123], v[180:183], v[96:99]
	v_mfma_f32_16x16x32_bf16 v[32:35], v[172:175], v[180:183], v[32:35]
	v_mfma_f32_16x16x32_bf16 v[36:39], v[120:123], v[188:191], v[36:39]
	v_mfma_f32_16x16x32_bf16 v[40:43], v[172:175], v[188:191], v[40:43]
	v_mfma_f32_16x16x32_bf16 v[44:47], v[120:123], v[196:199], v[44:47]
	v_mfma_f32_16x16x32_bf16 v[48:51], v[172:175], v[196:199], v[48:51]
	v_mfma_f32_16x16x32_bf16 v[52:55], v[120:123], v[204:207], v[52:55]
	v_mfma_f32_16x16x32_bf16 v[56:59], v[172:175], v[204:207], v[56:59]
	v_mfma_f32_16x16x32_bf16 v[96:99], v[124:127], v[184:187], v[96:99]
	v_mfma_f32_16x16x32_bf16 v[32:35], v[176:179], v[184:187], v[32:35]
	v_mfma_f32_16x16x32_bf16 v[36:39], v[124:127], v[192:195], v[36:39]
	v_mfma_f32_16x16x32_bf16 v[40:43], v[176:179], v[192:195], v[40:43]
	v_mfma_f32_16x16x32_bf16 v[44:47], v[124:127], v[200:203], v[44:47]
	v_mfma_f32_16x16x32_bf16 v[48:51], v[176:179], v[200:203], v[48:51]
	v_mfma_f32_16x16x32_bf16 v[52:55], v[124:127], v[208:211], v[52:55]
	v_mfma_f32_16x16x32_bf16 v[56:59], v[176:179], v[208:211], v[56:59]
	s_setprio 0
	s_barrier
; #define PG8_STAGE(bufoff, gbase, voff) do { _Pragma("unroll") for (int _i = 0; _i < 2; ++_i) \
;         __builtin_amdgcn_global_load_lds((const unsigned*)((const char*)(gbase) + (voff)[_i]), (PG8_LAS unsigned*)(lds + (bufoff) + ldsw + _i * 8192), 16, 0, 0); } while (0)
; #define PG8_LDA(dst, b, h) do { _Pragma("unroll") for (int m = 0; m < 4; ++m) _Pragma("unroll") for (int k = 0; k < 2; ++k) dst[m][k] = *(const PG8_LAS bf16x8*)(lds + PG8_SA(b, h) + aoff + m * 2048 + k * 1024); } while (0)
; #define PG8_LDB(dst, b, h) do { _Pragma("unroll") for (int n = 0; n < 2; ++n) _Pragma("unroll") for (int k = 0; k < 2; ++k) dst[n][k] = *(const PG8_LAS bf16x8*)(lds + PG8_SB(b, h) + boff + n * 2048 + k * 1024); } while (0)
; #define PG8_MMA(ai, bj, At, Bt) do { __builtin_amdgcn_s_setprio(1); _Pragma("unroll") for (int m = 0; m < 4; ++m) _Pragma("unroll") for (int n = 0; n < 2; ++n) _Pragma("unroll") for (int k = 0; k < 2; ++k) \
;         acc[ai][bj][m][n] = __builtin_amdgcn_mfma_f32_16x16x32_bf16(Bt[n][k], At[m][k], acc[ai][bj][m][n], 0, 0, 0); __builtin_amdgcn_s_setprio(0); } while (0)
; #define PG8_WAIT_V(n) asm volatile("s_waitcnt vmcnt(" #n ")" ::: "memory")
; #define PG8_WAIT_L(n) asm volatile("s_waitcnt lgkmcnt(" #n ")" ::: "memory")
; #define PG8_BAR __builtin_amdgcn_s_barrier()
; #define PG8_SCHED __builtin_amdgcn_sched_barrier(0)
; template <class Epi, class Sched, bool ALIGN_EPI = false, bool SP2 = false>
; __device__ __forceinline__ void gemm_phase(PG8_LAS unsigned char* lds, const Gemm g, const Sched& S, const Epi& E) {
;     ...
;             PG8_LDB(B0, 0, 0); PG8_LDB(B1, 0, 1); PG8_SCHED; PG8_LDA(At, 0, 0); PG8_STAGE(PG8_SA(1, 1), a1 + hstepA, voffA);
;             PG8_WAIT_V(8); PG8_WAIT_L(0); PG8_BAR; PG8_MMA(0, 0, At, B0); PG8_MMA(0, 1, At, B1); PG8_BAR; PG8_SCHED;
;     ...
;             PG8_LDA(At, 1, 1); PG8_STAGE(PG8_SB(1, 0), b3, voffB); PG8_STAGE(PG8_SB(1, 1), b3 + hstepB, voffB); PG8_STAGE(PG8_SA(1, 0), a3, voffA);
;             PG8_WAIT_V(8); PG8_WAIT_L(0); PG8_BAR; PG8_MMA(1, 0, At, B0); PG8_MMA(1, 1, At, B1); PG8_BAR; PG8_SCHED;
	s_add_i32 s79, s79, s53
	s_add_i32 s69, s79, 0x2000
	v_lshl_add_u64 v[140:141], v[140:141], 0, s[18:19]
	s_mov_b32 m0, s79
	s_add_u32 s70, s42, 0x10180
	ds_read_b128 v[180:183], v147 offset:49152
	ds_read_b128 v[184:187], v147 offset:50176
	ds_read_b128 v[188:191], v147 offset:51200
	ds_read_b128 v[192:195], v147 offset:52224
	ds_read_b128 v[196:199], v147 offset:53248
	ds_read_b128 v[200:203], v147 offset:54272
	ds_read_b128 v[204:207], v147 offset:55296
	ds_read_b128 v[208:211], v147 offset:56320
	global_load_lds_dwordx4 v[140:141], off
	v_lshl_add_u64 v[140:141], v[212:213], 0, s[18:19]
	s_mov_b32 m0, s69
	s_addc_u32 s71, s43, 0
	s_add_i32 s42, s80, s53
	global_load_lds_dwordx4 v[140:141], off
	v_lshl_add_u64 v[140:141], s[70:71], 0, v[130:131]
	s_mov_b32 m0, s42
	s_add_i32 s43, s42, 0x2000
	global_load_lds_dwordx4 v[140:141], off
	v_lshl_add_u64 v[140:141], s[70:71], 0, v[134:135]
	s_mov_b32 m0, s43
	s_nop 0
	global_load_lds_dwordx4 v[140:141], off
	v_lshl_add_u64 v[140:141], v[214:215], 0, s[18:19]
	s_mov_b32 m0, s56
	s_nop 0
	global_load_lds_dwordx4 v[140:141], off
	v_lshl_add_u64 v[140:141], v[216:217], 0, s[18:19]
	s_mov_b32 m0, s57
	s_nop 0
	global_load_lds_dwordx4 v[140:141], off
	s_waitcnt vmcnt(8)
	s_waitcnt lgkmcnt(0)
	s_barrier
	s_setprio 1
	v_mfma_f32_16x16x32_bf16 v[0:3], v[24:27], v[204:207], v[0:3]
	v_mfma_f32_16x16x32_bf16 v[4:7], v[112:115], v[204:207], v[4:7]
	v_mfma_f32_16x16x32_bf16 v[148:151], v[24:27], v[180:183], v[148:151]
	v_mfma_f32_16x16x32_bf16 v[152:155], v[112:115], v[180:183], v[152:155]
	v_mfma_f32_16x16x32_bf16 v[156:159], v[24:27], v[188:191], v[156:159]
	v_mfma_f32_16x16x32_bf16 v[160:163], v[112:115], v[188:191], v[160:163]
	v_mfma_f32_16x16x32_bf16 v[164:167], v[24:27], v[196:199], v[164:167]
	v_mfma_f32_16x16x32_bf16 v[168:171], v[112:115], v[196:199], v[168:171]
	v_mfma_f32_16x16x32_bf16 v[0:3], v[28:31], v[208:211], v[0:3]
	v_mfma_f32_16x16x32_bf16 v[4:7], v[116:119], v[208:211], v[4:7]
	v_mfma_f32_16x16x32_bf16 v[148:151], v[28:31], v[184:187], v[148:151]
	v_mfma_f32_16x16x32_bf16 v[152:155], v[116:119], v[184:187], v[152:155]
	v_mfma_f32_16x16x32_bf16 v[156:159], v[28:31], v[192:195], v[156:159]
	v_mfma_f32_16x16x32_bf16 v[160:163], v[116:119], v[192:195], v[160:163]
	v_mfma_f32_16x16x32_bf16 v[164:167], v[28:31], v[200:203], v[164:167]
	v_mfma_f32_16x16x32_bf16 v[168:171], v[116:119], v[200:203], v[168:171]
	v_mfma_f32_16x16x32_bf16 v[8:11], v[120:123], v[180:183], v[8:11]
	v_mfma_f32_16x16x32_bf16 v[12:15], v[172:175], v[180:183], v[12:15]
	v_mfma_f32_16x16x32_bf16 v[24:27], v[120:123], v[188:191], v[60:63]
	v_mfma_f32_16x16x32_bf16 v[28:31], v[172:175], v[188:191], v[100:103]
	v_mfma_f32_16x16x32_bf16 v[60:63], v[120:123], v[196:199], v[104:107]
	v_mfma_f32_16x16x32_bf16 v[100:103], v[172:175], v[196:199], v[108:111]
	v_mfma_f32_16x16x32_bf16 v[16:19], v[120:123], v[204:207], v[16:19]
	v_mfma_f32_16x16x32_bf16 v[20:23], v[172:175], v[204:207], v[20:23]
	v_mfma_f32_16x16x32_bf16 v[8:11], v[124:127], v[184:187], v[8:11]
	v_mfma_f32_16x16x32_bf16 v[12:15], v[176:179], v[184:187], v[12:15]
	v_mfma_f32_16x16x32_bf16 v[24:27], v[124:127], v[192:195], v[24:27]
	v_mfma_f32_16x16x32_bf16 v[28:31], v[176:179], v[192:195], v[28:31]
	v_mfma_f32_16x16x32_bf16 v[60:63], v[124:127], v[200:203], v[60:63]
	v_mfma_f32_16x16x32_bf16 v[100:103], v[176:179], v[200:203], v[100:103]
	v_mfma_f32_16x16x32_bf16 v[16:19], v[124:127], v[208:211], v[16:19]
	v_mfma_f32_16x16x32_bf16 v[20:23], v[176:179], v[208:211], v[20:23]
	s_setprio 0
	s_barrier
	ds_read_b128 v[104:107], v145
	ds_read_b128 v[108:111], v145 offset:1024
	ds_read_b128 v[112:115], v145 offset:2048
	ds_read_b128 v[116:119], v145 offset:3072
	ds_read_b128 v[120:123], v146
	ds_read_b128 v[124:127], v146 offset:1024
	ds_read_b128 v[172:175], v146 offset:2048
	ds_read_b128 v[176:179], v146 offset:3072
	s_add_u32 s40, s40, 0x10180
	s_addc_u32 s41, s41, 0
	s_mov_b32 m0, s78
	v_lshl_add_u64 v[140:141], s[40:41], 0, v[128:129]
	ds_read_b128 v[180:183], v147
	ds_read_b128 v[184:187], v147 offset:1024
	ds_read_b128 v[188:191], v147 offset:2048
	ds_read_b128 v[192:195], v147 offset:3072
	ds_read_b128 v[196:199], v147 offset:4096
	ds_read_b128 v[200:203], v147 offset:5120
	ds_read_b128 v[204:207], v147 offset:6144
	ds_read_b128 v[208:211], v147 offset:7168
	global_load_lds_dwordx4 v[140:141], off
	v_lshl_add_u64 v[140:141], s[40:41], 0, v[132:133]
	s_mov_b32 m0, s29
	s_nop 0
	global_load_lds_dwordx4 v[140:141], off
	s_waitcnt vmcnt(8)
	s_waitcnt lgkmcnt(0)
	s_barrier
; #define PG8_STAGE(bufoff, gbase, voff) do { _Pragma("unroll") for (int _i = 0; _i < 2; ++_i) \
;         __builtin_amdgcn_global_load_lds((const unsigned*)((const char*)(gbase) + (voff)[_i]), (PG8_LAS unsigned*)(lds + (bufoff) + ldsw + _i * 8192), 16, 0, 0); } while (0)
; #define PG8_LDA(dst, b, h) do { _Pragma("unroll") for (int m = 0; m < 4; ++m) _Pragma("unroll") for (int k = 0; k < 2; ++k) dst[m][k] = *(const PG8_LAS bf16x8*)(lds + PG8_SA(b, h) + aoff + m * 2048 + k * 1024); } while (0)
; #define PG8_MMA(ai, bj, At, Bt) do { __builtin_amdgcn_s_setprio(1); _Pragma("unroll") for (int m = 0; m < 4; ++m) _Pragma("unroll") for (int n = 0; n < 2; ++n) _Pragma("unroll") for (int k = 0; k < 2; ++k) \
;         acc[ai][bj][m][n] = __builtin_amdgcn_mfma_f32_16x16x32_bf16(Bt[n][k], At[m][k], acc[ai][bj][m][n], 0, 0, 0); __builtin_amdgcn_s_setprio(0); } while (0)
; #define PG8_WAIT_V(n) asm volatile("s_waitcnt vmcnt(" #n ")" ::: "memory")
; #define PG8_WAIT_L(n) asm volatile("s_waitcnt lgkmcnt(" #n ")" ::: "memory")
; #define PG8_BAR __builtin_amdgcn_s_barrier()
; #define PG8_SCHED __builtin_amdgcn_sched_barrier(0)
; template <class Epi, class Sched, bool ALIGN_EPI = false, bool SP2 = false>
; __device__ __forceinline__ void gemm_phase(PG8_LAS unsigned char* lds, const Gemm g, const Sched& S, const Epi& E) {
;     ...
;             PG8_WAIT_V(8); PG8_WAIT_L(0); PG8_BAR; PG8_MMA(0, 0, At, B0); PG8_MMA(0, 1, At, B1); PG8_BAR; PG8_SCHED;
;             PG8_LDA(At, 0, 1); PG8_STAGE(PG8_SB(0, 0), b2, voffB); PG8_STAGE(PG8_SB(0, 1), b2 + hstepB, voffB); PG8_STAGE(PG8_SA(0, 0), a2, voffA);
;             PG8_WAIT_V(8); PG8_WAIT_L(0); PG8_BAR; PG8_MMA(1, 0, At, B0); PG8_MMA(1, 1, At, B1); PG8_BAR; PG8_SCHED;
	s_setprio 1
	v_mfma_f32_16x16x32_bf16 v[88:91], v[104:107], v[204:207], v[88:91]
	v_mfma_f32_16x16x32_bf16 v[64:67], v[104:107], v[180:183], v[64:67]
	v_mfma_f32_16x16x32_bf16 v[68:71], v[112:115], v[180:183], v[68:71]
	v_mfma_f32_16x16x32_bf16 v[72:75], v[104:107], v[188:191], v[72:75]
	v_mfma_f32_16x16x32_bf16 v[76:79], v[112:115], v[188:191], v[76:79]
	v_mfma_f32_16x16x32_bf16 v[80:83], v[104:107], v[196:199], v[80:83]
	v_mfma_f32_16x16x32_bf16 v[84:87], v[112:115], v[196:199], v[84:87]
	v_mfma_f32_16x16x32_bf16 v[212:215], v[108:111], v[208:211], v[88:91]
	v_mfma_f32_16x16x32_bf16 v[88:91], v[112:115], v[204:207], v[92:95]
	v_mfma_f32_16x16x32_bf16 v[64:67], v[108:111], v[184:187], v[64:67]
	v_mfma_f32_16x16x32_bf16 v[68:71], v[116:119], v[184:187], v[68:71]
	v_mfma_f32_16x16x32_bf16 v[72:75], v[108:111], v[192:195], v[72:75]
	v_mfma_f32_16x16x32_bf16 v[76:79], v[116:119], v[192:195], v[76:79]
	v_mfma_f32_16x16x32_bf16 v[80:83], v[108:111], v[200:203], v[80:83]
	v_mfma_f32_16x16x32_bf16 v[84:87], v[116:119], v[200:203], v[84:87]
	v_mfma_f32_16x16x32_bf16 v[92:95], v[116:119], v[208:211], v[88:91]
	v_mfma_f32_16x16x32_bf16 v[48:51], v[172:175], v[196:199], v[48:51]
	v_mfma_f32_16x16x32_bf16 v[88:91], v[120:123], v[180:183], v[96:99]
	v_mfma_f32_16x16x32_bf16 v[32:35], v[172:175], v[180:183], v[32:35]
	v_mfma_f32_16x16x32_bf16 v[36:39], v[120:123], v[188:191], v[36:39]
	v_mfma_f32_16x16x32_bf16 v[40:43], v[172:175], v[188:191], v[40:43]
	v_mfma_f32_16x16x32_bf16 v[44:47], v[120:123], v[196:199], v[44:47]
	v_mfma_f32_16x16x32_bf16 v[180:183], v[176:179], v[200:203], v[48:51]
	v_mfma_f32_16x16x32_bf16 v[48:51], v[120:123], v[204:207], v[52:55]
	v_mfma_f32_16x16x32_bf16 v[32:35], v[176:179], v[184:187], v[32:35]
	v_mfma_f32_16x16x32_bf16 v[36:39], v[124:127], v[192:195], v[36:39]
	v_mfma_f32_16x16x32_bf16 v[40:43], v[176:179], v[192:195], v[40:43]
	v_mfma_f32_16x16x32_bf16 v[44:47], v[124:127], v[200:203], v[44:47]
	v_mfma_f32_16x16x32_bf16 v[52:55], v[124:127], v[208:211], v[48:51]
	v_mfma_f32_16x16x32_bf16 v[48:51], v[172:175], v[204:207], v[56:59]
	v_mfma_f32_16x16x32_bf16 v[216:219], v[124:127], v[184:187], v[88:91]
	v_mfma_f32_16x16x32_bf16 v[184:187], v[176:179], v[208:211], v[48:51]
	s_setprio 0
	s_barrier
	s_mov_b32 m0, s68
	v_lshl_add_u64 v[140:141], s[44:45], 0, v[130:131]
	s_add_u32 s40, s44, 0x10000
	s_nop 0
	ds_read_b128 v[48:51], v147 offset:16384
	ds_read_b128 v[56:59], v147 offset:17408
	ds_read_b128 v[88:91], v147 offset:18432
	ds_read_b128 v[96:99], v147 offset:19456
	ds_read_b128 v[188:191], v147 offset:20480
	ds_read_b128 v[192:195], v147 offset:21504
	ds_read_b128 v[196:199], v147 offset:22528
	ds_read_b128 v[200:203], v147 offset:23552
	global_load_lds_dwordx4 v[140:141], off
	v_lshl_add_u64 v[252:253], s[44:45], 0, v[134:135]
	s_mov_b32 m0, s31
	s_addc_u32 s41, s45, 0
	global_load_lds_dwordx4 v[252:253], off
	v_lshl_add_u64 v[204:205], s[40:41], 0, v[130:131]
	s_mov_b32 m0, s66
	v_lshl_add_u64 v[136:137], s[46:47], 0, v[128:129]
	global_load_lds_dwordx4 v[204:205], off
	v_lshl_add_u64 v[204:205], s[40:41], 0, v[134:135]
	s_mov_b32 m0, s67
	v_lshl_add_u64 v[138:139], s[46:47], 0, v[132:133]
	global_load_lds_dwordx4 v[204:205], off
	s_mov_b32 m0, s3
	s_nop 0
	global_load_lds_dwordx4 v[136:137], off
	s_mov_b32 m0, s39
	s_nop 0
	global_load_lds_dwordx4 v[138:139], off
	s_waitcnt vmcnt(8)
	s_waitcnt lgkmcnt(0)
	s_barrier
	s_setprio 1
	v_mfma_f32_16x16x32_bf16 v[0:3], v[104:107], v[196:199], v[0:3]
	v_mfma_f32_16x16x32_bf16 v[4:7], v[112:115], v[196:199], v[4:7]
	v_mfma_f32_16x16x32_bf16 v[148:151], v[104:107], v[48:51], v[148:151]
	v_mfma_f32_16x16x32_bf16 v[152:155], v[112:115], v[48:51], v[152:155]
	v_mfma_f32_16x16x32_bf16 v[156:159], v[104:107], v[88:91], v[156:159]
	v_mfma_f32_16x16x32_bf16 v[160:163], v[112:115], v[88:91], v[160:163]
	v_mfma_f32_16x16x32_bf16 v[164:167], v[104:107], v[188:191], v[164:167]
	v_mfma_f32_16x16x32_bf16 v[168:171], v[112:115], v[188:191], v[168:171]
	v_mfma_f32_16x16x32_bf16 v[0:3], v[108:111], v[200:203], v[0:3]
	v_mfma_f32_16x16x32_bf16 v[4:7], v[116:119], v[200:203], v[4:7]
	v_mfma_f32_16x16x32_bf16 v[148:151], v[108:111], v[56:59], v[148:151]
	v_mfma_f32_16x16x32_bf16 v[152:155], v[116:119], v[56:59], v[152:155]
	v_mfma_f32_16x16x32_bf16 v[156:159], v[108:111], v[96:99], v[156:159]
	v_mfma_f32_16x16x32_bf16 v[160:163], v[116:119], v[96:99], v[160:163]
	v_mfma_f32_16x16x32_bf16 v[164:167], v[108:111], v[192:195], v[164:167]
	v_mfma_f32_16x16x32_bf16 v[168:171], v[116:119], v[192:195], v[168:171]
	v_mfma_f32_16x16x32_bf16 v[12:15], v[172:175], v[48:51], v[12:15]
	v_mfma_f32_16x16x32_bf16 v[204:207], v[176:179], v[56:59], v[12:15]
	v_mfma_f32_16x16x32_bf16 v[12:15], v[120:123], v[88:91], v[24:27]
	v_mfma_f32_16x16x32_bf16 v[24:27], v[124:127], v[96:99], v[12:15]
	v_mfma_f32_16x16x32_bf16 v[12:15], v[172:175], v[88:91], v[28:31]
	v_mfma_f32_16x16x32_bf16 v[208:211], v[176:179], v[96:99], v[12:15]
	v_mfma_f32_16x16x32_bf16 v[12:15], v[120:123], v[188:191], v[60:63]
	v_mfma_f32_16x16x32_bf16 v[220:223], v[124:127], v[192:195], v[12:15]
	v_mfma_f32_16x16x32_bf16 v[12:15], v[172:175], v[188:191], v[100:103]
	v_mfma_f32_16x16x32_bf16 v[8:11], v[120:123], v[48:51], v[8:11]
	v_mfma_f32_16x16x32_bf16 v[188:191], v[176:179], v[192:195], v[12:15]
	v_mfma_f32_16x16x32_bf16 v[12:15], v[120:123], v[196:199], v[16:19]
	v_mfma_f32_16x16x32_bf16 v[8:11], v[124:127], v[56:59], v[8:11]
	v_mfma_f32_16x16x32_bf16 v[192:195], v[124:127], v[200:203], v[12:15]
	v_mfma_f32_16x16x32_bf16 v[12:15], v[172:175], v[196:199], v[20:23]
	v_mfma_f32_16x16x32_bf16 v[172:175], v[176:179], v[200:203], v[12:15]
	s_setprio 0
	s_barrier
; #define PG8_STAGE(bufoff, gbase, voff) do { _Pragma("unroll") for (int _i = 0; _i < 2; ++_i) \
;         __builtin_amdgcn_global_load_lds((const unsigned*)((const char*)(gbase) + (voff)[_i]), (PG8_LAS unsigned*)(lds + (bufoff) + ldsw + _i * 8192), 16, 0, 0); } while (0)
; #define PG8_LDA(dst, b, h) do { _Pragma("unroll") for (int m = 0; m < 4; ++m) _Pragma("unroll") for (int k = 0; k < 2; ++k) dst[m][k] = *(const PG8_LAS bf16x8*)(lds + PG8_SA(b, h) + aoff + m * 2048 + k * 1024); } while (0)
; #define PG8_LDB(dst, b, h) do { _Pragma("unroll") for (int n = 0; n < 2; ++n) _Pragma("unroll") for (int k = 0; k < 2; ++k) dst[n][k] = *(const PG8_LAS bf16x8*)(lds + PG8_SB(b, h) + boff + n * 2048 + k * 1024); } while (0)
; #define PG8_MMA(ai, bj, At, Bt) do { __builtin_amdgcn_s_setprio(1); _Pragma("unroll") for (int m = 0; m < 4; ++m) _Pragma("unroll") for (int n = 0; n < 2; ++n) _Pragma("unroll") for (int k = 0; k < 2; ++k) \
;         acc[ai][bj][m][n] = __builtin_amdgcn_mfma_f32_16x16x32_bf16(Bt[n][k], At[m][k], acc[ai][bj][m][n], 0, 0, 0); __builtin_amdgcn_s_setprio(0); } while (0)
; #define PG8_WAIT_V(n) asm volatile("s_waitcnt vmcnt(" #n ")" ::: "memory")
; #define PG8_WAIT_L(n) asm volatile("s_waitcnt lgkmcnt(" #n ")" ::: "memory")
; #define PG8_BAR __builtin_amdgcn_s_barrier()
; #define PG8_SCHED __builtin_amdgcn_sched_barrier(0)
; template <class Epi, class Sched, bool ALIGN_EPI = false, bool SP2 = false>
; __device__ __forceinline__ void gemm_phase(PG8_LAS unsigned char* lds, const Gemm g, const Sched& S, const Epi& E) {
;     ...
;             PG8_LDB(B0, 1, 0); PG8_LDB(B1, 1, 1); PG8_SCHED; PG8_LDA(At, 1, 0); PG8_STAGE(PG8_SA(0, 1), a2 + hstepA, voffA);
;             PG8_WAIT_V(8); PG8_WAIT_L(0); PG8_BAR; PG8_MMA(0, 0, At, B0); PG8_MMA(0, 1, At, B1); PG8_BAR; PG8_SCHED;
;             PG8_LDA(At, 1, 1); PG8_STAGE(PG8_SB(1, 0), b3, voffB); PG8_STAGE(PG8_SB(1, 1), b3 + hstepB, voffB); PG8_STAGE(PG8_SA(1, 0), a3, voffA);
;             PG8_WAIT_V(8); PG8_WAIT_L(0); PG8_BAR; PG8_MMA(1, 0, At, B0); PG8_MMA(1, 1, At, B1); PG8_BAR; PG8_SCHED;
	s_nop 4
	ds_read_b128 v[12:15], v224
	ds_read_b128 v[16:19], v224 offset:1024
	ds_read_b128 v[176:179], v224 offset:2048
	ds_read_b128 v[196:199], v224 offset:3072
	ds_read_b128 v[200:203], v232
	ds_read_b128 v[224:227], v232 offset:1024
	ds_read_b128 v[228:231], v232 offset:2048
	ds_read_b128 v[232:235], v232 offset:3072
	s_add_u32 s40, s46, 0x10000
	s_addc_u32 s41, s47, 0
	s_mov_b32 m0, s54
	v_lshl_add_u64 v[48:49], s[40:41], 0, v[128:129]
	ds_read_b128 v[20:23], v147 offset:32768
	ds_read_b128 v[28:31], v147 offset:33792
	ds_read_b128 v[60:63], v147 offset:34816
	ds_read_b128 v[100:103], v147 offset:35840
	ds_read_b128 v[236:239], v147 offset:36864
	ds_read_b128 v[240:243], v147 offset:37888
	ds_read_b128 v[244:247], v147 offset:38912
	ds_read_b128 v[248:251], v147 offset:39936
	global_load_lds_dwordx4 v[48:49], off
	v_lshl_add_u64 v[48:49], s[40:41], 0, v[132:133]
	s_mov_b32 m0, s55
	s_nop 0
	global_load_lds_dwordx4 v[48:49], off
	s_waitcnt vmcnt(8)
	s_waitcnt lgkmcnt(0)
	s_barrier
	s_setprio 1
	v_mfma_f32_16x16x32_bf16 v[48:51], v[12:15], v[20:23], v[64:67]
	v_mfma_f32_16x16x32_bf16 v[120:123], v[16:19], v[28:31], v[48:51]
	v_mfma_f32_16x16x32_bf16 v[48:51], v[176:179], v[20:23], v[68:71]
	v_mfma_f32_16x16x32_bf16 v[112:115], v[196:199], v[28:31], v[48:51]
	v_mfma_f32_16x16x32_bf16 v[48:51], v[12:15], v[60:63], v[72:75]
	v_mfma_f32_16x16x32_bf16 v[104:107], v[16:19], v[100:103], v[48:51]
	v_mfma_f32_16x16x32_bf16 v[48:51], v[176:179], v[60:63], v[76:79]
	v_mfma_f32_16x16x32_bf16 v[96:99], v[196:199], v[100:103], v[48:51]
	v_mfma_f32_16x16x32_bf16 v[48:51], v[12:15], v[236:239], v[80:83]
	v_mfma_f32_16x16x32_bf16 v[88:91], v[16:19], v[240:243], v[48:51]
	v_mfma_f32_16x16x32_bf16 v[48:51], v[176:179], v[236:239], v[84:87]
	v_mfma_f32_16x16x32_bf16 v[80:83], v[196:199], v[240:243], v[48:51]
	v_mfma_f32_16x16x32_bf16 v[48:51], v[12:15], v[244:247], v[212:215]
	v_mfma_f32_16x16x32_bf16 v[56:59], v[16:19], v[248:251], v[48:51]
	v_mfma_f32_16x16x32_bf16 v[48:51], v[176:179], v[244:247], v[92:95]
	v_mfma_f32_16x16x32_bf16 v[48:51], v[196:199], v[248:251], v[48:51]
	v_mfma_f32_16x16x32_bf16 v[64:67], v[200:203], v[20:23], v[216:219]
	v_mfma_f32_16x16x32_bf16 v[20:23], v[228:231], v[20:23], v[32:35]
	v_mfma_f32_16x16x32_bf16 v[116:119], v[232:235], v[28:31], v[20:23]
	v_mfma_f32_16x16x32_bf16 v[20:23], v[200:203], v[60:63], v[36:39]
	v_mfma_f32_16x16x32_bf16 v[108:111], v[224:227], v[100:103], v[20:23]
	v_mfma_f32_16x16x32_bf16 v[20:23], v[228:231], v[60:63], v[40:43]
	v_mfma_f32_16x16x32_bf16 v[100:103], v[232:235], v[100:103], v[20:23]
	v_mfma_f32_16x16x32_bf16 v[20:23], v[200:203], v[236:239], v[44:47]
	v_mfma_f32_16x16x32_bf16 v[92:95], v[224:227], v[240:243], v[20:23]
	v_mfma_f32_16x16x32_bf16 v[20:23], v[228:231], v[236:239], v[180:183]
	v_mfma_f32_16x16x32_bf16 v[84:87], v[232:235], v[240:243], v[20:23]
	v_mfma_f32_16x16x32_bf16 v[20:23], v[200:203], v[244:247], v[52:55]
	v_mfma_f32_16x16x32_bf16 v[60:63], v[224:227], v[248:251], v[20:23]
	v_mfma_f32_16x16x32_bf16 v[20:23], v[228:231], v[244:247], v[184:187]
	v_mfma_f32_16x16x32_bf16 v[124:127], v[224:227], v[28:31], v[64:67]
	v_mfma_f32_16x16x32_bf16 v[52:55], v[232:235], v[248:251], v[20:23]
	s_setprio 0
	s_barrier
	s_mov_b32 m0, s79
	s_nop 2
	v_lshl_add_u64 v[20:21], v[140:141], 0, s[10:11]
	s_add_u32 s40, s44, 0x10080
	ds_read_b128 v[32:35], v147 offset:49152
	ds_read_b128 v[40:43], v147 offset:50176
	ds_read_b128 v[180:183], v147 offset:51200
	ds_read_b128 v[184:187], v147 offset:52224
	ds_read_b128 v[212:215], v147 offset:53248
	ds_read_b128 v[216:219], v147 offset:54272
	ds_read_b128 v[236:239], v147 offset:55296
	ds_read_b128 v[240:243], v147 offset:56320
	global_load_lds_dwordx4 v[20:21], off
	v_lshl_add_u64 v[20:21], v[252:253], 0, s[10:11]
	s_mov_b32 m0, s69
	s_addc_u32 s41, s45, 0
	global_load_lds_dwordx4 v[20:21], off
	v_lshl_add_u64 v[20:21], s[40:41], 0, v[130:131]
	s_mov_b32 m0, s42
	s_nop 0
	global_load_lds_dwordx4 v[20:21], off
	v_lshl_add_u64 v[20:21], s[40:41], 0, v[134:135]
	s_mov_b32 m0, s43
	s_nop 0
	global_load_lds_dwordx4 v[20:21], off
	v_lshl_add_u64 v[20:21], v[136:137], 0, s[10:11]
	s_mov_b32 m0, s56
	s_nop 0
	global_load_lds_dwordx4 v[20:21], off
	v_lshl_add_u64 v[20:21], v[138:139], 0, s[10:11]
	s_mov_b32 m0, s57
	s_nop 0
	global_load_lds_dwordx4 v[20:21], off
	s_waitcnt vmcnt(8)
	s_waitcnt lgkmcnt(0)
	s_barrier
	s_setprio 1
	v_mfma_f32_16x16x32_bf16 v[20:23], v[12:15], v[32:35], v[148:151]
	v_mfma_f32_16x16x32_bf16 v[76:79], v[16:19], v[40:43], v[20:23]
	v_mfma_f32_16x16x32_bf16 v[20:23], v[176:179], v[32:35], v[152:155]
	v_mfma_f32_16x16x32_bf16 v[68:71], v[196:199], v[40:43], v[20:23]
	v_mfma_f32_16x16x32_bf16 v[20:23], v[12:15], v[180:183], v[156:159]
	v_mfma_f32_16x16x32_bf16 v[44:47], v[16:19], v[184:187], v[20:23]
	v_mfma_f32_16x16x32_bf16 v[20:23], v[176:179], v[180:183], v[160:163]
	v_mfma_f32_16x16x32_bf16 v[36:39], v[196:199], v[184:187], v[20:23]
	v_mfma_f32_16x16x32_bf16 v[20:23], v[12:15], v[212:215], v[164:167]
	v_mfma_f32_16x16x32_bf16 v[0:3], v[12:15], v[236:239], v[0:3]
	v_mfma_f32_16x16x32_bf16 v[28:31], v[16:19], v[216:219], v[20:23]
	v_mfma_f32_16x16x32_bf16 v[20:23], v[176:179], v[212:215], v[168:171]
	v_mfma_f32_16x16x32_bf16 v[12:15], v[16:19], v[240:243], v[0:3]
	v_mfma_f32_16x16x32_bf16 v[0:3], v[176:179], v[236:239], v[4:7]
	v_mfma_f32_16x16x32_bf16 v[20:23], v[196:199], v[216:219], v[20:23]
	v_mfma_f32_16x16x32_bf16 v[4:7], v[196:199], v[240:243], v[0:3]
	v_mfma_f32_16x16x32_bf16 v[0:3], v[200:203], v[32:35], v[8:11]
	v_mfma_f32_16x16x32_bf16 v[72:75], v[224:227], v[40:43], v[0:3]
	v_mfma_f32_16x16x32_bf16 v[0:3], v[228:231], v[32:35], v[204:207]
	v_mfma_f32_16x16x32_bf16 v[64:67], v[232:235], v[40:43], v[0:3]
	v_mfma_f32_16x16x32_bf16 v[0:3], v[200:203], v[180:183], v[24:27]
	v_mfma_f32_16x16x32_bf16 v[40:43], v[224:227], v[184:187], v[0:3]
	v_mfma_f32_16x16x32_bf16 v[0:3], v[228:231], v[180:183], v[208:211]
	v_mfma_f32_16x16x32_bf16 v[32:35], v[232:235], v[184:187], v[0:3]
	v_mfma_f32_16x16x32_bf16 v[0:3], v[200:203], v[212:215], v[220:223]
	v_mfma_f32_16x16x32_bf16 v[24:27], v[224:227], v[216:219], v[0:3]
	v_mfma_f32_16x16x32_bf16 v[0:3], v[228:231], v[212:215], v[188:191]
	v_mfma_f32_16x16x32_bf16 v[16:19], v[232:235], v[216:219], v[0:3]
	v_mfma_f32_16x16x32_bf16 v[0:3], v[200:203], v[236:239], v[192:195]
	v_mfma_f32_16x16x32_bf16 v[8:11], v[224:227], v[240:243], v[0:3]
	v_mfma_f32_16x16x32_bf16 v[0:3], v[228:231], v[236:239], v[172:175]
	v_mfma_f32_16x16x32_bf16 v[0:3], v[232:235], v[240:243], v[0:3]
	s_setprio 0
	s_barrier
	s_andn2_b64 vcc, exec, s[12:13]
	s_cbranch_vccnz .LBB0_1300
	s_barrier

; #define PG8_STAGE(bufoff, gbase, voff) do { _Pragma("unroll") for (int _i = 0; _i < 2; ++_i) \
;         __builtin_amdgcn_global_load_lds((const unsigned*)((const char*)(gbase) + (voff)[_i]), (PG8_LAS unsigned*)(lds + (bufoff) + ldsw + _i * 8192), 16, 0, 0); } while (0)
; #define PG8_LDA(dst, b, h) do { _Pragma("unroll") for (int m = 0; m < 4; ++m) _Pragma("unroll") for (int k = 0; k < 2; ++k) dst[m][k] = *(const PG8_LAS bf16x8*)(lds + PG8_SA(b, h) + aoff + m * 2048 + k * 1024); } while (0)
; #define PG8_LDB(dst, b, h) do { _Pragma("unroll") for (int n = 0; n < 2; ++n) _Pragma("unroll") for (int k = 0; k < 2; ++k) dst[n][k] = *(const PG8_LAS bf16x8*)(lds + PG8_SB(b, h) + boff + n * 2048 + k * 1024); } while (0)
; #define PG8_MMA(ai, bj, At, Bt) do { __builtin_amdgcn_s_setprio(1); _Pragma("unroll") for (int m = 0; m < 4; ++m) _Pragma("unroll") for (int n = 0; n < 2; ++n) _Pragma("unroll") for (int k = 0; k < 2; ++k) \
;         acc[ai][bj][m][n] = __builtin_amdgcn_mfma_f32_16x16x32_bf16(Bt[n][k], At[m][k], acc[ai][bj][m][n], 0, 0, 0); __builtin_amdgcn_s_setprio(0); } while (0)
; #define PG8_WAIT_V(n) asm volatile("s_waitcnt vmcnt(" #n ")" ::: "memory")
; #define PG8_WAIT_L(n) asm volatile("s_waitcnt lgkmcnt(" #n ")" ::: "memory")
; #define PG8_BAR __builtin_amdgcn_s_barrier()
; #define PG8_SCHED __builtin_amdgcn_sched_barrier(0)
; template <class Epi, class Sched, bool ALIGN_EPI = false, bool SP2 = false>
; __device__ __forceinline__ void gemm_phase(PG8_LAS unsigned char* lds, const Gemm g, const Sched& S, const Epi& E) {
;     ...
;             const bool last = (t == nt - 2);
;             const char* a1 = cA + PG8_AK(t + 1);
;             const char* a2 = last ? nA : cA + PG8_AK(t + 2); const char* b2 = last ? nB : cB + (size_t)(t + 2) * kstep;
;             const char* a3 = last ? nA + PG8_AK(1) : cA + PG8_AK(t + 3); const char* b3 = b2 + kstep;
;             if (last && has_next) S.a_ready(nxt);
;             if constexpr (SP2) {
;             PG8_LDB(B0, 0, 0); PG8_LDB(B1, 0, 1); PG8_SCHED; PG8_LDA(At, 0, 0); PG8_STAGE(PG8_SA(1, 1), a1 + hstepA, voffA);
;             PG8_WAIT_V(8); PG8_WAIT_L(0); PG8_BAR; PG8_MMA(0, 0, At, B0); PG8_MMA(0, 1, At, B1); PG8_BAR; PG8_SCHED;
;             PG8_LDA(At, 0, 1); PG8_STAGE(PG8_SB(0, 0), b2, voffB); PG8_STAGE(PG8_SB(0, 1), b2 + hstepB, voffB); PG8_STAGE(PG8_SA(0, 0), a2, voffA);
.LBB0_1379:
	ds_read_b128 v[124:127], v210
	ds_read_b128 v[128:131], v210 offset:1024
	ds_read_b128 v[132:135], v210 offset:2048
	ds_read_b128 v[144:147], v210 offset:3072
	ds_read_b128 v[148:151], v211
	ds_read_b128 v[170:173], v211 offset:1024
	ds_read_b128 v[174:177], v211 offset:2048
	ds_read_b128 v[178:181], v211 offset:3072
	s_add_u32 s42, s38, s40
	s_addc_u32 s43, s39, s41
	s_add_u32 s46, s42, 0x100
	s_addc_u32 s47, s43, 0
	s_add_u32 s44, s78, s40
	s_addc_u32 s45, s79, s41
	s_add_u32 s42, s42, 0x180
	s_addc_u32 s43, s43, 0
	s_cmpk_eq_i32 s40, 0x1500
	s_cselect_b32 s43, s10, s43
	s_cselect_b32 s42, s3, s42
	s_cselect_b32 s45, s37, s45
	s_cselect_b32 s44, s36, s44
	s_cselect_b32 s47, s9, s47
	s_cselect_b32 s46, s8, s46
	v_lshl_add_u64 v[206:207], v[122:123], 0, s[40:41]
	s_add_i32 m0, s53, 0xc000
	ds_read_b128 v[212:215], v191
	ds_read_b128 v[216:219], v191 offset:1024
	ds_read_b128 v[220:223], v191 offset:2048
	ds_read_b128 v[224:227], v191 offset:3072
	ds_read_b128 v[228:231], v191 offset:4096
	ds_read_b128 v[232:235], v191 offset:5120
	ds_read_b128 v[236:239], v191 offset:6144
	ds_read_b128 v[240:243], v191 offset:7168
	global_load_lds_dwordx4 v[206:207], off
	v_lshl_add_u64 v[206:207], v[120:121], 0, s[40:41]
	s_add_i32 m0, s53, 0xe000
	s_nop 0
	global_load_lds_dwordx4 v[206:207], off
	s_waitcnt vmcnt(8)
	s_waitcnt lgkmcnt(0)
	s_barrier
	s_setprio 1
	v_mfma_f32_16x16x32_bf16 v[140:143], v[124:127], v[212:215], v[140:143]
	v_mfma_f32_16x16x32_bf16 v[136:139], v[132:135], v[212:215], v[136:139]
	v_mfma_f32_16x16x32_bf16 v[116:119], v[124:127], v[220:223], v[116:119]
	v_mfma_f32_16x16x32_bf16 v[112:115], v[132:135], v[220:223], v[112:115]
	v_mfma_f32_16x16x32_bf16 v[108:111], v[124:127], v[228:231], v[108:111]
	v_mfma_f32_16x16x32_bf16 v[104:107], v[132:135], v[228:231], v[104:107]
	v_mfma_f32_16x16x32_bf16 v[100:103], v[124:127], v[236:239], v[100:103]
	v_mfma_f32_16x16x32_bf16 v[96:99], v[132:135], v[236:239], v[96:99]
	v_mfma_f32_16x16x32_bf16 v[140:143], v[128:131], v[216:219], v[140:143]
	v_mfma_f32_16x16x32_bf16 v[136:139], v[144:147], v[216:219], v[136:139]
	v_mfma_f32_16x16x32_bf16 v[116:119], v[128:131], v[224:227], v[116:119]
	v_mfma_f32_16x16x32_bf16 v[112:115], v[144:147], v[224:227], v[112:115]
	v_mfma_f32_16x16x32_bf16 v[108:111], v[128:131], v[232:235], v[108:111]
	v_mfma_f32_16x16x32_bf16 v[104:107], v[144:147], v[232:235], v[104:107]
	v_mfma_f32_16x16x32_bf16 v[100:103], v[128:131], v[240:243], v[100:103]
	v_mfma_f32_16x16x32_bf16 v[96:99], v[144:147], v[240:243], v[96:99]
	v_mfma_f32_16x16x32_bf16 v[60:63], v[148:151], v[212:215], v[60:63]
	v_mfma_f32_16x16x32_bf16 v[56:59], v[174:177], v[212:215], v[56:59]
	v_mfma_f32_16x16x32_bf16 v[52:55], v[148:151], v[220:223], v[52:55]
	v_mfma_f32_16x16x32_bf16 v[48:51], v[174:177], v[220:223], v[48:51]
	v_mfma_f32_16x16x32_bf16 v[44:47], v[148:151], v[228:231], v[44:47]
	v_mfma_f32_16x16x32_bf16 v[40:43], v[174:177], v[228:231], v[40:43]
	v_mfma_f32_16x16x32_bf16 v[36:39], v[148:151], v[236:239], v[36:39]
	v_mfma_f32_16x16x32_bf16 v[32:35], v[174:177], v[236:239], v[32:35]
	v_mfma_f32_16x16x32_bf16 v[60:63], v[170:173], v[216:219], v[60:63]
	v_mfma_f32_16x16x32_bf16 v[56:59], v[178:181], v[216:219], v[56:59]
	v_mfma_f32_16x16x32_bf16 v[52:55], v[170:173], v[224:227], v[52:55]
	v_mfma_f32_16x16x32_bf16 v[48:51], v[178:181], v[224:227], v[48:51]
	v_mfma_f32_16x16x32_bf16 v[44:47], v[170:173], v[232:235], v[44:47]
	v_mfma_f32_16x16x32_bf16 v[40:43], v[178:181], v[232:235], v[40:43]
	v_mfma_f32_16x16x32_bf16 v[36:39], v[170:173], v[240:243], v[36:39]
	v_mfma_f32_16x16x32_bf16 v[32:35], v[178:181], v[240:243], v[32:35]
	s_setprio 0
	s_barrier
	s_add_i32 s70, s67, s52
	v_lshl_add_u64 v[206:207], s[44:45], 0, v[154:155]
	s_mov_b32 m0, s70
	ds_read_b128 v[212:215], v191 offset:16384
	ds_read_b128 v[216:219], v191 offset:17408
	ds_read_b128 v[220:223], v191 offset:18432
	ds_read_b128 v[224:227], v191 offset:19456
	ds_read_b128 v[228:231], v191 offset:20480
	ds_read_b128 v[232:235], v191 offset:21504
	ds_read_b128 v[236:239], v191 offset:22528
	ds_read_b128 v[240:243], v191 offset:23552
	global_load_lds_dwordx4 v[206:207], off
	s_add_i32 m0, s70, 0x2000
	s_add_u32 s70, s44, 0xb0000
	v_lshl_add_u64 v[244:245], s[44:45], 0, v[158:159]
	s_addc_u32 s71, s45, 0
	s_add_i32 s85, s68, s52
	global_load_lds_dwordx4 v[244:245], off
	v_lshl_add_u64 v[246:247], s[70:71], 0, v[154:155]
	s_mov_b32 m0, s85
	s_nop 0
	global_load_lds_dwordx4 v[246:247], off
	v_lshl_add_u64 v[246:247], s[70:71], 0, v[158:159]
	s_add_i32 m0, s85, 0x2000
	s_nop 0
	global_load_lds_dwordx4 v[246:247], off
	v_lshl_add_u64 v[246:247], s[46:47], 0, v[152:153]
	s_mov_b32 m0, s53
	s_nop 0
	global_load_lds_dwordx4 v[246:247], off
	v_lshl_add_u64 v[246:247], s[46:47], 0, v[156:157]
	s_mov_b32 m0, s54
	s_nop 0
	global_load_lds_dwordx4 v[246:247], off
	s_waitcnt vmcnt(8)
	s_waitcnt lgkmcnt(0)
	s_barrier
; #define PG8_STAGE(bufoff, gbase, voff) do { _Pragma("unroll") for (int _i = 0; _i < 2; ++_i) \
;         __builtin_amdgcn_global_load_lds((const unsigned*)((const char*)(gbase) + (voff)[_i]), (PG8_LAS unsigned*)(lds + (bufoff) + ldsw + _i * 8192), 16, 0, 0); } while (0)
; #define PG8_LDA(dst, b, h) do { _Pragma("unroll") for (int m = 0; m < 4; ++m) _Pragma("unroll") for (int k = 0; k < 2; ++k) dst[m][k] = *(const PG8_LAS bf16x8*)(lds + PG8_SA(b, h) + aoff + m * 2048 + k * 1024); } while (0)
; #define PG8_LDB(dst, b, h) do { _Pragma("unroll") for (int n = 0; n < 2; ++n) _Pragma("unroll") for (int k = 0; k < 2; ++k) dst[n][k] = *(const PG8_LAS bf16x8*)(lds + PG8_SB(b, h) + boff + n * 2048 + k * 1024); } while (0)
; #define PG8_MMA(ai, bj, At, Bt) do { __builtin_amdgcn_s_setprio(1); _Pragma("unroll") for (int m = 0; m < 4; ++m) _Pragma("unroll") for (int n = 0; n < 2; ++n) _Pragma("unroll") for (int k = 0; k < 2; ++k) \
;         acc[ai][bj][m][n] = __builtin_amdgcn_mfma_f32_16x16x32_bf16(Bt[n][k], At[m][k], acc[ai][bj][m][n], 0, 0, 0); __builtin_amdgcn_s_setprio(0); } while (0)
; #define PG8_WAIT_V(n) asm volatile("s_waitcnt vmcnt(" #n ")" ::: "memory")
; #define PG8_WAIT_L(n) asm volatile("s_waitcnt lgkmcnt(" #n ")" ::: "memory")
; #define PG8_BAR __builtin_amdgcn_s_barrier()
; #define PG8_SCHED __builtin_amdgcn_sched_barrier(0)
; template <class Epi, class Sched, bool ALIGN_EPI = false, bool SP2 = false>
; __device__ __forceinline__ void gemm_phase(PG8_LAS unsigned char* lds, const Gemm g, const Sched& S, const Epi& E) {
;     ...
;             PG8_WAIT_V(8); PG8_WAIT_L(0); PG8_BAR; PG8_MMA(1, 0, At, B0); PG8_MMA(1, 1, At, B1); PG8_BAR; PG8_SCHED;
;             PG8_LDB(B0, 1, 0); PG8_LDB(B1, 1, 1); PG8_SCHED; PG8_LDA(At, 1, 0); PG8_STAGE(PG8_SA(0, 1), a2 + hstepA, voffA);
;             PG8_WAIT_V(8); PG8_WAIT_L(0); PG8_BAR; PG8_MMA(0, 0, At, B0); PG8_MMA(0, 1, At, B1); PG8_BAR; PG8_SCHED;
	s_setprio 1
	v_mfma_f32_16x16x32_bf16 v[92:95], v[124:127], v[212:215], v[92:95]
	v_mfma_f32_16x16x32_bf16 v[88:91], v[132:135], v[212:215], v[88:91]
	v_mfma_f32_16x16x32_bf16 v[84:87], v[124:127], v[220:223], v[84:87]
	v_mfma_f32_16x16x32_bf16 v[80:83], v[132:135], v[220:223], v[80:83]
	v_mfma_f32_16x16x32_bf16 v[76:79], v[124:127], v[228:231], v[76:79]
	v_mfma_f32_16x16x32_bf16 v[72:75], v[132:135], v[228:231], v[72:75]
	v_mfma_f32_16x16x32_bf16 v[68:71], v[124:127], v[236:239], v[68:71]
	v_mfma_f32_16x16x32_bf16 v[64:67], v[132:135], v[236:239], v[64:67]
	v_mfma_f32_16x16x32_bf16 v[92:95], v[128:131], v[216:219], v[92:95]
	v_mfma_f32_16x16x32_bf16 v[88:91], v[144:147], v[216:219], v[88:91]
	v_mfma_f32_16x16x32_bf16 v[84:87], v[128:131], v[224:227], v[84:87]
	v_mfma_f32_16x16x32_bf16 v[80:83], v[144:147], v[224:227], v[80:83]
	v_mfma_f32_16x16x32_bf16 v[76:79], v[128:131], v[232:235], v[76:79]
	v_mfma_f32_16x16x32_bf16 v[72:75], v[144:147], v[232:235], v[72:75]
	v_mfma_f32_16x16x32_bf16 v[68:71], v[128:131], v[240:243], v[68:71]
	v_mfma_f32_16x16x32_bf16 v[64:67], v[144:147], v[240:243], v[64:67]
	v_mfma_f32_16x16x32_bf16 v[28:31], v[148:151], v[212:215], v[28:31]
	v_mfma_f32_16x16x32_bf16 v[24:27], v[174:177], v[212:215], v[24:27]
	v_mfma_f32_16x16x32_bf16 v[20:23], v[148:151], v[220:223], v[20:23]
	v_mfma_f32_16x16x32_bf16 v[16:19], v[174:177], v[220:223], v[16:19]
	v_mfma_f32_16x16x32_bf16 v[12:15], v[148:151], v[228:231], v[12:15]
	v_mfma_f32_16x16x32_bf16 v[8:11], v[174:177], v[228:231], v[8:11]
	v_mfma_f32_16x16x32_bf16 v[4:7], v[148:151], v[236:239], v[4:7]
	v_mfma_f32_16x16x32_bf16 v[0:3], v[174:177], v[236:239], v[0:3]
	v_mfma_f32_16x16x32_bf16 v[28:31], v[170:173], v[216:219], v[28:31]
	v_mfma_f32_16x16x32_bf16 v[24:27], v[178:181], v[216:219], v[24:27]
	v_mfma_f32_16x16x32_bf16 v[20:23], v[170:173], v[224:227], v[20:23]
	v_mfma_f32_16x16x32_bf16 v[16:19], v[178:181], v[224:227], v[16:19]
	v_mfma_f32_16x16x32_bf16 v[12:15], v[170:173], v[232:235], v[12:15]
	v_mfma_f32_16x16x32_bf16 v[8:11], v[178:181], v[232:235], v[8:11]
	v_mfma_f32_16x16x32_bf16 v[4:7], v[170:173], v[240:243], v[4:7]
	v_mfma_f32_16x16x32_bf16 v[0:3], v[178:181], v[240:243], v[0:3]
	s_setprio 0
	s_barrier
	s_add_i32 s70, 0, 0x18000
	s_add_i32 s71, 0, 0x1c000
	v_add_u32_e32 v144, s70, v185
	v_add_u32_e32 v161, s71, v185
	ds_read_b128 v[124:127], v144
	ds_read_b128 v[128:131], v144 offset:1024
	ds_read_b128 v[132:135], v144 offset:2048
	ds_read_b128 v[144:147], v144 offset:3072
	ds_read_b128 v[148:151], v161
	ds_read_b128 v[170:173], v161 offset:1024
	ds_read_b128 v[174:177], v161 offset:2048
	ds_read_b128 v[178:181], v161 offset:3072
	s_add_u32 s46, s46, 0xb0000
	s_addc_u32 s47, s47, 0
	s_mov_b32 m0, s55
	v_lshl_add_u64 v[246:247], s[46:47], 0, v[152:153]
	ds_read_b128 v[212:215], v191 offset:32768
	ds_read_b128 v[216:219], v191 offset:33792
	ds_read_b128 v[220:223], v191 offset:34816
	ds_read_b128 v[224:227], v191 offset:35840
	ds_read_b128 v[228:231], v191 offset:36864
	ds_read_b128 v[232:235], v191 offset:37888
	ds_read_b128 v[236:239], v191 offset:38912
	ds_read_b128 v[240:243], v191 offset:39936
	global_load_lds_dwordx4 v[246:247], off
	v_lshl_add_u64 v[246:247], s[46:47], 0, v[156:157]
	s_mov_b32 m0, s56
	s_nop 0
	global_load_lds_dwordx4 v[246:247], off
	s_waitcnt vmcnt(8)
	s_waitcnt lgkmcnt(0)
	s_barrier
	s_setprio 1
	v_mfma_f32_16x16x32_bf16 v[140:143], v[124:127], v[212:215], v[140:143]
	v_mfma_f32_16x16x32_bf16 v[136:139], v[132:135], v[212:215], v[136:139]
	v_mfma_f32_16x16x32_bf16 v[116:119], v[124:127], v[220:223], v[116:119]
	v_mfma_f32_16x16x32_bf16 v[112:115], v[132:135], v[220:223], v[112:115]
	v_mfma_f32_16x16x32_bf16 v[108:111], v[124:127], v[228:231], v[108:111]
	v_mfma_f32_16x16x32_bf16 v[104:107], v[132:135], v[228:231], v[104:107]
	v_mfma_f32_16x16x32_bf16 v[100:103], v[124:127], v[236:239], v[100:103]
	v_mfma_f32_16x16x32_bf16 v[96:99], v[132:135], v[236:239], v[96:99]
	v_mfma_f32_16x16x32_bf16 v[140:143], v[128:131], v[216:219], v[140:143]
	v_mfma_f32_16x16x32_bf16 v[136:139], v[144:147], v[216:219], v[136:139]
	v_mfma_f32_16x16x32_bf16 v[116:119], v[128:131], v[224:227], v[116:119]
	v_mfma_f32_16x16x32_bf16 v[112:115], v[144:147], v[224:227], v[112:115]
	v_mfma_f32_16x16x32_bf16 v[108:111], v[128:131], v[232:235], v[108:111]
	v_mfma_f32_16x16x32_bf16 v[104:107], v[144:147], v[232:235], v[104:107]
	v_mfma_f32_16x16x32_bf16 v[100:103], v[128:131], v[240:243], v[100:103]
	v_mfma_f32_16x16x32_bf16 v[96:99], v[144:147], v[240:243], v[96:99]
	v_mfma_f32_16x16x32_bf16 v[60:63], v[148:151], v[212:215], v[60:63]
	v_mfma_f32_16x16x32_bf16 v[56:59], v[174:177], v[212:215], v[56:59]
	v_mfma_f32_16x16x32_bf16 v[52:55], v[148:151], v[220:223], v[52:55]
	v_mfma_f32_16x16x32_bf16 v[48:51], v[174:177], v[220:223], v[48:51]
	v_mfma_f32_16x16x32_bf16 v[44:47], v[148:151], v[228:231], v[44:47]
	v_mfma_f32_16x16x32_bf16 v[40:43], v[174:177], v[228:231], v[40:43]
	v_mfma_f32_16x16x32_bf16 v[36:39], v[148:151], v[236:239], v[36:39]
	v_mfma_f32_16x16x32_bf16 v[32:35], v[174:177], v[236:239], v[32:35]
	v_mfma_f32_16x16x32_bf16 v[60:63], v[170:173], v[216:219], v[60:63]
	v_mfma_f32_16x16x32_bf16 v[56:59], v[178:181], v[216:219], v[56:59]
	v_mfma_f32_16x16x32_bf16 v[52:55], v[170:173], v[224:227], v[52:55]
	v_mfma_f32_16x16x32_bf16 v[48:51], v[178:181], v[224:227], v[48:51]
	v_mfma_f32_16x16x32_bf16 v[44:47], v[170:173], v[232:235], v[44:47]
	v_mfma_f32_16x16x32_bf16 v[40:43], v[178:181], v[232:235], v[40:43]
	v_mfma_f32_16x16x32_bf16 v[36:39], v[170:173], v[240:243], v[36:39]
	v_mfma_f32_16x16x32_bf16 v[32:35], v[178:181], v[240:243], v[32:35]
	s_setprio 0
	s_barrier
; #define PG8_STAGE(bufoff, gbase, voff) do { _Pragma("unroll") for (int _i = 0; _i < 2; ++_i) \
;         __builtin_amdgcn_global_load_lds((const unsigned*)((const char*)(gbase) + (voff)[_i]), (PG8_LAS unsigned*)(lds + (bufoff) + ldsw + _i * 8192), 16, 0, 0); } while (0)
; #define PG8_LDA(dst, b, h) do { _Pragma("unroll") for (int m = 0; m < 4; ++m) _Pragma("unroll") for (int k = 0; k < 2; ++k) dst[m][k] = *(const PG8_LAS bf16x8*)(lds + PG8_SA(b, h) + aoff + m * 2048 + k * 1024); } while (0)
; #define PG8_MMA(ai, bj, At, Bt) do { __builtin_amdgcn_s_setprio(1); _Pragma("unroll") for (int m = 0; m < 4; ++m) _Pragma("unroll") for (int n = 0; n < 2; ++n) _Pragma("unroll") for (int k = 0; k < 2; ++k) \
;         acc[ai][bj][m][n] = __builtin_amdgcn_mfma_f32_16x16x32_bf16(Bt[n][k], At[m][k], acc[ai][bj][m][n], 0, 0, 0); __builtin_amdgcn_s_setprio(0); } while (0)
; #define PG8_WAIT_V(n) asm volatile("s_waitcnt vmcnt(" #n ")" ::: "memory")
; #define PG8_WAIT_L(n) asm volatile("s_waitcnt lgkmcnt(" #n ")" ::: "memory")
; #define PG8_BAR __builtin_amdgcn_s_barrier()
; #define PG8_SCHED __builtin_amdgcn_sched_barrier(0)
; template <class Epi, class Sched, bool ALIGN_EPI = false, bool SP2 = false>
; __device__ __forceinline__ void gemm_phase(PG8_LAS unsigned char* lds, const Gemm g, const Sched& S, const Epi& E) {
;     ...
;         for (int t = 0; t < nt; t += 2) {
;             const bool last = (t == nt - 2);
;     ...
;             PG8_LDA(At, 1, 1); PG8_STAGE(PG8_SB(1, 0), b3, voffB); PG8_STAGE(PG8_SB(1, 1), b3 + hstepB, voffB); PG8_STAGE(PG8_SA(1, 0), a3, voffA);
;             PG8_WAIT_V(8); PG8_WAIT_L(0); PG8_BAR; PG8_MMA(1, 0, At, B0); PG8_MMA(1, 1, At, B1); PG8_BAR; PG8_SCHED;
	s_add_i32 s46, s70, s52
	v_lshl_add_u64 v[206:207], v[206:207], 0, s[26:27]
	s_mov_b32 m0, s46
	ds_read_b128 v[212:215], v191 offset:49152
	ds_read_b128 v[216:219], v191 offset:50176
	ds_read_b128 v[220:223], v191 offset:51200
	ds_read_b128 v[224:227], v191 offset:52224
	ds_read_b128 v[228:231], v191 offset:53248
	ds_read_b128 v[232:235], v191 offset:54272
	ds_read_b128 v[236:239], v191 offset:55296
	ds_read_b128 v[240:243], v191 offset:56320
	global_load_lds_dwordx4 v[206:207], off
	s_add_i32 m0, s46, 0x2000
	s_add_u32 s44, s44, 0xb0080
	v_lshl_add_u64 v[206:207], v[244:245], 0, s[26:27]
	s_addc_u32 s45, s45, 0
	s_add_i32 s46, s71, s52
	global_load_lds_dwordx4 v[206:207], off
	v_lshl_add_u64 v[206:207], s[44:45], 0, v[154:155]
	s_mov_b32 m0, s46
	s_nop 0
	global_load_lds_dwordx4 v[206:207], off
	v_lshl_add_u64 v[206:207], s[44:45], 0, v[158:159]
	s_add_i32 m0, s46, 0x2000
	s_nop 0
	global_load_lds_dwordx4 v[206:207], off
	v_lshl_add_u64 v[206:207], s[42:43], 0, v[152:153]
	s_mov_b32 m0, s63
	s_nop 0
	global_load_lds_dwordx4 v[206:207], off
	v_lshl_add_u64 v[206:207], s[42:43], 0, v[156:157]
	s_mov_b32 m0, s64
	s_nop 0
	global_load_lds_dwordx4 v[206:207], off
	s_waitcnt vmcnt(8)
	s_waitcnt lgkmcnt(0)
	s_barrier
	s_setprio 1
	v_mfma_f32_16x16x32_bf16 v[92:95], v[124:127], v[212:215], v[92:95]
	v_mfma_f32_16x16x32_bf16 v[88:91], v[132:135], v[212:215], v[88:91]
	v_mfma_f32_16x16x32_bf16 v[84:87], v[124:127], v[220:223], v[84:87]
	v_mfma_f32_16x16x32_bf16 v[80:83], v[132:135], v[220:223], v[80:83]
	v_mfma_f32_16x16x32_bf16 v[76:79], v[124:127], v[228:231], v[76:79]
	v_mfma_f32_16x16x32_bf16 v[72:75], v[132:135], v[228:231], v[72:75]
	v_mfma_f32_16x16x32_bf16 v[68:71], v[124:127], v[236:239], v[68:71]
	v_mfma_f32_16x16x32_bf16 v[64:67], v[132:135], v[236:239], v[64:67]
	v_mfma_f32_16x16x32_bf16 v[92:95], v[128:131], v[216:219], v[92:95]
	v_mfma_f32_16x16x32_bf16 v[88:91], v[144:147], v[216:219], v[88:91]
	v_mfma_f32_16x16x32_bf16 v[84:87], v[128:131], v[224:227], v[84:87]
	v_mfma_f32_16x16x32_bf16 v[80:83], v[144:147], v[224:227], v[80:83]
	v_mfma_f32_16x16x32_bf16 v[76:79], v[128:131], v[232:235], v[76:79]
	v_mfma_f32_16x16x32_bf16 v[72:75], v[144:147], v[232:235], v[72:75]
	v_mfma_f32_16x16x32_bf16 v[68:71], v[128:131], v[240:243], v[68:71]
	v_mfma_f32_16x16x32_bf16 v[64:67], v[144:147], v[240:243], v[64:67]
	v_mfma_f32_16x16x32_bf16 v[28:31], v[148:151], v[212:215], v[28:31]
	v_mfma_f32_16x16x32_bf16 v[24:27], v[174:177], v[212:215], v[24:27]
	v_mfma_f32_16x16x32_bf16 v[20:23], v[148:151], v[220:223], v[20:23]
	v_mfma_f32_16x16x32_bf16 v[16:19], v[174:177], v[220:223], v[16:19]
	v_mfma_f32_16x16x32_bf16 v[12:15], v[148:151], v[228:231], v[12:15]
	v_mfma_f32_16x16x32_bf16 v[8:11], v[174:177], v[228:231], v[8:11]
	v_mfma_f32_16x16x32_bf16 v[4:7], v[148:151], v[236:239], v[4:7]
	v_mfma_f32_16x16x32_bf16 v[0:3], v[174:177], v[236:239], v[0:3]
	v_mfma_f32_16x16x32_bf16 v[28:31], v[170:173], v[216:219], v[28:31]
	v_mfma_f32_16x16x32_bf16 v[24:27], v[178:181], v[216:219], v[24:27]
	v_mfma_f32_16x16x32_bf16 v[20:23], v[170:173], v[224:227], v[20:23]
	v_mfma_f32_16x16x32_bf16 v[16:19], v[178:181], v[224:227], v[16:19]
	v_mfma_f32_16x16x32_bf16 v[12:15], v[170:173], v[232:235], v[12:15]
	v_mfma_f32_16x16x32_bf16 v[8:11], v[178:181], v[232:235], v[8:11]
	v_mfma_f32_16x16x32_bf16 v[4:7], v[170:173], v[240:243], v[4:7]
	v_mfma_f32_16x16x32_bf16 v[0:3], v[178:181], v[240:243], v[0:3]
	s_setprio 0
	s_barrier
	s_add_i32 s84, s84, 2
	s_add_u32 s40, s40, 0x100
	s_addc_u32 s41, s41, 0
	s_cmp_gt_u32 s84, 41
	s_cbranch_scc0 .LBB0_1379
	s_and_b64 vcc, exec, s[28:29]
	s_cbranch_vccz .LBB0_1382
	s_barrier

; #define PG8_STAGE(bufoff, gbase, voff) do { _Pragma("unroll") for (int _i = 0; _i < 2; ++_i) \
;         __builtin_amdgcn_global_load_lds((const unsigned*)((const char*)(gbase) + (voff)[_i]), (PG8_LAS unsigned*)(lds + (bufoff) + ldsw + _i * 8192), 16, 0, 0); } while (0)
; #define PG8_LDA(dst, b, h) do { _Pragma("unroll") for (int m = 0; m < 4; ++m) _Pragma("unroll") for (int k = 0; k < 2; ++k) dst[m][k] = *(const PG8_LAS bf16x8*)(lds + PG8_SA(b, h) + aoff + m * 2048 + k * 1024); } while (0)
; #define PG8_LDB(dst, b, h) do { _Pragma("unroll") for (int n = 0; n < 2; ++n) _Pragma("unroll") for (int k = 0; k < 2; ++k) dst[n][k] = *(const PG8_LAS bf16x8*)(lds + PG8_SB(b, h) + boff + n * 2048 + k * 1024); } while (0)
; #define PG8_MMA(ai, bj, At, Bt) do { __builtin_amdgcn_s_setprio(1); _Pragma("unroll") for (int m = 0; m < 4; ++m) _Pragma("unroll") for (int n = 0; n < 2; ++n) _Pragma("unroll") for (int k = 0; k < 2; ++k) \
;         acc[ai][bj][m][n] = __builtin_amdgcn_mfma_f32_16x16x32_bf16(Bt[n][k], At[m][k], acc[ai][bj][m][n], 0, 0, 0); __builtin_amdgcn_s_setprio(0); } while (0)
; #define PG8_WAIT_V(n) asm volatile("s_waitcnt vmcnt(" #n ")" ::: "memory")
; #define PG8_WAIT_L(n) asm volatile("s_waitcnt lgkmcnt(" #n ")" ::: "memory")
; #define PG8_BAR __builtin_amdgcn_s_barrier()
; #define PG8_SCHED __builtin_amdgcn_sched_barrier(0)
; template <class Epi, class Sched, bool ALIGN_EPI = false, bool SP2 = false>
; __device__ __forceinline__ void gemm_phase(PG8_LAS unsigned char* lds, const Gemm g, const Sched& S, const Epi& E) {
;     ...
;             const bool last = (t == nt - 2);
;             const char* a1 = cA + PG8_AK(t + 1);
;             const char* a2 = last ? nA : cA + PG8_AK(t + 2); const char* b2 = last ? nB : cB + (size_t)(t + 2) * kstep;
;             const char* a3 = last ? nA + PG8_AK(1) : cA + PG8_AK(t + 3); const char* b3 = b2 + kstep;
;             if (last && has_next) S.a_ready(nxt);
;             if constexpr (SP2) {
;             PG8_LDB(B0, 0, 0); PG8_LDB(B1, 0, 1); PG8_SCHED; PG8_LDA(At, 0, 0); PG8_STAGE(PG8_SA(1, 1), a1 + hstepA, voffA);
;             PG8_WAIT_V(8); PG8_WAIT_L(0); PG8_BAR; PG8_MMA(0, 0, At, B0); PG8_MMA(0, 1, At, B1); PG8_BAR; PG8_SCHED;
;             PG8_LDA(At, 0, 1); PG8_STAGE(PG8_SB(0, 0), b2, voffB); PG8_STAGE(PG8_SB(0, 1), b2 + hstepB, voffB); PG8_STAGE(PG8_SA(0, 0), a2, voffA);
.LBB0_1471:
	ds_read_b128 v[100:103], v222
	ds_read_b128 v[104:107], v222 offset:1024
	ds_read_b128 v[108:111], v222 offset:2048
	ds_read_b128 v[120:123], v222 offset:3072
	ds_read_b128 v[124:127], v223
	ds_read_b128 v[128:131], v223 offset:1024
	ds_read_b128 v[132:135], v223 offset:2048
	ds_read_b128 v[160:163], v223 offset:3072
	s_add_u32 s44, s40, s42
	s_addc_u32 s45, s41, s43
	s_add_u32 s48, s44, 0x100
	s_addc_u32 s49, s45, 0
	s_add_u32 s46, s83, s42
	s_addc_u32 s47, s84, s43
	s_add_u32 s44, s44, 0x180
	s_addc_u32 s45, s45, 0
	s_cmpk_eq_i32 s42, 0x700
	s_cselect_b32 s45, s82, s45
	s_cselect_b32 s44, s79, s44
	s_cselect_b32 s47, s29, s47
	s_cselect_b32 s46, s78, s46
	s_cselect_b32 s49, s3, s49
	s_cselect_b32 s48, s31, s48
	v_lshl_add_u64 v[200:201], v[98:99], 0, s[42:43]
	s_add_i32 m0, s57, 0xc000
	ds_read_b128 v[164:167], v203
	ds_read_b128 v[168:171], v203 offset:1024
	ds_read_b128 v[192:195], v203 offset:2048
	ds_read_b128 v[196:199], v203 offset:3072
	ds_read_b128 v[224:227], v203 offset:4096
	ds_read_b128 v[228:231], v203 offset:5120
	ds_read_b128 v[232:235], v203 offset:6144
	ds_read_b128 v[236:239], v203 offset:7168
	global_load_lds_dwordx4 v[200:201], off
	v_lshl_add_u64 v[200:201], v[96:97], 0, s[42:43]
	s_add_i32 m0, s57, 0xe000
	s_nop 0
	global_load_lds_dwordx4 v[200:201], off
	s_waitcnt vmcnt(8)
	s_waitcnt lgkmcnt(0)
	s_barrier
	s_setprio 1
	v_mfma_f32_16x16x32_bf16 v[156:159], v[100:103], v[164:167], v[156:159]
	v_mfma_f32_16x16x32_bf16 v[152:155], v[108:111], v[164:167], v[152:155]
	v_mfma_f32_16x16x32_bf16 v[148:151], v[100:103], v[192:195], v[148:151]
	v_mfma_f32_16x16x32_bf16 v[144:147], v[108:111], v[192:195], v[144:147]
	v_mfma_f32_16x16x32_bf16 v[140:143], v[100:103], v[224:227], v[140:143]
	v_mfma_f32_16x16x32_bf16 v[136:139], v[108:111], v[224:227], v[136:139]
	v_mfma_f32_16x16x32_bf16 v[116:119], v[100:103], v[232:235], v[116:119]
	v_mfma_f32_16x16x32_bf16 v[112:115], v[108:111], v[232:235], v[112:115]
	v_mfma_f32_16x16x32_bf16 v[156:159], v[104:107], v[168:171], v[156:159]
	v_mfma_f32_16x16x32_bf16 v[152:155], v[120:123], v[168:171], v[152:155]
	v_mfma_f32_16x16x32_bf16 v[148:151], v[104:107], v[196:199], v[148:151]
	v_mfma_f32_16x16x32_bf16 v[144:147], v[120:123], v[196:199], v[144:147]
	v_mfma_f32_16x16x32_bf16 v[140:143], v[104:107], v[228:231], v[140:143]
	v_mfma_f32_16x16x32_bf16 v[136:139], v[120:123], v[228:231], v[136:139]
	v_mfma_f32_16x16x32_bf16 v[116:119], v[104:107], v[236:239], v[116:119]
	v_mfma_f32_16x16x32_bf16 v[112:115], v[120:123], v[236:239], v[112:115]
	v_mfma_f32_16x16x32_bf16 v[60:63], v[124:127], v[164:167], v[60:63]
	v_mfma_f32_16x16x32_bf16 v[56:59], v[132:135], v[164:167], v[56:59]
	v_mfma_f32_16x16x32_bf16 v[52:55], v[124:127], v[192:195], v[52:55]
	v_mfma_f32_16x16x32_bf16 v[48:51], v[132:135], v[192:195], v[48:51]
	v_mfma_f32_16x16x32_bf16 v[44:47], v[124:127], v[224:227], v[44:47]
	v_mfma_f32_16x16x32_bf16 v[40:43], v[132:135], v[224:227], v[40:43]
	v_mfma_f32_16x16x32_bf16 v[36:39], v[124:127], v[232:235], v[36:39]
	v_mfma_f32_16x16x32_bf16 v[32:35], v[132:135], v[232:235], v[32:35]
	v_mfma_f32_16x16x32_bf16 v[60:63], v[128:131], v[168:171], v[60:63]
	v_mfma_f32_16x16x32_bf16 v[56:59], v[160:163], v[168:171], v[56:59]
	v_mfma_f32_16x16x32_bf16 v[52:55], v[128:131], v[196:199], v[52:55]
	v_mfma_f32_16x16x32_bf16 v[48:51], v[160:163], v[196:199], v[48:51]
	v_mfma_f32_16x16x32_bf16 v[44:47], v[128:131], v[228:231], v[44:47]
	v_mfma_f32_16x16x32_bf16 v[40:43], v[160:163], v[228:231], v[40:43]
	v_mfma_f32_16x16x32_bf16 v[36:39], v[128:131], v[236:239], v[36:39]
	v_mfma_f32_16x16x32_bf16 v[32:35], v[160:163], v[236:239], v[32:35]
	s_setprio 0
	s_barrier
	s_add_i32 s70, s69, s56
	v_lshl_add_u64 v[200:201], s[46:47], 0, v[174:175]
	s_mov_b32 m0, s70
	ds_read_b128 v[164:167], v203 offset:16384
	ds_read_b128 v[168:171], v203 offset:17408
	ds_read_b128 v[192:195], v203 offset:18432
	ds_read_b128 v[196:199], v203 offset:19456
	ds_read_b128 v[224:227], v203 offset:20480
	ds_read_b128 v[228:231], v203 offset:21504
	ds_read_b128 v[232:235], v203 offset:22528
	ds_read_b128 v[236:239], v203 offset:23552
	global_load_lds_dwordx4 v[200:201], off
	s_add_i32 m0, s70, 0x2000
	s_add_u32 s70, s46, 0x40000
	v_lshl_add_u64 v[206:207], s[46:47], 0, v[178:179]
	s_addc_u32 s71, s47, 0
	s_add_i32 s86, s80, s56
	global_load_lds_dwordx4 v[206:207], off
	v_lshl_add_u64 v[240:241], s[70:71], 0, v[174:175]
	s_mov_b32 m0, s86
	s_nop 0
	global_load_lds_dwordx4 v[240:241], off
	v_lshl_add_u64 v[240:241], s[70:71], 0, v[178:179]
	s_add_i32 m0, s86, 0x2000
	s_nop 0
	global_load_lds_dwordx4 v[240:241], off
	v_lshl_add_u64 v[240:241], s[48:49], 0, v[172:173]
	s_mov_b32 m0, s57
	s_nop 0
	global_load_lds_dwordx4 v[240:241], off
	v_lshl_add_u64 v[240:241], s[48:49], 0, v[176:177]
	s_mov_b32 m0, s58
	s_nop 0
	global_load_lds_dwordx4 v[240:241], off
	s_waitcnt vmcnt(8)
	s_waitcnt lgkmcnt(0)
	s_barrier
; #define PG8_STAGE(bufoff, gbase, voff) do { _Pragma("unroll") for (int _i = 0; _i < 2; ++_i) \
;         __builtin_amdgcn_global_load_lds((const unsigned*)((const char*)(gbase) + (voff)[_i]), (PG8_LAS unsigned*)(lds + (bufoff) + ldsw + _i * 8192), 16, 0, 0); } while (0)
; #define PG8_LDA(dst, b, h) do { _Pragma("unroll") for (int m = 0; m < 4; ++m) _Pragma("unroll") for (int k = 0; k < 2; ++k) dst[m][k] = *(const PG8_LAS bf16x8*)(lds + PG8_SA(b, h) + aoff + m * 2048 + k * 1024); } while (0)
; #define PG8_LDB(dst, b, h) do { _Pragma("unroll") for (int n = 0; n < 2; ++n) _Pragma("unroll") for (int k = 0; k < 2; ++k) dst[n][k] = *(const PG8_LAS bf16x8*)(lds + PG8_SB(b, h) + boff + n * 2048 + k * 1024); } while (0)
; #define PG8_MMA(ai, bj, At, Bt) do { __builtin_amdgcn_s_setprio(1); _Pragma("unroll") for (int m = 0; m < 4; ++m) _Pragma("unroll") for (int n = 0; n < 2; ++n) _Pragma("unroll") for (int k = 0; k < 2; ++k) \
;         acc[ai][bj][m][n] = __builtin_amdgcn_mfma_f32_16x16x32_bf16(Bt[n][k], At[m][k], acc[ai][bj][m][n], 0, 0, 0); __builtin_amdgcn_s_setprio(0); } while (0)
; #define PG8_WAIT_V(n) asm volatile("s_waitcnt vmcnt(" #n ")" ::: "memory")
; #define PG8_WAIT_L(n) asm volatile("s_waitcnt lgkmcnt(" #n ")" ::: "memory")
; #define PG8_BAR __builtin_amdgcn_s_barrier()
; #define PG8_SCHED __builtin_amdgcn_sched_barrier(0)
; template <class Epi, class Sched, bool ALIGN_EPI = false, bool SP2 = false>
; __device__ __forceinline__ void gemm_phase(PG8_LAS unsigned char* lds, const Gemm g, const Sched& S, const Epi& E) {
;     ...
;             PG8_WAIT_V(8); PG8_WAIT_L(0); PG8_BAR; PG8_MMA(1, 0, At, B0); PG8_MMA(1, 1, At, B1); PG8_BAR; PG8_SCHED;
;             PG8_LDB(B0, 1, 0); PG8_LDB(B1, 1, 1); PG8_SCHED; PG8_LDA(At, 1, 0); PG8_STAGE(PG8_SA(0, 1), a2 + hstepA, voffA);
;             PG8_WAIT_V(8); PG8_WAIT_L(0); PG8_BAR; PG8_MMA(0, 0, At, B0); PG8_MMA(0, 1, At, B1); PG8_BAR; PG8_SCHED;
	s_setprio 1
	v_mfma_f32_16x16x32_bf16 v[92:95], v[100:103], v[164:167], v[92:95]
	v_mfma_f32_16x16x32_bf16 v[88:91], v[108:111], v[164:167], v[88:91]
	v_mfma_f32_16x16x32_bf16 v[84:87], v[100:103], v[192:195], v[84:87]
	v_mfma_f32_16x16x32_bf16 v[80:83], v[108:111], v[192:195], v[80:83]
	v_mfma_f32_16x16x32_bf16 v[76:79], v[100:103], v[224:227], v[76:79]
	v_mfma_f32_16x16x32_bf16 v[72:75], v[108:111], v[224:227], v[72:75]
	v_mfma_f32_16x16x32_bf16 v[68:71], v[100:103], v[232:235], v[68:71]
	v_mfma_f32_16x16x32_bf16 v[64:67], v[108:111], v[232:235], v[64:67]
	v_mfma_f32_16x16x32_bf16 v[92:95], v[104:107], v[168:171], v[92:95]
	v_mfma_f32_16x16x32_bf16 v[88:91], v[120:123], v[168:171], v[88:91]
	v_mfma_f32_16x16x32_bf16 v[84:87], v[104:107], v[196:199], v[84:87]
	v_mfma_f32_16x16x32_bf16 v[80:83], v[120:123], v[196:199], v[80:83]
	v_mfma_f32_16x16x32_bf16 v[76:79], v[104:107], v[228:231], v[76:79]
	v_mfma_f32_16x16x32_bf16 v[72:75], v[120:123], v[228:231], v[72:75]
	v_mfma_f32_16x16x32_bf16 v[68:71], v[104:107], v[236:239], v[68:71]
	v_mfma_f32_16x16x32_bf16 v[64:67], v[120:123], v[236:239], v[64:67]
	v_mfma_f32_16x16x32_bf16 v[28:31], v[124:127], v[164:167], v[28:31]
	v_mfma_f32_16x16x32_bf16 v[24:27], v[132:135], v[164:167], v[24:27]
	v_mfma_f32_16x16x32_bf16 v[20:23], v[124:127], v[192:195], v[20:23]
	v_mfma_f32_16x16x32_bf16 v[16:19], v[132:135], v[192:195], v[16:19]
	v_mfma_f32_16x16x32_bf16 v[12:15], v[124:127], v[224:227], v[12:15]
	v_mfma_f32_16x16x32_bf16 v[8:11], v[132:135], v[224:227], v[8:11]
	v_mfma_f32_16x16x32_bf16 v[4:7], v[124:127], v[232:235], v[4:7]
	v_mfma_f32_16x16x32_bf16 v[0:3], v[132:135], v[232:235], v[0:3]
	v_mfma_f32_16x16x32_bf16 v[28:31], v[128:131], v[168:171], v[28:31]
	v_mfma_f32_16x16x32_bf16 v[24:27], v[160:163], v[168:171], v[24:27]
	v_mfma_f32_16x16x32_bf16 v[20:23], v[128:131], v[196:199], v[20:23]
	v_mfma_f32_16x16x32_bf16 v[16:19], v[160:163], v[196:199], v[16:19]
	v_mfma_f32_16x16x32_bf16 v[12:15], v[128:131], v[228:231], v[12:15]
	v_mfma_f32_16x16x32_bf16 v[8:11], v[160:163], v[228:231], v[8:11]
	v_mfma_f32_16x16x32_bf16 v[4:7], v[128:131], v[236:239], v[4:7]
	v_mfma_f32_16x16x32_bf16 v[0:3], v[160:163], v[236:239], v[0:3]
	s_setprio 0
	s_barrier
	s_add_i32 s70, 0, 0x18000
	s_add_i32 s71, 0, 0x1c000
	v_add_u32_e32 v120, s70, v189
	v_add_u32_e32 v160, s71, v189
	ds_read_b128 v[100:103], v120
	ds_read_b128 v[104:107], v120 offset:1024
	ds_read_b128 v[108:111], v120 offset:2048
	ds_read_b128 v[120:123], v120 offset:3072
	ds_read_b128 v[124:127], v160
	ds_read_b128 v[128:131], v160 offset:1024
	ds_read_b128 v[132:135], v160 offset:2048
	ds_read_b128 v[160:163], v160 offset:3072
	s_add_u32 s48, s48, 0x40000
	s_addc_u32 s49, s49, 0
	s_mov_b32 m0, s59
	v_lshl_add_u64 v[240:241], s[48:49], 0, v[172:173]
	ds_read_b128 v[164:167], v203 offset:32768
	ds_read_b128 v[168:171], v203 offset:33792
	ds_read_b128 v[192:195], v203 offset:34816
	ds_read_b128 v[196:199], v203 offset:35840
	ds_read_b128 v[224:227], v203 offset:36864
	ds_read_b128 v[228:231], v203 offset:37888
	ds_read_b128 v[232:235], v203 offset:38912
	ds_read_b128 v[236:239], v203 offset:39936
	global_load_lds_dwordx4 v[240:241], off
	v_lshl_add_u64 v[240:241], s[48:49], 0, v[176:177]
	s_mov_b32 m0, s60
	s_nop 0
	global_load_lds_dwordx4 v[240:241], off
	s_waitcnt vmcnt(8)
	s_waitcnt lgkmcnt(0)
	s_barrier
	s_setprio 1
	v_mfma_f32_16x16x32_bf16 v[156:159], v[100:103], v[164:167], v[156:159]
	v_mfma_f32_16x16x32_bf16 v[152:155], v[108:111], v[164:167], v[152:155]
	v_mfma_f32_16x16x32_bf16 v[148:151], v[100:103], v[192:195], v[148:151]
	v_mfma_f32_16x16x32_bf16 v[144:147], v[108:111], v[192:195], v[144:147]
	v_mfma_f32_16x16x32_bf16 v[140:143], v[100:103], v[224:227], v[140:143]
	v_mfma_f32_16x16x32_bf16 v[136:139], v[108:111], v[224:227], v[136:139]
	v_mfma_f32_16x16x32_bf16 v[116:119], v[100:103], v[232:235], v[116:119]
	v_mfma_f32_16x16x32_bf16 v[112:115], v[108:111], v[232:235], v[112:115]
	v_mfma_f32_16x16x32_bf16 v[156:159], v[104:107], v[168:171], v[156:159]
	v_mfma_f32_16x16x32_bf16 v[152:155], v[120:123], v[168:171], v[152:155]
	v_mfma_f32_16x16x32_bf16 v[148:151], v[104:107], v[196:199], v[148:151]
	v_mfma_f32_16x16x32_bf16 v[144:147], v[120:123], v[196:199], v[144:147]
	v_mfma_f32_16x16x32_bf16 v[140:143], v[104:107], v[228:231], v[140:143]
	v_mfma_f32_16x16x32_bf16 v[136:139], v[120:123], v[228:231], v[136:139]
	v_mfma_f32_16x16x32_bf16 v[116:119], v[104:107], v[236:239], v[116:119]
	v_mfma_f32_16x16x32_bf16 v[112:115], v[120:123], v[236:239], v[112:115]
	v_mfma_f32_16x16x32_bf16 v[60:63], v[124:127], v[164:167], v[60:63]
	v_mfma_f32_16x16x32_bf16 v[56:59], v[132:135], v[164:167], v[56:59]
	v_mfma_f32_16x16x32_bf16 v[52:55], v[124:127], v[192:195], v[52:55]
	v_mfma_f32_16x16x32_bf16 v[48:51], v[132:135], v[192:195], v[48:51]
	v_mfma_f32_16x16x32_bf16 v[44:47], v[124:127], v[224:227], v[44:47]
	v_mfma_f32_16x16x32_bf16 v[40:43], v[132:135], v[224:227], v[40:43]
	v_mfma_f32_16x16x32_bf16 v[36:39], v[124:127], v[232:235], v[36:39]
	v_mfma_f32_16x16x32_bf16 v[32:35], v[132:135], v[232:235], v[32:35]
	v_mfma_f32_16x16x32_bf16 v[60:63], v[128:131], v[168:171], v[60:63]
	v_mfma_f32_16x16x32_bf16 v[56:59], v[160:163], v[168:171], v[56:59]
	v_mfma_f32_16x16x32_bf16 v[52:55], v[128:131], v[196:199], v[52:55]
	v_mfma_f32_16x16x32_bf16 v[48:51], v[160:163], v[196:199], v[48:51]
	v_mfma_f32_16x16x32_bf16 v[44:47], v[128:131], v[228:231], v[44:47]
	v_mfma_f32_16x16x32_bf16 v[40:43], v[160:163], v[228:231], v[40:43]
	v_mfma_f32_16x16x32_bf16 v[36:39], v[128:131], v[236:239], v[36:39]
	v_mfma_f32_16x16x32_bf16 v[32:35], v[160:163], v[236:239], v[32:35]
	s_setprio 0
	s_barrier
; #define PG8_STAGE(bufoff, gbase, voff) do { _Pragma("unroll") for (int _i = 0; _i < 2; ++_i) \
;         __builtin_amdgcn_global_load_lds((const unsigned*)((const char*)(gbase) + (voff)[_i]), (PG8_LAS unsigned*)(lds + (bufoff) + ldsw + _i * 8192), 16, 0, 0); } while (0)
; #define PG8_LDA(dst, b, h) do { _Pragma("unroll") for (int m = 0; m < 4; ++m) _Pragma("unroll") for (int k = 0; k < 2; ++k) dst[m][k] = *(const PG8_LAS bf16x8*)(lds + PG8_SA(b, h) + aoff + m * 2048 + k * 1024); } while (0)
; #define PG8_MMA(ai, bj, At, Bt) do { __builtin_amdgcn_s_setprio(1); _Pragma("unroll") for (int m = 0; m < 4; ++m) _Pragma("unroll") for (int n = 0; n < 2; ++n) _Pragma("unroll") for (int k = 0; k < 2; ++k) \
;         acc[ai][bj][m][n] = __builtin_amdgcn_mfma_f32_16x16x32_bf16(Bt[n][k], At[m][k], acc[ai][bj][m][n], 0, 0, 0); __builtin_amdgcn_s_setprio(0); } while (0)
; #define PG8_WAIT_V(n) asm volatile("s_waitcnt vmcnt(" #n ")" ::: "memory")
; #define PG8_WAIT_L(n) asm volatile("s_waitcnt lgkmcnt(" #n ")" ::: "memory")
; #define PG8_BAR __builtin_amdgcn_s_barrier()
; #define PG8_SCHED __builtin_amdgcn_sched_barrier(0)
; template <class Epi, class Sched, bool ALIGN_EPI = false, bool SP2 = false>
; __device__ __forceinline__ void gemm_phase(PG8_LAS unsigned char* lds, const Gemm g, const Sched& S, const Epi& E) {
;     ...
;         for (int t = 0; t < nt; t += 2) {
;             const bool last = (t == nt - 2);
;     ...
;             PG8_LDA(At, 1, 1); PG8_STAGE(PG8_SB(1, 0), b3, voffB); PG8_STAGE(PG8_SB(1, 1), b3 + hstepB, voffB); PG8_STAGE(PG8_SA(1, 0), a3, voffA);
;             PG8_WAIT_V(8); PG8_WAIT_L(0); PG8_BAR; PG8_MMA(1, 0, At, B0); PG8_MMA(1, 1, At, B1); PG8_BAR; PG8_SCHED;
	s_add_i32 s48, s70, s56
	v_lshl_add_u64 v[200:201], v[200:201], 0, s[10:11]
	s_mov_b32 m0, s48
	ds_read_b128 v[164:167], v203 offset:49152
	ds_read_b128 v[168:171], v203 offset:50176
	ds_read_b128 v[192:195], v203 offset:51200
	ds_read_b128 v[196:199], v203 offset:52224
	ds_read_b128 v[224:227], v203 offset:53248
	ds_read_b128 v[228:231], v203 offset:54272
	ds_read_b128 v[232:235], v203 offset:55296
	ds_read_b128 v[236:239], v203 offset:56320
	global_load_lds_dwordx4 v[200:201], off
	s_add_i32 m0, s48, 0x2000
	s_add_u32 s46, s46, 0x40080
	v_lshl_add_u64 v[200:201], v[206:207], 0, s[10:11]
	s_addc_u32 s47, s47, 0
	s_add_i32 s48, s71, s56
	global_load_lds_dwordx4 v[200:201], off
	v_lshl_add_u64 v[200:201], s[46:47], 0, v[174:175]
	s_mov_b32 m0, s48
	s_nop 0
	global_load_lds_dwordx4 v[200:201], off
	v_lshl_add_u64 v[200:201], s[46:47], 0, v[178:179]
	s_add_i32 m0, s48, 0x2000
	s_nop 0
	global_load_lds_dwordx4 v[200:201], off
	v_lshl_add_u64 v[200:201], s[44:45], 0, v[172:173]
	s_mov_b32 m0, s66
	s_nop 0
	global_load_lds_dwordx4 v[200:201], off
	v_lshl_add_u64 v[200:201], s[44:45], 0, v[176:177]
	s_mov_b32 m0, s67
	s_nop 0
	global_load_lds_dwordx4 v[200:201], off
	s_waitcnt vmcnt(8)
	s_waitcnt lgkmcnt(0)
	s_barrier
	s_setprio 1
	v_mfma_f32_16x16x32_bf16 v[92:95], v[100:103], v[164:167], v[92:95]
	v_mfma_f32_16x16x32_bf16 v[88:91], v[108:111], v[164:167], v[88:91]
	v_mfma_f32_16x16x32_bf16 v[84:87], v[100:103], v[192:195], v[84:87]
	v_mfma_f32_16x16x32_bf16 v[80:83], v[108:111], v[192:195], v[80:83]
	v_mfma_f32_16x16x32_bf16 v[76:79], v[100:103], v[224:227], v[76:79]
	v_mfma_f32_16x16x32_bf16 v[72:75], v[108:111], v[224:227], v[72:75]
	v_mfma_f32_16x16x32_bf16 v[68:71], v[100:103], v[232:235], v[68:71]
	v_mfma_f32_16x16x32_bf16 v[64:67], v[108:111], v[232:235], v[64:67]
	v_mfma_f32_16x16x32_bf16 v[92:95], v[104:107], v[168:171], v[92:95]
	v_mfma_f32_16x16x32_bf16 v[88:91], v[120:123], v[168:171], v[88:91]
	v_mfma_f32_16x16x32_bf16 v[84:87], v[104:107], v[196:199], v[84:87]
	v_mfma_f32_16x16x32_bf16 v[80:83], v[120:123], v[196:199], v[80:83]
	v_mfma_f32_16x16x32_bf16 v[76:79], v[104:107], v[228:231], v[76:79]
	v_mfma_f32_16x16x32_bf16 v[72:75], v[120:123], v[228:231], v[72:75]
	v_mfma_f32_16x16x32_bf16 v[68:71], v[104:107], v[236:239], v[68:71]
	v_mfma_f32_16x16x32_bf16 v[64:67], v[120:123], v[236:239], v[64:67]
	v_mfma_f32_16x16x32_bf16 v[28:31], v[124:127], v[164:167], v[28:31]
	v_mfma_f32_16x16x32_bf16 v[24:27], v[132:135], v[164:167], v[24:27]
	v_mfma_f32_16x16x32_bf16 v[20:23], v[124:127], v[192:195], v[20:23]
	v_mfma_f32_16x16x32_bf16 v[16:19], v[132:135], v[192:195], v[16:19]
	v_mfma_f32_16x16x32_bf16 v[12:15], v[124:127], v[224:227], v[12:15]
	v_mfma_f32_16x16x32_bf16 v[8:11], v[132:135], v[224:227], v[8:11]
	v_mfma_f32_16x16x32_bf16 v[4:7], v[124:127], v[232:235], v[4:7]
	v_mfma_f32_16x16x32_bf16 v[0:3], v[132:135], v[232:235], v[0:3]
	v_mfma_f32_16x16x32_bf16 v[28:31], v[128:131], v[168:171], v[28:31]
	v_mfma_f32_16x16x32_bf16 v[24:27], v[160:163], v[168:171], v[24:27]
	v_mfma_f32_16x16x32_bf16 v[20:23], v[128:131], v[196:199], v[20:23]
	v_mfma_f32_16x16x32_bf16 v[16:19], v[160:163], v[196:199], v[16:19]
	v_mfma_f32_16x16x32_bf16 v[12:15], v[128:131], v[228:231], v[12:15]
	v_mfma_f32_16x16x32_bf16 v[8:11], v[160:163], v[228:231], v[8:11]
	v_mfma_f32_16x16x32_bf16 v[4:7], v[128:131], v[236:239], v[4:7]
	v_mfma_f32_16x16x32_bf16 v[0:3], v[160:163], v[236:239], v[0:3]
	s_setprio 0
	s_barrier
	s_add_i32 s85, s85, 2
	s_add_u32 s42, s42, 0x100
	s_addc_u32 s43, s43, 0
	s_cmp_gt_u32 s85, 13
	s_cbranch_scc0 .LBB0_1471
	s_and_b64 vcc, exec, s[24:25]
	s_cbranch_vccz .LBB0_1474
	s_barrier

; #define PG8_STAGE(bufoff, gbase, voff) do { _Pragma("unroll") for (int _i = 0; _i < 2; ++_i) \
;         __builtin_amdgcn_global_load_lds((const unsigned*)((const char*)(gbase) + (voff)[_i]), (PG8_LAS unsigned*)(lds + (bufoff) + ldsw + _i * 8192), 16, 0, 0); } while (0)
; #define PG8_LDA(dst, b, h) do { _Pragma("unroll") for (int m = 0; m < 4; ++m) _Pragma("unroll") for (int k = 0; k < 2; ++k) dst[m][k] = *(const PG8_LAS bf16x8*)(lds + PG8_SA(b, h) + aoff + m * 2048 + k * 1024); } while (0)
; #define PG8_LDB(dst, b, h) do { _Pragma("unroll") for (int n = 0; n < 2; ++n) _Pragma("unroll") for (int k = 0; k < 2; ++k) dst[n][k] = *(const PG8_LAS bf16x8*)(lds + PG8_SB(b, h) + boff + n * 2048 + k * 1024); } while (0)
; #define PG8_MMA(ai, bj, At, Bt) do { __builtin_amdgcn_s_setprio(1); _Pragma("unroll") for (int m = 0; m < 4; ++m) _Pragma("unroll") for (int n = 0; n < 2; ++n) _Pragma("unroll") for (int k = 0; k < 2; ++k) \
;         acc[ai][bj][m][n] = __builtin_amdgcn_mfma_f32_16x16x32_bf16(Bt[n][k], At[m][k], acc[ai][bj][m][n], 0, 0, 0); __builtin_amdgcn_s_setprio(0); } while (0)
; #define PG8_WAIT_V(n) asm volatile("s_waitcnt vmcnt(" #n ")" ::: "memory")
; #define PG8_WAIT_L(n) asm volatile("s_waitcnt lgkmcnt(" #n ")" ::: "memory")
; #define PG8_BAR __builtin_amdgcn_s_barrier()
; #define PG8_SCHED __builtin_amdgcn_sched_barrier(0)
; template <class Epi, class Sched, bool ALIGN_EPI = false, bool SP2 = false>
; __device__ __forceinline__ void gemm_phase(PG8_LAS unsigned char* lds, const Gemm g, const Sched& S, const Epi& E) {
;     ...
;             const bool last = (t == nt - 2);
;             const char* a1 = cA + PG8_AK(t + 1);
;             const char* a2 = last ? nA : cA + PG8_AK(t + 2); const char* b2 = last ? nB : cB + (size_t)(t + 2) * kstep;
;             const char* a3 = last ? nA + PG8_AK(1) : cA + PG8_AK(t + 3); const char* b3 = b2 + kstep;
;             if (last && has_next) S.a_ready(nxt);
;             if constexpr (SP2) {
;             PG8_LDB(B0, 0, 0); PG8_LDB(B1, 0, 1); PG8_SCHED; PG8_LDA(At, 0, 0); PG8_STAGE(PG8_SA(1, 1), a1 + hstepA, voffA);
;             PG8_WAIT_V(8); PG8_WAIT_L(0); PG8_BAR; PG8_MMA(0, 0, At, B0); PG8_MMA(0, 1, At, B1); PG8_BAR; PG8_SCHED;
;             PG8_LDA(At, 0, 1); PG8_STAGE(PG8_SB(0, 0), b2, voffB); PG8_STAGE(PG8_SB(0, 1), b2 + hstepB, voffB); PG8_STAGE(PG8_SA(0, 0), a2, voffA);
.LBB0_1638:
	ds_read_b128 v[132:135], v172
	ds_read_b128 v[158:161], v172 offset:1024
	ds_read_b128 v[176:179], v172 offset:2048
	ds_read_b128 v[180:183], v172 offset:3072
	ds_read_b128 v[184:187], v173
	ds_read_b128 v[188:191], v173 offset:1024
	ds_read_b128 v[192:195], v173 offset:2048
	ds_read_b128 v[196:199], v173 offset:3072
	s_add_u32 s38, s28, s34
	s_addc_u32 s39, s29, s35
	s_add_u32 s42, s38, 0x100
	s_addc_u32 s43, s39, 0
	s_add_u32 s40, s62, s34
	s_addc_u32 s41, s63, s35
	s_add_u32 s38, s38, 0x180
	s_addc_u32 s39, s39, 0
	s_cmpk_eq_i32 s34, 0x700
	s_cselect_b32 s39, s37, s39
	s_cselect_b32 s38, s31, s38
	s_cselect_b32 s41, s21, s41
	s_cselect_b32 s40, s23, s40
	s_cselect_b32 s43, s3, s43
	s_cselect_b32 s42, s10, s42
	v_lshl_add_u64 v[232:233], v[130:131], 0, s[34:35]
	s_add_i32 m0, s49, 0xc000
	ds_read_b128 v[200:203], v174
	ds_read_b128 v[204:207], v174 offset:1024
	ds_read_b128 v[208:211], v174 offset:2048
	ds_read_b128 v[212:215], v174 offset:3072
	ds_read_b128 v[216:219], v174 offset:4096
	ds_read_b128 v[220:223], v174 offset:5120
	ds_read_b128 v[224:227], v174 offset:6144
	ds_read_b128 v[228:231], v174 offset:7168
	global_load_lds_dwordx4 v[232:233], off
	v_lshl_add_u64 v[232:233], v[128:129], 0, s[34:35]
	s_add_i32 m0, s49, 0xe000
	s_nop 0
	global_load_lds_dwordx4 v[232:233], off
	s_waitcnt vmcnt(8)
	s_waitcnt lgkmcnt(0)
	s_barrier
	s_setprio 1
	v_mfma_f32_16x16x32_bf16 v[124:127], v[132:135], v[200:203], v[124:127]
	v_mfma_f32_16x16x32_bf16 v[120:123], v[176:179], v[200:203], v[120:123]
	v_mfma_f32_16x16x32_bf16 v[108:111], v[132:135], v[208:211], v[108:111]
	v_mfma_f32_16x16x32_bf16 v[104:107], v[176:179], v[208:211], v[104:107]
	v_mfma_f32_16x16x32_bf16 v[92:95], v[132:135], v[216:219], v[92:95]
	v_mfma_f32_16x16x32_bf16 v[88:91], v[176:179], v[216:219], v[88:91]
	v_mfma_f32_16x16x32_bf16 v[76:79], v[132:135], v[224:227], v[76:79]
	v_mfma_f32_16x16x32_bf16 v[72:75], v[176:179], v[224:227], v[72:75]
	v_mfma_f32_16x16x32_bf16 v[124:127], v[158:161], v[204:207], v[124:127]
	v_mfma_f32_16x16x32_bf16 v[120:123], v[180:183], v[204:207], v[120:123]
	v_mfma_f32_16x16x32_bf16 v[108:111], v[158:161], v[212:215], v[108:111]
	v_mfma_f32_16x16x32_bf16 v[104:107], v[180:183], v[212:215], v[104:107]
	v_mfma_f32_16x16x32_bf16 v[92:95], v[158:161], v[220:223], v[92:95]
	v_mfma_f32_16x16x32_bf16 v[88:91], v[180:183], v[220:223], v[88:91]
	v_mfma_f32_16x16x32_bf16 v[76:79], v[158:161], v[228:231], v[76:79]
	v_mfma_f32_16x16x32_bf16 v[72:75], v[180:183], v[228:231], v[72:75]
	v_mfma_f32_16x16x32_bf16 v[116:119], v[184:187], v[200:203], v[116:119]
	v_mfma_f32_16x16x32_bf16 v[112:115], v[192:195], v[200:203], v[112:115]
	v_mfma_f32_16x16x32_bf16 v[100:103], v[184:187], v[208:211], v[100:103]
	v_mfma_f32_16x16x32_bf16 v[96:99], v[192:195], v[208:211], v[96:99]
	v_mfma_f32_16x16x32_bf16 v[84:87], v[184:187], v[216:219], v[84:87]
	v_mfma_f32_16x16x32_bf16 v[80:83], v[192:195], v[216:219], v[80:83]
	v_mfma_f32_16x16x32_bf16 v[68:71], v[184:187], v[224:227], v[68:71]
	v_mfma_f32_16x16x32_bf16 v[64:67], v[192:195], v[224:227], v[64:67]
	v_mfma_f32_16x16x32_bf16 v[116:119], v[188:191], v[204:207], v[116:119]
	v_mfma_f32_16x16x32_bf16 v[112:115], v[196:199], v[204:207], v[112:115]
	v_mfma_f32_16x16x32_bf16 v[100:103], v[188:191], v[212:215], v[100:103]
	v_mfma_f32_16x16x32_bf16 v[96:99], v[196:199], v[212:215], v[96:99]
	v_mfma_f32_16x16x32_bf16 v[84:87], v[188:191], v[220:223], v[84:87]
	v_mfma_f32_16x16x32_bf16 v[80:83], v[196:199], v[220:223], v[80:83]
	v_mfma_f32_16x16x32_bf16 v[68:71], v[188:191], v[228:231], v[68:71]
	v_mfma_f32_16x16x32_bf16 v[64:67], v[196:199], v[228:231], v[64:67]
	s_setprio 0
	s_barrier
	s_add_i32 s65, s58, s48
	v_lshl_add_u64 v[232:233], s[40:41], 0, v[138:139]
	s_mov_b32 m0, s65
	ds_read_b128 v[200:203], v174 offset:16384
	ds_read_b128 v[204:207], v174 offset:17408
	ds_read_b128 v[208:211], v174 offset:18432
	ds_read_b128 v[212:215], v174 offset:19456
	ds_read_b128 v[216:219], v174 offset:20480
	ds_read_b128 v[220:223], v174 offset:21504
	ds_read_b128 v[224:227], v174 offset:22528
	ds_read_b128 v[228:231], v174 offset:23552
	global_load_lds_dwordx4 v[232:233], off
	s_add_i32 m0, s65, 0x2000
	s_add_u32 s66, s40, 0x40000
	v_lshl_add_u64 v[234:235], s[40:41], 0, v[142:143]
	s_addc_u32 s67, s41, 0
	s_add_i32 s65, s59, s48
	global_load_lds_dwordx4 v[234:235], off
	v_lshl_add_u64 v[236:237], s[66:67], 0, v[138:139]
	s_mov_b32 m0, s65
	s_nop 0
	global_load_lds_dwordx4 v[236:237], off
	v_lshl_add_u64 v[236:237], s[66:67], 0, v[142:143]
	s_add_i32 m0, s65, 0x2000
	s_nop 0
	global_load_lds_dwordx4 v[236:237], off
	v_lshl_add_u64 v[236:237], s[42:43], 0, v[136:137]
	s_mov_b32 m0, s49
	s_nop 0
	global_load_lds_dwordx4 v[236:237], off
	v_lshl_add_u64 v[236:237], s[42:43], 0, v[140:141]
	s_mov_b32 m0, s50
	s_nop 0
	global_load_lds_dwordx4 v[236:237], off
	s_waitcnt vmcnt(8)
	s_waitcnt lgkmcnt(0)
	s_barrier
; #define PG8_STAGE(bufoff, gbase, voff) do { _Pragma("unroll") for (int _i = 0; _i < 2; ++_i) \
;         __builtin_amdgcn_global_load_lds((const unsigned*)((const char*)(gbase) + (voff)[_i]), (PG8_LAS unsigned*)(lds + (bufoff) + ldsw + _i * 8192), 16, 0, 0); } while (0)
; #define PG8_LDA(dst, b, h) do { _Pragma("unroll") for (int m = 0; m < 4; ++m) _Pragma("unroll") for (int k = 0; k < 2; ++k) dst[m][k] = *(const PG8_LAS bf16x8*)(lds + PG8_SA(b, h) + aoff + m * 2048 + k * 1024); } while (0)
; #define PG8_LDB(dst, b, h) do { _Pragma("unroll") for (int n = 0; n < 2; ++n) _Pragma("unroll") for (int k = 0; k < 2; ++k) dst[n][k] = *(const PG8_LAS bf16x8*)(lds + PG8_SB(b, h) + boff + n * 2048 + k * 1024); } while (0)
; #define PG8_MMA(ai, bj, At, Bt) do { __builtin_amdgcn_s_setprio(1); _Pragma("unroll") for (int m = 0; m < 4; ++m) _Pragma("unroll") for (int n = 0; n < 2; ++n) _Pragma("unroll") for (int k = 0; k < 2; ++k) \
;         acc[ai][bj][m][n] = __builtin_amdgcn_mfma_f32_16x16x32_bf16(Bt[n][k], At[m][k], acc[ai][bj][m][n], 0, 0, 0); __builtin_amdgcn_s_setprio(0); } while (0)
; #define PG8_WAIT_V(n) asm volatile("s_waitcnt vmcnt(" #n ")" ::: "memory")
; #define PG8_WAIT_L(n) asm volatile("s_waitcnt lgkmcnt(" #n ")" ::: "memory")
; #define PG8_BAR __builtin_amdgcn_s_barrier()
; #define PG8_SCHED __builtin_amdgcn_sched_barrier(0)
; template <class Epi, class Sched, bool ALIGN_EPI = false, bool SP2 = false>
; __device__ __forceinline__ void gemm_phase(PG8_LAS unsigned char* lds, const Gemm g, const Sched& S, const Epi& E) {
;     ...
;             PG8_WAIT_V(8); PG8_WAIT_L(0); PG8_BAR; PG8_MMA(1, 0, At, B0); PG8_MMA(1, 1, At, B1); PG8_BAR; PG8_SCHED;
;             PG8_LDB(B0, 1, 0); PG8_LDB(B1, 1, 1); PG8_SCHED; PG8_LDA(At, 1, 0); PG8_STAGE(PG8_SA(0, 1), a2 + hstepA, voffA);
;             PG8_WAIT_V(8); PG8_WAIT_L(0); PG8_BAR; PG8_MMA(0, 0, At, B0); PG8_MMA(0, 1, At, B1); PG8_BAR; PG8_SCHED;
	s_setprio 1
	v_mfma_f32_16x16x32_bf16 v[60:63], v[132:135], v[200:203], v[60:63]
	v_mfma_f32_16x16x32_bf16 v[56:59], v[176:179], v[200:203], v[56:59]
	v_mfma_f32_16x16x32_bf16 v[44:47], v[132:135], v[208:211], v[44:47]
	v_mfma_f32_16x16x32_bf16 v[40:43], v[176:179], v[208:211], v[40:43]
	v_mfma_f32_16x16x32_bf16 v[28:31], v[132:135], v[216:219], v[28:31]
	v_mfma_f32_16x16x32_bf16 v[24:27], v[176:179], v[216:219], v[24:27]
	v_mfma_f32_16x16x32_bf16 v[12:15], v[132:135], v[224:227], v[12:15]
	v_mfma_f32_16x16x32_bf16 v[8:11], v[176:179], v[224:227], v[8:11]
	v_mfma_f32_16x16x32_bf16 v[60:63], v[158:161], v[204:207], v[60:63]
	v_mfma_f32_16x16x32_bf16 v[56:59], v[180:183], v[204:207], v[56:59]
	v_mfma_f32_16x16x32_bf16 v[44:47], v[158:161], v[212:215], v[44:47]
	v_mfma_f32_16x16x32_bf16 v[40:43], v[180:183], v[212:215], v[40:43]
	v_mfma_f32_16x16x32_bf16 v[28:31], v[158:161], v[220:223], v[28:31]
	v_mfma_f32_16x16x32_bf16 v[24:27], v[180:183], v[220:223], v[24:27]
	v_mfma_f32_16x16x32_bf16 v[12:15], v[158:161], v[228:231], v[12:15]
	v_mfma_f32_16x16x32_bf16 v[8:11], v[180:183], v[228:231], v[8:11]
	v_mfma_f32_16x16x32_bf16 v[52:55], v[184:187], v[200:203], v[52:55]
	v_mfma_f32_16x16x32_bf16 v[48:51], v[192:195], v[200:203], v[48:51]
	v_mfma_f32_16x16x32_bf16 v[36:39], v[184:187], v[208:211], v[36:39]
	v_mfma_f32_16x16x32_bf16 v[32:35], v[192:195], v[208:211], v[32:35]
	v_mfma_f32_16x16x32_bf16 v[20:23], v[184:187], v[216:219], v[20:23]
	v_mfma_f32_16x16x32_bf16 v[16:19], v[192:195], v[216:219], v[16:19]
	v_mfma_f32_16x16x32_bf16 v[4:7], v[184:187], v[224:227], v[4:7]
	v_mfma_f32_16x16x32_bf16 v[0:3], v[192:195], v[224:227], v[0:3]
	v_mfma_f32_16x16x32_bf16 v[52:55], v[188:191], v[204:207], v[52:55]
	v_mfma_f32_16x16x32_bf16 v[48:51], v[196:199], v[204:207], v[48:51]
	v_mfma_f32_16x16x32_bf16 v[36:39], v[188:191], v[212:215], v[36:39]
	v_mfma_f32_16x16x32_bf16 v[32:35], v[196:199], v[212:215], v[32:35]
	v_mfma_f32_16x16x32_bf16 v[20:23], v[188:191], v[220:223], v[20:23]
	v_mfma_f32_16x16x32_bf16 v[16:19], v[196:199], v[220:223], v[16:19]
	v_mfma_f32_16x16x32_bf16 v[4:7], v[188:191], v[228:231], v[4:7]
	v_mfma_f32_16x16x32_bf16 v[0:3], v[196:199], v[228:231], v[0:3]
	s_setprio 0
	s_barrier
	s_add_i32 s65, 0, 0x18000
	v_add_u32_e32 v144, s65, v163
	s_add_i32 s66, 0, 0x1c000
	ds_read_b128 v[132:135], v144
	ds_read_b128 v[158:161], v144 offset:1024
	ds_read_b128 v[176:179], v144 offset:2048
	ds_read_b128 v[180:183], v144 offset:3072
	v_add_u32_e32 v144, s66, v163
	ds_read_b128 v[184:187], v144
	ds_read_b128 v[188:191], v144 offset:1024
	ds_read_b128 v[192:195], v144 offset:2048
	ds_read_b128 v[196:199], v144 offset:3072
	s_add_u32 s42, s42, 0x40000
	s_addc_u32 s43, s43, 0
	s_mov_b32 m0, s51
	v_lshl_add_u64 v[236:237], s[42:43], 0, v[136:137]
	ds_read_b128 v[200:203], v174 offset:32768
	ds_read_b128 v[204:207], v174 offset:33792
	ds_read_b128 v[208:211], v174 offset:34816
	ds_read_b128 v[212:215], v174 offset:35840
	ds_read_b128 v[216:219], v174 offset:36864
	ds_read_b128 v[220:223], v174 offset:37888
	ds_read_b128 v[224:227], v174 offset:38912
	ds_read_b128 v[228:231], v174 offset:39936
	global_load_lds_dwordx4 v[236:237], off
	v_lshl_add_u64 v[236:237], s[42:43], 0, v[140:141]
	s_mov_b32 m0, s52
	s_nop 0
	global_load_lds_dwordx4 v[236:237], off
	s_waitcnt vmcnt(8)
	s_waitcnt lgkmcnt(0)
	s_barrier
	s_setprio 1
	v_mfma_f32_16x16x32_bf16 v[124:127], v[132:135], v[200:203], v[124:127]
	v_mfma_f32_16x16x32_bf16 v[120:123], v[176:179], v[200:203], v[120:123]
	v_mfma_f32_16x16x32_bf16 v[108:111], v[132:135], v[208:211], v[108:111]
	v_mfma_f32_16x16x32_bf16 v[104:107], v[176:179], v[208:211], v[104:107]
	v_mfma_f32_16x16x32_bf16 v[92:95], v[132:135], v[216:219], v[92:95]
	v_mfma_f32_16x16x32_bf16 v[88:91], v[176:179], v[216:219], v[88:91]
	v_mfma_f32_16x16x32_bf16 v[76:79], v[132:135], v[224:227], v[76:79]
	v_mfma_f32_16x16x32_bf16 v[72:75], v[176:179], v[224:227], v[72:75]
	v_mfma_f32_16x16x32_bf16 v[124:127], v[158:161], v[204:207], v[124:127]
	v_mfma_f32_16x16x32_bf16 v[120:123], v[180:183], v[204:207], v[120:123]
	v_mfma_f32_16x16x32_bf16 v[108:111], v[158:161], v[212:215], v[108:111]
	v_mfma_f32_16x16x32_bf16 v[104:107], v[180:183], v[212:215], v[104:107]
	v_mfma_f32_16x16x32_bf16 v[92:95], v[158:161], v[220:223], v[92:95]
	v_mfma_f32_16x16x32_bf16 v[88:91], v[180:183], v[220:223], v[88:91]
	v_mfma_f32_16x16x32_bf16 v[76:79], v[158:161], v[228:231], v[76:79]
	v_mfma_f32_16x16x32_bf16 v[72:75], v[180:183], v[228:231], v[72:75]
	v_mfma_f32_16x16x32_bf16 v[116:119], v[184:187], v[200:203], v[116:119]
	v_mfma_f32_16x16x32_bf16 v[112:115], v[192:195], v[200:203], v[112:115]
	v_mfma_f32_16x16x32_bf16 v[100:103], v[184:187], v[208:211], v[100:103]
	v_mfma_f32_16x16x32_bf16 v[96:99], v[192:195], v[208:211], v[96:99]
	v_mfma_f32_16x16x32_bf16 v[84:87], v[184:187], v[216:219], v[84:87]
	v_mfma_f32_16x16x32_bf16 v[80:83], v[192:195], v[216:219], v[80:83]
	v_mfma_f32_16x16x32_bf16 v[68:71], v[184:187], v[224:227], v[68:71]
	v_mfma_f32_16x16x32_bf16 v[64:67], v[192:195], v[224:227], v[64:67]
	v_mfma_f32_16x16x32_bf16 v[116:119], v[188:191], v[204:207], v[116:119]
	v_mfma_f32_16x16x32_bf16 v[112:115], v[196:199], v[204:207], v[112:115]
	v_mfma_f32_16x16x32_bf16 v[100:103], v[188:191], v[212:215], v[100:103]
	v_mfma_f32_16x16x32_bf16 v[96:99], v[196:199], v[212:215], v[96:99]
	v_mfma_f32_16x16x32_bf16 v[84:87], v[188:191], v[220:223], v[84:87]
	v_mfma_f32_16x16x32_bf16 v[80:83], v[196:199], v[220:223], v[80:83]
	v_mfma_f32_16x16x32_bf16 v[68:71], v[188:191], v[228:231], v[68:71]
	v_mfma_f32_16x16x32_bf16 v[64:67], v[196:199], v[228:231], v[64:67]
	s_setprio 0
	s_barrier
; #define PG8_STAGE(bufoff, gbase, voff) do { _Pragma("unroll") for (int _i = 0; _i < 2; ++_i) \
;         __builtin_amdgcn_global_load_lds((const unsigned*)((const char*)(gbase) + (voff)[_i]), (PG8_LAS unsigned*)(lds + (bufoff) + ldsw + _i * 8192), 16, 0, 0); } while (0)
; #define PG8_LDA(dst, b, h) do { _Pragma("unroll") for (int m = 0; m < 4; ++m) _Pragma("unroll") for (int k = 0; k < 2; ++k) dst[m][k] = *(const PG8_LAS bf16x8*)(lds + PG8_SA(b, h) + aoff + m * 2048 + k * 1024); } while (0)
; #define PG8_MMA(ai, bj, At, Bt) do { __builtin_amdgcn_s_setprio(1); _Pragma("unroll") for (int m = 0; m < 4; ++m) _Pragma("unroll") for (int n = 0; n < 2; ++n) _Pragma("unroll") for (int k = 0; k < 2; ++k) \
;         acc[ai][bj][m][n] = __builtin_amdgcn_mfma_f32_16x16x32_bf16(Bt[n][k], At[m][k], acc[ai][bj][m][n], 0, 0, 0); __builtin_amdgcn_s_setprio(0); } while (0)
; #define PG8_WAIT_V(n) asm volatile("s_waitcnt vmcnt(" #n ")" ::: "memory")
; #define PG8_WAIT_L(n) asm volatile("s_waitcnt lgkmcnt(" #n ")" ::: "memory")
; #define PG8_BAR __builtin_amdgcn_s_barrier()
; #define PG8_SCHED __builtin_amdgcn_sched_barrier(0)
; template <class Epi, class Sched, bool ALIGN_EPI = false, bool SP2 = false>
; __device__ __forceinline__ void gemm_phase(PG8_LAS unsigned char* lds, const Gemm g, const Sched& S, const Epi& E) {
;     ...
;         for (int t = 0; t < nt; t += 2) {
;             const bool last = (t == nt - 2);
;     ...
;             PG8_LDA(At, 1, 1); PG8_STAGE(PG8_SB(1, 0), b3, voffB); PG8_STAGE(PG8_SB(1, 1), b3 + hstepB, voffB); PG8_STAGE(PG8_SA(1, 0), a3, voffA);
;             PG8_WAIT_V(8); PG8_WAIT_L(0); PG8_BAR; PG8_MMA(1, 0, At, B0); PG8_MMA(1, 1, At, B1); PG8_BAR; PG8_SCHED;
	s_add_i32 s42, s65, s48
	v_lshl_add_u64 v[232:233], v[232:233], 0, s[14:15]
	s_mov_b32 m0, s42
	ds_read_b128 v[200:203], v174 offset:49152
	ds_read_b128 v[204:207], v174 offset:50176
	ds_read_b128 v[208:211], v174 offset:51200
	ds_read_b128 v[212:215], v174 offset:52224
	ds_read_b128 v[216:219], v174 offset:53248
	ds_read_b128 v[220:223], v174 offset:54272
	ds_read_b128 v[224:227], v174 offset:55296
	ds_read_b128 v[228:231], v174 offset:56320
	global_load_lds_dwordx4 v[232:233], off
	s_add_i32 m0, s42, 0x2000
	s_add_u32 s40, s40, 0x40080
	v_lshl_add_u64 v[232:233], v[234:235], 0, s[14:15]
	s_addc_u32 s41, s41, 0
	s_add_i32 s42, s66, s48
	global_load_lds_dwordx4 v[232:233], off
	v_lshl_add_u64 v[232:233], s[40:41], 0, v[138:139]
	s_mov_b32 m0, s42
	s_nop 0
	global_load_lds_dwordx4 v[232:233], off
	v_lshl_add_u64 v[232:233], s[40:41], 0, v[142:143]
	s_add_i32 m0, s42, 0x2000
	s_nop 0
	global_load_lds_dwordx4 v[232:233], off
	v_lshl_add_u64 v[232:233], s[38:39], 0, v[136:137]
	s_mov_b32 m0, s53
	s_nop 0
	global_load_lds_dwordx4 v[232:233], off
	v_lshl_add_u64 v[232:233], s[38:39], 0, v[140:141]
	s_mov_b32 m0, s54
	s_nop 0
	global_load_lds_dwordx4 v[232:233], off
	s_waitcnt vmcnt(8)
	s_waitcnt lgkmcnt(0)
	s_barrier
	s_setprio 1
	v_mfma_f32_16x16x32_bf16 v[60:63], v[132:135], v[200:203], v[60:63]
	v_mfma_f32_16x16x32_bf16 v[56:59], v[176:179], v[200:203], v[56:59]
	v_mfma_f32_16x16x32_bf16 v[44:47], v[132:135], v[208:211], v[44:47]
	v_mfma_f32_16x16x32_bf16 v[40:43], v[176:179], v[208:211], v[40:43]
	v_mfma_f32_16x16x32_bf16 v[28:31], v[132:135], v[216:219], v[28:31]
	v_mfma_f32_16x16x32_bf16 v[24:27], v[176:179], v[216:219], v[24:27]
	v_mfma_f32_16x16x32_bf16 v[12:15], v[132:135], v[224:227], v[12:15]
	v_mfma_f32_16x16x32_bf16 v[8:11], v[176:179], v[224:227], v[8:11]
	v_mfma_f32_16x16x32_bf16 v[60:63], v[158:161], v[204:207], v[60:63]
	v_mfma_f32_16x16x32_bf16 v[56:59], v[180:183], v[204:207], v[56:59]
	v_mfma_f32_16x16x32_bf16 v[44:47], v[158:161], v[212:215], v[44:47]
	v_mfma_f32_16x16x32_bf16 v[40:43], v[180:183], v[212:215], v[40:43]
	v_mfma_f32_16x16x32_bf16 v[28:31], v[158:161], v[220:223], v[28:31]
	v_mfma_f32_16x16x32_bf16 v[24:27], v[180:183], v[220:223], v[24:27]
	v_mfma_f32_16x16x32_bf16 v[12:15], v[158:161], v[228:231], v[12:15]
	v_mfma_f32_16x16x32_bf16 v[8:11], v[180:183], v[228:231], v[8:11]
	v_mfma_f32_16x16x32_bf16 v[52:55], v[184:187], v[200:203], v[52:55]
	v_mfma_f32_16x16x32_bf16 v[48:51], v[192:195], v[200:203], v[48:51]
	v_mfma_f32_16x16x32_bf16 v[36:39], v[184:187], v[208:211], v[36:39]
	v_mfma_f32_16x16x32_bf16 v[32:35], v[192:195], v[208:211], v[32:35]
	v_mfma_f32_16x16x32_bf16 v[20:23], v[184:187], v[216:219], v[20:23]
	v_mfma_f32_16x16x32_bf16 v[16:19], v[192:195], v[216:219], v[16:19]
	v_mfma_f32_16x16x32_bf16 v[4:7], v[184:187], v[224:227], v[4:7]
	v_mfma_f32_16x16x32_bf16 v[0:3], v[192:195], v[224:227], v[0:3]
	v_mfma_f32_16x16x32_bf16 v[52:55], v[188:191], v[204:207], v[52:55]
	v_mfma_f32_16x16x32_bf16 v[48:51], v[196:199], v[204:207], v[48:51]
	v_mfma_f32_16x16x32_bf16 v[36:39], v[188:191], v[212:215], v[36:39]
	v_mfma_f32_16x16x32_bf16 v[32:35], v[196:199], v[212:215], v[32:35]
	v_mfma_f32_16x16x32_bf16 v[20:23], v[188:191], v[220:223], v[20:23]
	v_mfma_f32_16x16x32_bf16 v[16:19], v[196:199], v[220:223], v[16:19]
	v_mfma_f32_16x16x32_bf16 v[4:7], v[188:191], v[228:231], v[4:7]
	v_mfma_f32_16x16x32_bf16 v[0:3], v[196:199], v[228:231], v[0:3]
	s_setprio 0
	s_barrier
	s_add_i32 s64, s64, 2
	s_add_u32 s34, s34, 0x100
	s_addc_u32 s35, s35, 0
	s_cmp_gt_u32 s64, 13
	s_cbranch_scc0 .LBB0_1638
	s_and_b64 vcc, exec, s[16:17]
	s_cbranch_vccz .LBB0_1643
	s_barrier
	s_cmp_gt_i32 s30, 3
	s_mov_b64 s[28:29], -1
	s_cbranch_scc1 .LBB0_1644

; #define PG8_STAGE(bufoff, gbase, voff) do { _Pragma("unroll") for (int _i = 0; _i < 2; ++_i) \
;         __builtin_amdgcn_global_load_lds((const unsigned*)((const char*)(gbase) + (voff)[_i]), (PG8_LAS unsigned*)(lds + (bufoff) + ldsw + _i * 8192), 16, 0, 0); } while (0)
; #define PG8_LDA(dst, b, h) do { _Pragma("unroll") for (int m = 0; m < 4; ++m) _Pragma("unroll") for (int k = 0; k < 2; ++k) dst[m][k] = *(const PG8_LAS bf16x8*)(lds + PG8_SA(b, h) + aoff + m * 2048 + k * 1024); } while (0)
; #define PG8_LDB(dst, b, h) do { _Pragma("unroll") for (int n = 0; n < 2; ++n) _Pragma("unroll") for (int k = 0; k < 2; ++k) dst[n][k] = *(const PG8_LAS bf16x8*)(lds + PG8_SB(b, h) + boff + n * 2048 + k * 1024); } while (0)
; #define PG8_MMA(ai, bj, At, Bt) do { __builtin_amdgcn_s_setprio(1); _Pragma("unroll") for (int m = 0; m < 4; ++m) _Pragma("unroll") for (int n = 0; n < 2; ++n) _Pragma("unroll") for (int k = 0; k < 2; ++k) \
;         acc[ai][bj][m][n] = __builtin_amdgcn_mfma_f32_16x16x32_bf16(Bt[n][k], At[m][k], acc[ai][bj][m][n], 0, 0, 0); __builtin_amdgcn_s_setprio(0); } while (0)
; #define PG8_WAIT_V(n) asm volatile("s_waitcnt vmcnt(" #n ")" ::: "memory")
; #define PG8_WAIT_L(n) asm volatile("s_waitcnt lgkmcnt(" #n ")" ::: "memory")
; #define PG8_BAR __builtin_amdgcn_s_barrier()
; #define PG8_SCHED __builtin_amdgcn_sched_barrier(0)
; template <class Epi, class Sched, bool ALIGN_EPI = false, bool SP2 = false>
; __device__ __forceinline__ void gemm_phase(PG8_LAS unsigned char* lds, const Gemm g, const Sched& S, const Epi& E) {
;     ...
;             const bool last = (t == nt - 2);
;             const char* a1 = cA + PG8_AK(t + 1);
;             const char* a2 = last ? nA : cA + PG8_AK(t + 2); const char* b2 = last ? nB : cB + (size_t)(t + 2) * kstep;
;             const char* a3 = last ? nA + PG8_AK(1) : cA + PG8_AK(t + 3); const char* b3 = b2 + kstep;
;             if (last && has_next) S.a_ready(nxt);
;             if constexpr (SP2) {
;             PG8_LDB(B0, 0, 0); PG8_LDB(B1, 0, 1); PG8_SCHED; PG8_LDA(At, 0, 0); PG8_STAGE(PG8_SA(1, 1), a1 + hstepA, voffA);
;             PG8_WAIT_V(8); PG8_WAIT_L(0); PG8_BAR; PG8_MMA(0, 0, At, B0); PG8_MMA(0, 1, At, B1); PG8_BAR; PG8_SCHED;
;             PG8_LDA(At, 0, 1); PG8_STAGE(PG8_SB(0, 0), b2, voffB); PG8_STAGE(PG8_SB(0, 1), b2 + hstepB, voffB); PG8_STAGE(PG8_SA(0, 0), a2, voffA);
.LBB0_1841:
	ds_read_b128 v[132:135], v191
	ds_read_b128 v[136:139], v191 offset:1024
	ds_read_b128 v[140:143], v191 offset:2048
	ds_read_b128 v[162:165], v191 offset:3072
	ds_read_b128 v[166:169], v192
	ds_read_b128 v[194:197], v192 offset:1024
	ds_read_b128 v[198:201], v192 offset:2048
	ds_read_b128 v[202:205], v192 offset:3072
	s_add_u32 s40, s36, s38
	s_addc_u32 s41, s37, s39
	s_add_u32 s42, s40, 0x100
	s_addc_u32 s43, s41, 0
	s_add_u32 s70, s69, s38
	s_addc_u32 s71, s78, s39
	s_add_u32 s40, s40, 0x180
	s_addc_u32 s41, s41, 0
	s_cmpk_eq_i32 s38, 0x700
	s_cselect_b32 s45, s3, s43
	s_cselect_b32 s44, s27, s42
	s_cselect_b32 s43, s25, s71
	s_cselect_b32 s42, s35, s70
	s_cselect_b32 s41, s68, s41
	s_cselect_b32 s40, s67, s40
	v_lshl_add_u64 v[170:171], v[130:131], 0, s[38:39]
	s_add_i32 m0, s52, 0xc000
	ds_read_b128 v[206:209], v174
	ds_read_b128 v[210:213], v174 offset:1024
	ds_read_b128 v[214:217], v174 offset:2048
	ds_read_b128 v[218:221], v174 offset:3072
	ds_read_b128 v[222:225], v174 offset:4096
	ds_read_b128 v[226:229], v174 offset:5120
	ds_read_b128 v[230:233], v174 offset:6144
	ds_read_b128 v[234:237], v174 offset:7168
	global_load_lds_dwordx4 v[170:171], off
	v_lshl_add_u64 v[170:171], v[128:129], 0, s[38:39]
	s_add_i32 m0, s52, 0xe000
	s_nop 0
	global_load_lds_dwordx4 v[170:171], off
	s_waitcnt vmcnt(8)
	s_waitcnt lgkmcnt(0)
	s_barrier
	s_setprio 1
	v_mfma_f32_16x16x32_bf16 v[124:127], v[132:135], v[206:209], v[124:127]
	v_mfma_f32_16x16x32_bf16 v[120:123], v[140:143], v[206:209], v[120:123]
	v_mfma_f32_16x16x32_bf16 v[116:119], v[132:135], v[214:217], v[116:119]
	v_mfma_f32_16x16x32_bf16 v[112:115], v[140:143], v[214:217], v[112:115]
	v_mfma_f32_16x16x32_bf16 v[108:111], v[132:135], v[222:225], v[108:111]
	v_mfma_f32_16x16x32_bf16 v[104:107], v[140:143], v[222:225], v[104:107]
	v_mfma_f32_16x16x32_bf16 v[100:103], v[132:135], v[230:233], v[100:103]
	v_mfma_f32_16x16x32_bf16 v[96:99], v[140:143], v[230:233], v[96:99]
	v_mfma_f32_16x16x32_bf16 v[124:127], v[136:139], v[210:213], v[124:127]
	v_mfma_f32_16x16x32_bf16 v[120:123], v[162:165], v[210:213], v[120:123]
	v_mfma_f32_16x16x32_bf16 v[116:119], v[136:139], v[218:221], v[116:119]
	v_mfma_f32_16x16x32_bf16 v[112:115], v[162:165], v[218:221], v[112:115]
	v_mfma_f32_16x16x32_bf16 v[108:111], v[136:139], v[226:229], v[108:111]
	v_mfma_f32_16x16x32_bf16 v[104:107], v[162:165], v[226:229], v[104:107]
	v_mfma_f32_16x16x32_bf16 v[100:103], v[136:139], v[234:237], v[100:103]
	v_mfma_f32_16x16x32_bf16 v[96:99], v[162:165], v[234:237], v[96:99]
	v_mfma_f32_16x16x32_bf16 v[60:63], v[166:169], v[206:209], v[60:63]
	v_mfma_f32_16x16x32_bf16 v[56:59], v[198:201], v[206:209], v[56:59]
	v_mfma_f32_16x16x32_bf16 v[52:55], v[166:169], v[214:217], v[52:55]
	v_mfma_f32_16x16x32_bf16 v[48:51], v[198:201], v[214:217], v[48:51]
	v_mfma_f32_16x16x32_bf16 v[44:47], v[166:169], v[222:225], v[44:47]
	v_mfma_f32_16x16x32_bf16 v[40:43], v[198:201], v[222:225], v[40:43]
	v_mfma_f32_16x16x32_bf16 v[36:39], v[166:169], v[230:233], v[36:39]
	v_mfma_f32_16x16x32_bf16 v[32:35], v[198:201], v[230:233], v[32:35]
	v_mfma_f32_16x16x32_bf16 v[60:63], v[194:197], v[210:213], v[60:63]
	v_mfma_f32_16x16x32_bf16 v[56:59], v[202:205], v[210:213], v[56:59]
	v_mfma_f32_16x16x32_bf16 v[52:55], v[194:197], v[218:221], v[52:55]
	v_mfma_f32_16x16x32_bf16 v[48:51], v[202:205], v[218:221], v[48:51]
	v_mfma_f32_16x16x32_bf16 v[44:47], v[194:197], v[226:229], v[44:47]
	v_mfma_f32_16x16x32_bf16 v[40:43], v[202:205], v[226:229], v[40:43]
	v_mfma_f32_16x16x32_bf16 v[36:39], v[194:197], v[234:237], v[36:39]
	v_mfma_f32_16x16x32_bf16 v[32:35], v[202:205], v[234:237], v[32:35]
	s_setprio 0
	s_barrier
	s_add_i32 s70, s64, s51
	v_lshl_add_u64 v[170:171], s[42:43], 0, v[146:147]
	s_mov_b32 m0, s70
	ds_read_b128 v[206:209], v174 offset:16384
	ds_read_b128 v[210:213], v174 offset:17408
	ds_read_b128 v[214:217], v174 offset:18432
	ds_read_b128 v[218:221], v174 offset:19456
	ds_read_b128 v[222:225], v174 offset:20480
	ds_read_b128 v[226:229], v174 offset:21504
	ds_read_b128 v[230:233], v174 offset:22528
	ds_read_b128 v[234:237], v174 offset:23552
	global_load_lds_dwordx4 v[170:171], off
	s_add_i32 m0, s70, 0x2000
	s_add_u32 s70, s42, 0x40000
	v_lshl_add_u64 v[238:239], s[42:43], 0, v[150:151]
	s_addc_u32 s71, s43, 0
	s_add_i32 s80, s65, s51
	global_load_lds_dwordx4 v[238:239], off
	v_lshl_add_u64 v[240:241], s[70:71], 0, v[146:147]
	s_mov_b32 m0, s80
	s_nop 0
	global_load_lds_dwordx4 v[240:241], off
	v_lshl_add_u64 v[240:241], s[70:71], 0, v[150:151]
	s_add_i32 m0, s80, 0x2000
	s_nop 0
	global_load_lds_dwordx4 v[240:241], off
	v_lshl_add_u64 v[240:241], s[44:45], 0, v[144:145]
	s_mov_b32 m0, s52
	s_nop 0
	global_load_lds_dwordx4 v[240:241], off
	v_lshl_add_u64 v[240:241], s[44:45], 0, v[148:149]
	s_mov_b32 m0, s53
	s_nop 0
	global_load_lds_dwordx4 v[240:241], off
	s_waitcnt vmcnt(8)
	s_waitcnt lgkmcnt(0)
	s_barrier
; #define PG8_STAGE(bufoff, gbase, voff) do { _Pragma("unroll") for (int _i = 0; _i < 2; ++_i) \
;         __builtin_amdgcn_global_load_lds((const unsigned*)((const char*)(gbase) + (voff)[_i]), (PG8_LAS unsigned*)(lds + (bufoff) + ldsw + _i * 8192), 16, 0, 0); } while (0)
; #define PG8_LDA(dst, b, h) do { _Pragma("unroll") for (int m = 0; m < 4; ++m) _Pragma("unroll") for (int k = 0; k < 2; ++k) dst[m][k] = *(const PG8_LAS bf16x8*)(lds + PG8_SA(b, h) + aoff + m * 2048 + k * 1024); } while (0)
; #define PG8_LDB(dst, b, h) do { _Pragma("unroll") for (int n = 0; n < 2; ++n) _Pragma("unroll") for (int k = 0; k < 2; ++k) dst[n][k] = *(const PG8_LAS bf16x8*)(lds + PG8_SB(b, h) + boff + n * 2048 + k * 1024); } while (0)
; #define PG8_MMA(ai, bj, At, Bt) do { __builtin_amdgcn_s_setprio(1); _Pragma("unroll") for (int m = 0; m < 4; ++m) _Pragma("unroll") for (int n = 0; n < 2; ++n) _Pragma("unroll") for (int k = 0; k < 2; ++k) \
;         acc[ai][bj][m][n] = __builtin_amdgcn_mfma_f32_16x16x32_bf16(Bt[n][k], At[m][k], acc[ai][bj][m][n], 0, 0, 0); __builtin_amdgcn_s_setprio(0); } while (0)
; #define PG8_WAIT_V(n) asm volatile("s_waitcnt vmcnt(" #n ")" ::: "memory")
; #define PG8_WAIT_L(n) asm volatile("s_waitcnt lgkmcnt(" #n ")" ::: "memory")
; #define PG8_BAR __builtin_amdgcn_s_barrier()
; #define PG8_SCHED __builtin_amdgcn_sched_barrier(0)
; template <class Epi, class Sched, bool ALIGN_EPI = false, bool SP2 = false>
; __device__ __forceinline__ void gemm_phase(PG8_LAS unsigned char* lds, const Gemm g, const Sched& S, const Epi& E) {
;     ...
;             PG8_WAIT_V(8); PG8_WAIT_L(0); PG8_BAR; PG8_MMA(1, 0, At, B0); PG8_MMA(1, 1, At, B1); PG8_BAR; PG8_SCHED;
;             PG8_LDB(B0, 1, 0); PG8_LDB(B1, 1, 1); PG8_SCHED; PG8_LDA(At, 1, 0); PG8_STAGE(PG8_SA(0, 1), a2 + hstepA, voffA);
;             PG8_WAIT_V(8); PG8_WAIT_L(0); PG8_BAR; PG8_MMA(0, 0, At, B0); PG8_MMA(0, 1, At, B1); PG8_BAR; PG8_SCHED;
	s_setprio 1
	v_mfma_f32_16x16x32_bf16 v[92:95], v[132:135], v[206:209], v[92:95]
	v_mfma_f32_16x16x32_bf16 v[88:91], v[140:143], v[206:209], v[88:91]
	v_mfma_f32_16x16x32_bf16 v[84:87], v[132:135], v[214:217], v[84:87]
	v_mfma_f32_16x16x32_bf16 v[80:83], v[140:143], v[214:217], v[80:83]
	v_mfma_f32_16x16x32_bf16 v[76:79], v[132:135], v[222:225], v[76:79]
	v_mfma_f32_16x16x32_bf16 v[72:75], v[140:143], v[222:225], v[72:75]
	v_mfma_f32_16x16x32_bf16 v[68:71], v[132:135], v[230:233], v[68:71]
	v_mfma_f32_16x16x32_bf16 v[64:67], v[140:143], v[230:233], v[64:67]
	v_mfma_f32_16x16x32_bf16 v[92:95], v[136:139], v[210:213], v[92:95]
	v_mfma_f32_16x16x32_bf16 v[88:91], v[162:165], v[210:213], v[88:91]
	v_mfma_f32_16x16x32_bf16 v[84:87], v[136:139], v[218:221], v[84:87]
	v_mfma_f32_16x16x32_bf16 v[80:83], v[162:165], v[218:221], v[80:83]
	v_mfma_f32_16x16x32_bf16 v[76:79], v[136:139], v[226:229], v[76:79]
	v_mfma_f32_16x16x32_bf16 v[72:75], v[162:165], v[226:229], v[72:75]
	v_mfma_f32_16x16x32_bf16 v[68:71], v[136:139], v[234:237], v[68:71]
	v_mfma_f32_16x16x32_bf16 v[64:67], v[162:165], v[234:237], v[64:67]
	v_mfma_f32_16x16x32_bf16 v[28:31], v[166:169], v[206:209], v[28:31]
	v_mfma_f32_16x16x32_bf16 v[24:27], v[198:201], v[206:209], v[24:27]
	v_mfma_f32_16x16x32_bf16 v[20:23], v[166:169], v[214:217], v[20:23]
	v_mfma_f32_16x16x32_bf16 v[16:19], v[198:201], v[214:217], v[16:19]
	v_mfma_f32_16x16x32_bf16 v[12:15], v[166:169], v[222:225], v[12:15]
	v_mfma_f32_16x16x32_bf16 v[8:11], v[198:201], v[222:225], v[8:11]
	v_mfma_f32_16x16x32_bf16 v[4:7], v[166:169], v[230:233], v[4:7]
	v_mfma_f32_16x16x32_bf16 v[0:3], v[198:201], v[230:233], v[0:3]
	v_mfma_f32_16x16x32_bf16 v[28:31], v[194:197], v[210:213], v[28:31]
	v_mfma_f32_16x16x32_bf16 v[24:27], v[202:205], v[210:213], v[24:27]
	v_mfma_f32_16x16x32_bf16 v[20:23], v[194:197], v[218:221], v[20:23]
	v_mfma_f32_16x16x32_bf16 v[16:19], v[202:205], v[218:221], v[16:19]
	v_mfma_f32_16x16x32_bf16 v[12:15], v[194:197], v[226:229], v[12:15]
	v_mfma_f32_16x16x32_bf16 v[8:11], v[202:205], v[226:229], v[8:11]
	v_mfma_f32_16x16x32_bf16 v[4:7], v[194:197], v[234:237], v[4:7]
	v_mfma_f32_16x16x32_bf16 v[0:3], v[202:205], v[234:237], v[0:3]
	s_setprio 0
	s_barrier
	s_add_i32 s70, 0, 0x18000
	v_add_u32_e32 v153, s70, v173
	s_add_i32 s71, 0, 0x1c000
	ds_read_b128 v[132:135], v153
	ds_read_b128 v[136:139], v153 offset:1024
	ds_read_b128 v[140:143], v153 offset:2048
	ds_read_b128 v[162:165], v153 offset:3072
	v_add_u32_e32 v153, s71, v173
	ds_read_b128 v[166:169], v153
	ds_read_b128 v[194:197], v153 offset:1024
	ds_read_b128 v[198:201], v153 offset:2048
	ds_read_b128 v[202:205], v153 offset:3072
	s_add_u32 s44, s44, 0x40000
	s_addc_u32 s45, s45, 0
	s_mov_b32 m0, s54
	v_lshl_add_u64 v[240:241], s[44:45], 0, v[144:145]
	ds_read_b128 v[206:209], v174 offset:32768
	ds_read_b128 v[210:213], v174 offset:33792
	ds_read_b128 v[214:217], v174 offset:34816
	ds_read_b128 v[218:221], v174 offset:35840
	ds_read_b128 v[222:225], v174 offset:36864
	ds_read_b128 v[226:229], v174 offset:37888
	ds_read_b128 v[230:233], v174 offset:38912
	ds_read_b128 v[234:237], v174 offset:39936
	global_load_lds_dwordx4 v[240:241], off
	v_lshl_add_u64 v[240:241], s[44:45], 0, v[148:149]
	s_mov_b32 m0, s55
	s_nop 0
	global_load_lds_dwordx4 v[240:241], off
	s_waitcnt vmcnt(8)
	s_waitcnt lgkmcnt(0)
	s_barrier
	s_setprio 1
	v_mfma_f32_16x16x32_bf16 v[124:127], v[132:135], v[206:209], v[124:127]
	v_mfma_f32_16x16x32_bf16 v[120:123], v[140:143], v[206:209], v[120:123]
	v_mfma_f32_16x16x32_bf16 v[116:119], v[132:135], v[214:217], v[116:119]
	v_mfma_f32_16x16x32_bf16 v[112:115], v[140:143], v[214:217], v[112:115]
	v_mfma_f32_16x16x32_bf16 v[108:111], v[132:135], v[222:225], v[108:111]
	v_mfma_f32_16x16x32_bf16 v[104:107], v[140:143], v[222:225], v[104:107]
	v_mfma_f32_16x16x32_bf16 v[100:103], v[132:135], v[230:233], v[100:103]
	v_mfma_f32_16x16x32_bf16 v[96:99], v[140:143], v[230:233], v[96:99]
	v_mfma_f32_16x16x32_bf16 v[124:127], v[136:139], v[210:213], v[124:127]
	v_mfma_f32_16x16x32_bf16 v[120:123], v[162:165], v[210:213], v[120:123]
	v_mfma_f32_16x16x32_bf16 v[116:119], v[136:139], v[218:221], v[116:119]
	v_mfma_f32_16x16x32_bf16 v[112:115], v[162:165], v[218:221], v[112:115]
	v_mfma_f32_16x16x32_bf16 v[108:111], v[136:139], v[226:229], v[108:111]
	v_mfma_f32_16x16x32_bf16 v[104:107], v[162:165], v[226:229], v[104:107]
	v_mfma_f32_16x16x32_bf16 v[100:103], v[136:139], v[234:237], v[100:103]
	v_mfma_f32_16x16x32_bf16 v[96:99], v[162:165], v[234:237], v[96:99]
	v_mfma_f32_16x16x32_bf16 v[60:63], v[166:169], v[206:209], v[60:63]
	v_mfma_f32_16x16x32_bf16 v[56:59], v[198:201], v[206:209], v[56:59]
	v_mfma_f32_16x16x32_bf16 v[52:55], v[166:169], v[214:217], v[52:55]
	v_mfma_f32_16x16x32_bf16 v[48:51], v[198:201], v[214:217], v[48:51]
	v_mfma_f32_16x16x32_bf16 v[44:47], v[166:169], v[222:225], v[44:47]
	v_mfma_f32_16x16x32_bf16 v[40:43], v[198:201], v[222:225], v[40:43]
	v_mfma_f32_16x16x32_bf16 v[36:39], v[166:169], v[230:233], v[36:39]
	v_mfma_f32_16x16x32_bf16 v[32:35], v[198:201], v[230:233], v[32:35]
	v_mfma_f32_16x16x32_bf16 v[60:63], v[194:197], v[210:213], v[60:63]
	v_mfma_f32_16x16x32_bf16 v[56:59], v[202:205], v[210:213], v[56:59]
	v_mfma_f32_16x16x32_bf16 v[52:55], v[194:197], v[218:221], v[52:55]
	v_mfma_f32_16x16x32_bf16 v[48:51], v[202:205], v[218:221], v[48:51]
	v_mfma_f32_16x16x32_bf16 v[44:47], v[194:197], v[226:229], v[44:47]
	v_mfma_f32_16x16x32_bf16 v[40:43], v[202:205], v[226:229], v[40:43]
	v_mfma_f32_16x16x32_bf16 v[36:39], v[194:197], v[234:237], v[36:39]
	v_mfma_f32_16x16x32_bf16 v[32:35], v[202:205], v[234:237], v[32:35]
	s_setprio 0
	s_barrier
; #define PG8_STAGE(bufoff, gbase, voff) do { _Pragma("unroll") for (int _i = 0; _i < 2; ++_i) \
;         __builtin_amdgcn_global_load_lds((const unsigned*)((const char*)(gbase) + (voff)[_i]), (PG8_LAS unsigned*)(lds + (bufoff) + ldsw + _i * 8192), 16, 0, 0); } while (0)
; #define PG8_LDA(dst, b, h) do { _Pragma("unroll") for (int m = 0; m < 4; ++m) _Pragma("unroll") for (int k = 0; k < 2; ++k) dst[m][k] = *(const PG8_LAS bf16x8*)(lds + PG8_SA(b, h) + aoff + m * 2048 + k * 1024); } while (0)
; #define PG8_MMA(ai, bj, At, Bt) do { __builtin_amdgcn_s_setprio(1); _Pragma("unroll") for (int m = 0; m < 4; ++m) _Pragma("unroll") for (int n = 0; n < 2; ++n) _Pragma("unroll") for (int k = 0; k < 2; ++k) \
;         acc[ai][bj][m][n] = __builtin_amdgcn_mfma_f32_16x16x32_bf16(Bt[n][k], At[m][k], acc[ai][bj][m][n], 0, 0, 0); __builtin_amdgcn_s_setprio(0); } while (0)
; #define PG8_WAIT_V(n) asm volatile("s_waitcnt vmcnt(" #n ")" ::: "memory")
; #define PG8_WAIT_L(n) asm volatile("s_waitcnt lgkmcnt(" #n ")" ::: "memory")
; #define PG8_BAR __builtin_amdgcn_s_barrier()
; #define PG8_SCHED __builtin_amdgcn_sched_barrier(0)
; template <class Epi, class Sched, bool ALIGN_EPI = false, bool SP2 = false>
; __device__ __forceinline__ void gemm_phase(PG8_LAS unsigned char* lds, const Gemm g, const Sched& S, const Epi& E) {
;     ...
;         for (int t = 0; t < nt; t += 2) {
;             const bool last = (t == nt - 2);
;     ...
;             PG8_LDA(At, 1, 1); PG8_STAGE(PG8_SB(1, 0), b3, voffB); PG8_STAGE(PG8_SB(1, 1), b3 + hstepB, voffB); PG8_STAGE(PG8_SA(1, 0), a3, voffA);
;             PG8_WAIT_V(8); PG8_WAIT_L(0); PG8_BAR; PG8_MMA(1, 0, At, B0); PG8_MMA(1, 1, At, B1); PG8_BAR; PG8_SCHED;
	s_add_i32 s44, s70, s51
	v_lshl_add_u64 v[170:171], v[170:171], 0, s[18:19]
	s_mov_b32 m0, s44
	ds_read_b128 v[206:209], v174 offset:49152
	ds_read_b128 v[210:213], v174 offset:50176
	ds_read_b128 v[214:217], v174 offset:51200
	ds_read_b128 v[218:221], v174 offset:52224
	ds_read_b128 v[222:225], v174 offset:53248
	ds_read_b128 v[226:229], v174 offset:54272
	ds_read_b128 v[230:233], v174 offset:55296
	ds_read_b128 v[234:237], v174 offset:56320
	global_load_lds_dwordx4 v[170:171], off
	s_add_i32 m0, s44, 0x2000
	s_add_u32 s42, s42, 0x40080
	v_lshl_add_u64 v[170:171], v[238:239], 0, s[18:19]
	s_addc_u32 s43, s43, 0
	s_add_i32 s44, s71, s51
	global_load_lds_dwordx4 v[170:171], off
	v_lshl_add_u64 v[170:171], s[42:43], 0, v[146:147]
	s_mov_b32 m0, s44
	s_nop 0
	global_load_lds_dwordx4 v[170:171], off
	v_lshl_add_u64 v[170:171], s[42:43], 0, v[150:151]
	s_add_i32 m0, s44, 0x2000
	s_nop 0
	global_load_lds_dwordx4 v[170:171], off
	v_lshl_add_u64 v[170:171], s[40:41], 0, v[144:145]
	s_mov_b32 m0, s60
	s_nop 0
	global_load_lds_dwordx4 v[170:171], off
	v_lshl_add_u64 v[170:171], s[40:41], 0, v[148:149]
	s_mov_b32 m0, s61
	s_nop 0
	global_load_lds_dwordx4 v[170:171], off
	s_waitcnt vmcnt(8)
	s_waitcnt lgkmcnt(0)
	s_barrier
	s_setprio 1
	v_mfma_f32_16x16x32_bf16 v[92:95], v[132:135], v[206:209], v[92:95]
	v_mfma_f32_16x16x32_bf16 v[88:91], v[140:143], v[206:209], v[88:91]
	v_mfma_f32_16x16x32_bf16 v[84:87], v[132:135], v[214:217], v[84:87]
	v_mfma_f32_16x16x32_bf16 v[80:83], v[140:143], v[214:217], v[80:83]
	v_mfma_f32_16x16x32_bf16 v[76:79], v[132:135], v[222:225], v[76:79]
	v_mfma_f32_16x16x32_bf16 v[72:75], v[140:143], v[222:225], v[72:75]
	v_mfma_f32_16x16x32_bf16 v[68:71], v[132:135], v[230:233], v[68:71]
	v_mfma_f32_16x16x32_bf16 v[64:67], v[140:143], v[230:233], v[64:67]
	v_mfma_f32_16x16x32_bf16 v[92:95], v[136:139], v[210:213], v[92:95]
	v_mfma_f32_16x16x32_bf16 v[88:91], v[162:165], v[210:213], v[88:91]
	v_mfma_f32_16x16x32_bf16 v[84:87], v[136:139], v[218:221], v[84:87]
	v_mfma_f32_16x16x32_bf16 v[80:83], v[162:165], v[218:221], v[80:83]
	v_mfma_f32_16x16x32_bf16 v[76:79], v[136:139], v[226:229], v[76:79]
	v_mfma_f32_16x16x32_bf16 v[72:75], v[162:165], v[226:229], v[72:75]
	v_mfma_f32_16x16x32_bf16 v[68:71], v[136:139], v[234:237], v[68:71]
	v_mfma_f32_16x16x32_bf16 v[64:67], v[162:165], v[234:237], v[64:67]
	v_mfma_f32_16x16x32_bf16 v[28:31], v[166:169], v[206:209], v[28:31]
	v_mfma_f32_16x16x32_bf16 v[24:27], v[198:201], v[206:209], v[24:27]
	v_mfma_f32_16x16x32_bf16 v[20:23], v[166:169], v[214:217], v[20:23]
	v_mfma_f32_16x16x32_bf16 v[16:19], v[198:201], v[214:217], v[16:19]
	v_mfma_f32_16x16x32_bf16 v[12:15], v[166:169], v[222:225], v[12:15]
	v_mfma_f32_16x16x32_bf16 v[8:11], v[198:201], v[222:225], v[8:11]
	v_mfma_f32_16x16x32_bf16 v[4:7], v[166:169], v[230:233], v[4:7]
	v_mfma_f32_16x16x32_bf16 v[0:3], v[198:201], v[230:233], v[0:3]
	v_mfma_f32_16x16x32_bf16 v[28:31], v[194:197], v[210:213], v[28:31]
	v_mfma_f32_16x16x32_bf16 v[24:27], v[202:205], v[210:213], v[24:27]
	v_mfma_f32_16x16x32_bf16 v[20:23], v[194:197], v[218:221], v[20:23]
	v_mfma_f32_16x16x32_bf16 v[16:19], v[202:205], v[218:221], v[16:19]
	v_mfma_f32_16x16x32_bf16 v[12:15], v[194:197], v[226:229], v[12:15]
	v_mfma_f32_16x16x32_bf16 v[8:11], v[202:205], v[226:229], v[8:11]
	v_mfma_f32_16x16x32_bf16 v[4:7], v[194:197], v[234:237], v[4:7]
	v_mfma_f32_16x16x32_bf16 v[0:3], v[202:205], v[234:237], v[0:3]
	s_setprio 0
	s_barrier
	s_add_i32 s79, s79, 2
	s_add_u32 s38, s38, 0x100
	s_addc_u32 s39, s39, 0
	s_cmp_gt_u32 s79, 13
	s_cbranch_scc0 .LBB0_1841
	s_and_b64 vcc, exec, s[20:21]
	s_cbranch_vccz .LBB0_1844
	s_barrier

; #define PG8_STAGE(bufoff, gbase, voff) do { _Pragma("unroll") for (int _i = 0; _i < 2; ++_i) \
;         __builtin_amdgcn_global_load_lds((const unsigned*)((const char*)(gbase) + (voff)[_i]), (PG8_LAS unsigned*)(lds + (bufoff) + ldsw + _i * 8192), 16, 0, 0); } while (0)
; #define PG8_LDA(dst, b, h) do { _Pragma("unroll") for (int m = 0; m < 4; ++m) _Pragma("unroll") for (int k = 0; k < 2; ++k) dst[m][k] = *(const PG8_LAS bf16x8*)(lds + PG8_SA(b, h) + aoff + m * 2048 + k * 1024); } while (0)
; #define PG8_LDB(dst, b, h) do { _Pragma("unroll") for (int n = 0; n < 2; ++n) _Pragma("unroll") for (int k = 0; k < 2; ++k) dst[n][k] = *(const PG8_LAS bf16x8*)(lds + PG8_SB(b, h) + boff + n * 2048 + k * 1024); } while (0)
; #define PG8_MMA(ai, bj, At, Bt) do { __builtin_amdgcn_s_setprio(1); _Pragma("unroll") for (int m = 0; m < 4; ++m) _Pragma("unroll") for (int n = 0; n < 2; ++n) _Pragma("unroll") for (int k = 0; k < 2; ++k) \
;         acc[ai][bj][m][n] = __builtin_amdgcn_mfma_f32_16x16x32_bf16(Bt[n][k], At[m][k], acc[ai][bj][m][n], 0, 0, 0); __builtin_amdgcn_s_setprio(0); } while (0)
; #define PG8_WAIT_V(n) asm volatile("s_waitcnt vmcnt(" #n ")" ::: "memory")
; #define PG8_WAIT_L(n) asm volatile("s_waitcnt lgkmcnt(" #n ")" ::: "memory")
; #define PG8_BAR __builtin_amdgcn_s_barrier()
; #define PG8_SCHED __builtin_amdgcn_sched_barrier(0)
; template <class Epi, class Sched, bool ALIGN_EPI = false, bool SP2 = false>
; __device__ __forceinline__ void gemm_phase(PG8_LAS unsigned char* lds, const Gemm g, const Sched& S, const Epi& E) {
;     ...
;             const bool last = (t == nt - 2);
;             const char* a1 = cA + PG8_AK(t + 1);
;             const char* a2 = last ? nA : cA + PG8_AK(t + 2); const char* b2 = last ? nB : cB + (size_t)(t + 2) * kstep;
;             const char* a3 = last ? nA + PG8_AK(1) : cA + PG8_AK(t + 3); const char* b3 = b2 + kstep;
;             if (last && has_next) S.a_ready(nxt);
;             if constexpr (SP2) {
;             PG8_LDB(B0, 0, 0); PG8_LDB(B1, 0, 1); PG8_SCHED; PG8_LDA(At, 0, 0); PG8_STAGE(PG8_SA(1, 1), a1 + hstepA, voffA);
;             PG8_WAIT_V(8); PG8_WAIT_L(0); PG8_BAR; PG8_MMA(0, 0, At, B0); PG8_MMA(0, 1, At, B1); PG8_BAR; PG8_SCHED;
;             PG8_LDA(At, 0, 1); PG8_STAGE(PG8_SB(0, 0), b2, voffB); PG8_STAGE(PG8_SB(0, 1), b2 + hstepB, voffB); PG8_STAGE(PG8_SA(0, 0), a2, voffA);
.LBB0_2888:
	ds_read_b128 v[124:127], v210
	ds_read_b128 v[128:131], v210 offset:1024
	ds_read_b128 v[132:135], v210 offset:2048
	ds_read_b128 v[144:147], v210 offset:3072
	ds_read_b128 v[148:151], v211
	ds_read_b128 v[170:173], v211 offset:1024
	ds_read_b128 v[174:177], v211 offset:2048
	ds_read_b128 v[178:181], v211 offset:3072
	s_add_u32 s42, s38, s40
	s_addc_u32 s43, s39, s41
	s_add_u32 s46, s42, 0x100
	s_addc_u32 s47, s43, 0
	s_add_u32 s44, s78, s40
	s_addc_u32 s45, s79, s41
	s_add_u32 s42, s42, 0x180
	s_addc_u32 s43, s43, 0
	s_cmpk_eq_i32 s40, 0x1500
	s_cselect_b32 s43, s10, s43
	s_cselect_b32 s42, s3, s42
	s_cselect_b32 s45, s37, s45
	s_cselect_b32 s44, s36, s44
	s_cselect_b32 s47, s9, s47
	s_cselect_b32 s46, s8, s46
	v_lshl_add_u64 v[206:207], v[122:123], 0, s[40:41]
	s_add_i32 m0, s53, 0xc000
	ds_read_b128 v[212:215], v191
	ds_read_b128 v[216:219], v191 offset:1024
	ds_read_b128 v[220:223], v191 offset:2048
	ds_read_b128 v[224:227], v191 offset:3072
	ds_read_b128 v[228:231], v191 offset:4096
	ds_read_b128 v[232:235], v191 offset:5120
	ds_read_b128 v[236:239], v191 offset:6144
	ds_read_b128 v[240:243], v191 offset:7168
	global_load_lds_dwordx4 v[206:207], off
	v_lshl_add_u64 v[206:207], v[120:121], 0, s[40:41]
	s_add_i32 m0, s53, 0xe000
	s_nop 0
	global_load_lds_dwordx4 v[206:207], off
	s_waitcnt vmcnt(8)
	s_waitcnt lgkmcnt(0)
	s_barrier
	s_setprio 1
	v_mfma_f32_16x16x32_bf16 v[140:143], v[124:127], v[212:215], v[140:143]
	v_mfma_f32_16x16x32_bf16 v[136:139], v[132:135], v[212:215], v[136:139]
	v_mfma_f32_16x16x32_bf16 v[116:119], v[124:127], v[220:223], v[116:119]
	v_mfma_f32_16x16x32_bf16 v[112:115], v[132:135], v[220:223], v[112:115]
	v_mfma_f32_16x16x32_bf16 v[108:111], v[124:127], v[228:231], v[108:111]
	v_mfma_f32_16x16x32_bf16 v[104:107], v[132:135], v[228:231], v[104:107]
	v_mfma_f32_16x16x32_bf16 v[100:103], v[124:127], v[236:239], v[100:103]
	v_mfma_f32_16x16x32_bf16 v[96:99], v[132:135], v[236:239], v[96:99]
	v_mfma_f32_16x16x32_bf16 v[140:143], v[128:131], v[216:219], v[140:143]
	v_mfma_f32_16x16x32_bf16 v[136:139], v[144:147], v[216:219], v[136:139]
	v_mfma_f32_16x16x32_bf16 v[116:119], v[128:131], v[224:227], v[116:119]
	v_mfma_f32_16x16x32_bf16 v[112:115], v[144:147], v[224:227], v[112:115]
	v_mfma_f32_16x16x32_bf16 v[108:111], v[128:131], v[232:235], v[108:111]
	v_mfma_f32_16x16x32_bf16 v[104:107], v[144:147], v[232:235], v[104:107]
	v_mfma_f32_16x16x32_bf16 v[100:103], v[128:131], v[240:243], v[100:103]
	v_mfma_f32_16x16x32_bf16 v[96:99], v[144:147], v[240:243], v[96:99]
	v_mfma_f32_16x16x32_bf16 v[60:63], v[148:151], v[212:215], v[60:63]
	v_mfma_f32_16x16x32_bf16 v[56:59], v[174:177], v[212:215], v[56:59]
	v_mfma_f32_16x16x32_bf16 v[52:55], v[148:151], v[220:223], v[52:55]
	v_mfma_f32_16x16x32_bf16 v[48:51], v[174:177], v[220:223], v[48:51]
	v_mfma_f32_16x16x32_bf16 v[44:47], v[148:151], v[228:231], v[44:47]
	v_mfma_f32_16x16x32_bf16 v[40:43], v[174:177], v[228:231], v[40:43]
	v_mfma_f32_16x16x32_bf16 v[36:39], v[148:151], v[236:239], v[36:39]
	v_mfma_f32_16x16x32_bf16 v[32:35], v[174:177], v[236:239], v[32:35]
	v_mfma_f32_16x16x32_bf16 v[60:63], v[170:173], v[216:219], v[60:63]
	v_mfma_f32_16x16x32_bf16 v[56:59], v[178:181], v[216:219], v[56:59]
	v_mfma_f32_16x16x32_bf16 v[52:55], v[170:173], v[224:227], v[52:55]
	v_mfma_f32_16x16x32_bf16 v[48:51], v[178:181], v[224:227], v[48:51]
	v_mfma_f32_16x16x32_bf16 v[44:47], v[170:173], v[232:235], v[44:47]
	v_mfma_f32_16x16x32_bf16 v[40:43], v[178:181], v[232:235], v[40:43]
	v_mfma_f32_16x16x32_bf16 v[36:39], v[170:173], v[240:243], v[36:39]
	v_mfma_f32_16x16x32_bf16 v[32:35], v[178:181], v[240:243], v[32:35]
	s_setprio 0
	s_barrier
	s_add_i32 s70, s69, s52
	v_lshl_add_u64 v[206:207], s[44:45], 0, v[154:155]
	s_mov_b32 m0, s70
	ds_read_b128 v[212:215], v191 offset:16384
	ds_read_b128 v[216:219], v191 offset:17408
	ds_read_b128 v[220:223], v191 offset:18432
	ds_read_b128 v[224:227], v191 offset:19456
	ds_read_b128 v[228:231], v191 offset:20480
	ds_read_b128 v[232:235], v191 offset:21504
	ds_read_b128 v[236:239], v191 offset:22528
	ds_read_b128 v[240:243], v191 offset:23552
	global_load_lds_dwordx4 v[206:207], off
	s_add_i32 m0, s70, 0x2000
	s_add_u32 s70, s44, 0xb0000
	v_lshl_add_u64 v[244:245], s[44:45], 0, v[158:159]
	s_addc_u32 s71, s45, 0
	s_add_i32 s87, s80, s52
	global_load_lds_dwordx4 v[244:245], off
	v_lshl_add_u64 v[246:247], s[70:71], 0, v[154:155]
	s_mov_b32 m0, s87
	s_nop 0
	global_load_lds_dwordx4 v[246:247], off
	v_lshl_add_u64 v[246:247], s[70:71], 0, v[158:159]
	s_add_i32 m0, s87, 0x2000
	s_nop 0
	global_load_lds_dwordx4 v[246:247], off
	v_lshl_add_u64 v[246:247], s[46:47], 0, v[152:153]
	s_mov_b32 m0, s53
	s_nop 0
	global_load_lds_dwordx4 v[246:247], off
	v_lshl_add_u64 v[246:247], s[46:47], 0, v[156:157]
	s_mov_b32 m0, s54
	s_nop 0
	global_load_lds_dwordx4 v[246:247], off
	s_waitcnt vmcnt(8)
	s_waitcnt lgkmcnt(0)
	s_barrier
; #define PG8_STAGE(bufoff, gbase, voff) do { _Pragma("unroll") for (int _i = 0; _i < 2; ++_i) \
;         __builtin_amdgcn_global_load_lds((const unsigned*)((const char*)(gbase) + (voff)[_i]), (PG8_LAS unsigned*)(lds + (bufoff) + ldsw + _i * 8192), 16, 0, 0); } while (0)
; #define PG8_LDA(dst, b, h) do { _Pragma("unroll") for (int m = 0; m < 4; ++m) _Pragma("unroll") for (int k = 0; k < 2; ++k) dst[m][k] = *(const PG8_LAS bf16x8*)(lds + PG8_SA(b, h) + aoff + m * 2048 + k * 1024); } while (0)
; #define PG8_LDB(dst, b, h) do { _Pragma("unroll") for (int n = 0; n < 2; ++n) _Pragma("unroll") for (int k = 0; k < 2; ++k) dst[n][k] = *(const PG8_LAS bf16x8*)(lds + PG8_SB(b, h) + boff + n * 2048 + k * 1024); } while (0)
; #define PG8_MMA(ai, bj, At, Bt) do { __builtin_amdgcn_s_setprio(1); _Pragma("unroll") for (int m = 0; m < 4; ++m) _Pragma("unroll") for (int n = 0; n < 2; ++n) _Pragma("unroll") for (int k = 0; k < 2; ++k) \
;         acc[ai][bj][m][n] = __builtin_amdgcn_mfma_f32_16x16x32_bf16(Bt[n][k], At[m][k], acc[ai][bj][m][n], 0, 0, 0); __builtin_amdgcn_s_setprio(0); } while (0)
; #define PG8_WAIT_V(n) asm volatile("s_waitcnt vmcnt(" #n ")" ::: "memory")
; #define PG8_WAIT_L(n) asm volatile("s_waitcnt lgkmcnt(" #n ")" ::: "memory")
; #define PG8_BAR __builtin_amdgcn_s_barrier()
; #define PG8_SCHED __builtin_amdgcn_sched_barrier(0)
; template <class Epi, class Sched, bool ALIGN_EPI = false, bool SP2 = false>
; __device__ __forceinline__ void gemm_phase(PG8_LAS unsigned char* lds, const Gemm g, const Sched& S, const Epi& E) {
;     ...
;             PG8_WAIT_V(8); PG8_WAIT_L(0); PG8_BAR; PG8_MMA(1, 0, At, B0); PG8_MMA(1, 1, At, B1); PG8_BAR; PG8_SCHED;
;             PG8_LDB(B0, 1, 0); PG8_LDB(B1, 1, 1); PG8_SCHED; PG8_LDA(At, 1, 0); PG8_STAGE(PG8_SA(0, 1), a2 + hstepA, voffA);
;             PG8_WAIT_V(8); PG8_WAIT_L(0); PG8_BAR; PG8_MMA(0, 0, At, B0); PG8_MMA(0, 1, At, B1); PG8_BAR; PG8_SCHED;
	s_setprio 1
	v_mfma_f32_16x16x32_bf16 v[92:95], v[124:127], v[212:215], v[92:95]
	v_mfma_f32_16x16x32_bf16 v[88:91], v[132:135], v[212:215], v[88:91]
	v_mfma_f32_16x16x32_bf16 v[84:87], v[124:127], v[220:223], v[84:87]
	v_mfma_f32_16x16x32_bf16 v[80:83], v[132:135], v[220:223], v[80:83]
	v_mfma_f32_16x16x32_bf16 v[76:79], v[124:127], v[228:231], v[76:79]
	v_mfma_f32_16x16x32_bf16 v[72:75], v[132:135], v[228:231], v[72:75]
	v_mfma_f32_16x16x32_bf16 v[68:71], v[124:127], v[236:239], v[68:71]
	v_mfma_f32_16x16x32_bf16 v[64:67], v[132:135], v[236:239], v[64:67]
	v_mfma_f32_16x16x32_bf16 v[92:95], v[128:131], v[216:219], v[92:95]
	v_mfma_f32_16x16x32_bf16 v[88:91], v[144:147], v[216:219], v[88:91]
	v_mfma_f32_16x16x32_bf16 v[84:87], v[128:131], v[224:227], v[84:87]
	v_mfma_f32_16x16x32_bf16 v[80:83], v[144:147], v[224:227], v[80:83]
	v_mfma_f32_16x16x32_bf16 v[76:79], v[128:131], v[232:235], v[76:79]
	v_mfma_f32_16x16x32_bf16 v[72:75], v[144:147], v[232:235], v[72:75]
	v_mfma_f32_16x16x32_bf16 v[68:71], v[128:131], v[240:243], v[68:71]
	v_mfma_f32_16x16x32_bf16 v[64:67], v[144:147], v[240:243], v[64:67]
	v_mfma_f32_16x16x32_bf16 v[28:31], v[148:151], v[212:215], v[28:31]
	v_mfma_f32_16x16x32_bf16 v[24:27], v[174:177], v[212:215], v[24:27]
	v_mfma_f32_16x16x32_bf16 v[20:23], v[148:151], v[220:223], v[20:23]
	v_mfma_f32_16x16x32_bf16 v[16:19], v[174:177], v[220:223], v[16:19]
	v_mfma_f32_16x16x32_bf16 v[12:15], v[148:151], v[228:231], v[12:15]
	v_mfma_f32_16x16x32_bf16 v[8:11], v[174:177], v[228:231], v[8:11]
	v_mfma_f32_16x16x32_bf16 v[4:7], v[148:151], v[236:239], v[4:7]
	v_mfma_f32_16x16x32_bf16 v[0:3], v[174:177], v[236:239], v[0:3]
	v_mfma_f32_16x16x32_bf16 v[28:31], v[170:173], v[216:219], v[28:31]
	v_mfma_f32_16x16x32_bf16 v[24:27], v[178:181], v[216:219], v[24:27]
	v_mfma_f32_16x16x32_bf16 v[20:23], v[170:173], v[224:227], v[20:23]
	v_mfma_f32_16x16x32_bf16 v[16:19], v[178:181], v[224:227], v[16:19]
	v_mfma_f32_16x16x32_bf16 v[12:15], v[170:173], v[232:235], v[12:15]
	v_mfma_f32_16x16x32_bf16 v[8:11], v[178:181], v[232:235], v[8:11]
	v_mfma_f32_16x16x32_bf16 v[4:7], v[170:173], v[240:243], v[4:7]
	v_mfma_f32_16x16x32_bf16 v[0:3], v[178:181], v[240:243], v[0:3]
	s_setprio 0
	s_barrier
	s_add_i32 s70, 0, 0x18000
	s_add_i32 s71, 0, 0x1c000
	v_add_u32_e32 v144, s70, v185
	v_add_u32_e32 v161, s71, v185
	ds_read_b128 v[124:127], v144
	ds_read_b128 v[128:131], v144 offset:1024
	ds_read_b128 v[132:135], v144 offset:2048
	ds_read_b128 v[144:147], v144 offset:3072
	ds_read_b128 v[148:151], v161
	ds_read_b128 v[170:173], v161 offset:1024
	ds_read_b128 v[174:177], v161 offset:2048
	ds_read_b128 v[178:181], v161 offset:3072
	s_add_u32 s46, s46, 0xb0000
	s_addc_u32 s47, s47, 0
	s_mov_b32 m0, s55
	v_lshl_add_u64 v[246:247], s[46:47], 0, v[152:153]
	ds_read_b128 v[212:215], v191 offset:32768
	ds_read_b128 v[216:219], v191 offset:33792
	ds_read_b128 v[220:223], v191 offset:34816
	ds_read_b128 v[224:227], v191 offset:35840
	ds_read_b128 v[228:231], v191 offset:36864
	ds_read_b128 v[232:235], v191 offset:37888
	ds_read_b128 v[236:239], v191 offset:38912
	ds_read_b128 v[240:243], v191 offset:39936
	global_load_lds_dwordx4 v[246:247], off
	v_lshl_add_u64 v[246:247], s[46:47], 0, v[156:157]
	s_mov_b32 m0, s56
	s_nop 0
	global_load_lds_dwordx4 v[246:247], off
	s_waitcnt vmcnt(8)
	s_waitcnt lgkmcnt(0)
	s_barrier
	s_setprio 1
	v_mfma_f32_16x16x32_bf16 v[140:143], v[124:127], v[212:215], v[140:143]
	v_mfma_f32_16x16x32_bf16 v[136:139], v[132:135], v[212:215], v[136:139]
	v_mfma_f32_16x16x32_bf16 v[116:119], v[124:127], v[220:223], v[116:119]
	v_mfma_f32_16x16x32_bf16 v[112:115], v[132:135], v[220:223], v[112:115]
	v_mfma_f32_16x16x32_bf16 v[108:111], v[124:127], v[228:231], v[108:111]
	v_mfma_f32_16x16x32_bf16 v[104:107], v[132:135], v[228:231], v[104:107]
	v_mfma_f32_16x16x32_bf16 v[100:103], v[124:127], v[236:239], v[100:103]
	v_mfma_f32_16x16x32_bf16 v[96:99], v[132:135], v[236:239], v[96:99]
	v_mfma_f32_16x16x32_bf16 v[140:143], v[128:131], v[216:219], v[140:143]
	v_mfma_f32_16x16x32_bf16 v[136:139], v[144:147], v[216:219], v[136:139]
	v_mfma_f32_16x16x32_bf16 v[116:119], v[128:131], v[224:227], v[116:119]
	v_mfma_f32_16x16x32_bf16 v[112:115], v[144:147], v[224:227], v[112:115]
	v_mfma_f32_16x16x32_bf16 v[108:111], v[128:131], v[232:235], v[108:111]
	v_mfma_f32_16x16x32_bf16 v[104:107], v[144:147], v[232:235], v[104:107]
	v_mfma_f32_16x16x32_bf16 v[100:103], v[128:131], v[240:243], v[100:103]
	v_mfma_f32_16x16x32_bf16 v[96:99], v[144:147], v[240:243], v[96:99]
	v_mfma_f32_16x16x32_bf16 v[60:63], v[148:151], v[212:215], v[60:63]
	v_mfma_f32_16x16x32_bf16 v[56:59], v[174:177], v[212:215], v[56:59]
	v_mfma_f32_16x16x32_bf16 v[52:55], v[148:151], v[220:223], v[52:55]
	v_mfma_f32_16x16x32_bf16 v[48:51], v[174:177], v[220:223], v[48:51]
	v_mfma_f32_16x16x32_bf16 v[44:47], v[148:151], v[228:231], v[44:47]
	v_mfma_f32_16x16x32_bf16 v[40:43], v[174:177], v[228:231], v[40:43]
	v_mfma_f32_16x16x32_bf16 v[36:39], v[148:151], v[236:239], v[36:39]
	v_mfma_f32_16x16x32_bf16 v[32:35], v[174:177], v[236:239], v[32:35]
	v_mfma_f32_16x16x32_bf16 v[60:63], v[170:173], v[216:219], v[60:63]
	v_mfma_f32_16x16x32_bf16 v[56:59], v[178:181], v[216:219], v[56:59]
	v_mfma_f32_16x16x32_bf16 v[52:55], v[170:173], v[224:227], v[52:55]
	v_mfma_f32_16x16x32_bf16 v[48:51], v[178:181], v[224:227], v[48:51]
	v_mfma_f32_16x16x32_bf16 v[44:47], v[170:173], v[232:235], v[44:47]
	v_mfma_f32_16x16x32_bf16 v[40:43], v[178:181], v[232:235], v[40:43]
	v_mfma_f32_16x16x32_bf16 v[36:39], v[170:173], v[240:243], v[36:39]
	v_mfma_f32_16x16x32_bf16 v[32:35], v[178:181], v[240:243], v[32:35]
	s_setprio 0
	s_barrier
; #define PG8_STAGE(bufoff, gbase, voff) do { _Pragma("unroll") for (int _i = 0; _i < 2; ++_i) \
;         __builtin_amdgcn_global_load_lds((const unsigned*)((const char*)(gbase) + (voff)[_i]), (PG8_LAS unsigned*)(lds + (bufoff) + ldsw + _i * 8192), 16, 0, 0); } while (0)
; #define PG8_LDA(dst, b, h) do { _Pragma("unroll") for (int m = 0; m < 4; ++m) _Pragma("unroll") for (int k = 0; k < 2; ++k) dst[m][k] = *(const PG8_LAS bf16x8*)(lds + PG8_SA(b, h) + aoff + m * 2048 + k * 1024); } while (0)
; #define PG8_MMA(ai, bj, At, Bt) do { __builtin_amdgcn_s_setprio(1); _Pragma("unroll") for (int m = 0; m < 4; ++m) _Pragma("unroll") for (int n = 0; n < 2; ++n) _Pragma("unroll") for (int k = 0; k < 2; ++k) \
;         acc[ai][bj][m][n] = __builtin_amdgcn_mfma_f32_16x16x32_bf16(Bt[n][k], At[m][k], acc[ai][bj][m][n], 0, 0, 0); __builtin_amdgcn_s_setprio(0); } while (0)
; #define PG8_WAIT_V(n) asm volatile("s_waitcnt vmcnt(" #n ")" ::: "memory")
; #define PG8_WAIT_L(n) asm volatile("s_waitcnt lgkmcnt(" #n ")" ::: "memory")
; #define PG8_BAR __builtin_amdgcn_s_barrier()
; #define PG8_SCHED __builtin_amdgcn_sched_barrier(0)
; template <class Epi, class Sched, bool ALIGN_EPI = false, bool SP2 = false>
; __device__ __forceinline__ void gemm_phase(PG8_LAS unsigned char* lds, const Gemm g, const Sched& S, const Epi& E) {
;     ...
;         for (int t = 0; t < nt; t += 2) {
;             const bool last = (t == nt - 2);
;     ...
;             PG8_LDA(At, 1, 1); PG8_STAGE(PG8_SB(1, 0), b3, voffB); PG8_STAGE(PG8_SB(1, 1), b3 + hstepB, voffB); PG8_STAGE(PG8_SA(1, 0), a3, voffA);
;             PG8_WAIT_V(8); PG8_WAIT_L(0); PG8_BAR; PG8_MMA(1, 0, At, B0); PG8_MMA(1, 1, At, B1); PG8_BAR; PG8_SCHED;
	s_add_i32 s46, s70, s52
	v_lshl_add_u64 v[206:207], v[206:207], 0, s[26:27]
	s_mov_b32 m0, s46
	ds_read_b128 v[212:215], v191 offset:49152
	ds_read_b128 v[216:219], v191 offset:50176
	ds_read_b128 v[220:223], v191 offset:51200
	ds_read_b128 v[224:227], v191 offset:52224
	ds_read_b128 v[228:231], v191 offset:53248
	ds_read_b128 v[232:235], v191 offset:54272
	ds_read_b128 v[236:239], v191 offset:55296
	ds_read_b128 v[240:243], v191 offset:56320
	global_load_lds_dwordx4 v[206:207], off
	s_add_i32 m0, s46, 0x2000
	s_add_u32 s44, s44, 0xb0080
	v_lshl_add_u64 v[206:207], v[244:245], 0, s[26:27]
	s_addc_u32 s45, s45, 0
	s_add_i32 s46, s71, s52
	global_load_lds_dwordx4 v[206:207], off
	v_lshl_add_u64 v[206:207], s[44:45], 0, v[154:155]
	s_mov_b32 m0, s46
	s_nop 0
	global_load_lds_dwordx4 v[206:207], off
	v_lshl_add_u64 v[206:207], s[44:45], 0, v[158:159]
	s_add_i32 m0, s46, 0x2000
	s_nop 0
	global_load_lds_dwordx4 v[206:207], off
	v_lshl_add_u64 v[206:207], s[42:43], 0, v[152:153]
	s_mov_b32 m0, s65
	s_nop 0
	global_load_lds_dwordx4 v[206:207], off
	v_lshl_add_u64 v[206:207], s[42:43], 0, v[156:157]
	s_mov_b32 m0, s66
	s_nop 0
	global_load_lds_dwordx4 v[206:207], off
	s_waitcnt vmcnt(8)
	s_waitcnt lgkmcnt(0)
	s_barrier
	s_setprio 1
	v_mfma_f32_16x16x32_bf16 v[92:95], v[124:127], v[212:215], v[92:95]
	v_mfma_f32_16x16x32_bf16 v[88:91], v[132:135], v[212:215], v[88:91]
	v_mfma_f32_16x16x32_bf16 v[84:87], v[124:127], v[220:223], v[84:87]
	v_mfma_f32_16x16x32_bf16 v[80:83], v[132:135], v[220:223], v[80:83]
	v_mfma_f32_16x16x32_bf16 v[76:79], v[124:127], v[228:231], v[76:79]
	v_mfma_f32_16x16x32_bf16 v[72:75], v[132:135], v[228:231], v[72:75]
	v_mfma_f32_16x16x32_bf16 v[68:71], v[124:127], v[236:239], v[68:71]
	v_mfma_f32_16x16x32_bf16 v[64:67], v[132:135], v[236:239], v[64:67]
	v_mfma_f32_16x16x32_bf16 v[92:95], v[128:131], v[216:219], v[92:95]
	v_mfma_f32_16x16x32_bf16 v[88:91], v[144:147], v[216:219], v[88:91]
	v_mfma_f32_16x16x32_bf16 v[84:87], v[128:131], v[224:227], v[84:87]
	v_mfma_f32_16x16x32_bf16 v[80:83], v[144:147], v[224:227], v[80:83]
	v_mfma_f32_16x16x32_bf16 v[76:79], v[128:131], v[232:235], v[76:79]
	v_mfma_f32_16x16x32_bf16 v[72:75], v[144:147], v[232:235], v[72:75]
	v_mfma_f32_16x16x32_bf16 v[68:71], v[128:131], v[240:243], v[68:71]
	v_mfma_f32_16x16x32_bf16 v[64:67], v[144:147], v[240:243], v[64:67]
	v_mfma_f32_16x16x32_bf16 v[28:31], v[148:151], v[212:215], v[28:31]
	v_mfma_f32_16x16x32_bf16 v[24:27], v[174:177], v[212:215], v[24:27]
	v_mfma_f32_16x16x32_bf16 v[20:23], v[148:151], v[220:223], v[20:23]
	v_mfma_f32_16x16x32_bf16 v[16:19], v[174:177], v[220:223], v[16:19]
	v_mfma_f32_16x16x32_bf16 v[12:15], v[148:151], v[228:231], v[12:15]
	v_mfma_f32_16x16x32_bf16 v[8:11], v[174:177], v[228:231], v[8:11]
	v_mfma_f32_16x16x32_bf16 v[4:7], v[148:151], v[236:239], v[4:7]
	v_mfma_f32_16x16x32_bf16 v[0:3], v[174:177], v[236:239], v[0:3]
	v_mfma_f32_16x16x32_bf16 v[28:31], v[170:173], v[216:219], v[28:31]
	v_mfma_f32_16x16x32_bf16 v[24:27], v[178:181], v[216:219], v[24:27]
	v_mfma_f32_16x16x32_bf16 v[20:23], v[170:173], v[224:227], v[20:23]
	v_mfma_f32_16x16x32_bf16 v[16:19], v[178:181], v[224:227], v[16:19]
	v_mfma_f32_16x16x32_bf16 v[12:15], v[170:173], v[232:235], v[12:15]
	v_mfma_f32_16x16x32_bf16 v[8:11], v[178:181], v[232:235], v[8:11]
	v_mfma_f32_16x16x32_bf16 v[4:7], v[170:173], v[240:243], v[4:7]
	v_mfma_f32_16x16x32_bf16 v[0:3], v[178:181], v[240:243], v[0:3]
	s_setprio 0
	s_barrier
	s_add_i32 s86, s86, 2
	s_add_u32 s40, s40, 0x100
	s_addc_u32 s41, s41, 0
	s_cmp_gt_u32 s86, 41
	s_cbranch_scc0 .LBB0_2888
	s_and_b64 vcc, exec, s[28:29]
	s_cbranch_vccz .LBB0_2891
	s_barrier

; #define PG8_STAGE(bufoff, gbase, voff) do { _Pragma("unroll") for (int _i = 0; _i < 2; ++_i) \
;         __builtin_amdgcn_global_load_lds((const unsigned*)((const char*)(gbase) + (voff)[_i]), (PG8_LAS unsigned*)(lds + (bufoff) + ldsw + _i * 8192), 16, 0, 0); } while (0)
; #define PG8_LDA(dst, b, h) do { _Pragma("unroll") for (int m = 0; m < 4; ++m) _Pragma("unroll") for (int k = 0; k < 2; ++k) dst[m][k] = *(const PG8_LAS bf16x8*)(lds + PG8_SA(b, h) + aoff + m * 2048 + k * 1024); } while (0)
; #define PG8_LDB(dst, b, h) do { _Pragma("unroll") for (int n = 0; n < 2; ++n) _Pragma("unroll") for (int k = 0; k < 2; ++k) dst[n][k] = *(const PG8_LAS bf16x8*)(lds + PG8_SB(b, h) + boff + n * 2048 + k * 1024); } while (0)
; #define PG8_MMA(ai, bj, At, Bt) do { __builtin_amdgcn_s_setprio(1); _Pragma("unroll") for (int m = 0; m < 4; ++m) _Pragma("unroll") for (int n = 0; n < 2; ++n) _Pragma("unroll") for (int k = 0; k < 2; ++k) \
;         acc[ai][bj][m][n] = __builtin_amdgcn_mfma_f32_16x16x32_bf16(Bt[n][k], At[m][k], acc[ai][bj][m][n], 0, 0, 0); __builtin_amdgcn_s_setprio(0); } while (0)
; #define PG8_WAIT_V(n) asm volatile("s_waitcnt vmcnt(" #n ")" ::: "memory")
; #define PG8_WAIT_L(n) asm volatile("s_waitcnt lgkmcnt(" #n ")" ::: "memory")
; #define PG8_BAR __builtin_amdgcn_s_barrier()
; #define PG8_SCHED __builtin_amdgcn_sched_barrier(0)
; template <class Epi, class Sched, bool ALIGN_EPI = false, bool SP2 = false>
; __device__ __forceinline__ void gemm_phase(PG8_LAS unsigned char* lds, const Gemm g, const Sched& S, const Epi& E) {
;     ...
;             const bool last = (t == nt - 2);
;             const char* a1 = cA + PG8_AK(t + 1);
;             const char* a2 = last ? nA : cA + PG8_AK(t + 2); const char* b2 = last ? nB : cB + (size_t)(t + 2) * kstep;
;             const char* a3 = last ? nA + PG8_AK(1) : cA + PG8_AK(t + 3); const char* b3 = b2 + kstep;
;             if (last && has_next) S.a_ready(nxt);
;             if constexpr (SP2) {
;             PG8_LDB(B0, 0, 0); PG8_LDB(B1, 0, 1); PG8_SCHED; PG8_LDA(At, 0, 0); PG8_STAGE(PG8_SA(1, 1), a1 + hstepA, voffA);
;             PG8_WAIT_V(8); PG8_WAIT_L(0); PG8_BAR; PG8_MMA(0, 0, At, B0); PG8_MMA(0, 1, At, B1); PG8_BAR; PG8_SCHED;
;             PG8_LDA(At, 0, 1); PG8_STAGE(PG8_SB(0, 0), b2, voffB); PG8_STAGE(PG8_SB(0, 1), b2 + hstepB, voffB); PG8_STAGE(PG8_SA(0, 0), a2, voffA);
.LBB0_2980:
	ds_read_b128 v[108:111], v191
	ds_read_b128 v[112:115], v191 offset:1024
	ds_read_b128 v[116:119], v191 offset:2048
	ds_read_b128 v[120:123], v191 offset:3072
	ds_read_b128 v[124:127], v193
	ds_read_b128 v[128:131], v193 offset:1024
	ds_read_b128 v[132:135], v193 offset:2048
	ds_read_b128 v[160:163], v193 offset:3072
	s_add_u32 s42, s38, s40
	s_addc_u32 s43, s39, s41
	s_add_u32 s46, s42, 0x100
	s_addc_u32 s47, s43, 0
	s_add_u32 s44, s80, s40
	s_addc_u32 s45, s81, s41
	s_add_u32 s42, s42, 0x180
	s_addc_u32 s43, s43, 0
	s_cmpk_eq_i32 s40, 0x700
	s_cselect_b32 s43, s79, s43
	s_cselect_b32 s42, s78, s42
	s_cselect_b32 s45, s27, s45
	s_cselect_b32 s44, s69, s44
	s_cselect_b32 s47, s3, s47
	s_cselect_b32 s46, s29, s46
	v_lshl_add_u64 v[242:243], v[106:107], 0, s[40:41]
	s_add_i32 m0, s54, 0xc000
	ds_read_b128 v[164:167], v187
	ds_read_b128 v[168:171], v187 offset:1024
	ds_read_b128 v[218:221], v187 offset:2048
	ds_read_b128 v[222:225], v187 offset:3072
	ds_read_b128 v[226:229], v187 offset:4096
	ds_read_b128 v[230:233], v187 offset:5120
	ds_read_b128 v[234:237], v187 offset:6144
	ds_read_b128 v[238:241], v187 offset:7168
	global_load_lds_dwordx4 v[242:243], off
	v_lshl_add_u64 v[242:243], v[104:105], 0, s[40:41]
	s_add_i32 m0, s54, 0xe000
	s_nop 0
	global_load_lds_dwordx4 v[242:243], off
	s_waitcnt vmcnt(8)
	s_waitcnt lgkmcnt(0)
	s_barrier
	s_setprio 1
	v_mfma_f32_16x16x32_bf16 v[156:159], v[108:111], v[164:167], v[156:159]
	v_mfma_f32_16x16x32_bf16 v[152:155], v[116:119], v[164:167], v[152:155]
	v_mfma_f32_16x16x32_bf16 v[148:151], v[108:111], v[218:221], v[148:151]
	v_mfma_f32_16x16x32_bf16 v[144:147], v[116:119], v[218:221], v[144:147]
	v_mfma_f32_16x16x32_bf16 v[140:143], v[108:111], v[226:229], v[140:143]
	v_mfma_f32_16x16x32_bf16 v[136:139], v[116:119], v[226:229], v[136:139]
	v_mfma_f32_16x16x32_bf16 v[100:103], v[108:111], v[234:237], v[100:103]
	v_mfma_f32_16x16x32_bf16 v[96:99], v[116:119], v[234:237], v[96:99]
	v_mfma_f32_16x16x32_bf16 v[156:159], v[112:115], v[168:171], v[156:159]
	v_mfma_f32_16x16x32_bf16 v[152:155], v[120:123], v[168:171], v[152:155]
	v_mfma_f32_16x16x32_bf16 v[148:151], v[112:115], v[222:225], v[148:151]
	v_mfma_f32_16x16x32_bf16 v[144:147], v[120:123], v[222:225], v[144:147]
	v_mfma_f32_16x16x32_bf16 v[140:143], v[112:115], v[230:233], v[140:143]
	v_mfma_f32_16x16x32_bf16 v[136:139], v[120:123], v[230:233], v[136:139]
	v_mfma_f32_16x16x32_bf16 v[100:103], v[112:115], v[238:241], v[100:103]
	v_mfma_f32_16x16x32_bf16 v[96:99], v[120:123], v[238:241], v[96:99]
	v_mfma_f32_16x16x32_bf16 v[60:63], v[124:127], v[164:167], v[60:63]
	v_mfma_f32_16x16x32_bf16 v[56:59], v[132:135], v[164:167], v[56:59]
	v_mfma_f32_16x16x32_bf16 v[52:55], v[124:127], v[218:221], v[52:55]
	v_mfma_f32_16x16x32_bf16 v[48:51], v[132:135], v[218:221], v[48:51]
	v_mfma_f32_16x16x32_bf16 v[44:47], v[124:127], v[226:229], v[44:47]
	v_mfma_f32_16x16x32_bf16 v[40:43], v[132:135], v[226:229], v[40:43]
	v_mfma_f32_16x16x32_bf16 v[36:39], v[124:127], v[234:237], v[36:39]
	v_mfma_f32_16x16x32_bf16 v[32:35], v[132:135], v[234:237], v[32:35]
	v_mfma_f32_16x16x32_bf16 v[60:63], v[128:131], v[168:171], v[60:63]
	v_mfma_f32_16x16x32_bf16 v[56:59], v[160:163], v[168:171], v[56:59]
	v_mfma_f32_16x16x32_bf16 v[52:55], v[128:131], v[222:225], v[52:55]
	v_mfma_f32_16x16x32_bf16 v[48:51], v[160:163], v[222:225], v[48:51]
	v_mfma_f32_16x16x32_bf16 v[44:47], v[128:131], v[230:233], v[44:47]
	v_mfma_f32_16x16x32_bf16 v[40:43], v[160:163], v[230:233], v[40:43]
	v_mfma_f32_16x16x32_bf16 v[36:39], v[128:131], v[238:241], v[36:39]
	v_mfma_f32_16x16x32_bf16 v[32:35], v[160:163], v[238:241], v[32:35]
	s_setprio 0
	s_barrier
	s_add_i32 s70, s66, s53
	v_lshl_add_u64 v[242:243], s[44:45], 0, v[174:175]
	s_mov_b32 m0, s70
	ds_read_b128 v[164:167], v187 offset:16384
	ds_read_b128 v[168:171], v187 offset:17408
	ds_read_b128 v[218:221], v187 offset:18432
	ds_read_b128 v[222:225], v187 offset:19456
	ds_read_b128 v[226:229], v187 offset:20480
	ds_read_b128 v[230:233], v187 offset:21504
	ds_read_b128 v[234:237], v187 offset:22528
	ds_read_b128 v[238:241], v187 offset:23552
	global_load_lds_dwordx4 v[242:243], off
	s_add_i32 m0, s70, 0x2000
	s_add_u32 s70, s44, 0x40000
	v_lshl_add_u64 v[244:245], s[44:45], 0, v[178:179]
	s_addc_u32 s71, s45, 0
	s_add_i32 s83, s67, s53
	global_load_lds_dwordx4 v[244:245], off
	v_lshl_add_u64 v[246:247], s[70:71], 0, v[174:175]
	s_mov_b32 m0, s83
	s_nop 0
	global_load_lds_dwordx4 v[246:247], off
	v_lshl_add_u64 v[246:247], s[70:71], 0, v[178:179]
	s_add_i32 m0, s83, 0x2000
	s_nop 0
	global_load_lds_dwordx4 v[246:247], off
	v_lshl_add_u64 v[246:247], s[46:47], 0, v[172:173]
	s_mov_b32 m0, s54
	s_nop 0
	global_load_lds_dwordx4 v[246:247], off
	v_lshl_add_u64 v[246:247], s[46:47], 0, v[176:177]
	s_mov_b32 m0, s55
	s_nop 0
	global_load_lds_dwordx4 v[246:247], off
	s_waitcnt vmcnt(8)
	s_waitcnt lgkmcnt(0)
	s_barrier
; #define PG8_STAGE(bufoff, gbase, voff) do { _Pragma("unroll") for (int _i = 0; _i < 2; ++_i) \
;         __builtin_amdgcn_global_load_lds((const unsigned*)((const char*)(gbase) + (voff)[_i]), (PG8_LAS unsigned*)(lds + (bufoff) + ldsw + _i * 8192), 16, 0, 0); } while (0)
; #define PG8_LDA(dst, b, h) do { _Pragma("unroll") for (int m = 0; m < 4; ++m) _Pragma("unroll") for (int k = 0; k < 2; ++k) dst[m][k] = *(const PG8_LAS bf16x8*)(lds + PG8_SA(b, h) + aoff + m * 2048 + k * 1024); } while (0)
; #define PG8_LDB(dst, b, h) do { _Pragma("unroll") for (int n = 0; n < 2; ++n) _Pragma("unroll") for (int k = 0; k < 2; ++k) dst[n][k] = *(const PG8_LAS bf16x8*)(lds + PG8_SB(b, h) + boff + n * 2048 + k * 1024); } while (0)
; #define PG8_MMA(ai, bj, At, Bt) do { __builtin_amdgcn_s_setprio(1); _Pragma("unroll") for (int m = 0; m < 4; ++m) _Pragma("unroll") for (int n = 0; n < 2; ++n) _Pragma("unroll") for (int k = 0; k < 2; ++k) \
;         acc[ai][bj][m][n] = __builtin_amdgcn_mfma_f32_16x16x32_bf16(Bt[n][k], At[m][k], acc[ai][bj][m][n], 0, 0, 0); __builtin_amdgcn_s_setprio(0); } while (0)
; #define PG8_WAIT_V(n) asm volatile("s_waitcnt vmcnt(" #n ")" ::: "memory")
; #define PG8_WAIT_L(n) asm volatile("s_waitcnt lgkmcnt(" #n ")" ::: "memory")
; #define PG8_BAR __builtin_amdgcn_s_barrier()
; #define PG8_SCHED __builtin_amdgcn_sched_barrier(0)
; template <class Epi, class Sched, bool ALIGN_EPI = false, bool SP2 = false>
; __device__ __forceinline__ void gemm_phase(PG8_LAS unsigned char* lds, const Gemm g, const Sched& S, const Epi& E) {
;     ...
;             PG8_WAIT_V(8); PG8_WAIT_L(0); PG8_BAR; PG8_MMA(1, 0, At, B0); PG8_MMA(1, 1, At, B1); PG8_BAR; PG8_SCHED;
;             PG8_LDB(B0, 1, 0); PG8_LDB(B1, 1, 1); PG8_SCHED; PG8_LDA(At, 1, 0); PG8_STAGE(PG8_SA(0, 1), a2 + hstepA, voffA);
;             PG8_WAIT_V(8); PG8_WAIT_L(0); PG8_BAR; PG8_MMA(0, 0, At, B0); PG8_MMA(0, 1, At, B1); PG8_BAR; PG8_SCHED;
	s_setprio 1
	v_mfma_f32_16x16x32_bf16 v[92:95], v[108:111], v[164:167], v[92:95]
	v_mfma_f32_16x16x32_bf16 v[88:91], v[116:119], v[164:167], v[88:91]
	v_mfma_f32_16x16x32_bf16 v[84:87], v[108:111], v[218:221], v[84:87]
	v_mfma_f32_16x16x32_bf16 v[80:83], v[116:119], v[218:221], v[80:83]
	v_mfma_f32_16x16x32_bf16 v[76:79], v[108:111], v[226:229], v[76:79]
	v_mfma_f32_16x16x32_bf16 v[72:75], v[116:119], v[226:229], v[72:75]
	v_mfma_f32_16x16x32_bf16 v[68:71], v[108:111], v[234:237], v[68:71]
	v_mfma_f32_16x16x32_bf16 v[64:67], v[116:119], v[234:237], v[64:67]
	v_mfma_f32_16x16x32_bf16 v[92:95], v[112:115], v[168:171], v[92:95]
	v_mfma_f32_16x16x32_bf16 v[88:91], v[120:123], v[168:171], v[88:91]
	v_mfma_f32_16x16x32_bf16 v[84:87], v[112:115], v[222:225], v[84:87]
	v_mfma_f32_16x16x32_bf16 v[80:83], v[120:123], v[222:225], v[80:83]
	v_mfma_f32_16x16x32_bf16 v[76:79], v[112:115], v[230:233], v[76:79]
	v_mfma_f32_16x16x32_bf16 v[72:75], v[120:123], v[230:233], v[72:75]
	v_mfma_f32_16x16x32_bf16 v[68:71], v[112:115], v[238:241], v[68:71]
	v_mfma_f32_16x16x32_bf16 v[64:67], v[120:123], v[238:241], v[64:67]
	v_mfma_f32_16x16x32_bf16 v[28:31], v[124:127], v[164:167], v[28:31]
	v_mfma_f32_16x16x32_bf16 v[24:27], v[132:135], v[164:167], v[24:27]
	v_mfma_f32_16x16x32_bf16 v[20:23], v[124:127], v[218:221], v[20:23]
	v_mfma_f32_16x16x32_bf16 v[16:19], v[132:135], v[218:221], v[16:19]
	v_mfma_f32_16x16x32_bf16 v[12:15], v[124:127], v[226:229], v[12:15]
	v_mfma_f32_16x16x32_bf16 v[8:11], v[132:135], v[226:229], v[8:11]
	v_mfma_f32_16x16x32_bf16 v[4:7], v[124:127], v[234:237], v[4:7]
	v_mfma_f32_16x16x32_bf16 v[0:3], v[132:135], v[234:237], v[0:3]
	v_mfma_f32_16x16x32_bf16 v[28:31], v[128:131], v[168:171], v[28:31]
	v_mfma_f32_16x16x32_bf16 v[24:27], v[160:163], v[168:171], v[24:27]
	v_mfma_f32_16x16x32_bf16 v[20:23], v[128:131], v[222:225], v[20:23]
	v_mfma_f32_16x16x32_bf16 v[16:19], v[160:163], v[222:225], v[16:19]
	v_mfma_f32_16x16x32_bf16 v[12:15], v[128:131], v[230:233], v[12:15]
	v_mfma_f32_16x16x32_bf16 v[8:11], v[160:163], v[230:233], v[8:11]
	v_mfma_f32_16x16x32_bf16 v[4:7], v[128:131], v[238:241], v[4:7]
	v_mfma_f32_16x16x32_bf16 v[0:3], v[160:163], v[238:241], v[0:3]
	s_setprio 0
	s_barrier
	s_add_i32 s70, 0, 0x18000
	s_add_i32 s71, 0, 0x1c000
	v_add_u32_e32 v120, s70, v181
	v_add_u32_e32 v160, s71, v181
	ds_read_b128 v[108:111], v120
	ds_read_b128 v[112:115], v120 offset:1024
	ds_read_b128 v[116:119], v120 offset:2048
	ds_read_b128 v[120:123], v120 offset:3072
	ds_read_b128 v[124:127], v160
	ds_read_b128 v[128:131], v160 offset:1024
	ds_read_b128 v[132:135], v160 offset:2048
	ds_read_b128 v[160:163], v160 offset:3072
	s_add_u32 s46, s46, 0x40000
	s_addc_u32 s47, s47, 0
	s_mov_b32 m0, s56
	v_lshl_add_u64 v[246:247], s[46:47], 0, v[172:173]
	ds_read_b128 v[164:167], v187 offset:32768
	ds_read_b128 v[168:171], v187 offset:33792
	ds_read_b128 v[218:221], v187 offset:34816
	ds_read_b128 v[222:225], v187 offset:35840
	ds_read_b128 v[226:229], v187 offset:36864
	ds_read_b128 v[230:233], v187 offset:37888
	ds_read_b128 v[234:237], v187 offset:38912
	ds_read_b128 v[238:241], v187 offset:39936
	global_load_lds_dwordx4 v[246:247], off
	v_lshl_add_u64 v[246:247], s[46:47], 0, v[176:177]
	s_mov_b32 m0, s57
	s_nop 0
	global_load_lds_dwordx4 v[246:247], off
	s_waitcnt vmcnt(8)
	s_waitcnt lgkmcnt(0)
	s_barrier
	s_setprio 1
	v_mfma_f32_16x16x32_bf16 v[156:159], v[108:111], v[164:167], v[156:159]
	v_mfma_f32_16x16x32_bf16 v[152:155], v[116:119], v[164:167], v[152:155]
	v_mfma_f32_16x16x32_bf16 v[148:151], v[108:111], v[218:221], v[148:151]
	v_mfma_f32_16x16x32_bf16 v[144:147], v[116:119], v[218:221], v[144:147]
	v_mfma_f32_16x16x32_bf16 v[140:143], v[108:111], v[226:229], v[140:143]
	v_mfma_f32_16x16x32_bf16 v[136:139], v[116:119], v[226:229], v[136:139]
	v_mfma_f32_16x16x32_bf16 v[100:103], v[108:111], v[234:237], v[100:103]
	v_mfma_f32_16x16x32_bf16 v[96:99], v[116:119], v[234:237], v[96:99]
	v_mfma_f32_16x16x32_bf16 v[156:159], v[112:115], v[168:171], v[156:159]
	v_mfma_f32_16x16x32_bf16 v[152:155], v[120:123], v[168:171], v[152:155]
	v_mfma_f32_16x16x32_bf16 v[148:151], v[112:115], v[222:225], v[148:151]
	v_mfma_f32_16x16x32_bf16 v[144:147], v[120:123], v[222:225], v[144:147]
	v_mfma_f32_16x16x32_bf16 v[140:143], v[112:115], v[230:233], v[140:143]
	v_mfma_f32_16x16x32_bf16 v[136:139], v[120:123], v[230:233], v[136:139]
	v_mfma_f32_16x16x32_bf16 v[100:103], v[112:115], v[238:241], v[100:103]
	v_mfma_f32_16x16x32_bf16 v[96:99], v[120:123], v[238:241], v[96:99]
	v_mfma_f32_16x16x32_bf16 v[60:63], v[124:127], v[164:167], v[60:63]
	v_mfma_f32_16x16x32_bf16 v[56:59], v[132:135], v[164:167], v[56:59]
	v_mfma_f32_16x16x32_bf16 v[52:55], v[124:127], v[218:221], v[52:55]
	v_mfma_f32_16x16x32_bf16 v[48:51], v[132:135], v[218:221], v[48:51]
	v_mfma_f32_16x16x32_bf16 v[44:47], v[124:127], v[226:229], v[44:47]
	v_mfma_f32_16x16x32_bf16 v[40:43], v[132:135], v[226:229], v[40:43]
	v_mfma_f32_16x16x32_bf16 v[36:39], v[124:127], v[234:237], v[36:39]
	v_mfma_f32_16x16x32_bf16 v[32:35], v[132:135], v[234:237], v[32:35]
	v_mfma_f32_16x16x32_bf16 v[60:63], v[128:131], v[168:171], v[60:63]
	v_mfma_f32_16x16x32_bf16 v[56:59], v[160:163], v[168:171], v[56:59]
	v_mfma_f32_16x16x32_bf16 v[52:55], v[128:131], v[222:225], v[52:55]
	v_mfma_f32_16x16x32_bf16 v[48:51], v[160:163], v[222:225], v[48:51]
	v_mfma_f32_16x16x32_bf16 v[44:47], v[128:131], v[230:233], v[44:47]
	v_mfma_f32_16x16x32_bf16 v[40:43], v[160:163], v[230:233], v[40:43]
	v_mfma_f32_16x16x32_bf16 v[36:39], v[128:131], v[238:241], v[36:39]
	v_mfma_f32_16x16x32_bf16 v[32:35], v[160:163], v[238:241], v[32:35]
	s_setprio 0
	s_barrier
; #define PG8_STAGE(bufoff, gbase, voff) do { _Pragma("unroll") for (int _i = 0; _i < 2; ++_i) \
;         __builtin_amdgcn_global_load_lds((const unsigned*)((const char*)(gbase) + (voff)[_i]), (PG8_LAS unsigned*)(lds + (bufoff) + ldsw + _i * 8192), 16, 0, 0); } while (0)
; #define PG8_LDA(dst, b, h) do { _Pragma("unroll") for (int m = 0; m < 4; ++m) _Pragma("unroll") for (int k = 0; k < 2; ++k) dst[m][k] = *(const PG8_LAS bf16x8*)(lds + PG8_SA(b, h) + aoff + m * 2048 + k * 1024); } while (0)
; #define PG8_MMA(ai, bj, At, Bt) do { __builtin_amdgcn_s_setprio(1); _Pragma("unroll") for (int m = 0; m < 4; ++m) _Pragma("unroll") for (int n = 0; n < 2; ++n) _Pragma("unroll") for (int k = 0; k < 2; ++k) \
;         acc[ai][bj][m][n] = __builtin_amdgcn_mfma_f32_16x16x32_bf16(Bt[n][k], At[m][k], acc[ai][bj][m][n], 0, 0, 0); __builtin_amdgcn_s_setprio(0); } while (0)
; #define PG8_WAIT_V(n) asm volatile("s_waitcnt vmcnt(" #n ")" ::: "memory")
; #define PG8_WAIT_L(n) asm volatile("s_waitcnt lgkmcnt(" #n ")" ::: "memory")
; #define PG8_BAR __builtin_amdgcn_s_barrier()
; #define PG8_SCHED __builtin_amdgcn_sched_barrier(0)
; template <class Epi, class Sched, bool ALIGN_EPI = false, bool SP2 = false>
; __device__ __forceinline__ void gemm_phase(PG8_LAS unsigned char* lds, const Gemm g, const Sched& S, const Epi& E) {
;     ...
;         for (int t = 0; t < nt; t += 2) {
;             const bool last = (t == nt - 2);
;     ...
;             PG8_LDA(At, 1, 1); PG8_STAGE(PG8_SB(1, 0), b3, voffB); PG8_STAGE(PG8_SB(1, 1), b3 + hstepB, voffB); PG8_STAGE(PG8_SA(1, 0), a3, voffA);
;             PG8_WAIT_V(8); PG8_WAIT_L(0); PG8_BAR; PG8_MMA(1, 0, At, B0); PG8_MMA(1, 1, At, B1); PG8_BAR; PG8_SCHED;
	s_add_i32 s46, s70, s53
	v_lshl_add_u64 v[242:243], v[242:243], 0, s[6:7]
	s_mov_b32 m0, s46
	ds_read_b128 v[164:167], v187 offset:49152
	ds_read_b128 v[168:171], v187 offset:50176
	ds_read_b128 v[218:221], v187 offset:51200
	ds_read_b128 v[222:225], v187 offset:52224
	ds_read_b128 v[226:229], v187 offset:53248
	ds_read_b128 v[230:233], v187 offset:54272
	ds_read_b128 v[234:237], v187 offset:55296
	ds_read_b128 v[238:241], v187 offset:56320
	global_load_lds_dwordx4 v[242:243], off
	s_add_i32 m0, s46, 0x2000
	s_add_u32 s44, s44, 0x40080
	v_lshl_add_u64 v[242:243], v[244:245], 0, s[6:7]
	s_addc_u32 s45, s45, 0
	s_add_i32 s46, s71, s53
	global_load_lds_dwordx4 v[242:243], off
	v_lshl_add_u64 v[242:243], s[44:45], 0, v[174:175]
	s_mov_b32 m0, s46
	s_nop 0
	global_load_lds_dwordx4 v[242:243], off
	v_lshl_add_u64 v[242:243], s[44:45], 0, v[178:179]
	s_add_i32 m0, s46, 0x2000
	s_nop 0
	global_load_lds_dwordx4 v[242:243], off
	v_lshl_add_u64 v[242:243], s[42:43], 0, v[172:173]
	s_mov_b32 m0, s63
	s_nop 0
	global_load_lds_dwordx4 v[242:243], off
	v_lshl_add_u64 v[242:243], s[42:43], 0, v[176:177]
	s_mov_b32 m0, s64
	s_nop 0
	global_load_lds_dwordx4 v[242:243], off
	s_waitcnt vmcnt(8)
	s_waitcnt lgkmcnt(0)
	s_barrier
	s_setprio 1
	v_mfma_f32_16x16x32_bf16 v[92:95], v[108:111], v[164:167], v[92:95]
	v_mfma_f32_16x16x32_bf16 v[88:91], v[116:119], v[164:167], v[88:91]
	v_mfma_f32_16x16x32_bf16 v[84:87], v[108:111], v[218:221], v[84:87]
	v_mfma_f32_16x16x32_bf16 v[80:83], v[116:119], v[218:221], v[80:83]
	v_mfma_f32_16x16x32_bf16 v[76:79], v[108:111], v[226:229], v[76:79]
	v_mfma_f32_16x16x32_bf16 v[72:75], v[116:119], v[226:229], v[72:75]
	v_mfma_f32_16x16x32_bf16 v[68:71], v[108:111], v[234:237], v[68:71]
	v_mfma_f32_16x16x32_bf16 v[64:67], v[116:119], v[234:237], v[64:67]
	v_mfma_f32_16x16x32_bf16 v[92:95], v[112:115], v[168:171], v[92:95]
	v_mfma_f32_16x16x32_bf16 v[88:91], v[120:123], v[168:171], v[88:91]
	v_mfma_f32_16x16x32_bf16 v[84:87], v[112:115], v[222:225], v[84:87]
	v_mfma_f32_16x16x32_bf16 v[80:83], v[120:123], v[222:225], v[80:83]
	v_mfma_f32_16x16x32_bf16 v[76:79], v[112:115], v[230:233], v[76:79]
	v_mfma_f32_16x16x32_bf16 v[72:75], v[120:123], v[230:233], v[72:75]
	v_mfma_f32_16x16x32_bf16 v[68:71], v[112:115], v[238:241], v[68:71]
	v_mfma_f32_16x16x32_bf16 v[64:67], v[120:123], v[238:241], v[64:67]
	v_mfma_f32_16x16x32_bf16 v[28:31], v[124:127], v[164:167], v[28:31]
	v_mfma_f32_16x16x32_bf16 v[24:27], v[132:135], v[164:167], v[24:27]
	v_mfma_f32_16x16x32_bf16 v[20:23], v[124:127], v[218:221], v[20:23]
	v_mfma_f32_16x16x32_bf16 v[16:19], v[132:135], v[218:221], v[16:19]
	v_mfma_f32_16x16x32_bf16 v[12:15], v[124:127], v[226:229], v[12:15]
	v_mfma_f32_16x16x32_bf16 v[8:11], v[132:135], v[226:229], v[8:11]
	v_mfma_f32_16x16x32_bf16 v[4:7], v[124:127], v[234:237], v[4:7]
	v_mfma_f32_16x16x32_bf16 v[0:3], v[132:135], v[234:237], v[0:3]
	v_mfma_f32_16x16x32_bf16 v[28:31], v[128:131], v[168:171], v[28:31]
	v_mfma_f32_16x16x32_bf16 v[24:27], v[160:163], v[168:171], v[24:27]
	v_mfma_f32_16x16x32_bf16 v[20:23], v[128:131], v[222:225], v[20:23]
	v_mfma_f32_16x16x32_bf16 v[16:19], v[160:163], v[222:225], v[16:19]
	v_mfma_f32_16x16x32_bf16 v[12:15], v[128:131], v[230:233], v[12:15]
	v_mfma_f32_16x16x32_bf16 v[8:11], v[160:163], v[230:233], v[8:11]
	v_mfma_f32_16x16x32_bf16 v[4:7], v[128:131], v[238:241], v[4:7]
	v_mfma_f32_16x16x32_bf16 v[0:3], v[160:163], v[238:241], v[0:3]
	s_setprio 0
	s_barrier
	s_add_i32 s82, s82, 2
	s_add_u32 s40, s40, 0x100
	s_addc_u32 s41, s41, 0
	s_cmp_gt_u32 s82, 13
	s_cbranch_scc0 .LBB0_2980
	s_and_b64 vcc, exec, s[22:23]
	s_cbranch_vccz .LBB0_2983
	s_barrier
